# K-loop load segments: ds_reads issued in first-use order of the next compute block, counted lgkmcnt waits regenerated per MFMA pair
# baseline (speedup 1.0000x reference)
; #define PG8_STAGE(bufoff, gbase, voff) do { _Pragma("unroll") for (int _i = 0; _i < 2; ++_i) \
;         __builtin_amdgcn_global_load_lds((const unsigned*)((const char*)(gbase) + (voff)[_i]), (PG8_LAS unsigned*)(lds + (bufoff) + ldsw + _i * 8192), 16, 0, 0); } while (0)
; #define PG8_LDA(dst, b, h) do { _Pragma("unroll") for (int m = 0; m < 4; ++m) _Pragma("unroll") for (int k = 0; k < 2; ++k) dst[m][k] = *(const PG8_LAS bf16x8*)(lds + PG8_SA(b, h) + aoff + m * 2048 + k * 1024); } while (0)
; #define PG8_LDB(dst, b, h) do { _Pragma("unroll") for (int n = 0; n < 2; ++n) _Pragma("unroll") for (int k = 0; k < 2; ++k) dst[n][k] = *(const PG8_LAS bf16x8*)(lds + PG8_SB(b, h) + boff + n * 2048 + k * 1024); } while (0)
; #define PG8_SCHED __builtin_amdgcn_sched_barrier(0)
; template <class Epi, class Sched>
; __device__ __forceinline__ void gemm_phase(PG8_LAS unsigned char* lds, const Gemm g, const Sched& S, const Epi& E) {
;     ...
;             const bool last = (t == nt - 2);
;             const char* a1 = cA + (size_t)(t + 1) * kstep;
;             const char* a2 = last ? nA : cA + (size_t)(t + 2) * kstep; const char* b2 = last ? nB : cB + (size_t)(t + 2) * kstep;
;             const char* a3 = a2 + kstep; const char* b3 = b2 + kstep;
;             if (last && has_next) S.a_ready(nxt);
;             PG8_LDB(B0, 0, 0); PG8_SCHED; PG8_LDA(At, 0, 0); PG8_STAGE(PG8_SA(1, 1), a1 + hstep, voffA);
.LBB0_267:
	s_add_u32 s16, s16, 0x80
	s_addc_u32 s17, s17, 0
	s_add_u32 s24, s20, 0x100
	s_addc_u32 s25, s21, 0
	s_mov_b32 s20, 0
	s_add_i32 s42, s20, 2
	s_add_u32 s22, s16, 0x80
	s_addc_u32 s21, s17, 0
	s_add_i32 s43, 0, 0x10000
	v_add_u32_e32 v142, s43, v170
	ds_read_b128 v[130:133], v142
	ds_read_b128 v[134:137], v142 offset:1024
	ds_read_b128 v[138:141], v142 offset:2048
	ds_read_b128 v[142:145], v142 offset:3072
	s_cmp_eq_u32 s66, s20
	s_cselect_b32 s20, s2, s22
	s_cselect_b32 s21, s3, s21
	s_cselect_b32 s23, s13, s25
	s_cselect_b32 s22, s12, s24
	v_lshl_add_u64 v[168:169], s[16:17], 0, v[164:165]
	s_add_i32 m0, s36, 0xc000
	ds_read_b128 v[176:179], v172
	ds_read_b128 v[184:187], v172 offset:2048
	ds_read_b128 v[192:195], v172 offset:4096
	ds_read_b128 v[200:203], v172 offset:6144
	ds_read_b128 v[180:183], v172 offset:1024
	ds_read_b128 v[188:191], v172 offset:3072
	ds_read_b128 v[196:199], v172 offset:5120
	ds_read_b128 v[204:207], v172 offset:7168
	global_load_lds_dwordx4 v[168:169], off
	s_add_i32 m0, s36, 0xe000
	v_lshl_add_u64 v[168:169], s[16:17], 0, v[166:167]
	global_load_lds_dwordx4 v[168:169], off
	s_waitcnt lgkmcnt(8)
	s_barrier

; #define PG8_MMA(ai, bj, At, Bt) do { __builtin_amdgcn_s_setprio(1); _Pragma("unroll") for (int m = 0; m < 4; ++m) _Pragma("unroll") for (int n = 0; n < 2; ++n) _Pragma("unroll") for (int k = 0; k < 2; ++k) \
;         acc[ai][bj][m][n] = __builtin_amdgcn_mfma_f32_16x16x32_bf16(Bt[n][k], At[m][k], acc[ai][bj][m][n], 0, 0, 0); __builtin_amdgcn_s_setprio(0); } while (0)
; #define PG8_WAIT_L(n) asm volatile("s_waitcnt lgkmcnt(" #n ")" ::: "memory")
; #define PG8_BAR __builtin_amdgcn_s_barrier()
; #define PG8_SCHED __builtin_amdgcn_sched_barrier(0)
; template <class Epi, class Sched>
; __device__ __forceinline__ void gemm_phase(PG8_LAS unsigned char* lds, const Gemm g, const Sched& S, const Epi& E) {
;     ...
;             PG8_WAIT_L(8); PG8_BAR; PG8_WAIT_L(0); PG8_MMA(0, 0, At, B0); PG8_BAR; PG8_SCHED;
	s_waitcnt lgkmcnt(7)
	v_mfma_f32_16x16x32_bf16 v[126:129], v[130:133], v[176:179], 0
	v_mfma_f32_16x16x32_bf16 v[122:125], v[138:141], v[176:179], 0

; #define PG8_MMA(ai, bj, At, Bt) do { __builtin_amdgcn_s_setprio(1); _Pragma("unroll") for (int m = 0; m < 4; ++m) _Pragma("unroll") for (int n = 0; n < 2; ++n) _Pragma("unroll") for (int k = 0; k < 2; ++k) \
;         acc[ai][bj][m][n] = __builtin_amdgcn_mfma_f32_16x16x32_bf16(Bt[n][k], At[m][k], acc[ai][bj][m][n], 0, 0, 0); __builtin_amdgcn_s_setprio(0); } while (0)
; #define PG8_WAIT_L(n) asm volatile("s_waitcnt lgkmcnt(" #n ")" ::: "memory")
; #define PG8_BAR __builtin_amdgcn_s_barrier()
; #define PG8_SCHED __builtin_amdgcn_sched_barrier(0)
; template <class Epi, class Sched>
; __device__ __forceinline__ void gemm_phase(PG8_LAS unsigned char* lds, const Gemm g, const Sched& S, const Epi& E) {
;     ...
;             PG8_WAIT_L(8); PG8_BAR; PG8_WAIT_L(0); PG8_MMA(0, 0, At, B0); PG8_BAR; PG8_SCHED;
	s_waitcnt lgkmcnt(6)
	v_mfma_f32_16x16x32_bf16 v[114:117], v[130:133], v[184:187], 0
	v_mfma_f32_16x16x32_bf16 v[110:113], v[138:141], v[184:187], 0

; #define PG8_MMA(ai, bj, At, Bt) do { __builtin_amdgcn_s_setprio(1); _Pragma("unroll") for (int m = 0; m < 4; ++m) _Pragma("unroll") for (int n = 0; n < 2; ++n) _Pragma("unroll") for (int k = 0; k < 2; ++k) \
;         acc[ai][bj][m][n] = __builtin_amdgcn_mfma_f32_16x16x32_bf16(Bt[n][k], At[m][k], acc[ai][bj][m][n], 0, 0, 0); __builtin_amdgcn_s_setprio(0); } while (0)
; #define PG8_WAIT_L(n) asm volatile("s_waitcnt lgkmcnt(" #n ")" ::: "memory")
; #define PG8_BAR __builtin_amdgcn_s_barrier()
; #define PG8_SCHED __builtin_amdgcn_sched_barrier(0)
; template <class Epi, class Sched>
; __device__ __forceinline__ void gemm_phase(PG8_LAS unsigned char* lds, const Gemm g, const Sched& S, const Epi& E) {
;     ...
;             PG8_WAIT_L(8); PG8_BAR; PG8_WAIT_L(0); PG8_MMA(0, 0, At, B0); PG8_BAR; PG8_SCHED;
	s_waitcnt lgkmcnt(5)
	v_mfma_f32_16x16x32_bf16 v[98:101], v[130:133], v[192:195], 0
	v_mfma_f32_16x16x32_bf16 v[94:97], v[138:141], v[192:195], 0

; #define PG8_MMA(ai, bj, At, Bt) do { __builtin_amdgcn_s_setprio(1); _Pragma("unroll") for (int m = 0; m < 4; ++m) _Pragma("unroll") for (int n = 0; n < 2; ++n) _Pragma("unroll") for (int k = 0; k < 2; ++k) \
;         acc[ai][bj][m][n] = __builtin_amdgcn_mfma_f32_16x16x32_bf16(Bt[n][k], At[m][k], acc[ai][bj][m][n], 0, 0, 0); __builtin_amdgcn_s_setprio(0); } while (0)
; #define PG8_WAIT_L(n) asm volatile("s_waitcnt lgkmcnt(" #n ")" ::: "memory")
; #define PG8_BAR __builtin_amdgcn_s_barrier()
; #define PG8_SCHED __builtin_amdgcn_sched_barrier(0)
; template <class Epi, class Sched>
; __device__ __forceinline__ void gemm_phase(PG8_LAS unsigned char* lds, const Gemm g, const Sched& S, const Epi& E) {
;     ...
;             PG8_WAIT_L(8); PG8_BAR; PG8_WAIT_L(0); PG8_MMA(0, 0, At, B0); PG8_BAR; PG8_SCHED;
	s_waitcnt lgkmcnt(4)
	v_mfma_f32_16x16x32_bf16 v[82:85], v[130:133], v[200:203], 0
	v_mfma_f32_16x16x32_bf16 v[78:81], v[138:141], v[200:203], 0
	s_waitcnt lgkmcnt(3)
	v_mfma_f32_16x16x32_bf16 v[126:129], v[134:137], v[180:183], v[126:129]
	v_mfma_f32_16x16x32_bf16 v[122:125], v[142:145], v[180:183], v[122:125]
	s_waitcnt lgkmcnt(2)
	v_mfma_f32_16x16x32_bf16 v[114:117], v[134:137], v[188:191], v[114:117]
	v_mfma_f32_16x16x32_bf16 v[110:113], v[142:145], v[188:191], v[110:113]
	s_waitcnt lgkmcnt(1)
	v_mfma_f32_16x16x32_bf16 v[98:101], v[134:137], v[196:199], v[98:101]
	v_mfma_f32_16x16x32_bf16 v[94:97], v[142:145], v[196:199], v[94:97]

; #define PG8_STAGE(bufoff, gbase, voff) do { _Pragma("unroll") for (int _i = 0; _i < 2; ++_i) \
;         __builtin_amdgcn_global_load_lds((const unsigned*)((const char*)(gbase) + (voff)[_i]), (PG8_LAS unsigned*)(lds + (bufoff) + ldsw + _i * 8192), 16, 0, 0); } while (0)
; #define PG8_LDB(dst, b, h) do { _Pragma("unroll") for (int n = 0; n < 2; ++n) _Pragma("unroll") for (int k = 0; k < 2; ++k) dst[n][k] = *(const PG8_LAS bf16x8*)(lds + PG8_SB(b, h) + boff + n * 2048 + k * 1024); } while (0)
; #define PG8_MMA(ai, bj, At, Bt) do { __builtin_amdgcn_s_setprio(1); _Pragma("unroll") for (int m = 0; m < 4; ++m) _Pragma("unroll") for (int n = 0; n < 2; ++n) _Pragma("unroll") for (int k = 0; k < 2; ++k) \
;         acc[ai][bj][m][n] = __builtin_amdgcn_mfma_f32_16x16x32_bf16(Bt[n][k], At[m][k], acc[ai][bj][m][n], 0, 0, 0); __builtin_amdgcn_s_setprio(0); } while (0)
; #define PG8_WAIT_L(n) asm volatile("s_waitcnt lgkmcnt(" #n ")" ::: "memory")
; #define PG8_BAR __builtin_amdgcn_s_barrier()
; #define PG8_SCHED __builtin_amdgcn_sched_barrier(0)
; template <class Epi, class Sched>
; __device__ __forceinline__ void gemm_phase(PG8_LAS unsigned char* lds, const Gemm g, const Sched& S, const Epi& E) {
;     ...
;             PG8_WAIT_L(8); PG8_BAR; PG8_WAIT_L(0); PG8_MMA(0, 0, At, B0); PG8_BAR; PG8_SCHED;
;             PG8_LDB(B1, 0, 1); PG8_STAGE(PG8_SB(0, 0), b2, voffB);
;             PG8_BAR; PG8_WAIT_L(0); PG8_MMA(0, 1, At, B1); PG8_BAR;
	s_waitcnt lgkmcnt(0)
	v_mfma_f32_16x16x32_bf16 v[82:85], v[134:137], v[204:207], v[82:85]
	v_mfma_f32_16x16x32_bf16 v[78:81], v[142:145], v[204:207], v[78:81]
	s_barrier
	s_add_i32 s44, 0, 0x14000
	v_add_u32_e32 v168, s44, v170
	s_add_i32 s43, s43, s35
	ds_read_b128 v[208:211], v168
	ds_read_b128 v[216:219], v168 offset:2048
	ds_read_b128 v[212:215], v168 offset:1024
	ds_read_b128 v[234:237], v168 offset:3072
	v_lshl_add_u64 v[168:169], s[22:23], 0, v[48:49]
	s_mov_b32 m0, s43
	v_lshl_add_u64 v[224:225], s[22:23], 0, v[146:147]
	global_load_lds_dwordx4 v[168:169], off
	s_add_i32 m0, s43, 0x2000
	s_nop 0
	global_load_lds_dwordx4 v[224:225], off
	s_barrier

; #define PG8_MMA(ai, bj, At, Bt) do { __builtin_amdgcn_s_setprio(1); _Pragma("unroll") for (int m = 0; m < 4; ++m) _Pragma("unroll") for (int n = 0; n < 2; ++n) _Pragma("unroll") for (int k = 0; k < 2; ++k) \
;         acc[ai][bj][m][n] = __builtin_amdgcn_mfma_f32_16x16x32_bf16(Bt[n][k], At[m][k], acc[ai][bj][m][n], 0, 0, 0); __builtin_amdgcn_s_setprio(0); } while (0)
; #define PG8_WAIT_L(n) asm volatile("s_waitcnt lgkmcnt(" #n ")" ::: "memory")
; #define PG8_BAR __builtin_amdgcn_s_barrier()
; template <class Epi, class Sched>
; __device__ __forceinline__ void gemm_phase(PG8_LAS unsigned char* lds, const Gemm g, const Sched& S, const Epi& E) {
;     ...
;             PG8_BAR; PG8_WAIT_L(0); PG8_MMA(0, 1, At, B1); PG8_BAR;
	s_waitcnt lgkmcnt(3)
	v_mfma_f32_16x16x32_bf16 v[118:121], v[208:211], v[176:179], 0

; #define PG8_MMA(ai, bj, At, Bt) do { __builtin_amdgcn_s_setprio(1); _Pragma("unroll") for (int m = 0; m < 4; ++m) _Pragma("unroll") for (int n = 0; n < 2; ++n) _Pragma("unroll") for (int k = 0; k < 2; ++k) \
;         acc[ai][bj][m][n] = __builtin_amdgcn_mfma_f32_16x16x32_bf16(Bt[n][k], At[m][k], acc[ai][bj][m][n], 0, 0, 0); __builtin_amdgcn_s_setprio(0); } while (0)
; #define PG8_WAIT_L(n) asm volatile("s_waitcnt lgkmcnt(" #n ")" ::: "memory")
; #define PG8_BAR __builtin_amdgcn_s_barrier()
; template <class Epi, class Sched>
; __device__ __forceinline__ void gemm_phase(PG8_LAS unsigned char* lds, const Gemm g, const Sched& S, const Epi& E) {
;     ...
;             PG8_BAR; PG8_WAIT_L(0); PG8_MMA(0, 1, At, B1); PG8_BAR;
	s_waitcnt lgkmcnt(2)
	v_mfma_f32_16x16x32_bf16 v[106:109], v[216:219], v[176:179], 0
	v_mfma_f32_16x16x32_bf16 v[102:105], v[208:211], v[184:187], 0
	v_mfma_f32_16x16x32_bf16 v[90:93], v[216:219], v[184:187], 0
	v_mfma_f32_16x16x32_bf16 v[86:89], v[208:211], v[192:195], 0
	v_mfma_f32_16x16x32_bf16 v[74:77], v[216:219], v[192:195], 0
	v_mfma_f32_16x16x32_bf16 v[70:73], v[208:211], v[200:203], 0
	v_mfma_f32_16x16x32_bf16 v[66:69], v[216:219], v[200:203], 0
	s_waitcnt lgkmcnt(1)
	v_mfma_f32_16x16x32_bf16 v[118:121], v[212:215], v[180:183], v[118:121]

; #define PG8_STAGE(bufoff, gbase, voff) do { _Pragma("unroll") for (int _i = 0; _i < 2; ++_i) \
;         __builtin_amdgcn_global_load_lds((const unsigned*)((const char*)(gbase) + (voff)[_i]), (PG8_LAS unsigned*)(lds + (bufoff) + ldsw + _i * 8192), 16, 0, 0); } while (0)
; #define PG8_LDA(dst, b, h) do { _Pragma("unroll") for (int m = 0; m < 4; ++m) _Pragma("unroll") for (int k = 0; k < 2; ++k) dst[m][k] = *(const PG8_LAS bf16x8*)(lds + PG8_SA(b, h) + aoff + m * 2048 + k * 1024); } while (0)
; #define PG8_MMA(ai, bj, At, Bt) do { __builtin_amdgcn_s_setprio(1); _Pragma("unroll") for (int m = 0; m < 4; ++m) _Pragma("unroll") for (int n = 0; n < 2; ++n) _Pragma("unroll") for (int k = 0; k < 2; ++k) \
;         acc[ai][bj][m][n] = __builtin_amdgcn_mfma_f32_16x16x32_bf16(Bt[n][k], At[m][k], acc[ai][bj][m][n], 0, 0, 0); __builtin_amdgcn_s_setprio(0); } while (0)
; #define PG8_WAIT_L(n) asm volatile("s_waitcnt lgkmcnt(" #n ")" ::: "memory")
; #define PG8_BAR __builtin_amdgcn_s_barrier()
; #define PG8_SCHED __builtin_amdgcn_sched_barrier(0)
; template <class Epi, class Sched>
; __device__ __forceinline__ void gemm_phase(PG8_LAS unsigned char* lds, const Gemm g, const Sched& S, const Epi& E) {
;     ...
;             PG8_BAR; PG8_WAIT_L(0); PG8_MMA(0, 1, At, B1); PG8_BAR;
;             PG8_LDA(At, 0, 1); PG8_STAGE(PG8_SA(0, 0), a2, voffA);
;             PG8_BAR; PG8_WAIT_L(0); PG8_MMA(1, 0, At, B0); PG8_BAR; PG8_SCHED;
	s_waitcnt lgkmcnt(0)
	v_mfma_f32_16x16x32_bf16 v[106:109], v[234:237], v[180:183], v[106:109]
	v_mfma_f32_16x16x32_bf16 v[102:105], v[212:215], v[188:191], v[102:105]
	v_mfma_f32_16x16x32_bf16 v[90:93], v[234:237], v[188:191], v[90:93]
	v_mfma_f32_16x16x32_bf16 v[86:89], v[212:215], v[196:199], v[86:89]
	v_mfma_f32_16x16x32_bf16 v[74:77], v[234:237], v[196:199], v[74:77]
	v_mfma_f32_16x16x32_bf16 v[70:73], v[212:215], v[204:207], v[70:73]
	v_mfma_f32_16x16x32_bf16 v[66:69], v[234:237], v[204:207], v[66:69]
	s_mov_b32 m0, s36
	v_lshl_add_u64 v[228:229], s[20:21], 0, v[48:49]
	s_barrier
	ds_read_b128 v[176:179], v172 offset:16384
	ds_read_b128 v[184:187], v172 offset:18432
	ds_read_b128 v[192:195], v172 offset:20480
	ds_read_b128 v[200:203], v172 offset:22528
	ds_read_b128 v[180:183], v172 offset:17408
	ds_read_b128 v[188:191], v172 offset:19456
	ds_read_b128 v[196:199], v172 offset:21504
	ds_read_b128 v[204:207], v172 offset:23552
	global_load_lds_dwordx4 v[228:229], off
	s_mov_b32 m0, s37
	v_lshl_add_u64 v[238:239], s[20:21], 0, v[146:147]
	global_load_lds_dwordx4 v[238:239], off
	s_barrier

; #define PG8_MMA(ai, bj, At, Bt) do { __builtin_amdgcn_s_setprio(1); _Pragma("unroll") for (int m = 0; m < 4; ++m) _Pragma("unroll") for (int n = 0; n < 2; ++n) _Pragma("unroll") for (int k = 0; k < 2; ++k) \
;         acc[ai][bj][m][n] = __builtin_amdgcn_mfma_f32_16x16x32_bf16(Bt[n][k], At[m][k], acc[ai][bj][m][n], 0, 0, 0); __builtin_amdgcn_s_setprio(0); } while (0)
; #define PG8_WAIT_L(n) asm volatile("s_waitcnt lgkmcnt(" #n ")" ::: "memory")
; #define PG8_BAR __builtin_amdgcn_s_barrier()
; #define PG8_SCHED __builtin_amdgcn_sched_barrier(0)
; template <class Epi, class Sched>
; __device__ __forceinline__ void gemm_phase(PG8_LAS unsigned char* lds, const Gemm g, const Sched& S, const Epi& E) {
;     ...
;             PG8_BAR; PG8_WAIT_L(0); PG8_MMA(1, 0, At, B0); PG8_BAR; PG8_SCHED;
	s_waitcnt lgkmcnt(7)
	v_mfma_f32_16x16x32_bf16 v[62:65], v[130:133], v[176:179], 0
	v_mfma_f32_16x16x32_bf16 v[58:61], v[138:141], v[176:179], 0

; #define PG8_MMA(ai, bj, At, Bt) do { __builtin_amdgcn_s_setprio(1); _Pragma("unroll") for (int m = 0; m < 4; ++m) _Pragma("unroll") for (int n = 0; n < 2; ++n) _Pragma("unroll") for (int k = 0; k < 2; ++k) \
;         acc[ai][bj][m][n] = __builtin_amdgcn_mfma_f32_16x16x32_bf16(Bt[n][k], At[m][k], acc[ai][bj][m][n], 0, 0, 0); __builtin_amdgcn_s_setprio(0); } while (0)
; #define PG8_WAIT_L(n) asm volatile("s_waitcnt lgkmcnt(" #n ")" ::: "memory")
; #define PG8_BAR __builtin_amdgcn_s_barrier()
; #define PG8_SCHED __builtin_amdgcn_sched_barrier(0)
; template <class Epi, class Sched>
; __device__ __forceinline__ void gemm_phase(PG8_LAS unsigned char* lds, const Gemm g, const Sched& S, const Epi& E) {
;     ...
;             PG8_BAR; PG8_WAIT_L(0); PG8_MMA(1, 0, At, B0); PG8_BAR; PG8_SCHED;
	s_waitcnt lgkmcnt(6)
	v_mfma_f32_16x16x32_bf16 v[50:53], v[130:133], v[184:187], 0
	v_mfma_f32_16x16x32_bf16 v[44:47], v[138:141], v[184:187], 0

; #define PG8_MMA(ai, bj, At, Bt) do { __builtin_amdgcn_s_setprio(1); _Pragma("unroll") for (int m = 0; m < 4; ++m) _Pragma("unroll") for (int n = 0; n < 2; ++n) _Pragma("unroll") for (int k = 0; k < 2; ++k) \
;         acc[ai][bj][m][n] = __builtin_amdgcn_mfma_f32_16x16x32_bf16(Bt[n][k], At[m][k], acc[ai][bj][m][n], 0, 0, 0); __builtin_amdgcn_s_setprio(0); } while (0)
; #define PG8_WAIT_L(n) asm volatile("s_waitcnt lgkmcnt(" #n ")" ::: "memory")
; #define PG8_BAR __builtin_amdgcn_s_barrier()
; #define PG8_SCHED __builtin_amdgcn_sched_barrier(0)
; template <class Epi, class Sched>
; __device__ __forceinline__ void gemm_phase(PG8_LAS unsigned char* lds, const Gemm g, const Sched& S, const Epi& E) {
;     ...
;             PG8_BAR; PG8_WAIT_L(0); PG8_MMA(1, 0, At, B0); PG8_BAR; PG8_SCHED;
	s_waitcnt lgkmcnt(5)
	v_mfma_f32_16x16x32_bf16 v[32:35], v[130:133], v[192:195], 0
	v_mfma_f32_16x16x32_bf16 v[28:31], v[138:141], v[192:195], 0

; #define PG8_MMA(ai, bj, At, Bt) do { __builtin_amdgcn_s_setprio(1); _Pragma("unroll") for (int m = 0; m < 4; ++m) _Pragma("unroll") for (int n = 0; n < 2; ++n) _Pragma("unroll") for (int k = 0; k < 2; ++k) \
;         acc[ai][bj][m][n] = __builtin_amdgcn_mfma_f32_16x16x32_bf16(Bt[n][k], At[m][k], acc[ai][bj][m][n], 0, 0, 0); __builtin_amdgcn_s_setprio(0); } while (0)
; #define PG8_WAIT_L(n) asm volatile("s_waitcnt lgkmcnt(" #n ")" ::: "memory")
; #define PG8_BAR __builtin_amdgcn_s_barrier()
; #define PG8_SCHED __builtin_amdgcn_sched_barrier(0)
; template <class Epi, class Sched>
; __device__ __forceinline__ void gemm_phase(PG8_LAS unsigned char* lds, const Gemm g, const Sched& S, const Epi& E) {
;     ...
;             PG8_BAR; PG8_WAIT_L(0); PG8_MMA(1, 0, At, B0); PG8_BAR; PG8_SCHED;
	s_waitcnt lgkmcnt(4)
	v_mfma_f32_16x16x32_bf16 v[16:19], v[130:133], v[200:203], 0
	v_mfma_f32_16x16x32_bf16 v[12:15], v[138:141], v[200:203], 0
	s_waitcnt lgkmcnt(3)
	v_mfma_f32_16x16x32_bf16 v[62:65], v[134:137], v[180:183], v[62:65]
	v_mfma_f32_16x16x32_bf16 v[58:61], v[142:145], v[180:183], v[58:61]
	s_waitcnt lgkmcnt(2)
	v_mfma_f32_16x16x32_bf16 v[50:53], v[134:137], v[188:191], v[50:53]
	v_mfma_f32_16x16x32_bf16 v[44:47], v[142:145], v[188:191], v[44:47]
	s_waitcnt lgkmcnt(1)
	v_mfma_f32_16x16x32_bf16 v[32:35], v[134:137], v[196:199], v[32:35]
	v_mfma_f32_16x16x32_bf16 v[28:31], v[142:145], v[196:199], v[28:31]

; #define PG8_STAGE(bufoff, gbase, voff) do { _Pragma("unroll") for (int _i = 0; _i < 2; ++_i) \
;         __builtin_amdgcn_global_load_lds((const unsigned*)((const char*)(gbase) + (voff)[_i]), (PG8_LAS unsigned*)(lds + (bufoff) + ldsw + _i * 8192), 16, 0, 0); } while (0)
; #define PG8_LDA(dst, b, h) do { _Pragma("unroll") for (int m = 0; m < 4; ++m) _Pragma("unroll") for (int k = 0; k < 2; ++k) dst[m][k] = *(const PG8_LAS bf16x8*)(lds + PG8_SA(b, h) + aoff + m * 2048 + k * 1024); } while (0)
; #define PG8_LDB(dst, b, h) do { _Pragma("unroll") for (int n = 0; n < 2; ++n) _Pragma("unroll") for (int k = 0; k < 2; ++k) dst[n][k] = *(const PG8_LAS bf16x8*)(lds + PG8_SB(b, h) + boff + n * 2048 + k * 1024); } while (0)
; #define PG8_MMA(ai, bj, At, Bt) do { __builtin_amdgcn_s_setprio(1); _Pragma("unroll") for (int m = 0; m < 4; ++m) _Pragma("unroll") for (int n = 0; n < 2; ++n) _Pragma("unroll") for (int k = 0; k < 2; ++k) \
;         acc[ai][bj][m][n] = __builtin_amdgcn_mfma_f32_16x16x32_bf16(Bt[n][k], At[m][k], acc[ai][bj][m][n], 0, 0, 0); __builtin_amdgcn_s_setprio(0); } while (0)
; #define PG8_WAIT_V(n) asm volatile("s_waitcnt vmcnt(" #n ")" ::: "memory")
; #define PG8_WAIT_L(n) asm volatile("s_waitcnt lgkmcnt(" #n ")" ::: "memory")
; #define PG8_BAR __builtin_amdgcn_s_barrier()
; #define PG8_SCHED __builtin_amdgcn_sched_barrier(0)
; template <class Epi, class Sched>
; __device__ __forceinline__ void gemm_phase(PG8_LAS unsigned char* lds, const Gemm g, const Sched& S, const Epi& E) {
;     ...
;             PG8_BAR; PG8_WAIT_L(0); PG8_MMA(1, 0, At, B0); PG8_BAR; PG8_SCHED;
;             PG8_STAGE(PG8_SB(0, 1), b2 + hstep, voffB);
;             PG8_WAIT_V(6); PG8_BAR; PG8_MMA(1, 1, At, B1); PG8_BAR;
;             PG8_LDB(B0, 1, 0); PG8_SCHED; PG8_LDA(At, 1, 0); PG8_STAGE(PG8_SA(0, 1), a2 + hstep, voffA);
;             PG8_WAIT_L(8); PG8_BAR; PG8_WAIT_L(0); PG8_MMA(0, 0, At, B0); PG8_BAR; PG8_SCHED;
	s_waitcnt lgkmcnt(0)
	v_mfma_f32_16x16x32_bf16 v[16:19], v[134:137], v[204:207], v[16:19]
	v_mfma_f32_16x16x32_bf16 v[12:15], v[142:145], v[204:207], v[12:15]
	s_barrier
	s_add_u32 s22, s22, s10
	s_addc_u32 s23, s23, 0
	s_add_i32 s43, s44, s35
	v_lshl_add_u64 v[240:241], s[22:23], 0, v[48:49]
	s_mov_b32 m0, s43
	v_lshl_add_u64 v[242:243], s[22:23], 0, v[146:147]
	global_load_lds_dwordx4 v[240:241], off
	s_add_i32 m0, s43, 0x2000
	s_nop 0
	global_load_lds_dwordx4 v[242:243], off
	s_waitcnt vmcnt(6)
	s_barrier
	v_mfma_f32_16x16x32_bf16 v[54:57], v[208:211], v[176:179], 0
	v_mfma_f32_16x16x32_bf16 v[40:43], v[216:219], v[176:179], 0
	v_mfma_f32_16x16x32_bf16 v[36:39], v[208:211], v[184:187], 0
	v_mfma_f32_16x16x32_bf16 v[24:27], v[216:219], v[184:187], 0
	v_mfma_f32_16x16x32_bf16 v[20:23], v[208:211], v[192:195], 0
	v_mfma_f32_16x16x32_bf16 v[8:11], v[216:219], v[192:195], 0
	v_mfma_f32_16x16x32_bf16 v[4:7], v[208:211], v[200:203], 0
	v_mfma_f32_16x16x32_bf16 v[0:3], v[216:219], v[200:203], 0
	v_mfma_f32_16x16x32_bf16 v[54:57], v[212:215], v[180:183], v[54:57]
	v_mfma_f32_16x16x32_bf16 v[40:43], v[234:237], v[180:183], v[40:43]
	v_mfma_f32_16x16x32_bf16 v[36:39], v[212:215], v[188:191], v[36:39]
	v_mfma_f32_16x16x32_bf16 v[24:27], v[234:237], v[188:191], v[24:27]
	v_mfma_f32_16x16x32_bf16 v[20:23], v[212:215], v[196:199], v[20:23]
	v_mfma_f32_16x16x32_bf16 v[8:11], v[234:237], v[196:199], v[8:11]
	v_mfma_f32_16x16x32_bf16 v[4:7], v[212:215], v[204:207], v[4:7]
	v_mfma_f32_16x16x32_bf16 v[0:3], v[234:237], v[204:207], v[0:3]
	s_add_i32 s22, 0, 0x18000
	v_add_u32_e32 v142, s22, v170
	s_barrier
	ds_read_b128 v[130:133], v142
	ds_read_b128 v[134:137], v142 offset:1024
	ds_read_b128 v[138:141], v142 offset:2048
	ds_read_b128 v[142:145], v142 offset:3072
	s_add_u32 s20, s20, s10
	s_addc_u32 s21, s21, 0
	s_mov_b32 m0, s38
	v_lshl_add_u64 v[208:209], s[20:21], 0, v[48:49]
	ds_read_b128 v[176:179], v172 offset:32768
	ds_read_b128 v[184:187], v172 offset:34816
	ds_read_b128 v[192:195], v172 offset:36864
	ds_read_b128 v[200:203], v172 offset:38912
	ds_read_b128 v[180:183], v172 offset:33792
	ds_read_b128 v[188:191], v172 offset:35840
	ds_read_b128 v[196:199], v172 offset:37888
	ds_read_b128 v[204:207], v172 offset:39936
	global_load_lds_dwordx4 v[208:209], off
	s_mov_b32 m0, s39
	v_lshl_add_u64 v[208:209], s[20:21], 0, v[146:147]
	global_load_lds_dwordx4 v[208:209], off
	s_waitcnt lgkmcnt(8)
	s_barrier

; #define PG8_MMA(ai, bj, At, Bt) do { __builtin_amdgcn_s_setprio(1); _Pragma("unroll") for (int m = 0; m < 4; ++m) _Pragma("unroll") for (int n = 0; n < 2; ++n) _Pragma("unroll") for (int k = 0; k < 2; ++k) \
;         acc[ai][bj][m][n] = __builtin_amdgcn_mfma_f32_16x16x32_bf16(Bt[n][k], At[m][k], acc[ai][bj][m][n], 0, 0, 0); __builtin_amdgcn_s_setprio(0); } while (0)
; #define PG8_WAIT_L(n) asm volatile("s_waitcnt lgkmcnt(" #n ")" ::: "memory")
; #define PG8_BAR __builtin_amdgcn_s_barrier()
; #define PG8_SCHED __builtin_amdgcn_sched_barrier(0)
; template <class Epi, class Sched>
; __device__ __forceinline__ void gemm_phase(PG8_LAS unsigned char* lds, const Gemm g, const Sched& S, const Epi& E) {
;     ...
;             PG8_WAIT_L(8); PG8_BAR; PG8_WAIT_L(0); PG8_MMA(0, 0, At, B0); PG8_BAR; PG8_SCHED;
	s_waitcnt lgkmcnt(7)
	v_mfma_f32_16x16x32_bf16 v[126:129], v[130:133], v[176:179], v[126:129]
	v_mfma_f32_16x16x32_bf16 v[122:125], v[138:141], v[176:179], v[122:125]

; #define PG8_MMA(ai, bj, At, Bt) do { __builtin_amdgcn_s_setprio(1); _Pragma("unroll") for (int m = 0; m < 4; ++m) _Pragma("unroll") for (int n = 0; n < 2; ++n) _Pragma("unroll") for (int k = 0; k < 2; ++k) \
;         acc[ai][bj][m][n] = __builtin_amdgcn_mfma_f32_16x16x32_bf16(Bt[n][k], At[m][k], acc[ai][bj][m][n], 0, 0, 0); __builtin_amdgcn_s_setprio(0); } while (0)
; #define PG8_WAIT_L(n) asm volatile("s_waitcnt lgkmcnt(" #n ")" ::: "memory")
; #define PG8_BAR __builtin_amdgcn_s_barrier()
; #define PG8_SCHED __builtin_amdgcn_sched_barrier(0)
; template <class Epi, class Sched>
; __device__ __forceinline__ void gemm_phase(PG8_LAS unsigned char* lds, const Gemm g, const Sched& S, const Epi& E) {
;     ...
;             PG8_WAIT_L(8); PG8_BAR; PG8_WAIT_L(0); PG8_MMA(0, 0, At, B0); PG8_BAR; PG8_SCHED;
	s_waitcnt lgkmcnt(6)
	v_mfma_f32_16x16x32_bf16 v[114:117], v[130:133], v[184:187], v[114:117]
	v_mfma_f32_16x16x32_bf16 v[110:113], v[138:141], v[184:187], v[110:113]

; #define PG8_MMA(ai, bj, At, Bt) do { __builtin_amdgcn_s_setprio(1); _Pragma("unroll") for (int m = 0; m < 4; ++m) _Pragma("unroll") for (int n = 0; n < 2; ++n) _Pragma("unroll") for (int k = 0; k < 2; ++k) \
;         acc[ai][bj][m][n] = __builtin_amdgcn_mfma_f32_16x16x32_bf16(Bt[n][k], At[m][k], acc[ai][bj][m][n], 0, 0, 0); __builtin_amdgcn_s_setprio(0); } while (0)
; #define PG8_WAIT_L(n) asm volatile("s_waitcnt lgkmcnt(" #n ")" ::: "memory")
; #define PG8_BAR __builtin_amdgcn_s_barrier()
; #define PG8_SCHED __builtin_amdgcn_sched_barrier(0)
; template <class Epi, class Sched>
; __device__ __forceinline__ void gemm_phase(PG8_LAS unsigned char* lds, const Gemm g, const Sched& S, const Epi& E) {
;     ...
;             PG8_WAIT_L(8); PG8_BAR; PG8_WAIT_L(0); PG8_MMA(0, 0, At, B0); PG8_BAR; PG8_SCHED;
	s_waitcnt lgkmcnt(5)
	v_mfma_f32_16x16x32_bf16 v[98:101], v[130:133], v[192:195], v[98:101]
	v_mfma_f32_16x16x32_bf16 v[94:97], v[138:141], v[192:195], v[94:97]

; #define PG8_MMA(ai, bj, At, Bt) do { __builtin_amdgcn_s_setprio(1); _Pragma("unroll") for (int m = 0; m < 4; ++m) _Pragma("unroll") for (int n = 0; n < 2; ++n) _Pragma("unroll") for (int k = 0; k < 2; ++k) \
;         acc[ai][bj][m][n] = __builtin_amdgcn_mfma_f32_16x16x32_bf16(Bt[n][k], At[m][k], acc[ai][bj][m][n], 0, 0, 0); __builtin_amdgcn_s_setprio(0); } while (0)
; #define PG8_WAIT_L(n) asm volatile("s_waitcnt lgkmcnt(" #n ")" ::: "memory")
; #define PG8_BAR __builtin_amdgcn_s_barrier()
; #define PG8_SCHED __builtin_amdgcn_sched_barrier(0)
; template <class Epi, class Sched>
; __device__ __forceinline__ void gemm_phase(PG8_LAS unsigned char* lds, const Gemm g, const Sched& S, const Epi& E) {
;     ...
;             PG8_WAIT_L(8); PG8_BAR; PG8_WAIT_L(0); PG8_MMA(0, 0, At, B0); PG8_BAR; PG8_SCHED;
	s_waitcnt lgkmcnt(4)
	v_mfma_f32_16x16x32_bf16 v[82:85], v[130:133], v[200:203], v[82:85]
	v_mfma_f32_16x16x32_bf16 v[78:81], v[138:141], v[200:203], v[78:81]
	s_waitcnt lgkmcnt(3)
	v_mfma_f32_16x16x32_bf16 v[126:129], v[134:137], v[180:183], v[126:129]
	v_mfma_f32_16x16x32_bf16 v[122:125], v[142:145], v[180:183], v[122:125]
	s_waitcnt lgkmcnt(2)
	v_mfma_f32_16x16x32_bf16 v[114:117], v[134:137], v[188:191], v[114:117]
	v_mfma_f32_16x16x32_bf16 v[110:113], v[142:145], v[188:191], v[110:113]
	s_waitcnt lgkmcnt(1)
	v_mfma_f32_16x16x32_bf16 v[98:101], v[134:137], v[196:199], v[98:101]
	v_mfma_f32_16x16x32_bf16 v[94:97], v[142:145], v[196:199], v[94:97]

; #define PG8_STAGE(bufoff, gbase, voff) do { _Pragma("unroll") for (int _i = 0; _i < 2; ++_i) \
;         __builtin_amdgcn_global_load_lds((const unsigned*)((const char*)(gbase) + (voff)[_i]), (PG8_LAS unsigned*)(lds + (bufoff) + ldsw + _i * 8192), 16, 0, 0); } while (0)
; #define PG8_LDB(dst, b, h) do { _Pragma("unroll") for (int n = 0; n < 2; ++n) _Pragma("unroll") for (int k = 0; k < 2; ++k) dst[n][k] = *(const PG8_LAS bf16x8*)(lds + PG8_SB(b, h) + boff + n * 2048 + k * 1024); } while (0)
; #define PG8_MMA(ai, bj, At, Bt) do { __builtin_amdgcn_s_setprio(1); _Pragma("unroll") for (int m = 0; m < 4; ++m) _Pragma("unroll") for (int n = 0; n < 2; ++n) _Pragma("unroll") for (int k = 0; k < 2; ++k) \
;         acc[ai][bj][m][n] = __builtin_amdgcn_mfma_f32_16x16x32_bf16(Bt[n][k], At[m][k], acc[ai][bj][m][n], 0, 0, 0); __builtin_amdgcn_s_setprio(0); } while (0)
; #define PG8_WAIT_L(n) asm volatile("s_waitcnt lgkmcnt(" #n ")" ::: "memory")
; #define PG8_BAR __builtin_amdgcn_s_barrier()
; #define PG8_SCHED __builtin_amdgcn_sched_barrier(0)
; template <class Epi, class Sched>
; __device__ __forceinline__ void gemm_phase(PG8_LAS unsigned char* lds, const Gemm g, const Sched& S, const Epi& E) {
;     ...
;             PG8_WAIT_L(8); PG8_BAR; PG8_WAIT_L(0); PG8_MMA(0, 0, At, B0); PG8_BAR; PG8_SCHED;
;             PG8_LDB(B1, 1, 1); PG8_STAGE(PG8_SB(1, 0), b3, voffB);
;             PG8_BAR; PG8_WAIT_L(0); PG8_MMA(0, 1, At, B1); PG8_BAR;
	s_waitcnt lgkmcnt(0)
	v_mfma_f32_16x16x32_bf16 v[82:85], v[134:137], v[204:207], v[82:85]
	v_mfma_f32_16x16x32_bf16 v[78:81], v[142:145], v[204:207], v[78:81]
	s_barrier
	s_add_i32 s20, 0, 0x1c000
	s_add_i32 s21, s22, s35
	v_add_u32_e32 v173, s20, v170
	v_lshl_add_u64 v[168:169], v[168:169], 0, s[0:1]
	s_mov_b32 m0, s21
	ds_read_b128 v[208:211], v173
	ds_read_b128 v[216:219], v173 offset:2048
	ds_read_b128 v[212:215], v173 offset:1024
	ds_read_b128 v[234:237], v173 offset:3072
	global_load_lds_dwordx4 v[168:169], off
	s_add_i32 m0, s21, 0x2000
	v_lshl_add_u64 v[168:169], v[224:225], 0, s[0:1]
	global_load_lds_dwordx4 v[168:169], off
	s_barrier

; #define PG8_MMA(ai, bj, At, Bt) do { __builtin_amdgcn_s_setprio(1); _Pragma("unroll") for (int m = 0; m < 4; ++m) _Pragma("unroll") for (int n = 0; n < 2; ++n) _Pragma("unroll") for (int k = 0; k < 2; ++k) \
;         acc[ai][bj][m][n] = __builtin_amdgcn_mfma_f32_16x16x32_bf16(Bt[n][k], At[m][k], acc[ai][bj][m][n], 0, 0, 0); __builtin_amdgcn_s_setprio(0); } while (0)
; #define PG8_WAIT_L(n) asm volatile("s_waitcnt lgkmcnt(" #n ")" ::: "memory")
; #define PG8_BAR __builtin_amdgcn_s_barrier()
; template <class Epi, class Sched>
; __device__ __forceinline__ void gemm_phase(PG8_LAS unsigned char* lds, const Gemm g, const Sched& S, const Epi& E) {
;     ...
;             PG8_BAR; PG8_WAIT_L(0); PG8_MMA(0, 1, At, B1); PG8_BAR;
	s_waitcnt lgkmcnt(3)
	v_mfma_f32_16x16x32_bf16 v[118:121], v[208:211], v[176:179], v[118:121]

; #define PG8_MMA(ai, bj, At, Bt) do { __builtin_amdgcn_s_setprio(1); _Pragma("unroll") for (int m = 0; m < 4; ++m) _Pragma("unroll") for (int n = 0; n < 2; ++n) _Pragma("unroll") for (int k = 0; k < 2; ++k) \
;         acc[ai][bj][m][n] = __builtin_amdgcn_mfma_f32_16x16x32_bf16(Bt[n][k], At[m][k], acc[ai][bj][m][n], 0, 0, 0); __builtin_amdgcn_s_setprio(0); } while (0)
; #define PG8_WAIT_L(n) asm volatile("s_waitcnt lgkmcnt(" #n ")" ::: "memory")
; #define PG8_BAR __builtin_amdgcn_s_barrier()
; template <class Epi, class Sched>
; __device__ __forceinline__ void gemm_phase(PG8_LAS unsigned char* lds, const Gemm g, const Sched& S, const Epi& E) {
;     ...
;             PG8_BAR; PG8_WAIT_L(0); PG8_MMA(0, 1, At, B1); PG8_BAR;
	s_waitcnt lgkmcnt(2)
	v_mfma_f32_16x16x32_bf16 v[106:109], v[216:219], v[176:179], v[106:109]
	v_mfma_f32_16x16x32_bf16 v[102:105], v[208:211], v[184:187], v[102:105]
	v_mfma_f32_16x16x32_bf16 v[90:93], v[216:219], v[184:187], v[90:93]
	v_mfma_f32_16x16x32_bf16 v[86:89], v[208:211], v[192:195], v[86:89]
	v_mfma_f32_16x16x32_bf16 v[74:77], v[216:219], v[192:195], v[74:77]
	v_mfma_f32_16x16x32_bf16 v[70:73], v[208:211], v[200:203], v[70:73]
	v_mfma_f32_16x16x32_bf16 v[66:69], v[216:219], v[200:203], v[66:69]
	s_waitcnt lgkmcnt(1)
	v_mfma_f32_16x16x32_bf16 v[118:121], v[212:215], v[180:183], v[118:121]

; #define PG8_STAGE(bufoff, gbase, voff) do { _Pragma("unroll") for (int _i = 0; _i < 2; ++_i) \
;         __builtin_amdgcn_global_load_lds((const unsigned*)((const char*)(gbase) + (voff)[_i]), (PG8_LAS unsigned*)(lds + (bufoff) + ldsw + _i * 8192), 16, 0, 0); } while (0)
; #define PG8_LDA(dst, b, h) do { _Pragma("unroll") for (int m = 0; m < 4; ++m) _Pragma("unroll") for (int k = 0; k < 2; ++k) dst[m][k] = *(const PG8_LAS bf16x8*)(lds + PG8_SA(b, h) + aoff + m * 2048 + k * 1024); } while (0)
; #define PG8_MMA(ai, bj, At, Bt) do { __builtin_amdgcn_s_setprio(1); _Pragma("unroll") for (int m = 0; m < 4; ++m) _Pragma("unroll") for (int n = 0; n < 2; ++n) _Pragma("unroll") for (int k = 0; k < 2; ++k) \
;         acc[ai][bj][m][n] = __builtin_amdgcn_mfma_f32_16x16x32_bf16(Bt[n][k], At[m][k], acc[ai][bj][m][n], 0, 0, 0); __builtin_amdgcn_s_setprio(0); } while (0)
; #define PG8_WAIT_L(n) asm volatile("s_waitcnt lgkmcnt(" #n ")" ::: "memory")
; #define PG8_BAR __builtin_amdgcn_s_barrier()
; #define PG8_SCHED __builtin_amdgcn_sched_barrier(0)
; template <class Epi, class Sched>
; __device__ __forceinline__ void gemm_phase(PG8_LAS unsigned char* lds, const Gemm g, const Sched& S, const Epi& E) {
;     ...
;             PG8_BAR; PG8_WAIT_L(0); PG8_MMA(0, 1, At, B1); PG8_BAR;
;             PG8_LDA(At, 1, 1); PG8_STAGE(PG8_SA(1, 0), a3, voffA);
;             PG8_BAR; PG8_WAIT_L(0); PG8_MMA(1, 0, At, B0); PG8_BAR; PG8_SCHED;
	s_waitcnt lgkmcnt(0)
	v_mfma_f32_16x16x32_bf16 v[106:109], v[234:237], v[180:183], v[106:109]
	v_mfma_f32_16x16x32_bf16 v[102:105], v[212:215], v[188:191], v[102:105]
	v_mfma_f32_16x16x32_bf16 v[90:93], v[234:237], v[188:191], v[90:93]
	v_mfma_f32_16x16x32_bf16 v[86:89], v[212:215], v[196:199], v[86:89]
	v_mfma_f32_16x16x32_bf16 v[74:77], v[234:237], v[196:199], v[74:77]
	v_mfma_f32_16x16x32_bf16 v[70:73], v[212:215], v[204:207], v[70:73]
	v_mfma_f32_16x16x32_bf16 v[66:69], v[234:237], v[204:207], v[66:69]
	s_mov_b32 m0, s64
	v_lshl_add_u64 v[168:169], v[228:229], 0, s[0:1]
	s_barrier
	ds_read_b128 v[176:179], v172 offset:49152
	ds_read_b128 v[184:187], v172 offset:51200
	ds_read_b128 v[192:195], v172 offset:53248
	ds_read_b128 v[200:203], v172 offset:55296
	ds_read_b128 v[180:183], v172 offset:50176
	ds_read_b128 v[188:191], v172 offset:52224
	ds_read_b128 v[196:199], v172 offset:54272
	ds_read_b128 v[204:207], v172 offset:56320
	global_load_lds_dwordx4 v[168:169], off
	s_mov_b32 m0, s65
	v_lshl_add_u64 v[168:169], v[238:239], 0, s[0:1]
	global_load_lds_dwordx4 v[168:169], off
	s_barrier

; #define PG8_MMA(ai, bj, At, Bt) do { __builtin_amdgcn_s_setprio(1); _Pragma("unroll") for (int m = 0; m < 4; ++m) _Pragma("unroll") for (int n = 0; n < 2; ++n) _Pragma("unroll") for (int k = 0; k < 2; ++k) \
;         acc[ai][bj][m][n] = __builtin_amdgcn_mfma_f32_16x16x32_bf16(Bt[n][k], At[m][k], acc[ai][bj][m][n], 0, 0, 0); __builtin_amdgcn_s_setprio(0); } while (0)
; #define PG8_WAIT_L(n) asm volatile("s_waitcnt lgkmcnt(" #n ")" ::: "memory")
; #define PG8_BAR __builtin_amdgcn_s_barrier()
; #define PG8_SCHED __builtin_amdgcn_sched_barrier(0)
; template <class Epi, class Sched>
; __device__ __forceinline__ void gemm_phase(PG8_LAS unsigned char* lds, const Gemm g, const Sched& S, const Epi& E) {
;     ...
;             PG8_BAR; PG8_WAIT_L(0); PG8_MMA(1, 0, At, B0); PG8_BAR; PG8_SCHED;
	s_waitcnt lgkmcnt(7)
	v_mfma_f32_16x16x32_bf16 v[62:65], v[130:133], v[176:179], v[62:65]
	v_mfma_f32_16x16x32_bf16 v[58:61], v[138:141], v[176:179], v[58:61]

; #define PG8_MMA(ai, bj, At, Bt) do { __builtin_amdgcn_s_setprio(1); _Pragma("unroll") for (int m = 0; m < 4; ++m) _Pragma("unroll") for (int n = 0; n < 2; ++n) _Pragma("unroll") for (int k = 0; k < 2; ++k) \
;         acc[ai][bj][m][n] = __builtin_amdgcn_mfma_f32_16x16x32_bf16(Bt[n][k], At[m][k], acc[ai][bj][m][n], 0, 0, 0); __builtin_amdgcn_s_setprio(0); } while (0)
; #define PG8_WAIT_L(n) asm volatile("s_waitcnt lgkmcnt(" #n ")" ::: "memory")
; #define PG8_BAR __builtin_amdgcn_s_barrier()
; #define PG8_SCHED __builtin_amdgcn_sched_barrier(0)
; template <class Epi, class Sched>
; __device__ __forceinline__ void gemm_phase(PG8_LAS unsigned char* lds, const Gemm g, const Sched& S, const Epi& E) {
;     ...
;             PG8_BAR; PG8_WAIT_L(0); PG8_MMA(1, 0, At, B0); PG8_BAR; PG8_SCHED;
	s_waitcnt lgkmcnt(6)
	v_mfma_f32_16x16x32_bf16 v[50:53], v[130:133], v[184:187], v[50:53]
	v_mfma_f32_16x16x32_bf16 v[44:47], v[138:141], v[184:187], v[44:47]

; #define PG8_MMA(ai, bj, At, Bt) do { __builtin_amdgcn_s_setprio(1); _Pragma("unroll") for (int m = 0; m < 4; ++m) _Pragma("unroll") for (int n = 0; n < 2; ++n) _Pragma("unroll") for (int k = 0; k < 2; ++k) \
;         acc[ai][bj][m][n] = __builtin_amdgcn_mfma_f32_16x16x32_bf16(Bt[n][k], At[m][k], acc[ai][bj][m][n], 0, 0, 0); __builtin_amdgcn_s_setprio(0); } while (0)
; #define PG8_WAIT_L(n) asm volatile("s_waitcnt lgkmcnt(" #n ")" ::: "memory")
; #define PG8_BAR __builtin_amdgcn_s_barrier()
; #define PG8_SCHED __builtin_amdgcn_sched_barrier(0)
; template <class Epi, class Sched>
; __device__ __forceinline__ void gemm_phase(PG8_LAS unsigned char* lds, const Gemm g, const Sched& S, const Epi& E) {
;     ...
;             PG8_BAR; PG8_WAIT_L(0); PG8_MMA(1, 0, At, B0); PG8_BAR; PG8_SCHED;
	s_waitcnt lgkmcnt(5)
	v_mfma_f32_16x16x32_bf16 v[32:35], v[130:133], v[192:195], v[32:35]
	v_mfma_f32_16x16x32_bf16 v[28:31], v[138:141], v[192:195], v[28:31]

; #define PG8_MMA(ai, bj, At, Bt) do { __builtin_amdgcn_s_setprio(1); _Pragma("unroll") for (int m = 0; m < 4; ++m) _Pragma("unroll") for (int n = 0; n < 2; ++n) _Pragma("unroll") for (int k = 0; k < 2; ++k) \
;         acc[ai][bj][m][n] = __builtin_amdgcn_mfma_f32_16x16x32_bf16(Bt[n][k], At[m][k], acc[ai][bj][m][n], 0, 0, 0); __builtin_amdgcn_s_setprio(0); } while (0)
; #define PG8_WAIT_L(n) asm volatile("s_waitcnt lgkmcnt(" #n ")" ::: "memory")
; #define PG8_BAR __builtin_amdgcn_s_barrier()
; #define PG8_SCHED __builtin_amdgcn_sched_barrier(0)
; template <class Epi, class Sched>
; __device__ __forceinline__ void gemm_phase(PG8_LAS unsigned char* lds, const Gemm g, const Sched& S, const Epi& E) {
;     ...
;             PG8_BAR; PG8_WAIT_L(0); PG8_MMA(1, 0, At, B0); PG8_BAR; PG8_SCHED;
	s_waitcnt lgkmcnt(4)
	v_mfma_f32_16x16x32_bf16 v[16:19], v[130:133], v[200:203], v[16:19]
	v_mfma_f32_16x16x32_bf16 v[12:15], v[138:141], v[200:203], v[12:15]
	s_waitcnt lgkmcnt(3)
	v_mfma_f32_16x16x32_bf16 v[62:65], v[134:137], v[180:183], v[62:65]
	v_mfma_f32_16x16x32_bf16 v[58:61], v[142:145], v[180:183], v[58:61]
	s_waitcnt lgkmcnt(2)
	v_mfma_f32_16x16x32_bf16 v[50:53], v[134:137], v[188:191], v[50:53]
	v_mfma_f32_16x16x32_bf16 v[44:47], v[142:145], v[188:191], v[44:47]
	s_waitcnt lgkmcnt(1)
	v_mfma_f32_16x16x32_bf16 v[32:35], v[134:137], v[196:199], v[32:35]
	v_mfma_f32_16x16x32_bf16 v[28:31], v[142:145], v[196:199], v[28:31]

; #define PG8_STAGE(bufoff, gbase, voff) do { _Pragma("unroll") for (int _i = 0; _i < 2; ++_i) \
;         __builtin_amdgcn_global_load_lds((const unsigned*)((const char*)(gbase) + (voff)[_i]), (PG8_LAS unsigned*)(lds + (bufoff) + ldsw + _i * 8192), 16, 0, 0); } while (0)
; #define PG8_LDA(dst, b, h) do { _Pragma("unroll") for (int m = 0; m < 4; ++m) _Pragma("unroll") for (int k = 0; k < 2; ++k) dst[m][k] = *(const PG8_LAS bf16x8*)(lds + PG8_SA(b, h) + aoff + m * 2048 + k * 1024); } while (0)
; #define PG8_LDB(dst, b, h) do { _Pragma("unroll") for (int n = 0; n < 2; ++n) _Pragma("unroll") for (int k = 0; k < 2; ++k) dst[n][k] = *(const PG8_LAS bf16x8*)(lds + PG8_SB(b, h) + boff + n * 2048 + k * 1024); } while (0)
; #define PG8_MMA(ai, bj, At, Bt) do { __builtin_amdgcn_s_setprio(1); _Pragma("unroll") for (int m = 0; m < 4; ++m) _Pragma("unroll") for (int n = 0; n < 2; ++n) _Pragma("unroll") for (int k = 0; k < 2; ++k) \
;         acc[ai][bj][m][n] = __builtin_amdgcn_mfma_f32_16x16x32_bf16(Bt[n][k], At[m][k], acc[ai][bj][m][n], 0, 0, 0); __builtin_amdgcn_s_setprio(0); } while (0)
; #define PG8_WAIT_V(n) asm volatile("s_waitcnt vmcnt(" #n ")" ::: "memory")
; #define PG8_WAIT_L(n) asm volatile("s_waitcnt lgkmcnt(" #n ")" ::: "memory")
; #define PG8_BAR __builtin_amdgcn_s_barrier()
; #define PG8_SCHED __builtin_amdgcn_sched_barrier(0)
; template <class Epi, class Sched>
; __device__ __forceinline__ void gemm_phase(PG8_LAS unsigned char* lds, const Gemm g, const Sched& S, const Epi& E) {
;     ...
;             const bool last = (t == nt - 2);
;             const char* a1 = cA + (size_t)(t + 1) * kstep;
;             const char* a2 = last ? nA : cA + (size_t)(t + 2) * kstep; const char* b2 = last ? nB : cB + (size_t)(t + 2) * kstep;
;             const char* a3 = a2 + kstep; const char* b3 = b2 + kstep;
;             if (last && has_next) S.a_ready(nxt);
;             PG8_LDB(B0, 0, 0); PG8_SCHED; PG8_LDA(At, 0, 0); PG8_STAGE(PG8_SA(1, 1), a1 + hstep, voffA);
;             PG8_WAIT_L(8); PG8_BAR; PG8_WAIT_L(0); PG8_MMA(0, 0, At, B0); PG8_BAR; PG8_SCHED;
;     ...
;             PG8_BAR; PG8_WAIT_L(0); PG8_MMA(1, 0, At, B0); PG8_BAR; PG8_SCHED;
;             PG8_STAGE(PG8_SB(1, 1), b3 + hstep, voffB);
;             PG8_WAIT_V(6); PG8_BAR; PG8_MMA(1, 1, At, B1); PG8_BAR;
	s_waitcnt lgkmcnt(0)
	v_mfma_f32_16x16x32_bf16 v[16:19], v[134:137], v[204:207], v[16:19]
	v_mfma_f32_16x16x32_bf16 v[12:15], v[142:145], v[204:207], v[12:15]
	s_barrier
	s_add_i32 s20, s20, s35
	s_mov_b32 m0, s20
	v_lshl_add_u64 v[130:131], v[240:241], 0, s[0:1]
	global_load_lds_dwordx4 v[130:131], off
	s_add_i32 m0, s20, 0x2000
	v_lshl_add_u64 v[130:131], v[242:243], 0, s[0:1]
	global_load_lds_dwordx4 v[130:131], off
	s_waitcnt vmcnt(6)
	s_barrier
	v_mfma_f32_16x16x32_bf16 v[54:57], v[208:211], v[176:179], v[54:57]
	v_mfma_f32_16x16x32_bf16 v[40:43], v[216:219], v[176:179], v[40:43]
	v_mfma_f32_16x16x32_bf16 v[36:39], v[208:211], v[184:187], v[36:39]
	v_mfma_f32_16x16x32_bf16 v[24:27], v[216:219], v[184:187], v[24:27]
	v_mfma_f32_16x16x32_bf16 v[20:23], v[208:211], v[192:195], v[20:23]
	v_mfma_f32_16x16x32_bf16 v[8:11], v[216:219], v[192:195], v[8:11]
	v_mfma_f32_16x16x32_bf16 v[4:7], v[208:211], v[200:203], v[4:7]
	v_mfma_f32_16x16x32_bf16 v[0:3], v[216:219], v[200:203], v[0:3]
	v_mfma_f32_16x16x32_bf16 v[54:57], v[212:215], v[180:183], v[54:57]
	v_mfma_f32_16x16x32_bf16 v[40:43], v[234:237], v[180:183], v[40:43]
	v_mfma_f32_16x16x32_bf16 v[36:39], v[212:215], v[188:191], v[36:39]
	v_mfma_f32_16x16x32_bf16 v[24:27], v[234:237], v[188:191], v[24:27]
	v_mfma_f32_16x16x32_bf16 v[20:23], v[212:215], v[196:199], v[20:23]
	v_mfma_f32_16x16x32_bf16 v[8:11], v[234:237], v[196:199], v[8:11]
	v_mfma_f32_16x16x32_bf16 v[4:7], v[212:215], v[204:207], v[4:7]
	v_mfma_f32_16x16x32_bf16 v[0:3], v[234:237], v[204:207], v[0:3]
	s_add_u32 s16, s16, 0x100
	s_addc_u32 s17, s17, 0
	s_add_u32 s24, s24, 0x100
	s_addc_u32 s25, s25, 0
	s_cmp_ge_u32 s42, s54
	s_mov_b32 s20, s42
	s_barrier
	s_cbranch_scc1 .Lkpeel_exit_268
.LBB0_268:
	s_add_i32 s42, s20, 2
	s_add_u32 s22, s16, 0x80
	s_addc_u32 s21, s17, 0
	s_add_i32 s43, 0, 0x10000
	v_add_u32_e32 v142, s43, v170
	ds_read_b128 v[130:133], v142
	ds_read_b128 v[134:137], v142 offset:1024
	ds_read_b128 v[138:141], v142 offset:2048
	ds_read_b128 v[142:145], v142 offset:3072
	s_cmp_eq_u32 s66, s20
	s_cselect_b32 s20, s2, s22
	s_cselect_b32 s21, s3, s21
	s_cselect_b32 s23, s13, s25
	s_cselect_b32 s22, s12, s24
	v_lshl_add_u64 v[168:169], s[16:17], 0, v[164:165]
	s_add_i32 m0, s36, 0xc000
	ds_read_b128 v[176:179], v172
	ds_read_b128 v[184:187], v172 offset:2048
	ds_read_b128 v[192:195], v172 offset:4096
	ds_read_b128 v[200:203], v172 offset:6144
	ds_read_b128 v[180:183], v172 offset:1024
	ds_read_b128 v[188:191], v172 offset:3072
	ds_read_b128 v[196:199], v172 offset:5120
	ds_read_b128 v[204:207], v172 offset:7168
	global_load_lds_dwordx4 v[168:169], off
	s_add_i32 m0, s36, 0xe000
	v_lshl_add_u64 v[168:169], s[16:17], 0, v[166:167]
	global_load_lds_dwordx4 v[168:169], off
	s_waitcnt lgkmcnt(8)
	s_barrier

; #define PG8_MMA(ai, bj, At, Bt) do { __builtin_amdgcn_s_setprio(1); _Pragma("unroll") for (int m = 0; m < 4; ++m) _Pragma("unroll") for (int n = 0; n < 2; ++n) _Pragma("unroll") for (int k = 0; k < 2; ++k) \
;         acc[ai][bj][m][n] = __builtin_amdgcn_mfma_f32_16x16x32_bf16(Bt[n][k], At[m][k], acc[ai][bj][m][n], 0, 0, 0); __builtin_amdgcn_s_setprio(0); } while (0)
; #define PG8_WAIT_L(n) asm volatile("s_waitcnt lgkmcnt(" #n ")" ::: "memory")
; #define PG8_BAR __builtin_amdgcn_s_barrier()
; #define PG8_SCHED __builtin_amdgcn_sched_barrier(0)
; template <class Epi, class Sched>
; __device__ __forceinline__ void gemm_phase(PG8_LAS unsigned char* lds, const Gemm g, const Sched& S, const Epi& E) {
;     ...
;             PG8_WAIT_L(8); PG8_BAR; PG8_WAIT_L(0); PG8_MMA(0, 0, At, B0); PG8_BAR; PG8_SCHED;
	s_waitcnt lgkmcnt(7)
	v_mfma_f32_16x16x32_bf16 v[126:129], v[130:133], v[176:179], v[126:129]
	v_mfma_f32_16x16x32_bf16 v[122:125], v[138:141], v[176:179], v[122:125]

; #define PG8_MMA(ai, bj, At, Bt) do { __builtin_amdgcn_s_setprio(1); _Pragma("unroll") for (int m = 0; m < 4; ++m) _Pragma("unroll") for (int n = 0; n < 2; ++n) _Pragma("unroll") for (int k = 0; k < 2; ++k) \
;         acc[ai][bj][m][n] = __builtin_amdgcn_mfma_f32_16x16x32_bf16(Bt[n][k], At[m][k], acc[ai][bj][m][n], 0, 0, 0); __builtin_amdgcn_s_setprio(0); } while (0)
; #define PG8_WAIT_L(n) asm volatile("s_waitcnt lgkmcnt(" #n ")" ::: "memory")
; #define PG8_BAR __builtin_amdgcn_s_barrier()
; #define PG8_SCHED __builtin_amdgcn_sched_barrier(0)
; template <class Epi, class Sched>
; __device__ __forceinline__ void gemm_phase(PG8_LAS unsigned char* lds, const Gemm g, const Sched& S, const Epi& E) {
;     ...
;             PG8_WAIT_L(8); PG8_BAR; PG8_WAIT_L(0); PG8_MMA(0, 0, At, B0); PG8_BAR; PG8_SCHED;
	s_waitcnt lgkmcnt(6)
	v_mfma_f32_16x16x32_bf16 v[114:117], v[130:133], v[184:187], v[114:117]
	v_mfma_f32_16x16x32_bf16 v[110:113], v[138:141], v[184:187], v[110:113]

; #define PG8_MMA(ai, bj, At, Bt) do { __builtin_amdgcn_s_setprio(1); _Pragma("unroll") for (int m = 0; m < 4; ++m) _Pragma("unroll") for (int n = 0; n < 2; ++n) _Pragma("unroll") for (int k = 0; k < 2; ++k) \
;         acc[ai][bj][m][n] = __builtin_amdgcn_mfma_f32_16x16x32_bf16(Bt[n][k], At[m][k], acc[ai][bj][m][n], 0, 0, 0); __builtin_amdgcn_s_setprio(0); } while (0)
; #define PG8_WAIT_L(n) asm volatile("s_waitcnt lgkmcnt(" #n ")" ::: "memory")
; #define PG8_BAR __builtin_amdgcn_s_barrier()
; #define PG8_SCHED __builtin_amdgcn_sched_barrier(0)
; template <class Epi, class Sched>
; __device__ __forceinline__ void gemm_phase(PG8_LAS unsigned char* lds, const Gemm g, const Sched& S, const Epi& E) {
;     ...
;             PG8_WAIT_L(8); PG8_BAR; PG8_WAIT_L(0); PG8_MMA(0, 0, At, B0); PG8_BAR; PG8_SCHED;
	s_waitcnt lgkmcnt(5)
	v_mfma_f32_16x16x32_bf16 v[98:101], v[130:133], v[192:195], v[98:101]
	v_mfma_f32_16x16x32_bf16 v[94:97], v[138:141], v[192:195], v[94:97]

; #define PG8_MMA(ai, bj, At, Bt) do { __builtin_amdgcn_s_setprio(1); _Pragma("unroll") for (int m = 0; m < 4; ++m) _Pragma("unroll") for (int n = 0; n < 2; ++n) _Pragma("unroll") for (int k = 0; k < 2; ++k) \
;         acc[ai][bj][m][n] = __builtin_amdgcn_mfma_f32_16x16x32_bf16(Bt[n][k], At[m][k], acc[ai][bj][m][n], 0, 0, 0); __builtin_amdgcn_s_setprio(0); } while (0)
; #define PG8_WAIT_L(n) asm volatile("s_waitcnt lgkmcnt(" #n ")" ::: "memory")
; #define PG8_BAR __builtin_amdgcn_s_barrier()
; #define PG8_SCHED __builtin_amdgcn_sched_barrier(0)
; template <class Epi, class Sched>
; __device__ __forceinline__ void gemm_phase(PG8_LAS unsigned char* lds, const Gemm g, const Sched& S, const Epi& E) {
;     ...
;             PG8_WAIT_L(8); PG8_BAR; PG8_WAIT_L(0); PG8_MMA(0, 0, At, B0); PG8_BAR; PG8_SCHED;
	s_waitcnt lgkmcnt(4)
	v_mfma_f32_16x16x32_bf16 v[82:85], v[130:133], v[200:203], v[82:85]
	v_mfma_f32_16x16x32_bf16 v[78:81], v[138:141], v[200:203], v[78:81]
	s_waitcnt lgkmcnt(3)
	v_mfma_f32_16x16x32_bf16 v[126:129], v[134:137], v[180:183], v[126:129]
	v_mfma_f32_16x16x32_bf16 v[122:125], v[142:145], v[180:183], v[122:125]
	s_waitcnt lgkmcnt(2)
	v_mfma_f32_16x16x32_bf16 v[114:117], v[134:137], v[188:191], v[114:117]
	v_mfma_f32_16x16x32_bf16 v[110:113], v[142:145], v[188:191], v[110:113]
	s_waitcnt lgkmcnt(1)
	v_mfma_f32_16x16x32_bf16 v[98:101], v[134:137], v[196:199], v[98:101]
	v_mfma_f32_16x16x32_bf16 v[94:97], v[142:145], v[196:199], v[94:97]

; #define PG8_STAGE(bufoff, gbase, voff) do { _Pragma("unroll") for (int _i = 0; _i < 2; ++_i) \
;         __builtin_amdgcn_global_load_lds((const unsigned*)((const char*)(gbase) + (voff)[_i]), (PG8_LAS unsigned*)(lds + (bufoff) + ldsw + _i * 8192), 16, 0, 0); } while (0)
; #define PG8_LDB(dst, b, h) do { _Pragma("unroll") for (int n = 0; n < 2; ++n) _Pragma("unroll") for (int k = 0; k < 2; ++k) dst[n][k] = *(const PG8_LAS bf16x8*)(lds + PG8_SB(b, h) + boff + n * 2048 + k * 1024); } while (0)
; #define PG8_MMA(ai, bj, At, Bt) do { __builtin_amdgcn_s_setprio(1); _Pragma("unroll") for (int m = 0; m < 4; ++m) _Pragma("unroll") for (int n = 0; n < 2; ++n) _Pragma("unroll") for (int k = 0; k < 2; ++k) \
;         acc[ai][bj][m][n] = __builtin_amdgcn_mfma_f32_16x16x32_bf16(Bt[n][k], At[m][k], acc[ai][bj][m][n], 0, 0, 0); __builtin_amdgcn_s_setprio(0); } while (0)
; #define PG8_WAIT_L(n) asm volatile("s_waitcnt lgkmcnt(" #n ")" ::: "memory")
; #define PG8_BAR __builtin_amdgcn_s_barrier()
; #define PG8_SCHED __builtin_amdgcn_sched_barrier(0)
; template <class Epi, class Sched>
; __device__ __forceinline__ void gemm_phase(PG8_LAS unsigned char* lds, const Gemm g, const Sched& S, const Epi& E) {
;     ...
;             PG8_WAIT_L(8); PG8_BAR; PG8_WAIT_L(0); PG8_MMA(0, 0, At, B0); PG8_BAR; PG8_SCHED;
;             PG8_LDB(B1, 0, 1); PG8_STAGE(PG8_SB(0, 0), b2, voffB);
;             PG8_BAR; PG8_WAIT_L(0); PG8_MMA(0, 1, At, B1); PG8_BAR;
	s_waitcnt lgkmcnt(0)
	v_mfma_f32_16x16x32_bf16 v[82:85], v[134:137], v[204:207], v[82:85]
	v_mfma_f32_16x16x32_bf16 v[78:81], v[142:145], v[204:207], v[78:81]
	s_barrier
	s_add_i32 s44, 0, 0x14000
	v_add_u32_e32 v168, s44, v170
	s_add_i32 s43, s43, s35
	ds_read_b128 v[208:211], v168
	ds_read_b128 v[216:219], v168 offset:2048
	ds_read_b128 v[212:215], v168 offset:1024
	ds_read_b128 v[234:237], v168 offset:3072
	v_lshl_add_u64 v[168:169], s[22:23], 0, v[48:49]
	s_mov_b32 m0, s43
	v_lshl_add_u64 v[224:225], s[22:23], 0, v[146:147]
	global_load_lds_dwordx4 v[168:169], off
	s_add_i32 m0, s43, 0x2000
	s_nop 0
	global_load_lds_dwordx4 v[224:225], off
	s_barrier

; #define PG8_MMA(ai, bj, At, Bt) do { __builtin_amdgcn_s_setprio(1); _Pragma("unroll") for (int m = 0; m < 4; ++m) _Pragma("unroll") for (int n = 0; n < 2; ++n) _Pragma("unroll") for (int k = 0; k < 2; ++k) \
;         acc[ai][bj][m][n] = __builtin_amdgcn_mfma_f32_16x16x32_bf16(Bt[n][k], At[m][k], acc[ai][bj][m][n], 0, 0, 0); __builtin_amdgcn_s_setprio(0); } while (0)
; #define PG8_WAIT_L(n) asm volatile("s_waitcnt lgkmcnt(" #n ")" ::: "memory")
; #define PG8_BAR __builtin_amdgcn_s_barrier()
; template <class Epi, class Sched>
; __device__ __forceinline__ void gemm_phase(PG8_LAS unsigned char* lds, const Gemm g, const Sched& S, const Epi& E) {
;     ...
;             PG8_BAR; PG8_WAIT_L(0); PG8_MMA(0, 1, At, B1); PG8_BAR;
	s_waitcnt lgkmcnt(3)
	v_mfma_f32_16x16x32_bf16 v[118:121], v[208:211], v[176:179], v[118:121]

; #define PG8_MMA(ai, bj, At, Bt) do { __builtin_amdgcn_s_setprio(1); _Pragma("unroll") for (int m = 0; m < 4; ++m) _Pragma("unroll") for (int n = 0; n < 2; ++n) _Pragma("unroll") for (int k = 0; k < 2; ++k) \
;         acc[ai][bj][m][n] = __builtin_amdgcn_mfma_f32_16x16x32_bf16(Bt[n][k], At[m][k], acc[ai][bj][m][n], 0, 0, 0); __builtin_amdgcn_s_setprio(0); } while (0)
; #define PG8_WAIT_L(n) asm volatile("s_waitcnt lgkmcnt(" #n ")" ::: "memory")
; #define PG8_BAR __builtin_amdgcn_s_barrier()
; template <class Epi, class Sched>
; __device__ __forceinline__ void gemm_phase(PG8_LAS unsigned char* lds, const Gemm g, const Sched& S, const Epi& E) {
;     ...
;             PG8_BAR; PG8_WAIT_L(0); PG8_MMA(0, 1, At, B1); PG8_BAR;
	s_waitcnt lgkmcnt(2)
	v_mfma_f32_16x16x32_bf16 v[106:109], v[216:219], v[176:179], v[106:109]
	v_mfma_f32_16x16x32_bf16 v[102:105], v[208:211], v[184:187], v[102:105]
	v_mfma_f32_16x16x32_bf16 v[90:93], v[216:219], v[184:187], v[90:93]
	v_mfma_f32_16x16x32_bf16 v[86:89], v[208:211], v[192:195], v[86:89]
	v_mfma_f32_16x16x32_bf16 v[74:77], v[216:219], v[192:195], v[74:77]
	v_mfma_f32_16x16x32_bf16 v[70:73], v[208:211], v[200:203], v[70:73]
	v_mfma_f32_16x16x32_bf16 v[66:69], v[216:219], v[200:203], v[66:69]
	s_waitcnt lgkmcnt(1)
	v_mfma_f32_16x16x32_bf16 v[118:121], v[212:215], v[180:183], v[118:121]

; #define PG8_STAGE(bufoff, gbase, voff) do { _Pragma("unroll") for (int _i = 0; _i < 2; ++_i) \
;         __builtin_amdgcn_global_load_lds((const unsigned*)((const char*)(gbase) + (voff)[_i]), (PG8_LAS unsigned*)(lds + (bufoff) + ldsw + _i * 8192), 16, 0, 0); } while (0)
; #define PG8_LDA(dst, b, h) do { _Pragma("unroll") for (int m = 0; m < 4; ++m) _Pragma("unroll") for (int k = 0; k < 2; ++k) dst[m][k] = *(const PG8_LAS bf16x8*)(lds + PG8_SA(b, h) + aoff + m * 2048 + k * 1024); } while (0)
; #define PG8_MMA(ai, bj, At, Bt) do { __builtin_amdgcn_s_setprio(1); _Pragma("unroll") for (int m = 0; m < 4; ++m) _Pragma("unroll") for (int n = 0; n < 2; ++n) _Pragma("unroll") for (int k = 0; k < 2; ++k) \
;         acc[ai][bj][m][n] = __builtin_amdgcn_mfma_f32_16x16x32_bf16(Bt[n][k], At[m][k], acc[ai][bj][m][n], 0, 0, 0); __builtin_amdgcn_s_setprio(0); } while (0)
; #define PG8_WAIT_L(n) asm volatile("s_waitcnt lgkmcnt(" #n ")" ::: "memory")
; #define PG8_BAR __builtin_amdgcn_s_barrier()
; #define PG8_SCHED __builtin_amdgcn_sched_barrier(0)
; template <class Epi, class Sched>
; __device__ __forceinline__ void gemm_phase(PG8_LAS unsigned char* lds, const Gemm g, const Sched& S, const Epi& E) {
;     ...
;             PG8_BAR; PG8_WAIT_L(0); PG8_MMA(0, 1, At, B1); PG8_BAR;
;             PG8_LDA(At, 0, 1); PG8_STAGE(PG8_SA(0, 0), a2, voffA);
;             PG8_BAR; PG8_WAIT_L(0); PG8_MMA(1, 0, At, B0); PG8_BAR; PG8_SCHED;
	s_waitcnt lgkmcnt(0)
	v_mfma_f32_16x16x32_bf16 v[106:109], v[234:237], v[180:183], v[106:109]
	v_mfma_f32_16x16x32_bf16 v[102:105], v[212:215], v[188:191], v[102:105]
	v_mfma_f32_16x16x32_bf16 v[90:93], v[234:237], v[188:191], v[90:93]
	v_mfma_f32_16x16x32_bf16 v[86:89], v[212:215], v[196:199], v[86:89]
	v_mfma_f32_16x16x32_bf16 v[74:77], v[234:237], v[196:199], v[74:77]
	v_mfma_f32_16x16x32_bf16 v[70:73], v[212:215], v[204:207], v[70:73]
	v_mfma_f32_16x16x32_bf16 v[66:69], v[234:237], v[204:207], v[66:69]
	s_mov_b32 m0, s36
	v_lshl_add_u64 v[228:229], s[20:21], 0, v[48:49]
	s_barrier
	ds_read_b128 v[176:179], v172 offset:16384
	ds_read_b128 v[184:187], v172 offset:18432
	ds_read_b128 v[192:195], v172 offset:20480
	ds_read_b128 v[200:203], v172 offset:22528
	ds_read_b128 v[180:183], v172 offset:17408
	ds_read_b128 v[188:191], v172 offset:19456
	ds_read_b128 v[196:199], v172 offset:21504
	ds_read_b128 v[204:207], v172 offset:23552
	global_load_lds_dwordx4 v[228:229], off
	s_mov_b32 m0, s37
	v_lshl_add_u64 v[238:239], s[20:21], 0, v[146:147]
	global_load_lds_dwordx4 v[238:239], off
	s_barrier

; #define PG8_MMA(ai, bj, At, Bt) do { __builtin_amdgcn_s_setprio(1); _Pragma("unroll") for (int m = 0; m < 4; ++m) _Pragma("unroll") for (int n = 0; n < 2; ++n) _Pragma("unroll") for (int k = 0; k < 2; ++k) \
;         acc[ai][bj][m][n] = __builtin_amdgcn_mfma_f32_16x16x32_bf16(Bt[n][k], At[m][k], acc[ai][bj][m][n], 0, 0, 0); __builtin_amdgcn_s_setprio(0); } while (0)
; #define PG8_WAIT_L(n) asm volatile("s_waitcnt lgkmcnt(" #n ")" ::: "memory")
; #define PG8_BAR __builtin_amdgcn_s_barrier()
; #define PG8_SCHED __builtin_amdgcn_sched_barrier(0)
; template <class Epi, class Sched>
; __device__ __forceinline__ void gemm_phase(PG8_LAS unsigned char* lds, const Gemm g, const Sched& S, const Epi& E) {
;     ...
;             PG8_BAR; PG8_WAIT_L(0); PG8_MMA(1, 0, At, B0); PG8_BAR; PG8_SCHED;
	s_waitcnt lgkmcnt(7)
	v_mfma_f32_16x16x32_bf16 v[62:65], v[130:133], v[176:179], v[62:65]
	v_mfma_f32_16x16x32_bf16 v[58:61], v[138:141], v[176:179], v[58:61]

; #define PG8_MMA(ai, bj, At, Bt) do { __builtin_amdgcn_s_setprio(1); _Pragma("unroll") for (int m = 0; m < 4; ++m) _Pragma("unroll") for (int n = 0; n < 2; ++n) _Pragma("unroll") for (int k = 0; k < 2; ++k) \
;         acc[ai][bj][m][n] = __builtin_amdgcn_mfma_f32_16x16x32_bf16(Bt[n][k], At[m][k], acc[ai][bj][m][n], 0, 0, 0); __builtin_amdgcn_s_setprio(0); } while (0)
; #define PG8_WAIT_L(n) asm volatile("s_waitcnt lgkmcnt(" #n ")" ::: "memory")
; #define PG8_BAR __builtin_amdgcn_s_barrier()
; #define PG8_SCHED __builtin_amdgcn_sched_barrier(0)
; template <class Epi, class Sched>
; __device__ __forceinline__ void gemm_phase(PG8_LAS unsigned char* lds, const Gemm g, const Sched& S, const Epi& E) {
;     ...
;             PG8_BAR; PG8_WAIT_L(0); PG8_MMA(1, 0, At, B0); PG8_BAR; PG8_SCHED;
	s_waitcnt lgkmcnt(6)
	v_mfma_f32_16x16x32_bf16 v[50:53], v[130:133], v[184:187], v[50:53]
	v_mfma_f32_16x16x32_bf16 v[44:47], v[138:141], v[184:187], v[44:47]

; #define PG8_MMA(ai, bj, At, Bt) do { __builtin_amdgcn_s_setprio(1); _Pragma("unroll") for (int m = 0; m < 4; ++m) _Pragma("unroll") for (int n = 0; n < 2; ++n) _Pragma("unroll") for (int k = 0; k < 2; ++k) \
;         acc[ai][bj][m][n] = __builtin_amdgcn_mfma_f32_16x16x32_bf16(Bt[n][k], At[m][k], acc[ai][bj][m][n], 0, 0, 0); __builtin_amdgcn_s_setprio(0); } while (0)
; #define PG8_WAIT_L(n) asm volatile("s_waitcnt lgkmcnt(" #n ")" ::: "memory")
; #define PG8_BAR __builtin_amdgcn_s_barrier()
; #define PG8_SCHED __builtin_amdgcn_sched_barrier(0)
; template <class Epi, class Sched>
; __device__ __forceinline__ void gemm_phase(PG8_LAS unsigned char* lds, const Gemm g, const Sched& S, const Epi& E) {
;     ...
;             PG8_BAR; PG8_WAIT_L(0); PG8_MMA(1, 0, At, B0); PG8_BAR; PG8_SCHED;
	s_waitcnt lgkmcnt(5)
	v_mfma_f32_16x16x32_bf16 v[32:35], v[130:133], v[192:195], v[32:35]
	v_mfma_f32_16x16x32_bf16 v[28:31], v[138:141], v[192:195], v[28:31]

; #define PG8_MMA(ai, bj, At, Bt) do { __builtin_amdgcn_s_setprio(1); _Pragma("unroll") for (int m = 0; m < 4; ++m) _Pragma("unroll") for (int n = 0; n < 2; ++n) _Pragma("unroll") for (int k = 0; k < 2; ++k) \
;         acc[ai][bj][m][n] = __builtin_amdgcn_mfma_f32_16x16x32_bf16(Bt[n][k], At[m][k], acc[ai][bj][m][n], 0, 0, 0); __builtin_amdgcn_s_setprio(0); } while (0)
; #define PG8_WAIT_L(n) asm volatile("s_waitcnt lgkmcnt(" #n ")" ::: "memory")
; #define PG8_BAR __builtin_amdgcn_s_barrier()
; #define PG8_SCHED __builtin_amdgcn_sched_barrier(0)
; template <class Epi, class Sched>
; __device__ __forceinline__ void gemm_phase(PG8_LAS unsigned char* lds, const Gemm g, const Sched& S, const Epi& E) {
;     ...
;             PG8_BAR; PG8_WAIT_L(0); PG8_MMA(1, 0, At, B0); PG8_BAR; PG8_SCHED;
	s_waitcnt lgkmcnt(4)
	v_mfma_f32_16x16x32_bf16 v[16:19], v[130:133], v[200:203], v[16:19]
	v_mfma_f32_16x16x32_bf16 v[12:15], v[138:141], v[200:203], v[12:15]
	s_waitcnt lgkmcnt(3)
	v_mfma_f32_16x16x32_bf16 v[62:65], v[134:137], v[180:183], v[62:65]
	v_mfma_f32_16x16x32_bf16 v[58:61], v[142:145], v[180:183], v[58:61]
	s_waitcnt lgkmcnt(2)
	v_mfma_f32_16x16x32_bf16 v[50:53], v[134:137], v[188:191], v[50:53]
	v_mfma_f32_16x16x32_bf16 v[44:47], v[142:145], v[188:191], v[44:47]
	s_waitcnt lgkmcnt(1)
	v_mfma_f32_16x16x32_bf16 v[32:35], v[134:137], v[196:199], v[32:35]
	v_mfma_f32_16x16x32_bf16 v[28:31], v[142:145], v[196:199], v[28:31]

; #define PG8_STAGE(bufoff, gbase, voff) do { _Pragma("unroll") for (int _i = 0; _i < 2; ++_i) \
;         __builtin_amdgcn_global_load_lds((const unsigned*)((const char*)(gbase) + (voff)[_i]), (PG8_LAS unsigned*)(lds + (bufoff) + ldsw + _i * 8192), 16, 0, 0); } while (0)
; #define PG8_LDA(dst, b, h) do { _Pragma("unroll") for (int m = 0; m < 4; ++m) _Pragma("unroll") for (int k = 0; k < 2; ++k) dst[m][k] = *(const PG8_LAS bf16x8*)(lds + PG8_SA(b, h) + aoff + m * 2048 + k * 1024); } while (0)
; #define PG8_LDB(dst, b, h) do { _Pragma("unroll") for (int n = 0; n < 2; ++n) _Pragma("unroll") for (int k = 0; k < 2; ++k) dst[n][k] = *(const PG8_LAS bf16x8*)(lds + PG8_SB(b, h) + boff + n * 2048 + k * 1024); } while (0)
; #define PG8_MMA(ai, bj, At, Bt) do { __builtin_amdgcn_s_setprio(1); _Pragma("unroll") for (int m = 0; m < 4; ++m) _Pragma("unroll") for (int n = 0; n < 2; ++n) _Pragma("unroll") for (int k = 0; k < 2; ++k) \
;         acc[ai][bj][m][n] = __builtin_amdgcn_mfma_f32_16x16x32_bf16(Bt[n][k], At[m][k], acc[ai][bj][m][n], 0, 0, 0); __builtin_amdgcn_s_setprio(0); } while (0)
; #define PG8_WAIT_V(n) asm volatile("s_waitcnt vmcnt(" #n ")" ::: "memory")
; #define PG8_WAIT_L(n) asm volatile("s_waitcnt lgkmcnt(" #n ")" ::: "memory")
; #define PG8_BAR __builtin_amdgcn_s_barrier()
; #define PG8_SCHED __builtin_amdgcn_sched_barrier(0)
; template <class Epi, class Sched>
; __device__ __forceinline__ void gemm_phase(PG8_LAS unsigned char* lds, const Gemm g, const Sched& S, const Epi& E) {
;     ...
;             PG8_BAR; PG8_WAIT_L(0); PG8_MMA(1, 0, At, B0); PG8_BAR; PG8_SCHED;
;             PG8_STAGE(PG8_SB(0, 1), b2 + hstep, voffB);
;             PG8_WAIT_V(6); PG8_BAR; PG8_MMA(1, 1, At, B1); PG8_BAR;
;             PG8_LDB(B0, 1, 0); PG8_SCHED; PG8_LDA(At, 1, 0); PG8_STAGE(PG8_SA(0, 1), a2 + hstep, voffA);
;             PG8_WAIT_L(8); PG8_BAR; PG8_WAIT_L(0); PG8_MMA(0, 0, At, B0); PG8_BAR; PG8_SCHED;
	s_waitcnt lgkmcnt(0)
	v_mfma_f32_16x16x32_bf16 v[16:19], v[134:137], v[204:207], v[16:19]
	v_mfma_f32_16x16x32_bf16 v[12:15], v[142:145], v[204:207], v[12:15]
	s_barrier
	s_add_u32 s22, s22, s10
	s_addc_u32 s23, s23, 0
	s_add_i32 s43, s44, s35
	v_lshl_add_u64 v[240:241], s[22:23], 0, v[48:49]
	s_mov_b32 m0, s43
	v_lshl_add_u64 v[242:243], s[22:23], 0, v[146:147]
	global_load_lds_dwordx4 v[240:241], off
	s_add_i32 m0, s43, 0x2000
	s_nop 0
	global_load_lds_dwordx4 v[242:243], off
	s_waitcnt vmcnt(6)
	s_barrier
	v_mfma_f32_16x16x32_bf16 v[54:57], v[208:211], v[176:179], v[54:57]
	v_mfma_f32_16x16x32_bf16 v[40:43], v[216:219], v[176:179], v[40:43]
	v_mfma_f32_16x16x32_bf16 v[36:39], v[208:211], v[184:187], v[36:39]
	v_mfma_f32_16x16x32_bf16 v[24:27], v[216:219], v[184:187], v[24:27]
	v_mfma_f32_16x16x32_bf16 v[20:23], v[208:211], v[192:195], v[20:23]
	v_mfma_f32_16x16x32_bf16 v[8:11], v[216:219], v[192:195], v[8:11]
	v_mfma_f32_16x16x32_bf16 v[4:7], v[208:211], v[200:203], v[4:7]
	v_mfma_f32_16x16x32_bf16 v[0:3], v[216:219], v[200:203], v[0:3]
	v_mfma_f32_16x16x32_bf16 v[54:57], v[212:215], v[180:183], v[54:57]
	v_mfma_f32_16x16x32_bf16 v[40:43], v[234:237], v[180:183], v[40:43]
	v_mfma_f32_16x16x32_bf16 v[36:39], v[212:215], v[188:191], v[36:39]
	v_mfma_f32_16x16x32_bf16 v[24:27], v[234:237], v[188:191], v[24:27]
	v_mfma_f32_16x16x32_bf16 v[20:23], v[212:215], v[196:199], v[20:23]
	v_mfma_f32_16x16x32_bf16 v[8:11], v[234:237], v[196:199], v[8:11]
	v_mfma_f32_16x16x32_bf16 v[4:7], v[212:215], v[204:207], v[4:7]
	v_mfma_f32_16x16x32_bf16 v[0:3], v[234:237], v[204:207], v[0:3]
	s_add_i32 s22, 0, 0x18000
	v_add_u32_e32 v142, s22, v170
	s_barrier
	ds_read_b128 v[130:133], v142
	ds_read_b128 v[134:137], v142 offset:1024
	ds_read_b128 v[138:141], v142 offset:2048
	ds_read_b128 v[142:145], v142 offset:3072
	s_add_u32 s20, s20, s10
	s_addc_u32 s21, s21, 0
	s_mov_b32 m0, s38
	v_lshl_add_u64 v[208:209], s[20:21], 0, v[48:49]
	ds_read_b128 v[176:179], v172 offset:32768
	ds_read_b128 v[184:187], v172 offset:34816
	ds_read_b128 v[192:195], v172 offset:36864
	ds_read_b128 v[200:203], v172 offset:38912
	ds_read_b128 v[180:183], v172 offset:33792
	ds_read_b128 v[188:191], v172 offset:35840
	ds_read_b128 v[196:199], v172 offset:37888
	ds_read_b128 v[204:207], v172 offset:39936
	global_load_lds_dwordx4 v[208:209], off
	s_mov_b32 m0, s39
	v_lshl_add_u64 v[208:209], s[20:21], 0, v[146:147]
	global_load_lds_dwordx4 v[208:209], off
	s_waitcnt lgkmcnt(8)
	s_barrier

; #define PG8_MMA(ai, bj, At, Bt) do { __builtin_amdgcn_s_setprio(1); _Pragma("unroll") for (int m = 0; m < 4; ++m) _Pragma("unroll") for (int n = 0; n < 2; ++n) _Pragma("unroll") for (int k = 0; k < 2; ++k) \
;         acc[ai][bj][m][n] = __builtin_amdgcn_mfma_f32_16x16x32_bf16(Bt[n][k], At[m][k], acc[ai][bj][m][n], 0, 0, 0); __builtin_amdgcn_s_setprio(0); } while (0)
; #define PG8_WAIT_L(n) asm volatile("s_waitcnt lgkmcnt(" #n ")" ::: "memory")
; #define PG8_BAR __builtin_amdgcn_s_barrier()
; #define PG8_SCHED __builtin_amdgcn_sched_barrier(0)
; template <class Epi, class Sched>
; __device__ __forceinline__ void gemm_phase(PG8_LAS unsigned char* lds, const Gemm g, const Sched& S, const Epi& E) {
;     ...
;             PG8_WAIT_L(8); PG8_BAR; PG8_WAIT_L(0); PG8_MMA(0, 0, At, B0); PG8_BAR; PG8_SCHED;
	s_waitcnt lgkmcnt(7)
	v_mfma_f32_16x16x32_bf16 v[126:129], v[130:133], v[176:179], v[126:129]
	v_mfma_f32_16x16x32_bf16 v[122:125], v[138:141], v[176:179], v[122:125]

; #define PG8_MMA(ai, bj, At, Bt) do { __builtin_amdgcn_s_setprio(1); _Pragma("unroll") for (int m = 0; m < 4; ++m) _Pragma("unroll") for (int n = 0; n < 2; ++n) _Pragma("unroll") for (int k = 0; k < 2; ++k) \
;         acc[ai][bj][m][n] = __builtin_amdgcn_mfma_f32_16x16x32_bf16(Bt[n][k], At[m][k], acc[ai][bj][m][n], 0, 0, 0); __builtin_amdgcn_s_setprio(0); } while (0)
; #define PG8_WAIT_L(n) asm volatile("s_waitcnt lgkmcnt(" #n ")" ::: "memory")
; #define PG8_BAR __builtin_amdgcn_s_barrier()
; #define PG8_SCHED __builtin_amdgcn_sched_barrier(0)
; template <class Epi, class Sched>
; __device__ __forceinline__ void gemm_phase(PG8_LAS unsigned char* lds, const Gemm g, const Sched& S, const Epi& E) {
;     ...
;             PG8_WAIT_L(8); PG8_BAR; PG8_WAIT_L(0); PG8_MMA(0, 0, At, B0); PG8_BAR; PG8_SCHED;
	s_waitcnt lgkmcnt(6)
	v_mfma_f32_16x16x32_bf16 v[114:117], v[130:133], v[184:187], v[114:117]
	v_mfma_f32_16x16x32_bf16 v[110:113], v[138:141], v[184:187], v[110:113]

; #define PG8_MMA(ai, bj, At, Bt) do { __builtin_amdgcn_s_setprio(1); _Pragma("unroll") for (int m = 0; m < 4; ++m) _Pragma("unroll") for (int n = 0; n < 2; ++n) _Pragma("unroll") for (int k = 0; k < 2; ++k) \
;         acc[ai][bj][m][n] = __builtin_amdgcn_mfma_f32_16x16x32_bf16(Bt[n][k], At[m][k], acc[ai][bj][m][n], 0, 0, 0); __builtin_amdgcn_s_setprio(0); } while (0)
; #define PG8_WAIT_L(n) asm volatile("s_waitcnt lgkmcnt(" #n ")" ::: "memory")
; #define PG8_BAR __builtin_amdgcn_s_barrier()
; #define PG8_SCHED __builtin_amdgcn_sched_barrier(0)
; template <class Epi, class Sched>
; __device__ __forceinline__ void gemm_phase(PG8_LAS unsigned char* lds, const Gemm g, const Sched& S, const Epi& E) {
;     ...
;             PG8_WAIT_L(8); PG8_BAR; PG8_WAIT_L(0); PG8_MMA(0, 0, At, B0); PG8_BAR; PG8_SCHED;
	s_waitcnt lgkmcnt(5)
	v_mfma_f32_16x16x32_bf16 v[98:101], v[130:133], v[192:195], v[98:101]
	v_mfma_f32_16x16x32_bf16 v[94:97], v[138:141], v[192:195], v[94:97]

; #define PG8_MMA(ai, bj, At, Bt) do { __builtin_amdgcn_s_setprio(1); _Pragma("unroll") for (int m = 0; m < 4; ++m) _Pragma("unroll") for (int n = 0; n < 2; ++n) _Pragma("unroll") for (int k = 0; k < 2; ++k) \
;         acc[ai][bj][m][n] = __builtin_amdgcn_mfma_f32_16x16x32_bf16(Bt[n][k], At[m][k], acc[ai][bj][m][n], 0, 0, 0); __builtin_amdgcn_s_setprio(0); } while (0)
; #define PG8_WAIT_L(n) asm volatile("s_waitcnt lgkmcnt(" #n ")" ::: "memory")
; #define PG8_BAR __builtin_amdgcn_s_barrier()
; #define PG8_SCHED __builtin_amdgcn_sched_barrier(0)
; template <class Epi, class Sched>
; __device__ __forceinline__ void gemm_phase(PG8_LAS unsigned char* lds, const Gemm g, const Sched& S, const Epi& E) {
;     ...
;             PG8_WAIT_L(8); PG8_BAR; PG8_WAIT_L(0); PG8_MMA(0, 0, At, B0); PG8_BAR; PG8_SCHED;
	s_waitcnt lgkmcnt(4)
	v_mfma_f32_16x16x32_bf16 v[82:85], v[130:133], v[200:203], v[82:85]
	v_mfma_f32_16x16x32_bf16 v[78:81], v[138:141], v[200:203], v[78:81]
	s_waitcnt lgkmcnt(3)
	v_mfma_f32_16x16x32_bf16 v[126:129], v[134:137], v[180:183], v[126:129]
	v_mfma_f32_16x16x32_bf16 v[122:125], v[142:145], v[180:183], v[122:125]
	s_waitcnt lgkmcnt(2)
	v_mfma_f32_16x16x32_bf16 v[114:117], v[134:137], v[188:191], v[114:117]
	v_mfma_f32_16x16x32_bf16 v[110:113], v[142:145], v[188:191], v[110:113]
	s_waitcnt lgkmcnt(1)
	v_mfma_f32_16x16x32_bf16 v[98:101], v[134:137], v[196:199], v[98:101]
	v_mfma_f32_16x16x32_bf16 v[94:97], v[142:145], v[196:199], v[94:97]

; #define PG8_STAGE(bufoff, gbase, voff) do { _Pragma("unroll") for (int _i = 0; _i < 2; ++_i) \
;         __builtin_amdgcn_global_load_lds((const unsigned*)((const char*)(gbase) + (voff)[_i]), (PG8_LAS unsigned*)(lds + (bufoff) + ldsw + _i * 8192), 16, 0, 0); } while (0)
; #define PG8_LDB(dst, b, h) do { _Pragma("unroll") for (int n = 0; n < 2; ++n) _Pragma("unroll") for (int k = 0; k < 2; ++k) dst[n][k] = *(const PG8_LAS bf16x8*)(lds + PG8_SB(b, h) + boff + n * 2048 + k * 1024); } while (0)
; #define PG8_MMA(ai, bj, At, Bt) do { __builtin_amdgcn_s_setprio(1); _Pragma("unroll") for (int m = 0; m < 4; ++m) _Pragma("unroll") for (int n = 0; n < 2; ++n) _Pragma("unroll") for (int k = 0; k < 2; ++k) \
;         acc[ai][bj][m][n] = __builtin_amdgcn_mfma_f32_16x16x32_bf16(Bt[n][k], At[m][k], acc[ai][bj][m][n], 0, 0, 0); __builtin_amdgcn_s_setprio(0); } while (0)
; #define PG8_WAIT_L(n) asm volatile("s_waitcnt lgkmcnt(" #n ")" ::: "memory")
; #define PG8_BAR __builtin_amdgcn_s_barrier()
; #define PG8_SCHED __builtin_amdgcn_sched_barrier(0)
; template <class Epi, class Sched>
; __device__ __forceinline__ void gemm_phase(PG8_LAS unsigned char* lds, const Gemm g, const Sched& S, const Epi& E) {
;     ...
;             PG8_WAIT_L(8); PG8_BAR; PG8_WAIT_L(0); PG8_MMA(0, 0, At, B0); PG8_BAR; PG8_SCHED;
;             PG8_LDB(B1, 1, 1); PG8_STAGE(PG8_SB(1, 0), b3, voffB);
;             PG8_BAR; PG8_WAIT_L(0); PG8_MMA(0, 1, At, B1); PG8_BAR;
	s_waitcnt lgkmcnt(0)
	v_mfma_f32_16x16x32_bf16 v[82:85], v[134:137], v[204:207], v[82:85]
	v_mfma_f32_16x16x32_bf16 v[78:81], v[142:145], v[204:207], v[78:81]
	s_barrier
	s_add_i32 s20, 0, 0x1c000
	s_add_i32 s21, s22, s35
	v_add_u32_e32 v173, s20, v170
	v_lshl_add_u64 v[168:169], v[168:169], 0, s[0:1]
	s_mov_b32 m0, s21
	ds_read_b128 v[208:211], v173
	ds_read_b128 v[216:219], v173 offset:2048
	ds_read_b128 v[212:215], v173 offset:1024
	ds_read_b128 v[234:237], v173 offset:3072
	global_load_lds_dwordx4 v[168:169], off
	s_add_i32 m0, s21, 0x2000
	v_lshl_add_u64 v[168:169], v[224:225], 0, s[0:1]
	global_load_lds_dwordx4 v[168:169], off
	s_barrier

; #define PG8_MMA(ai, bj, At, Bt) do { __builtin_amdgcn_s_setprio(1); _Pragma("unroll") for (int m = 0; m < 4; ++m) _Pragma("unroll") for (int n = 0; n < 2; ++n) _Pragma("unroll") for (int k = 0; k < 2; ++k) \
;         acc[ai][bj][m][n] = __builtin_amdgcn_mfma_f32_16x16x32_bf16(Bt[n][k], At[m][k], acc[ai][bj][m][n], 0, 0, 0); __builtin_amdgcn_s_setprio(0); } while (0)
; #define PG8_WAIT_L(n) asm volatile("s_waitcnt lgkmcnt(" #n ")" ::: "memory")
; #define PG8_BAR __builtin_amdgcn_s_barrier()
; template <class Epi, class Sched>
; __device__ __forceinline__ void gemm_phase(PG8_LAS unsigned char* lds, const Gemm g, const Sched& S, const Epi& E) {
;     ...
;             PG8_BAR; PG8_WAIT_L(0); PG8_MMA(0, 1, At, B1); PG8_BAR;
	s_waitcnt lgkmcnt(3)
	v_mfma_f32_16x16x32_bf16 v[118:121], v[208:211], v[176:179], v[118:121]

; #define PG8_MMA(ai, bj, At, Bt) do { __builtin_amdgcn_s_setprio(1); _Pragma("unroll") for (int m = 0; m < 4; ++m) _Pragma("unroll") for (int n = 0; n < 2; ++n) _Pragma("unroll") for (int k = 0; k < 2; ++k) \
;         acc[ai][bj][m][n] = __builtin_amdgcn_mfma_f32_16x16x32_bf16(Bt[n][k], At[m][k], acc[ai][bj][m][n], 0, 0, 0); __builtin_amdgcn_s_setprio(0); } while (0)
; #define PG8_WAIT_L(n) asm volatile("s_waitcnt lgkmcnt(" #n ")" ::: "memory")
; #define PG8_BAR __builtin_amdgcn_s_barrier()
; template <class Epi, class Sched>
; __device__ __forceinline__ void gemm_phase(PG8_LAS unsigned char* lds, const Gemm g, const Sched& S, const Epi& E) {
;     ...
;             PG8_BAR; PG8_WAIT_L(0); PG8_MMA(0, 1, At, B1); PG8_BAR;
	s_waitcnt lgkmcnt(2)
	v_mfma_f32_16x16x32_bf16 v[106:109], v[216:219], v[176:179], v[106:109]
	v_mfma_f32_16x16x32_bf16 v[102:105], v[208:211], v[184:187], v[102:105]
	v_mfma_f32_16x16x32_bf16 v[90:93], v[216:219], v[184:187], v[90:93]
	v_mfma_f32_16x16x32_bf16 v[86:89], v[208:211], v[192:195], v[86:89]
	v_mfma_f32_16x16x32_bf16 v[74:77], v[216:219], v[192:195], v[74:77]
	v_mfma_f32_16x16x32_bf16 v[70:73], v[208:211], v[200:203], v[70:73]
	v_mfma_f32_16x16x32_bf16 v[66:69], v[216:219], v[200:203], v[66:69]
	s_waitcnt lgkmcnt(1)
	v_mfma_f32_16x16x32_bf16 v[118:121], v[212:215], v[180:183], v[118:121]

; #define PG8_STAGE(bufoff, gbase, voff) do { _Pragma("unroll") for (int _i = 0; _i < 2; ++_i) \
;         __builtin_amdgcn_global_load_lds((const unsigned*)((const char*)(gbase) + (voff)[_i]), (PG8_LAS unsigned*)(lds + (bufoff) + ldsw + _i * 8192), 16, 0, 0); } while (0)
; #define PG8_LDA(dst, b, h) do { _Pragma("unroll") for (int m = 0; m < 4; ++m) _Pragma("unroll") for (int k = 0; k < 2; ++k) dst[m][k] = *(const PG8_LAS bf16x8*)(lds + PG8_SA(b, h) + aoff + m * 2048 + k * 1024); } while (0)
; #define PG8_MMA(ai, bj, At, Bt) do { __builtin_amdgcn_s_setprio(1); _Pragma("unroll") for (int m = 0; m < 4; ++m) _Pragma("unroll") for (int n = 0; n < 2; ++n) _Pragma("unroll") for (int k = 0; k < 2; ++k) \
;         acc[ai][bj][m][n] = __builtin_amdgcn_mfma_f32_16x16x32_bf16(Bt[n][k], At[m][k], acc[ai][bj][m][n], 0, 0, 0); __builtin_amdgcn_s_setprio(0); } while (0)
; #define PG8_WAIT_L(n) asm volatile("s_waitcnt lgkmcnt(" #n ")" ::: "memory")
; #define PG8_BAR __builtin_amdgcn_s_barrier()
; #define PG8_SCHED __builtin_amdgcn_sched_barrier(0)
; template <class Epi, class Sched>
; __device__ __forceinline__ void gemm_phase(PG8_LAS unsigned char* lds, const Gemm g, const Sched& S, const Epi& E) {
;     ...
;             PG8_BAR; PG8_WAIT_L(0); PG8_MMA(0, 1, At, B1); PG8_BAR;
;             PG8_LDA(At, 1, 1); PG8_STAGE(PG8_SA(1, 0), a3, voffA);
;             PG8_BAR; PG8_WAIT_L(0); PG8_MMA(1, 0, At, B0); PG8_BAR; PG8_SCHED;
	s_waitcnt lgkmcnt(0)
	v_mfma_f32_16x16x32_bf16 v[106:109], v[234:237], v[180:183], v[106:109]
	v_mfma_f32_16x16x32_bf16 v[102:105], v[212:215], v[188:191], v[102:105]
	v_mfma_f32_16x16x32_bf16 v[90:93], v[234:237], v[188:191], v[90:93]
	v_mfma_f32_16x16x32_bf16 v[86:89], v[212:215], v[196:199], v[86:89]
	v_mfma_f32_16x16x32_bf16 v[74:77], v[234:237], v[196:199], v[74:77]
	v_mfma_f32_16x16x32_bf16 v[70:73], v[212:215], v[204:207], v[70:73]
	v_mfma_f32_16x16x32_bf16 v[66:69], v[234:237], v[204:207], v[66:69]
	s_mov_b32 m0, s64
	v_lshl_add_u64 v[168:169], v[228:229], 0, s[0:1]
	s_barrier
	ds_read_b128 v[176:179], v172 offset:49152
	ds_read_b128 v[184:187], v172 offset:51200
	ds_read_b128 v[192:195], v172 offset:53248
	ds_read_b128 v[200:203], v172 offset:55296
	ds_read_b128 v[180:183], v172 offset:50176
	ds_read_b128 v[188:191], v172 offset:52224
	ds_read_b128 v[196:199], v172 offset:54272
	ds_read_b128 v[204:207], v172 offset:56320
	global_load_lds_dwordx4 v[168:169], off
	s_mov_b32 m0, s65
	v_lshl_add_u64 v[168:169], v[238:239], 0, s[0:1]
	global_load_lds_dwordx4 v[168:169], off
	s_barrier

; #define PG8_MMA(ai, bj, At, Bt) do { __builtin_amdgcn_s_setprio(1); _Pragma("unroll") for (int m = 0; m < 4; ++m) _Pragma("unroll") for (int n = 0; n < 2; ++n) _Pragma("unroll") for (int k = 0; k < 2; ++k) \
;         acc[ai][bj][m][n] = __builtin_amdgcn_mfma_f32_16x16x32_bf16(Bt[n][k], At[m][k], acc[ai][bj][m][n], 0, 0, 0); __builtin_amdgcn_s_setprio(0); } while (0)
; #define PG8_WAIT_L(n) asm volatile("s_waitcnt lgkmcnt(" #n ")" ::: "memory")
; #define PG8_BAR __builtin_amdgcn_s_barrier()
; #define PG8_SCHED __builtin_amdgcn_sched_barrier(0)
; template <class Epi, class Sched>
; __device__ __forceinline__ void gemm_phase(PG8_LAS unsigned char* lds, const Gemm g, const Sched& S, const Epi& E) {
;     ...
;             PG8_BAR; PG8_WAIT_L(0); PG8_MMA(1, 0, At, B0); PG8_BAR; PG8_SCHED;
	s_waitcnt lgkmcnt(7)
	v_mfma_f32_16x16x32_bf16 v[62:65], v[130:133], v[176:179], v[62:65]
	v_mfma_f32_16x16x32_bf16 v[58:61], v[138:141], v[176:179], v[58:61]

; #define PG8_MMA(ai, bj, At, Bt) do { __builtin_amdgcn_s_setprio(1); _Pragma("unroll") for (int m = 0; m < 4; ++m) _Pragma("unroll") for (int n = 0; n < 2; ++n) _Pragma("unroll") for (int k = 0; k < 2; ++k) \
;         acc[ai][bj][m][n] = __builtin_amdgcn_mfma_f32_16x16x32_bf16(Bt[n][k], At[m][k], acc[ai][bj][m][n], 0, 0, 0); __builtin_amdgcn_s_setprio(0); } while (0)
; #define PG8_WAIT_L(n) asm volatile("s_waitcnt lgkmcnt(" #n ")" ::: "memory")
; #define PG8_BAR __builtin_amdgcn_s_barrier()
; #define PG8_SCHED __builtin_amdgcn_sched_barrier(0)
; template <class Epi, class Sched>
; __device__ __forceinline__ void gemm_phase(PG8_LAS unsigned char* lds, const Gemm g, const Sched& S, const Epi& E) {
;     ...
;             PG8_BAR; PG8_WAIT_L(0); PG8_MMA(1, 0, At, B0); PG8_BAR; PG8_SCHED;
	s_waitcnt lgkmcnt(6)
	v_mfma_f32_16x16x32_bf16 v[50:53], v[130:133], v[184:187], v[50:53]
	v_mfma_f32_16x16x32_bf16 v[44:47], v[138:141], v[184:187], v[44:47]

; #define PG8_MMA(ai, bj, At, Bt) do { __builtin_amdgcn_s_setprio(1); _Pragma("unroll") for (int m = 0; m < 4; ++m) _Pragma("unroll") for (int n = 0; n < 2; ++n) _Pragma("unroll") for (int k = 0; k < 2; ++k) \
;         acc[ai][bj][m][n] = __builtin_amdgcn_mfma_f32_16x16x32_bf16(Bt[n][k], At[m][k], acc[ai][bj][m][n], 0, 0, 0); __builtin_amdgcn_s_setprio(0); } while (0)
; #define PG8_WAIT_L(n) asm volatile("s_waitcnt lgkmcnt(" #n ")" ::: "memory")
; #define PG8_BAR __builtin_amdgcn_s_barrier()
; #define PG8_SCHED __builtin_amdgcn_sched_barrier(0)
; template <class Epi, class Sched>
; __device__ __forceinline__ void gemm_phase(PG8_LAS unsigned char* lds, const Gemm g, const Sched& S, const Epi& E) {
;     ...
;             PG8_BAR; PG8_WAIT_L(0); PG8_MMA(1, 0, At, B0); PG8_BAR; PG8_SCHED;
	s_waitcnt lgkmcnt(5)
	v_mfma_f32_16x16x32_bf16 v[32:35], v[130:133], v[192:195], v[32:35]
	v_mfma_f32_16x16x32_bf16 v[28:31], v[138:141], v[192:195], v[28:31]

; #define PG8_MMA(ai, bj, At, Bt) do { __builtin_amdgcn_s_setprio(1); _Pragma("unroll") for (int m = 0; m < 4; ++m) _Pragma("unroll") for (int n = 0; n < 2; ++n) _Pragma("unroll") for (int k = 0; k < 2; ++k) \
;         acc[ai][bj][m][n] = __builtin_amdgcn_mfma_f32_16x16x32_bf16(Bt[n][k], At[m][k], acc[ai][bj][m][n], 0, 0, 0); __builtin_amdgcn_s_setprio(0); } while (0)
; #define PG8_WAIT_L(n) asm volatile("s_waitcnt lgkmcnt(" #n ")" ::: "memory")
; #define PG8_BAR __builtin_amdgcn_s_barrier()
; #define PG8_SCHED __builtin_amdgcn_sched_barrier(0)
; template <class Epi, class Sched>
; __device__ __forceinline__ void gemm_phase(PG8_LAS unsigned char* lds, const Gemm g, const Sched& S, const Epi& E) {
;     ...
;             PG8_BAR; PG8_WAIT_L(0); PG8_MMA(1, 0, At, B0); PG8_BAR; PG8_SCHED;
	s_waitcnt lgkmcnt(4)
	v_mfma_f32_16x16x32_bf16 v[16:19], v[130:133], v[200:203], v[16:19]
	v_mfma_f32_16x16x32_bf16 v[12:15], v[138:141], v[200:203], v[12:15]
	s_waitcnt lgkmcnt(3)
	v_mfma_f32_16x16x32_bf16 v[62:65], v[134:137], v[180:183], v[62:65]
	v_mfma_f32_16x16x32_bf16 v[58:61], v[142:145], v[180:183], v[58:61]
	s_waitcnt lgkmcnt(2)
	v_mfma_f32_16x16x32_bf16 v[50:53], v[134:137], v[188:191], v[50:53]
	v_mfma_f32_16x16x32_bf16 v[44:47], v[142:145], v[188:191], v[44:47]
	s_waitcnt lgkmcnt(1)
	v_mfma_f32_16x16x32_bf16 v[32:35], v[134:137], v[196:199], v[32:35]
	v_mfma_f32_16x16x32_bf16 v[28:31], v[142:145], v[196:199], v[28:31]

; #define PG8_STAGE(bufoff, gbase, voff) do { _Pragma("unroll") for (int _i = 0; _i < 2; ++_i) \
;         __builtin_amdgcn_global_load_lds((const unsigned*)((const char*)(gbase) + (voff)[_i]), (PG8_LAS unsigned*)(lds + (bufoff) + ldsw + _i * 8192), 16, 0, 0); } while (0)
; #define PG8_MMA(ai, bj, At, Bt) do { __builtin_amdgcn_s_setprio(1); _Pragma("unroll") for (int m = 0; m < 4; ++m) _Pragma("unroll") for (int n = 0; n < 2; ++n) _Pragma("unroll") for (int k = 0; k < 2; ++k) \
;         acc[ai][bj][m][n] = __builtin_amdgcn_mfma_f32_16x16x32_bf16(Bt[n][k], At[m][k], acc[ai][bj][m][n], 0, 0, 0); __builtin_amdgcn_s_setprio(0); } while (0)
; #define PG8_WAIT_V(n) asm volatile("s_waitcnt vmcnt(" #n ")" ::: "memory")
; #define PG8_WAIT_L(n) asm volatile("s_waitcnt lgkmcnt(" #n ")" ::: "memory")
; #define PG8_BAR __builtin_amdgcn_s_barrier()
; #define PG8_SCHED __builtin_amdgcn_sched_barrier(0)
; template <class Epi, class Sched>
; __device__ __forceinline__ void gemm_phase(PG8_LAS unsigned char* lds, const Gemm g, const Sched& S, const Epi& E) {
;     ...
;             PG8_BAR; PG8_WAIT_L(0); PG8_MMA(1, 0, At, B0); PG8_BAR; PG8_SCHED;
;             PG8_STAGE(PG8_SB(1, 1), b3 + hstep, voffB);
;             PG8_WAIT_V(6); PG8_BAR; PG8_MMA(1, 1, At, B1); PG8_BAR;
	s_waitcnt lgkmcnt(0)
	v_mfma_f32_16x16x32_bf16 v[16:19], v[134:137], v[204:207], v[16:19]
	v_mfma_f32_16x16x32_bf16 v[12:15], v[142:145], v[204:207], v[12:15]
	s_barrier
	s_add_i32 s20, s20, s35
	s_mov_b32 m0, s20
	v_lshl_add_u64 v[130:131], v[240:241], 0, s[0:1]
	global_load_lds_dwordx4 v[130:131], off
	s_add_i32 m0, s20, 0x2000
	v_lshl_add_u64 v[130:131], v[242:243], 0, s[0:1]
	global_load_lds_dwordx4 v[130:131], off
	s_waitcnt vmcnt(6)
	s_barrier
	v_mfma_f32_16x16x32_bf16 v[54:57], v[208:211], v[176:179], v[54:57]
	v_mfma_f32_16x16x32_bf16 v[40:43], v[216:219], v[176:179], v[40:43]
	v_mfma_f32_16x16x32_bf16 v[36:39], v[208:211], v[184:187], v[36:39]
	v_mfma_f32_16x16x32_bf16 v[24:27], v[216:219], v[184:187], v[24:27]
	v_mfma_f32_16x16x32_bf16 v[20:23], v[208:211], v[192:195], v[20:23]
	v_mfma_f32_16x16x32_bf16 v[8:11], v[216:219], v[192:195], v[8:11]
	v_mfma_f32_16x16x32_bf16 v[4:7], v[208:211], v[200:203], v[4:7]
	v_mfma_f32_16x16x32_bf16 v[0:3], v[216:219], v[200:203], v[0:3]
	v_mfma_f32_16x16x32_bf16 v[54:57], v[212:215], v[180:183], v[54:57]
	v_mfma_f32_16x16x32_bf16 v[40:43], v[234:237], v[180:183], v[40:43]
	v_mfma_f32_16x16x32_bf16 v[36:39], v[212:215], v[188:191], v[36:39]
	v_mfma_f32_16x16x32_bf16 v[24:27], v[234:237], v[188:191], v[24:27]
	v_mfma_f32_16x16x32_bf16 v[20:23], v[212:215], v[196:199], v[20:23]
	v_mfma_f32_16x16x32_bf16 v[8:11], v[234:237], v[196:199], v[8:11]
	v_mfma_f32_16x16x32_bf16 v[4:7], v[212:215], v[204:207], v[4:7]
	v_mfma_f32_16x16x32_bf16 v[0:3], v[234:237], v[204:207], v[0:3]
	s_add_u32 s16, s16, 0x100
	s_addc_u32 s17, s17, 0
	s_add_u32 s24, s24, 0x100
	s_addc_u32 s25, s25, 0
	s_cmp_ge_u32 s42, s54
	s_mov_b32 s20, s42
	s_barrier
	s_cbranch_scc0 .LBB0_268

; #define PG8_STAGE(bufoff, gbase, voff) do { _Pragma("unroll") for (int _i = 0; _i < 2; ++_i) \
;         __builtin_amdgcn_global_load_lds((const unsigned*)((const char*)(gbase) + (voff)[_i]), (PG8_LAS unsigned*)(lds + (bufoff) + ldsw + _i * 8192), 16, 0, 0); } while (0)
; #define PG8_LDA(dst, b, h) do { _Pragma("unroll") for (int m = 0; m < 4; ++m) _Pragma("unroll") for (int k = 0; k < 2; ++k) dst[m][k] = *(const PG8_LAS bf16x8*)(lds + PG8_SA(b, h) + aoff + m * 2048 + k * 1024); } while (0)
; #define PG8_LDB(dst, b, h) do { _Pragma("unroll") for (int n = 0; n < 2; ++n) _Pragma("unroll") for (int k = 0; k < 2; ++k) dst[n][k] = *(const PG8_LAS bf16x8*)(lds + PG8_SB(b, h) + boff + n * 2048 + k * 1024); } while (0)
; #define PG8_SCHED __builtin_amdgcn_sched_barrier(0)
; template <class Epi, class Sched>
; __device__ __forceinline__ void gemm_phase(PG8_LAS unsigned char* lds, const Gemm g, const Sched& S, const Epi& E) {
;     ...
;             const bool last = (t == nt - 2);
;             const char* a1 = cA + (size_t)(t + 1) * kstep;
;             const char* a2 = last ? nA : cA + (size_t)(t + 2) * kstep; const char* b2 = last ? nB : cB + (size_t)(t + 2) * kstep;
;             const char* a3 = a2 + kstep; const char* b3 = b2 + kstep;
;             if (last && has_next) S.a_ready(nxt);
;             PG8_LDB(B0, 0, 0); PG8_SCHED; PG8_LDA(At, 0, 0); PG8_STAGE(PG8_SA(1, 1), a1 + hstep, voffA);
.LBB0_287:
	s_add_u32 s20, s20, 0x80
	s_addc_u32 s21, s21, 0
	s_add_u32 s3, s22, 0x100
	s_addc_u32 s40, s23, 0
	s_mov_b32 s22, 0
	s_add_i32 s41, s22, 2
	s_add_u32 s24, s20, 0x80
	s_addc_u32 s23, s21, 0
	s_add_i32 s63, 0, 0x10000
	v_add_u32_e32 v155, s63, v152
	ds_read_b128 v[156:159], v155
	ds_read_b128 v[160:163], v155 offset:1024
	ds_read_b128 v[164:167], v155 offset:2048
	ds_read_b128 v[168:171], v155 offset:3072
	s_cmp_eq_u32 s55, s22
	s_cselect_b32 s22, s12, s24
	s_cselect_b32 s23, s13, s23
	s_cselect_b32 s25, s17, s40
	s_cselect_b32 s24, s16, s3
	v_lshl_add_u64 v[172:173], s[20:21], 0, v[148:149]
	s_add_i32 m0, s43, 0xc000
	ds_read_b128 v[176:179], v154
	ds_read_b128 v[184:187], v154 offset:2048
	ds_read_b128 v[192:195], v154 offset:4096
	ds_read_b128 v[200:203], v154 offset:6144
	ds_read_b128 v[180:183], v154 offset:1024
	ds_read_b128 v[188:191], v154 offset:3072
	ds_read_b128 v[196:199], v154 offset:5120
	ds_read_b128 v[204:207], v154 offset:7168
	global_load_lds_dwordx4 v[172:173], off
	s_add_i32 m0, s43, 0xe000
	v_lshl_add_u64 v[172:173], s[20:21], 0, v[150:151]
	global_load_lds_dwordx4 v[172:173], off
	s_waitcnt lgkmcnt(8)
	s_barrier

; #define PG8_MMA(ai, bj, At, Bt) do { __builtin_amdgcn_s_setprio(1); _Pragma("unroll") for (int m = 0; m < 4; ++m) _Pragma("unroll") for (int n = 0; n < 2; ++n) _Pragma("unroll") for (int k = 0; k < 2; ++k) \
;         acc[ai][bj][m][n] = __builtin_amdgcn_mfma_f32_16x16x32_bf16(Bt[n][k], At[m][k], acc[ai][bj][m][n], 0, 0, 0); __builtin_amdgcn_s_setprio(0); } while (0)
; #define PG8_WAIT_L(n) asm volatile("s_waitcnt lgkmcnt(" #n ")" ::: "memory")
; #define PG8_BAR __builtin_amdgcn_s_barrier()
; #define PG8_SCHED __builtin_amdgcn_sched_barrier(0)
; template <class Epi, class Sched>
; __device__ __forceinline__ void gemm_phase(PG8_LAS unsigned char* lds, const Gemm g, const Sched& S, const Epi& E) {
;     ...
;             PG8_WAIT_L(8); PG8_BAR; PG8_WAIT_L(0); PG8_MMA(0, 0, At, B0); PG8_BAR; PG8_SCHED;
	s_waitcnt lgkmcnt(7)
	v_mfma_f32_16x16x32_bf16 v[126:129], v[156:159], v[176:179], 0
	v_mfma_f32_16x16x32_bf16 v[122:125], v[164:167], v[176:179], 0

; #define PG8_MMA(ai, bj, At, Bt) do { __builtin_amdgcn_s_setprio(1); _Pragma("unroll") for (int m = 0; m < 4; ++m) _Pragma("unroll") for (int n = 0; n < 2; ++n) _Pragma("unroll") for (int k = 0; k < 2; ++k) \
;         acc[ai][bj][m][n] = __builtin_amdgcn_mfma_f32_16x16x32_bf16(Bt[n][k], At[m][k], acc[ai][bj][m][n], 0, 0, 0); __builtin_amdgcn_s_setprio(0); } while (0)
; #define PG8_WAIT_L(n) asm volatile("s_waitcnt lgkmcnt(" #n ")" ::: "memory")
; #define PG8_BAR __builtin_amdgcn_s_barrier()
; #define PG8_SCHED __builtin_amdgcn_sched_barrier(0)
; template <class Epi, class Sched>
; __device__ __forceinline__ void gemm_phase(PG8_LAS unsigned char* lds, const Gemm g, const Sched& S, const Epi& E) {
;     ...
;             PG8_WAIT_L(8); PG8_BAR; PG8_WAIT_L(0); PG8_MMA(0, 0, At, B0); PG8_BAR; PG8_SCHED;
	s_waitcnt lgkmcnt(6)
	v_mfma_f32_16x16x32_bf16 v[118:121], v[156:159], v[184:187], 0
	v_mfma_f32_16x16x32_bf16 v[114:117], v[164:167], v[184:187], 0

; #define PG8_MMA(ai, bj, At, Bt) do { __builtin_amdgcn_s_setprio(1); _Pragma("unroll") for (int m = 0; m < 4; ++m) _Pragma("unroll") for (int n = 0; n < 2; ++n) _Pragma("unroll") for (int k = 0; k < 2; ++k) \
;         acc[ai][bj][m][n] = __builtin_amdgcn_mfma_f32_16x16x32_bf16(Bt[n][k], At[m][k], acc[ai][bj][m][n], 0, 0, 0); __builtin_amdgcn_s_setprio(0); } while (0)
; #define PG8_WAIT_L(n) asm volatile("s_waitcnt lgkmcnt(" #n ")" ::: "memory")
; #define PG8_BAR __builtin_amdgcn_s_barrier()
; #define PG8_SCHED __builtin_amdgcn_sched_barrier(0)
; template <class Epi, class Sched>
; __device__ __forceinline__ void gemm_phase(PG8_LAS unsigned char* lds, const Gemm g, const Sched& S, const Epi& E) {
;     ...
;             PG8_WAIT_L(8); PG8_BAR; PG8_WAIT_L(0); PG8_MMA(0, 0, At, B0); PG8_BAR; PG8_SCHED;
	s_waitcnt lgkmcnt(5)
	v_mfma_f32_16x16x32_bf16 v[110:113], v[156:159], v[192:195], 0
	v_mfma_f32_16x16x32_bf16 v[106:109], v[164:167], v[192:195], 0

; #define PG8_MMA(ai, bj, At, Bt) do { __builtin_amdgcn_s_setprio(1); _Pragma("unroll") for (int m = 0; m < 4; ++m) _Pragma("unroll") for (int n = 0; n < 2; ++n) _Pragma("unroll") for (int k = 0; k < 2; ++k) \
;         acc[ai][bj][m][n] = __builtin_amdgcn_mfma_f32_16x16x32_bf16(Bt[n][k], At[m][k], acc[ai][bj][m][n], 0, 0, 0); __builtin_amdgcn_s_setprio(0); } while (0)
; #define PG8_WAIT_L(n) asm volatile("s_waitcnt lgkmcnt(" #n ")" ::: "memory")
; #define PG8_BAR __builtin_amdgcn_s_barrier()
; #define PG8_SCHED __builtin_amdgcn_sched_barrier(0)
; template <class Epi, class Sched>
; __device__ __forceinline__ void gemm_phase(PG8_LAS unsigned char* lds, const Gemm g, const Sched& S, const Epi& E) {
;     ...
;             PG8_WAIT_L(8); PG8_BAR; PG8_WAIT_L(0); PG8_MMA(0, 0, At, B0); PG8_BAR; PG8_SCHED;
	s_waitcnt lgkmcnt(4)
	v_mfma_f32_16x16x32_bf16 v[98:101], v[156:159], v[200:203], 0
	v_mfma_f32_16x16x32_bf16 v[90:93], v[164:167], v[200:203], 0
	s_waitcnt lgkmcnt(3)
	v_mfma_f32_16x16x32_bf16 v[126:129], v[160:163], v[180:183], v[126:129]
	v_mfma_f32_16x16x32_bf16 v[122:125], v[168:171], v[180:183], v[122:125]
	s_waitcnt lgkmcnt(2)
	v_mfma_f32_16x16x32_bf16 v[118:121], v[160:163], v[188:191], v[118:121]
	v_mfma_f32_16x16x32_bf16 v[114:117], v[168:171], v[188:191], v[114:117]
	s_waitcnt lgkmcnt(1)
	v_mfma_f32_16x16x32_bf16 v[110:113], v[160:163], v[196:199], v[110:113]
	v_mfma_f32_16x16x32_bf16 v[106:109], v[168:171], v[196:199], v[106:109]

; #define PG8_STAGE(bufoff, gbase, voff) do { _Pragma("unroll") for (int _i = 0; _i < 2; ++_i) \
;         __builtin_amdgcn_global_load_lds((const unsigned*)((const char*)(gbase) + (voff)[_i]), (PG8_LAS unsigned*)(lds + (bufoff) + ldsw + _i * 8192), 16, 0, 0); } while (0)
; #define PG8_LDB(dst, b, h) do { _Pragma("unroll") for (int n = 0; n < 2; ++n) _Pragma("unroll") for (int k = 0; k < 2; ++k) dst[n][k] = *(const PG8_LAS bf16x8*)(lds + PG8_SB(b, h) + boff + n * 2048 + k * 1024); } while (0)
; #define PG8_MMA(ai, bj, At, Bt) do { __builtin_amdgcn_s_setprio(1); _Pragma("unroll") for (int m = 0; m < 4; ++m) _Pragma("unroll") for (int n = 0; n < 2; ++n) _Pragma("unroll") for (int k = 0; k < 2; ++k) \
;         acc[ai][bj][m][n] = __builtin_amdgcn_mfma_f32_16x16x32_bf16(Bt[n][k], At[m][k], acc[ai][bj][m][n], 0, 0, 0); __builtin_amdgcn_s_setprio(0); } while (0)
; #define PG8_WAIT_L(n) asm volatile("s_waitcnt lgkmcnt(" #n ")" ::: "memory")
; #define PG8_BAR __builtin_amdgcn_s_barrier()
; #define PG8_SCHED __builtin_amdgcn_sched_barrier(0)
; template <class Epi, class Sched>
; __device__ __forceinline__ void gemm_phase(PG8_LAS unsigned char* lds, const Gemm g, const Sched& S, const Epi& E) {
;     ...
;             PG8_WAIT_L(8); PG8_BAR; PG8_WAIT_L(0); PG8_MMA(0, 0, At, B0); PG8_BAR; PG8_SCHED;
;             PG8_LDB(B1, 0, 1); PG8_STAGE(PG8_SB(0, 0), b2, voffB);
;             PG8_BAR; PG8_WAIT_L(0); PG8_MMA(0, 1, At, B1); PG8_BAR;
	s_waitcnt lgkmcnt(0)
	v_mfma_f32_16x16x32_bf16 v[98:101], v[160:163], v[204:207], v[98:101]
	v_mfma_f32_16x16x32_bf16 v[90:93], v[168:171], v[204:207], v[90:93]
	s_barrier
	s_add_i32 s64, 0, 0x14000
	s_add_i32 s63, s63, s37
	v_add_u32_e32 v155, s64, v152
	v_lshl_add_u64 v[172:173], s[24:25], 0, v[48:49]
	s_mov_b32 m0, s63
	ds_read_b128 v[208:211], v155
	ds_read_b128 v[216:219], v155 offset:2048
	ds_read_b128 v[212:215], v155 offset:1024
	ds_read_b128 v[234:237], v155 offset:3072
	global_load_lds_dwordx4 v[172:173], off
	s_add_i32 m0, s63, 0x2000
	v_lshl_add_u64 v[224:225], s[24:25], 0, v[130:131]
	global_load_lds_dwordx4 v[224:225], off
	s_barrier

; #define PG8_STAGE(bufoff, gbase, voff) do { _Pragma("unroll") for (int _i = 0; _i < 2; ++_i) \
;         __builtin_amdgcn_global_load_lds((const unsigned*)((const char*)(gbase) + (voff)[_i]), (PG8_LAS unsigned*)(lds + (bufoff) + ldsw + _i * 8192), 16, 0, 0); } while (0)
; #define PG8_LDB(dst, b, h) do { _Pragma("unroll") for (int n = 0; n < 2; ++n) _Pragma("unroll") for (int k = 0; k < 2; ++k) dst[n][k] = *(const PG8_LAS bf16x8*)(lds + PG8_SB(b, h) + boff + n * 2048 + k * 1024); } while (0)
; #define PG8_MMA(ai, bj, At, Bt) do { __builtin_amdgcn_s_setprio(1); _Pragma("unroll") for (int m = 0; m < 4; ++m) _Pragma("unroll") for (int n = 0; n < 2; ++n) _Pragma("unroll") for (int k = 0; k < 2; ++k) \
;         acc[ai][bj][m][n] = __builtin_amdgcn_mfma_f32_16x16x32_bf16(Bt[n][k], At[m][k], acc[ai][bj][m][n], 0, 0, 0); __builtin_amdgcn_s_setprio(0); } while (0)
; #define PG8_WAIT_L(n) asm volatile("s_waitcnt lgkmcnt(" #n ")" ::: "memory")
; #define PG8_BAR __builtin_amdgcn_s_barrier()
; template <class Epi, class Sched>
; __device__ __forceinline__ void gemm_phase(PG8_LAS unsigned char* lds, const Gemm g, const Sched& S, const Epi& E) {
;     ...
;             PG8_LDB(B1, 0, 1); PG8_STAGE(PG8_SB(0, 0), b2, voffB);
;             PG8_BAR; PG8_WAIT_L(0); PG8_MMA(0, 1, At, B1); PG8_BAR;
	s_waitcnt lgkmcnt(3)
	v_mfma_f32_16x16x32_bf16 v[102:105], v[208:211], v[176:179], 0

; #define PG8_MMA(ai, bj, At, Bt) do { __builtin_amdgcn_s_setprio(1); _Pragma("unroll") for (int m = 0; m < 4; ++m) _Pragma("unroll") for (int n = 0; n < 2; ++n) _Pragma("unroll") for (int k = 0; k < 2; ++k) \
;         acc[ai][bj][m][n] = __builtin_amdgcn_mfma_f32_16x16x32_bf16(Bt[n][k], At[m][k], acc[ai][bj][m][n], 0, 0, 0); __builtin_amdgcn_s_setprio(0); } while (0)
; #define PG8_WAIT_L(n) asm volatile("s_waitcnt lgkmcnt(" #n ")" ::: "memory")
; #define PG8_BAR __builtin_amdgcn_s_barrier()
; template <class Epi, class Sched>
; __device__ __forceinline__ void gemm_phase(PG8_LAS unsigned char* lds, const Gemm g, const Sched& S, const Epi& E) {
;     ...
;             PG8_BAR; PG8_WAIT_L(0); PG8_MMA(0, 1, At, B1); PG8_BAR;
	s_waitcnt lgkmcnt(2)
	v_mfma_f32_16x16x32_bf16 v[94:97], v[216:219], v[176:179], 0
	v_mfma_f32_16x16x32_bf16 v[86:89], v[208:211], v[184:187], 0
	v_mfma_f32_16x16x32_bf16 v[82:85], v[216:219], v[184:187], 0
	v_mfma_f32_16x16x32_bf16 v[78:81], v[208:211], v[192:195], 0
	v_mfma_f32_16x16x32_bf16 v[74:77], v[216:219], v[192:195], 0
	v_mfma_f32_16x16x32_bf16 v[70:73], v[208:211], v[200:203], 0
	v_mfma_f32_16x16x32_bf16 v[66:69], v[216:219], v[200:203], 0
	s_waitcnt lgkmcnt(1)
	v_mfma_f32_16x16x32_bf16 v[102:105], v[212:215], v[180:183], v[102:105]

; #define PG8_STAGE(bufoff, gbase, voff) do { _Pragma("unroll") for (int _i = 0; _i < 2; ++_i) \
;         __builtin_amdgcn_global_load_lds((const unsigned*)((const char*)(gbase) + (voff)[_i]), (PG8_LAS unsigned*)(lds + (bufoff) + ldsw + _i * 8192), 16, 0, 0); } while (0)
; #define PG8_LDA(dst, b, h) do { _Pragma("unroll") for (int m = 0; m < 4; ++m) _Pragma("unroll") for (int k = 0; k < 2; ++k) dst[m][k] = *(const PG8_LAS bf16x8*)(lds + PG8_SA(b, h) + aoff + m * 2048 + k * 1024); } while (0)
; #define PG8_MMA(ai, bj, At, Bt) do { __builtin_amdgcn_s_setprio(1); _Pragma("unroll") for (int m = 0; m < 4; ++m) _Pragma("unroll") for (int n = 0; n < 2; ++n) _Pragma("unroll") for (int k = 0; k < 2; ++k) \
;         acc[ai][bj][m][n] = __builtin_amdgcn_mfma_f32_16x16x32_bf16(Bt[n][k], At[m][k], acc[ai][bj][m][n], 0, 0, 0); __builtin_amdgcn_s_setprio(0); } while (0)
; #define PG8_WAIT_L(n) asm volatile("s_waitcnt lgkmcnt(" #n ")" ::: "memory")
; #define PG8_BAR __builtin_amdgcn_s_barrier()
; #define PG8_SCHED __builtin_amdgcn_sched_barrier(0)
; template <class Epi, class Sched>
; __device__ __forceinline__ void gemm_phase(PG8_LAS unsigned char* lds, const Gemm g, const Sched& S, const Epi& E) {
;     ...
;             PG8_BAR; PG8_WAIT_L(0); PG8_MMA(0, 1, At, B1); PG8_BAR;
;             PG8_LDA(At, 0, 1); PG8_STAGE(PG8_SA(0, 0), a2, voffA);
;             PG8_BAR; PG8_WAIT_L(0); PG8_MMA(1, 0, At, B0); PG8_BAR; PG8_SCHED;
	s_waitcnt lgkmcnt(0)
	v_mfma_f32_16x16x32_bf16 v[94:97], v[234:237], v[180:183], v[94:97]
	v_mfma_f32_16x16x32_bf16 v[86:89], v[212:215], v[188:191], v[86:89]
	v_mfma_f32_16x16x32_bf16 v[82:85], v[234:237], v[188:191], v[82:85]
	v_mfma_f32_16x16x32_bf16 v[78:81], v[212:215], v[196:199], v[78:81]
	v_mfma_f32_16x16x32_bf16 v[74:77], v[234:237], v[196:199], v[74:77]
	v_mfma_f32_16x16x32_bf16 v[70:73], v[212:215], v[204:207], v[70:73]
	v_mfma_f32_16x16x32_bf16 v[66:69], v[234:237], v[204:207], v[66:69]
	s_mov_b32 m0, s43
	v_lshl_add_u64 v[228:229], s[22:23], 0, v[48:49]
	s_barrier
	ds_read_b128 v[176:179], v154 offset:16384
	ds_read_b128 v[184:187], v154 offset:18432
	ds_read_b128 v[192:195], v154 offset:20480
	ds_read_b128 v[200:203], v154 offset:22528
	ds_read_b128 v[180:183], v154 offset:17408
	ds_read_b128 v[188:191], v154 offset:19456
	ds_read_b128 v[196:199], v154 offset:21504
	ds_read_b128 v[204:207], v154 offset:23552
	global_load_lds_dwordx4 v[228:229], off
	s_mov_b32 m0, s44
	v_lshl_add_u64 v[238:239], s[22:23], 0, v[130:131]
	global_load_lds_dwordx4 v[238:239], off
	s_barrier

; #define PG8_MMA(ai, bj, At, Bt) do { __builtin_amdgcn_s_setprio(1); _Pragma("unroll") for (int m = 0; m < 4; ++m) _Pragma("unroll") for (int n = 0; n < 2; ++n) _Pragma("unroll") for (int k = 0; k < 2; ++k) \
;         acc[ai][bj][m][n] = __builtin_amdgcn_mfma_f32_16x16x32_bf16(Bt[n][k], At[m][k], acc[ai][bj][m][n], 0, 0, 0); __builtin_amdgcn_s_setprio(0); } while (0)
; #define PG8_WAIT_L(n) asm volatile("s_waitcnt lgkmcnt(" #n ")" ::: "memory")
; #define PG8_BAR __builtin_amdgcn_s_barrier()
; #define PG8_SCHED __builtin_amdgcn_sched_barrier(0)
; template <class Epi, class Sched>
; __device__ __forceinline__ void gemm_phase(PG8_LAS unsigned char* lds, const Gemm g, const Sched& S, const Epi& E) {
;     ...
;             PG8_BAR; PG8_WAIT_L(0); PG8_MMA(1, 0, At, B0); PG8_BAR; PG8_SCHED;
	s_waitcnt lgkmcnt(7)
	v_mfma_f32_16x16x32_bf16 v[62:65], v[156:159], v[176:179], 0
	v_mfma_f32_16x16x32_bf16 v[58:61], v[164:167], v[176:179], 0

; #define PG8_MMA(ai, bj, At, Bt) do { __builtin_amdgcn_s_setprio(1); _Pragma("unroll") for (int m = 0; m < 4; ++m) _Pragma("unroll") for (int n = 0; n < 2; ++n) _Pragma("unroll") for (int k = 0; k < 2; ++k) \
;         acc[ai][bj][m][n] = __builtin_amdgcn_mfma_f32_16x16x32_bf16(Bt[n][k], At[m][k], acc[ai][bj][m][n], 0, 0, 0); __builtin_amdgcn_s_setprio(0); } while (0)
; #define PG8_WAIT_L(n) asm volatile("s_waitcnt lgkmcnt(" #n ")" ::: "memory")
; #define PG8_BAR __builtin_amdgcn_s_barrier()
; #define PG8_SCHED __builtin_amdgcn_sched_barrier(0)
; template <class Epi, class Sched>
; __device__ __forceinline__ void gemm_phase(PG8_LAS unsigned char* lds, const Gemm g, const Sched& S, const Epi& E) {
;     ...
;             PG8_BAR; PG8_WAIT_L(0); PG8_MMA(1, 0, At, B0); PG8_BAR; PG8_SCHED;
	s_waitcnt lgkmcnt(6)
	v_mfma_f32_16x16x32_bf16 v[54:57], v[156:159], v[184:187], 0
	v_mfma_f32_16x16x32_bf16 v[50:53], v[164:167], v[184:187], 0

; #define PG8_MMA(ai, bj, At, Bt) do { __builtin_amdgcn_s_setprio(1); _Pragma("unroll") for (int m = 0; m < 4; ++m) _Pragma("unroll") for (int n = 0; n < 2; ++n) _Pragma("unroll") for (int k = 0; k < 2; ++k) \
;         acc[ai][bj][m][n] = __builtin_amdgcn_mfma_f32_16x16x32_bf16(Bt[n][k], At[m][k], acc[ai][bj][m][n], 0, 0, 0); __builtin_amdgcn_s_setprio(0); } while (0)
; #define PG8_WAIT_L(n) asm volatile("s_waitcnt lgkmcnt(" #n ")" ::: "memory")
; #define PG8_BAR __builtin_amdgcn_s_barrier()
; #define PG8_SCHED __builtin_amdgcn_sched_barrier(0)
; template <class Epi, class Sched>
; __device__ __forceinline__ void gemm_phase(PG8_LAS unsigned char* lds, const Gemm g, const Sched& S, const Epi& E) {
;     ...
;             PG8_BAR; PG8_WAIT_L(0); PG8_MMA(1, 0, At, B0); PG8_BAR; PG8_SCHED;
	s_waitcnt lgkmcnt(5)
	v_mfma_f32_16x16x32_bf16 v[44:47], v[156:159], v[192:195], 0
	v_mfma_f32_16x16x32_bf16 v[40:43], v[164:167], v[192:195], 0

; #define PG8_MMA(ai, bj, At, Bt) do { __builtin_amdgcn_s_setprio(1); _Pragma("unroll") for (int m = 0; m < 4; ++m) _Pragma("unroll") for (int n = 0; n < 2; ++n) _Pragma("unroll") for (int k = 0; k < 2; ++k) \
;         acc[ai][bj][m][n] = __builtin_amdgcn_mfma_f32_16x16x32_bf16(Bt[n][k], At[m][k], acc[ai][bj][m][n], 0, 0, 0); __builtin_amdgcn_s_setprio(0); } while (0)
; #define PG8_WAIT_L(n) asm volatile("s_waitcnt lgkmcnt(" #n ")" ::: "memory")
; #define PG8_BAR __builtin_amdgcn_s_barrier()
; #define PG8_SCHED __builtin_amdgcn_sched_barrier(0)
; template <class Epi, class Sched>
; __device__ __forceinline__ void gemm_phase(PG8_LAS unsigned char* lds, const Gemm g, const Sched& S, const Epi& E) {
;     ...
;             PG8_BAR; PG8_WAIT_L(0); PG8_MMA(1, 0, At, B0); PG8_BAR; PG8_SCHED;
	s_waitcnt lgkmcnt(4)
	v_mfma_f32_16x16x32_bf16 v[32:35], v[156:159], v[200:203], 0
	v_mfma_f32_16x16x32_bf16 v[24:27], v[164:167], v[200:203], 0
	s_waitcnt lgkmcnt(3)
	v_mfma_f32_16x16x32_bf16 v[62:65], v[160:163], v[180:183], v[62:65]
	v_mfma_f32_16x16x32_bf16 v[58:61], v[168:171], v[180:183], v[58:61]
	s_waitcnt lgkmcnt(2)
	v_mfma_f32_16x16x32_bf16 v[54:57], v[160:163], v[188:191], v[54:57]
	v_mfma_f32_16x16x32_bf16 v[50:53], v[168:171], v[188:191], v[50:53]
	s_waitcnt lgkmcnt(1)
	v_mfma_f32_16x16x32_bf16 v[44:47], v[160:163], v[196:199], v[44:47]
	v_mfma_f32_16x16x32_bf16 v[40:43], v[168:171], v[196:199], v[40:43]

; #define PG8_STAGE(bufoff, gbase, voff) do { _Pragma("unroll") for (int _i = 0; _i < 2; ++_i) \
;         __builtin_amdgcn_global_load_lds((const unsigned*)((const char*)(gbase) + (voff)[_i]), (PG8_LAS unsigned*)(lds + (bufoff) + ldsw + _i * 8192), 16, 0, 0); } while (0)
; #define PG8_LDA(dst, b, h) do { _Pragma("unroll") for (int m = 0; m < 4; ++m) _Pragma("unroll") for (int k = 0; k < 2; ++k) dst[m][k] = *(const PG8_LAS bf16x8*)(lds + PG8_SA(b, h) + aoff + m * 2048 + k * 1024); } while (0)
; #define PG8_LDB(dst, b, h) do { _Pragma("unroll") for (int n = 0; n < 2; ++n) _Pragma("unroll") for (int k = 0; k < 2; ++k) dst[n][k] = *(const PG8_LAS bf16x8*)(lds + PG8_SB(b, h) + boff + n * 2048 + k * 1024); } while (0)
; #define PG8_MMA(ai, bj, At, Bt) do { __builtin_amdgcn_s_setprio(1); _Pragma("unroll") for (int m = 0; m < 4; ++m) _Pragma("unroll") for (int n = 0; n < 2; ++n) _Pragma("unroll") for (int k = 0; k < 2; ++k) \
;         acc[ai][bj][m][n] = __builtin_amdgcn_mfma_f32_16x16x32_bf16(Bt[n][k], At[m][k], acc[ai][bj][m][n], 0, 0, 0); __builtin_amdgcn_s_setprio(0); } while (0)
; #define PG8_WAIT_V(n) asm volatile("s_waitcnt vmcnt(" #n ")" ::: "memory")
; #define PG8_WAIT_L(n) asm volatile("s_waitcnt lgkmcnt(" #n ")" ::: "memory")
; #define PG8_BAR __builtin_amdgcn_s_barrier()
; #define PG8_SCHED __builtin_amdgcn_sched_barrier(0)
; template <class Epi, class Sched>
; __device__ __forceinline__ void gemm_phase(PG8_LAS unsigned char* lds, const Gemm g, const Sched& S, const Epi& E) {
;     ...
;             PG8_BAR; PG8_WAIT_L(0); PG8_MMA(1, 0, At, B0); PG8_BAR; PG8_SCHED;
;             PG8_STAGE(PG8_SB(0, 1), b2 + hstep, voffB);
;             PG8_WAIT_V(6); PG8_BAR; PG8_MMA(1, 1, At, B1); PG8_BAR;
;             PG8_LDB(B0, 1, 0); PG8_SCHED; PG8_LDA(At, 1, 0); PG8_STAGE(PG8_SA(0, 1), a2 + hstep, voffA);
;             PG8_WAIT_L(8); PG8_BAR; PG8_WAIT_L(0); PG8_MMA(0, 0, At, B0); PG8_BAR; PG8_SCHED;
	s_waitcnt lgkmcnt(0)
	v_mfma_f32_16x16x32_bf16 v[32:35], v[160:163], v[204:207], v[32:35]
	v_mfma_f32_16x16x32_bf16 v[24:27], v[168:171], v[204:207], v[24:27]
	s_barrier
	s_add_u32 s24, s24, s10
	s_addc_u32 s25, s25, 0
	s_add_i32 s63, s64, s37
	v_lshl_add_u64 v[240:241], s[24:25], 0, v[48:49]
	s_mov_b32 m0, s63
	v_lshl_add_u64 v[242:243], s[24:25], 0, v[130:131]
	global_load_lds_dwordx4 v[240:241], off
	s_add_i32 m0, s63, 0x2000
	s_nop 0
	global_load_lds_dwordx4 v[242:243], off
	s_waitcnt vmcnt(6)
	s_barrier
	v_mfma_f32_16x16x32_bf16 v[36:39], v[208:211], v[176:179], 0
	v_mfma_f32_16x16x32_bf16 v[28:31], v[216:219], v[176:179], 0
	v_mfma_f32_16x16x32_bf16 v[20:23], v[208:211], v[184:187], 0
	v_mfma_f32_16x16x32_bf16 v[16:19], v[216:219], v[184:187], 0
	v_mfma_f32_16x16x32_bf16 v[12:15], v[208:211], v[192:195], 0
	v_mfma_f32_16x16x32_bf16 v[8:11], v[216:219], v[192:195], 0
	v_mfma_f32_16x16x32_bf16 v[4:7], v[208:211], v[200:203], 0
	v_mfma_f32_16x16x32_bf16 v[0:3], v[216:219], v[200:203], 0
	v_mfma_f32_16x16x32_bf16 v[36:39], v[212:215], v[180:183], v[36:39]
	v_mfma_f32_16x16x32_bf16 v[28:31], v[234:237], v[180:183], v[28:31]
	v_mfma_f32_16x16x32_bf16 v[20:23], v[212:215], v[188:191], v[20:23]
	v_mfma_f32_16x16x32_bf16 v[16:19], v[234:237], v[188:191], v[16:19]
	v_mfma_f32_16x16x32_bf16 v[12:15], v[212:215], v[196:199], v[12:15]
	v_mfma_f32_16x16x32_bf16 v[8:11], v[234:237], v[196:199], v[8:11]
	v_mfma_f32_16x16x32_bf16 v[4:7], v[212:215], v[204:207], v[4:7]
	v_mfma_f32_16x16x32_bf16 v[0:3], v[234:237], v[204:207], v[0:3]
	s_add_i32 s24, 0, 0x18000
	v_add_u32_e32 v155, s24, v152
	s_barrier
	ds_read_b128 v[156:159], v155
	ds_read_b128 v[160:163], v155 offset:1024
	ds_read_b128 v[164:167], v155 offset:2048
	ds_read_b128 v[168:171], v155 offset:3072
	s_add_u32 s22, s22, s10
	s_addc_u32 s23, s23, 0
	s_mov_b32 m0, s46
	v_lshl_add_u64 v[208:209], s[22:23], 0, v[48:49]
	ds_read_b128 v[176:179], v154 offset:32768
	ds_read_b128 v[184:187], v154 offset:34816
	ds_read_b128 v[192:195], v154 offset:36864
	ds_read_b128 v[200:203], v154 offset:38912
	ds_read_b128 v[180:183], v154 offset:33792
	ds_read_b128 v[188:191], v154 offset:35840
	ds_read_b128 v[196:199], v154 offset:37888
	ds_read_b128 v[204:207], v154 offset:39936
	global_load_lds_dwordx4 v[208:209], off
	s_mov_b32 m0, s47
	v_lshl_add_u64 v[208:209], s[22:23], 0, v[130:131]
	global_load_lds_dwordx4 v[208:209], off
	s_waitcnt lgkmcnt(8)
	s_barrier

; #define PG8_MMA(ai, bj, At, Bt) do { __builtin_amdgcn_s_setprio(1); _Pragma("unroll") for (int m = 0; m < 4; ++m) _Pragma("unroll") for (int n = 0; n < 2; ++n) _Pragma("unroll") for (int k = 0; k < 2; ++k) \
;         acc[ai][bj][m][n] = __builtin_amdgcn_mfma_f32_16x16x32_bf16(Bt[n][k], At[m][k], acc[ai][bj][m][n], 0, 0, 0); __builtin_amdgcn_s_setprio(0); } while (0)
; #define PG8_WAIT_L(n) asm volatile("s_waitcnt lgkmcnt(" #n ")" ::: "memory")
; #define PG8_BAR __builtin_amdgcn_s_barrier()
; #define PG8_SCHED __builtin_amdgcn_sched_barrier(0)
; template <class Epi, class Sched>
; __device__ __forceinline__ void gemm_phase(PG8_LAS unsigned char* lds, const Gemm g, const Sched& S, const Epi& E) {
;     ...
;             PG8_WAIT_L(8); PG8_BAR; PG8_WAIT_L(0); PG8_MMA(0, 0, At, B0); PG8_BAR; PG8_SCHED;
	s_waitcnt lgkmcnt(7)
	v_mfma_f32_16x16x32_bf16 v[126:129], v[156:159], v[176:179], v[126:129]
	v_mfma_f32_16x16x32_bf16 v[122:125], v[164:167], v[176:179], v[122:125]

; #define PG8_MMA(ai, bj, At, Bt) do { __builtin_amdgcn_s_setprio(1); _Pragma("unroll") for (int m = 0; m < 4; ++m) _Pragma("unroll") for (int n = 0; n < 2; ++n) _Pragma("unroll") for (int k = 0; k < 2; ++k) \
;         acc[ai][bj][m][n] = __builtin_amdgcn_mfma_f32_16x16x32_bf16(Bt[n][k], At[m][k], acc[ai][bj][m][n], 0, 0, 0); __builtin_amdgcn_s_setprio(0); } while (0)
; #define PG8_WAIT_L(n) asm volatile("s_waitcnt lgkmcnt(" #n ")" ::: "memory")
; #define PG8_BAR __builtin_amdgcn_s_barrier()
; #define PG8_SCHED __builtin_amdgcn_sched_barrier(0)
; template <class Epi, class Sched>
; __device__ __forceinline__ void gemm_phase(PG8_LAS unsigned char* lds, const Gemm g, const Sched& S, const Epi& E) {
;     ...
;             PG8_WAIT_L(8); PG8_BAR; PG8_WAIT_L(0); PG8_MMA(0, 0, At, B0); PG8_BAR; PG8_SCHED;
	s_waitcnt lgkmcnt(6)
	v_mfma_f32_16x16x32_bf16 v[118:121], v[156:159], v[184:187], v[118:121]
	v_mfma_f32_16x16x32_bf16 v[114:117], v[164:167], v[184:187], v[114:117]

; #define PG8_MMA(ai, bj, At, Bt) do { __builtin_amdgcn_s_setprio(1); _Pragma("unroll") for (int m = 0; m < 4; ++m) _Pragma("unroll") for (int n = 0; n < 2; ++n) _Pragma("unroll") for (int k = 0; k < 2; ++k) \
;         acc[ai][bj][m][n] = __builtin_amdgcn_mfma_f32_16x16x32_bf16(Bt[n][k], At[m][k], acc[ai][bj][m][n], 0, 0, 0); __builtin_amdgcn_s_setprio(0); } while (0)
; #define PG8_WAIT_L(n) asm volatile("s_waitcnt lgkmcnt(" #n ")" ::: "memory")
; #define PG8_BAR __builtin_amdgcn_s_barrier()
; #define PG8_SCHED __builtin_amdgcn_sched_barrier(0)
; template <class Epi, class Sched>
; __device__ __forceinline__ void gemm_phase(PG8_LAS unsigned char* lds, const Gemm g, const Sched& S, const Epi& E) {
;     ...
;             PG8_WAIT_L(8); PG8_BAR; PG8_WAIT_L(0); PG8_MMA(0, 0, At, B0); PG8_BAR; PG8_SCHED;
	s_waitcnt lgkmcnt(5)
	v_mfma_f32_16x16x32_bf16 v[110:113], v[156:159], v[192:195], v[110:113]
	v_mfma_f32_16x16x32_bf16 v[106:109], v[164:167], v[192:195], v[106:109]

; #define PG8_MMA(ai, bj, At, Bt) do { __builtin_amdgcn_s_setprio(1); _Pragma("unroll") for (int m = 0; m < 4; ++m) _Pragma("unroll") for (int n = 0; n < 2; ++n) _Pragma("unroll") for (int k = 0; k < 2; ++k) \
;         acc[ai][bj][m][n] = __builtin_amdgcn_mfma_f32_16x16x32_bf16(Bt[n][k], At[m][k], acc[ai][bj][m][n], 0, 0, 0); __builtin_amdgcn_s_setprio(0); } while (0)
; #define PG8_WAIT_L(n) asm volatile("s_waitcnt lgkmcnt(" #n ")" ::: "memory")
; #define PG8_BAR __builtin_amdgcn_s_barrier()
; #define PG8_SCHED __builtin_amdgcn_sched_barrier(0)
; template <class Epi, class Sched>
; __device__ __forceinline__ void gemm_phase(PG8_LAS unsigned char* lds, const Gemm g, const Sched& S, const Epi& E) {
;     ...
;             PG8_WAIT_L(8); PG8_BAR; PG8_WAIT_L(0); PG8_MMA(0, 0, At, B0); PG8_BAR; PG8_SCHED;
	s_waitcnt lgkmcnt(4)
	v_mfma_f32_16x16x32_bf16 v[98:101], v[156:159], v[200:203], v[98:101]
	v_mfma_f32_16x16x32_bf16 v[90:93], v[164:167], v[200:203], v[90:93]
	s_waitcnt lgkmcnt(3)
	v_mfma_f32_16x16x32_bf16 v[126:129], v[160:163], v[180:183], v[126:129]
	v_mfma_f32_16x16x32_bf16 v[122:125], v[168:171], v[180:183], v[122:125]
	s_waitcnt lgkmcnt(2)
	v_mfma_f32_16x16x32_bf16 v[118:121], v[160:163], v[188:191], v[118:121]
	v_mfma_f32_16x16x32_bf16 v[114:117], v[168:171], v[188:191], v[114:117]
	s_waitcnt lgkmcnt(1)
	v_mfma_f32_16x16x32_bf16 v[110:113], v[160:163], v[196:199], v[110:113]
	v_mfma_f32_16x16x32_bf16 v[106:109], v[168:171], v[196:199], v[106:109]

; #define PG8_STAGE(bufoff, gbase, voff) do { _Pragma("unroll") for (int _i = 0; _i < 2; ++_i) \
;         __builtin_amdgcn_global_load_lds((const unsigned*)((const char*)(gbase) + (voff)[_i]), (PG8_LAS unsigned*)(lds + (bufoff) + ldsw + _i * 8192), 16, 0, 0); } while (0)
; #define PG8_LDB(dst, b, h) do { _Pragma("unroll") for (int n = 0; n < 2; ++n) _Pragma("unroll") for (int k = 0; k < 2; ++k) dst[n][k] = *(const PG8_LAS bf16x8*)(lds + PG8_SB(b, h) + boff + n * 2048 + k * 1024); } while (0)
; #define PG8_MMA(ai, bj, At, Bt) do { __builtin_amdgcn_s_setprio(1); _Pragma("unroll") for (int m = 0; m < 4; ++m) _Pragma("unroll") for (int n = 0; n < 2; ++n) _Pragma("unroll") for (int k = 0; k < 2; ++k) \
;         acc[ai][bj][m][n] = __builtin_amdgcn_mfma_f32_16x16x32_bf16(Bt[n][k], At[m][k], acc[ai][bj][m][n], 0, 0, 0); __builtin_amdgcn_s_setprio(0); } while (0)
; #define PG8_WAIT_L(n) asm volatile("s_waitcnt lgkmcnt(" #n ")" ::: "memory")
; #define PG8_BAR __builtin_amdgcn_s_barrier()
; #define PG8_SCHED __builtin_amdgcn_sched_barrier(0)
; template <class Epi, class Sched>
; __device__ __forceinline__ void gemm_phase(PG8_LAS unsigned char* lds, const Gemm g, const Sched& S, const Epi& E) {
;     ...
;             PG8_WAIT_L(8); PG8_BAR; PG8_WAIT_L(0); PG8_MMA(0, 0, At, B0); PG8_BAR; PG8_SCHED;
;             PG8_LDB(B1, 1, 1); PG8_STAGE(PG8_SB(1, 0), b3, voffB);
	s_waitcnt lgkmcnt(0)
	v_mfma_f32_16x16x32_bf16 v[98:101], v[160:163], v[204:207], v[98:101]
	v_mfma_f32_16x16x32_bf16 v[90:93], v[168:171], v[204:207], v[90:93]
	s_barrier
	s_add_i32 s22, 0, 0x1c000
	s_add_i32 s23, s24, s37
	v_add_u32_e32 v155, s22, v152
	v_lshl_add_u64 v[172:173], v[172:173], 0, s[0:1]
	s_mov_b32 m0, s23
	ds_read_b128 v[208:211], v155
	ds_read_b128 v[216:219], v155 offset:2048
	ds_read_b128 v[212:215], v155 offset:1024
	ds_read_b128 v[234:237], v155 offset:3072
	global_load_lds_dwordx4 v[172:173], off
	s_add_i32 m0, s23, 0x2000
	v_lshl_add_u64 v[172:173], v[224:225], 0, s[0:1]
	global_load_lds_dwordx4 v[172:173], off
	s_barrier

; #define PG8_MMA(ai, bj, At, Bt) do { __builtin_amdgcn_s_setprio(1); _Pragma("unroll") for (int m = 0; m < 4; ++m) _Pragma("unroll") for (int n = 0; n < 2; ++n) _Pragma("unroll") for (int k = 0; k < 2; ++k) \
;         acc[ai][bj][m][n] = __builtin_amdgcn_mfma_f32_16x16x32_bf16(Bt[n][k], At[m][k], acc[ai][bj][m][n], 0, 0, 0); __builtin_amdgcn_s_setprio(0); } while (0)
; #define PG8_WAIT_L(n) asm volatile("s_waitcnt lgkmcnt(" #n ")" ::: "memory")
; #define PG8_BAR __builtin_amdgcn_s_barrier()
; template <class Epi, class Sched>
; __device__ __forceinline__ void gemm_phase(PG8_LAS unsigned char* lds, const Gemm g, const Sched& S, const Epi& E) {
;     ...
;             PG8_BAR; PG8_WAIT_L(0); PG8_MMA(0, 1, At, B1); PG8_BAR;
	s_waitcnt lgkmcnt(3)
	v_mfma_f32_16x16x32_bf16 v[102:105], v[208:211], v[176:179], v[102:105]

; #define PG8_MMA(ai, bj, At, Bt) do { __builtin_amdgcn_s_setprio(1); _Pragma("unroll") for (int m = 0; m < 4; ++m) _Pragma("unroll") for (int n = 0; n < 2; ++n) _Pragma("unroll") for (int k = 0; k < 2; ++k) \
;         acc[ai][bj][m][n] = __builtin_amdgcn_mfma_f32_16x16x32_bf16(Bt[n][k], At[m][k], acc[ai][bj][m][n], 0, 0, 0); __builtin_amdgcn_s_setprio(0); } while (0)
; #define PG8_WAIT_L(n) asm volatile("s_waitcnt lgkmcnt(" #n ")" ::: "memory")
; #define PG8_BAR __builtin_amdgcn_s_barrier()
; template <class Epi, class Sched>
; __device__ __forceinline__ void gemm_phase(PG8_LAS unsigned char* lds, const Gemm g, const Sched& S, const Epi& E) {
;     ...
;             PG8_BAR; PG8_WAIT_L(0); PG8_MMA(0, 1, At, B1); PG8_BAR;
	s_waitcnt lgkmcnt(2)
	v_mfma_f32_16x16x32_bf16 v[94:97], v[216:219], v[176:179], v[94:97]
	v_mfma_f32_16x16x32_bf16 v[86:89], v[208:211], v[184:187], v[86:89]
	v_mfma_f32_16x16x32_bf16 v[82:85], v[216:219], v[184:187], v[82:85]
	v_mfma_f32_16x16x32_bf16 v[78:81], v[208:211], v[192:195], v[78:81]
	v_mfma_f32_16x16x32_bf16 v[74:77], v[216:219], v[192:195], v[74:77]
	v_mfma_f32_16x16x32_bf16 v[70:73], v[208:211], v[200:203], v[70:73]
	v_mfma_f32_16x16x32_bf16 v[66:69], v[216:219], v[200:203], v[66:69]
	s_waitcnt lgkmcnt(1)
	v_mfma_f32_16x16x32_bf16 v[102:105], v[212:215], v[180:183], v[102:105]

; #define PG8_STAGE(bufoff, gbase, voff) do { _Pragma("unroll") for (int _i = 0; _i < 2; ++_i) \
;         __builtin_amdgcn_global_load_lds((const unsigned*)((const char*)(gbase) + (voff)[_i]), (PG8_LAS unsigned*)(lds + (bufoff) + ldsw + _i * 8192), 16, 0, 0); } while (0)
; #define PG8_LDA(dst, b, h) do { _Pragma("unroll") for (int m = 0; m < 4; ++m) _Pragma("unroll") for (int k = 0; k < 2; ++k) dst[m][k] = *(const PG8_LAS bf16x8*)(lds + PG8_SA(b, h) + aoff + m * 2048 + k * 1024); } while (0)
; #define PG8_MMA(ai, bj, At, Bt) do { __builtin_amdgcn_s_setprio(1); _Pragma("unroll") for (int m = 0; m < 4; ++m) _Pragma("unroll") for (int n = 0; n < 2; ++n) _Pragma("unroll") for (int k = 0; k < 2; ++k) \
;         acc[ai][bj][m][n] = __builtin_amdgcn_mfma_f32_16x16x32_bf16(Bt[n][k], At[m][k], acc[ai][bj][m][n], 0, 0, 0); __builtin_amdgcn_s_setprio(0); } while (0)
; #define PG8_WAIT_L(n) asm volatile("s_waitcnt lgkmcnt(" #n ")" ::: "memory")
; #define PG8_BAR __builtin_amdgcn_s_barrier()
; #define PG8_SCHED __builtin_amdgcn_sched_barrier(0)
; template <class Epi, class Sched>
; __device__ __forceinline__ void gemm_phase(PG8_LAS unsigned char* lds, const Gemm g, const Sched& S, const Epi& E) {
;     ...
;             PG8_BAR; PG8_WAIT_L(0); PG8_MMA(0, 1, At, B1); PG8_BAR;
;             PG8_LDA(At, 1, 1); PG8_STAGE(PG8_SA(1, 0), a3, voffA);
;             PG8_BAR; PG8_WAIT_L(0); PG8_MMA(1, 0, At, B0); PG8_BAR; PG8_SCHED;
	s_waitcnt lgkmcnt(0)
	v_mfma_f32_16x16x32_bf16 v[94:97], v[234:237], v[180:183], v[94:97]
	v_mfma_f32_16x16x32_bf16 v[86:89], v[212:215], v[188:191], v[86:89]
	v_mfma_f32_16x16x32_bf16 v[82:85], v[234:237], v[188:191], v[82:85]
	v_mfma_f32_16x16x32_bf16 v[78:81], v[212:215], v[196:199], v[78:81]
	v_mfma_f32_16x16x32_bf16 v[74:77], v[234:237], v[196:199], v[74:77]
	v_mfma_f32_16x16x32_bf16 v[70:73], v[212:215], v[204:207], v[70:73]
	v_mfma_f32_16x16x32_bf16 v[66:69], v[234:237], v[204:207], v[66:69]
	s_mov_b32 m0, s50
	v_lshl_add_u64 v[172:173], v[228:229], 0, s[0:1]
	s_barrier
	ds_read_b128 v[176:179], v154 offset:49152
	ds_read_b128 v[184:187], v154 offset:51200
	ds_read_b128 v[192:195], v154 offset:53248
	ds_read_b128 v[200:203], v154 offset:55296
	ds_read_b128 v[180:183], v154 offset:50176
	ds_read_b128 v[188:191], v154 offset:52224
	ds_read_b128 v[196:199], v154 offset:54272
	ds_read_b128 v[204:207], v154 offset:56320
	global_load_lds_dwordx4 v[172:173], off
	s_mov_b32 m0, s51
	v_lshl_add_u64 v[172:173], v[238:239], 0, s[0:1]
	global_load_lds_dwordx4 v[172:173], off
	s_barrier

; #define PG8_MMA(ai, bj, At, Bt) do { __builtin_amdgcn_s_setprio(1); _Pragma("unroll") for (int m = 0; m < 4; ++m) _Pragma("unroll") for (int n = 0; n < 2; ++n) _Pragma("unroll") for (int k = 0; k < 2; ++k) \
;         acc[ai][bj][m][n] = __builtin_amdgcn_mfma_f32_16x16x32_bf16(Bt[n][k], At[m][k], acc[ai][bj][m][n], 0, 0, 0); __builtin_amdgcn_s_setprio(0); } while (0)
; #define PG8_WAIT_L(n) asm volatile("s_waitcnt lgkmcnt(" #n ")" ::: "memory")
; #define PG8_BAR __builtin_amdgcn_s_barrier()
; #define PG8_SCHED __builtin_amdgcn_sched_barrier(0)
; template <class Epi, class Sched>
; __device__ __forceinline__ void gemm_phase(PG8_LAS unsigned char* lds, const Gemm g, const Sched& S, const Epi& E) {
;     ...
;             PG8_BAR; PG8_WAIT_L(0); PG8_MMA(1, 0, At, B0); PG8_BAR; PG8_SCHED;
	s_waitcnt lgkmcnt(7)
	v_mfma_f32_16x16x32_bf16 v[62:65], v[156:159], v[176:179], v[62:65]
	v_mfma_f32_16x16x32_bf16 v[58:61], v[164:167], v[176:179], v[58:61]

; #define PG8_MMA(ai, bj, At, Bt) do { __builtin_amdgcn_s_setprio(1); _Pragma("unroll") for (int m = 0; m < 4; ++m) _Pragma("unroll") for (int n = 0; n < 2; ++n) _Pragma("unroll") for (int k = 0; k < 2; ++k) \
;         acc[ai][bj][m][n] = __builtin_amdgcn_mfma_f32_16x16x32_bf16(Bt[n][k], At[m][k], acc[ai][bj][m][n], 0, 0, 0); __builtin_amdgcn_s_setprio(0); } while (0)
; #define PG8_WAIT_L(n) asm volatile("s_waitcnt lgkmcnt(" #n ")" ::: "memory")
; #define PG8_BAR __builtin_amdgcn_s_barrier()
; #define PG8_SCHED __builtin_amdgcn_sched_barrier(0)
; template <class Epi, class Sched>
; __device__ __forceinline__ void gemm_phase(PG8_LAS unsigned char* lds, const Gemm g, const Sched& S, const Epi& E) {
;     ...
;             PG8_BAR; PG8_WAIT_L(0); PG8_MMA(1, 0, At, B0); PG8_BAR; PG8_SCHED;
	s_waitcnt lgkmcnt(6)
	v_mfma_f32_16x16x32_bf16 v[54:57], v[156:159], v[184:187], v[54:57]
	v_mfma_f32_16x16x32_bf16 v[50:53], v[164:167], v[184:187], v[50:53]

; #define PG8_MMA(ai, bj, At, Bt) do { __builtin_amdgcn_s_setprio(1); _Pragma("unroll") for (int m = 0; m < 4; ++m) _Pragma("unroll") for (int n = 0; n < 2; ++n) _Pragma("unroll") for (int k = 0; k < 2; ++k) \
;         acc[ai][bj][m][n] = __builtin_amdgcn_mfma_f32_16x16x32_bf16(Bt[n][k], At[m][k], acc[ai][bj][m][n], 0, 0, 0); __builtin_amdgcn_s_setprio(0); } while (0)
; #define PG8_WAIT_L(n) asm volatile("s_waitcnt lgkmcnt(" #n ")" ::: "memory")
; #define PG8_BAR __builtin_amdgcn_s_barrier()
; #define PG8_SCHED __builtin_amdgcn_sched_barrier(0)
; template <class Epi, class Sched>
; __device__ __forceinline__ void gemm_phase(PG8_LAS unsigned char* lds, const Gemm g, const Sched& S, const Epi& E) {
;     ...
;             PG8_BAR; PG8_WAIT_L(0); PG8_MMA(1, 0, At, B0); PG8_BAR; PG8_SCHED;
	s_waitcnt lgkmcnt(5)
	v_mfma_f32_16x16x32_bf16 v[44:47], v[156:159], v[192:195], v[44:47]
	v_mfma_f32_16x16x32_bf16 v[40:43], v[164:167], v[192:195], v[40:43]

; #define PG8_MMA(ai, bj, At, Bt) do { __builtin_amdgcn_s_setprio(1); _Pragma("unroll") for (int m = 0; m < 4; ++m) _Pragma("unroll") for (int n = 0; n < 2; ++n) _Pragma("unroll") for (int k = 0; k < 2; ++k) \
;         acc[ai][bj][m][n] = __builtin_amdgcn_mfma_f32_16x16x32_bf16(Bt[n][k], At[m][k], acc[ai][bj][m][n], 0, 0, 0); __builtin_amdgcn_s_setprio(0); } while (0)
; #define PG8_WAIT_L(n) asm volatile("s_waitcnt lgkmcnt(" #n ")" ::: "memory")
; #define PG8_BAR __builtin_amdgcn_s_barrier()
; #define PG8_SCHED __builtin_amdgcn_sched_barrier(0)
; template <class Epi, class Sched>
; __device__ __forceinline__ void gemm_phase(PG8_LAS unsigned char* lds, const Gemm g, const Sched& S, const Epi& E) {
;     ...
;             PG8_BAR; PG8_WAIT_L(0); PG8_MMA(1, 0, At, B0); PG8_BAR; PG8_SCHED;
	s_waitcnt lgkmcnt(4)
	v_mfma_f32_16x16x32_bf16 v[32:35], v[156:159], v[200:203], v[32:35]
	v_mfma_f32_16x16x32_bf16 v[24:27], v[164:167], v[200:203], v[24:27]
	s_waitcnt lgkmcnt(3)
	v_mfma_f32_16x16x32_bf16 v[62:65], v[160:163], v[180:183], v[62:65]
	v_mfma_f32_16x16x32_bf16 v[58:61], v[168:171], v[180:183], v[58:61]
	s_waitcnt lgkmcnt(2)
	v_mfma_f32_16x16x32_bf16 v[54:57], v[160:163], v[188:191], v[54:57]
	v_mfma_f32_16x16x32_bf16 v[50:53], v[168:171], v[188:191], v[50:53]
	s_waitcnt lgkmcnt(1)
	v_mfma_f32_16x16x32_bf16 v[44:47], v[160:163], v[196:199], v[44:47]
	v_mfma_f32_16x16x32_bf16 v[40:43], v[168:171], v[196:199], v[40:43]

; #define PG8_STAGE(bufoff, gbase, voff) do { _Pragma("unroll") for (int _i = 0; _i < 2; ++_i) \
;         __builtin_amdgcn_global_load_lds((const unsigned*)((const char*)(gbase) + (voff)[_i]), (PG8_LAS unsigned*)(lds + (bufoff) + ldsw + _i * 8192), 16, 0, 0); } while (0)
; #define PG8_LDA(dst, b, h) do { _Pragma("unroll") for (int m = 0; m < 4; ++m) _Pragma("unroll") for (int k = 0; k < 2; ++k) dst[m][k] = *(const PG8_LAS bf16x8*)(lds + PG8_SA(b, h) + aoff + m * 2048 + k * 1024); } while (0)
; #define PG8_LDB(dst, b, h) do { _Pragma("unroll") for (int n = 0; n < 2; ++n) _Pragma("unroll") for (int k = 0; k < 2; ++k) dst[n][k] = *(const PG8_LAS bf16x8*)(lds + PG8_SB(b, h) + boff + n * 2048 + k * 1024); } while (0)
; #define PG8_MMA(ai, bj, At, Bt) do { __builtin_amdgcn_s_setprio(1); _Pragma("unroll") for (int m = 0; m < 4; ++m) _Pragma("unroll") for (int n = 0; n < 2; ++n) _Pragma("unroll") for (int k = 0; k < 2; ++k) \
;         acc[ai][bj][m][n] = __builtin_amdgcn_mfma_f32_16x16x32_bf16(Bt[n][k], At[m][k], acc[ai][bj][m][n], 0, 0, 0); __builtin_amdgcn_s_setprio(0); } while (0)
; #define PG8_WAIT_V(n) asm volatile("s_waitcnt vmcnt(" #n ")" ::: "memory")
; #define PG8_WAIT_L(n) asm volatile("s_waitcnt lgkmcnt(" #n ")" ::: "memory")
; #define PG8_BAR __builtin_amdgcn_s_barrier()
; #define PG8_SCHED __builtin_amdgcn_sched_barrier(0)
; template <class Epi, class Sched>
; __device__ __forceinline__ void gemm_phase(PG8_LAS unsigned char* lds, const Gemm g, const Sched& S, const Epi& E) {
;     ...
;         for (int t = 0; t < nt; t += 2) {
;             const bool last = (t == nt - 2);
;             const char* a1 = cA + (size_t)(t + 1) * kstep;
;             const char* a2 = last ? nA : cA + (size_t)(t + 2) * kstep; const char* b2 = last ? nB : cB + (size_t)(t + 2) * kstep;
;             const char* a3 = a2 + kstep; const char* b3 = b2 + kstep;
;             if (last && has_next) S.a_ready(nxt);
;             PG8_LDB(B0, 0, 0); PG8_SCHED; PG8_LDA(At, 0, 0); PG8_STAGE(PG8_SA(1, 1), a1 + hstep, voffA);
;             PG8_WAIT_L(8); PG8_BAR; PG8_WAIT_L(0); PG8_MMA(0, 0, At, B0); PG8_BAR; PG8_SCHED;
;     ...
;             PG8_STAGE(PG8_SB(1, 1), b3 + hstep, voffB);
;             PG8_WAIT_V(6); PG8_BAR; PG8_MMA(1, 1, At, B1); PG8_BAR;
	s_waitcnt lgkmcnt(0)
	v_mfma_f32_16x16x32_bf16 v[32:35], v[160:163], v[204:207], v[32:35]
	v_mfma_f32_16x16x32_bf16 v[24:27], v[168:171], v[204:207], v[24:27]
	s_barrier
	s_add_i32 s22, s22, s37
	s_mov_b32 m0, s22
	v_lshl_add_u64 v[156:157], v[240:241], 0, s[0:1]
	global_load_lds_dwordx4 v[156:157], off
	s_add_i32 m0, s22, 0x2000
	v_lshl_add_u64 v[156:157], v[242:243], 0, s[0:1]
	global_load_lds_dwordx4 v[156:157], off
	s_waitcnt vmcnt(6)
	s_barrier
	v_mfma_f32_16x16x32_bf16 v[36:39], v[208:211], v[176:179], v[36:39]
	v_mfma_f32_16x16x32_bf16 v[28:31], v[216:219], v[176:179], v[28:31]
	v_mfma_f32_16x16x32_bf16 v[20:23], v[208:211], v[184:187], v[20:23]
	v_mfma_f32_16x16x32_bf16 v[16:19], v[216:219], v[184:187], v[16:19]
	v_mfma_f32_16x16x32_bf16 v[12:15], v[208:211], v[192:195], v[12:15]
	v_mfma_f32_16x16x32_bf16 v[8:11], v[216:219], v[192:195], v[8:11]
	v_mfma_f32_16x16x32_bf16 v[4:7], v[208:211], v[200:203], v[4:7]
	v_mfma_f32_16x16x32_bf16 v[0:3], v[216:219], v[200:203], v[0:3]
	v_mfma_f32_16x16x32_bf16 v[36:39], v[212:215], v[180:183], v[36:39]
	v_mfma_f32_16x16x32_bf16 v[28:31], v[234:237], v[180:183], v[28:31]
	v_mfma_f32_16x16x32_bf16 v[20:23], v[212:215], v[188:191], v[20:23]
	v_mfma_f32_16x16x32_bf16 v[16:19], v[234:237], v[188:191], v[16:19]
	v_mfma_f32_16x16x32_bf16 v[12:15], v[212:215], v[196:199], v[12:15]
	v_mfma_f32_16x16x32_bf16 v[8:11], v[234:237], v[196:199], v[8:11]
	v_mfma_f32_16x16x32_bf16 v[4:7], v[212:215], v[204:207], v[4:7]
	v_mfma_f32_16x16x32_bf16 v[0:3], v[234:237], v[204:207], v[0:3]
	s_add_u32 s20, s20, 0x100
	s_addc_u32 s21, s21, 0
	s_add_u32 s3, s3, 0x100
	s_addc_u32 s40, s40, 0
	s_cmp_ge_u32 s41, s54
	s_mov_b32 s22, s41
	s_barrier
	s_cbranch_scc1 .Lkpeel_exit_288
.LBB0_288:
	s_add_i32 s41, s22, 2
	s_add_u32 s24, s20, 0x80
	s_addc_u32 s23, s21, 0
	s_add_i32 s63, 0, 0x10000
	v_add_u32_e32 v155, s63, v152
	ds_read_b128 v[156:159], v155
	ds_read_b128 v[160:163], v155 offset:1024
	ds_read_b128 v[164:167], v155 offset:2048
	ds_read_b128 v[168:171], v155 offset:3072
	s_cmp_eq_u32 s55, s22
	s_cselect_b32 s22, s12, s24
	s_cselect_b32 s23, s13, s23
	s_cselect_b32 s25, s17, s40
	s_cselect_b32 s24, s16, s3
	v_lshl_add_u64 v[172:173], s[20:21], 0, v[148:149]
	s_add_i32 m0, s43, 0xc000
	ds_read_b128 v[176:179], v154
	ds_read_b128 v[184:187], v154 offset:2048
	ds_read_b128 v[192:195], v154 offset:4096
	ds_read_b128 v[200:203], v154 offset:6144
	ds_read_b128 v[180:183], v154 offset:1024
	ds_read_b128 v[188:191], v154 offset:3072
	ds_read_b128 v[196:199], v154 offset:5120
	ds_read_b128 v[204:207], v154 offset:7168
	global_load_lds_dwordx4 v[172:173], off
	s_add_i32 m0, s43, 0xe000
	v_lshl_add_u64 v[172:173], s[20:21], 0, v[150:151]
	global_load_lds_dwordx4 v[172:173], off
	s_waitcnt lgkmcnt(8)
	s_barrier

; #define PG8_MMA(ai, bj, At, Bt) do { __builtin_amdgcn_s_setprio(1); _Pragma("unroll") for (int m = 0; m < 4; ++m) _Pragma("unroll") for (int n = 0; n < 2; ++n) _Pragma("unroll") for (int k = 0; k < 2; ++k) \
;         acc[ai][bj][m][n] = __builtin_amdgcn_mfma_f32_16x16x32_bf16(Bt[n][k], At[m][k], acc[ai][bj][m][n], 0, 0, 0); __builtin_amdgcn_s_setprio(0); } while (0)
; #define PG8_WAIT_L(n) asm volatile("s_waitcnt lgkmcnt(" #n ")" ::: "memory")
; #define PG8_BAR __builtin_amdgcn_s_barrier()
; #define PG8_SCHED __builtin_amdgcn_sched_barrier(0)
; template <class Epi, class Sched>
; __device__ __forceinline__ void gemm_phase(PG8_LAS unsigned char* lds, const Gemm g, const Sched& S, const Epi& E) {
;     ...
;             PG8_WAIT_L(8); PG8_BAR; PG8_WAIT_L(0); PG8_MMA(0, 0, At, B0); PG8_BAR; PG8_SCHED;
	s_waitcnt lgkmcnt(7)
	v_mfma_f32_16x16x32_bf16 v[126:129], v[156:159], v[176:179], v[126:129]
	v_mfma_f32_16x16x32_bf16 v[122:125], v[164:167], v[176:179], v[122:125]

; #define PG8_MMA(ai, bj, At, Bt) do { __builtin_amdgcn_s_setprio(1); _Pragma("unroll") for (int m = 0; m < 4; ++m) _Pragma("unroll") for (int n = 0; n < 2; ++n) _Pragma("unroll") for (int k = 0; k < 2; ++k) \
;         acc[ai][bj][m][n] = __builtin_amdgcn_mfma_f32_16x16x32_bf16(Bt[n][k], At[m][k], acc[ai][bj][m][n], 0, 0, 0); __builtin_amdgcn_s_setprio(0); } while (0)
; #define PG8_WAIT_L(n) asm volatile("s_waitcnt lgkmcnt(" #n ")" ::: "memory")
; #define PG8_BAR __builtin_amdgcn_s_barrier()
; #define PG8_SCHED __builtin_amdgcn_sched_barrier(0)
; template <class Epi, class Sched>
; __device__ __forceinline__ void gemm_phase(PG8_LAS unsigned char* lds, const Gemm g, const Sched& S, const Epi& E) {
;     ...
;             PG8_WAIT_L(8); PG8_BAR; PG8_WAIT_L(0); PG8_MMA(0, 0, At, B0); PG8_BAR; PG8_SCHED;
	s_waitcnt lgkmcnt(6)
	v_mfma_f32_16x16x32_bf16 v[118:121], v[156:159], v[184:187], v[118:121]
	v_mfma_f32_16x16x32_bf16 v[114:117], v[164:167], v[184:187], v[114:117]

; #define PG8_MMA(ai, bj, At, Bt) do { __builtin_amdgcn_s_setprio(1); _Pragma("unroll") for (int m = 0; m < 4; ++m) _Pragma("unroll") for (int n = 0; n < 2; ++n) _Pragma("unroll") for (int k = 0; k < 2; ++k) \
;         acc[ai][bj][m][n] = __builtin_amdgcn_mfma_f32_16x16x32_bf16(Bt[n][k], At[m][k], acc[ai][bj][m][n], 0, 0, 0); __builtin_amdgcn_s_setprio(0); } while (0)
; #define PG8_WAIT_L(n) asm volatile("s_waitcnt lgkmcnt(" #n ")" ::: "memory")
; #define PG8_BAR __builtin_amdgcn_s_barrier()
; #define PG8_SCHED __builtin_amdgcn_sched_barrier(0)
; template <class Epi, class Sched>
; __device__ __forceinline__ void gemm_phase(PG8_LAS unsigned char* lds, const Gemm g, const Sched& S, const Epi& E) {
;     ...
;             PG8_WAIT_L(8); PG8_BAR; PG8_WAIT_L(0); PG8_MMA(0, 0, At, B0); PG8_BAR; PG8_SCHED;
	s_waitcnt lgkmcnt(5)
	v_mfma_f32_16x16x32_bf16 v[110:113], v[156:159], v[192:195], v[110:113]
	v_mfma_f32_16x16x32_bf16 v[106:109], v[164:167], v[192:195], v[106:109]

; #define PG8_MMA(ai, bj, At, Bt) do { __builtin_amdgcn_s_setprio(1); _Pragma("unroll") for (int m = 0; m < 4; ++m) _Pragma("unroll") for (int n = 0; n < 2; ++n) _Pragma("unroll") for (int k = 0; k < 2; ++k) \
;         acc[ai][bj][m][n] = __builtin_amdgcn_mfma_f32_16x16x32_bf16(Bt[n][k], At[m][k], acc[ai][bj][m][n], 0, 0, 0); __builtin_amdgcn_s_setprio(0); } while (0)
; #define PG8_WAIT_L(n) asm volatile("s_waitcnt lgkmcnt(" #n ")" ::: "memory")
; #define PG8_BAR __builtin_amdgcn_s_barrier()
; #define PG8_SCHED __builtin_amdgcn_sched_barrier(0)
; template <class Epi, class Sched>
; __device__ __forceinline__ void gemm_phase(PG8_LAS unsigned char* lds, const Gemm g, const Sched& S, const Epi& E) {
;     ...
;             PG8_WAIT_L(8); PG8_BAR; PG8_WAIT_L(0); PG8_MMA(0, 0, At, B0); PG8_BAR; PG8_SCHED;
	s_waitcnt lgkmcnt(4)
	v_mfma_f32_16x16x32_bf16 v[98:101], v[156:159], v[200:203], v[98:101]
	v_mfma_f32_16x16x32_bf16 v[90:93], v[164:167], v[200:203], v[90:93]
	s_waitcnt lgkmcnt(3)
	v_mfma_f32_16x16x32_bf16 v[126:129], v[160:163], v[180:183], v[126:129]
	v_mfma_f32_16x16x32_bf16 v[122:125], v[168:171], v[180:183], v[122:125]
	s_waitcnt lgkmcnt(2)
	v_mfma_f32_16x16x32_bf16 v[118:121], v[160:163], v[188:191], v[118:121]
	v_mfma_f32_16x16x32_bf16 v[114:117], v[168:171], v[188:191], v[114:117]
	s_waitcnt lgkmcnt(1)
	v_mfma_f32_16x16x32_bf16 v[110:113], v[160:163], v[196:199], v[110:113]
	v_mfma_f32_16x16x32_bf16 v[106:109], v[168:171], v[196:199], v[106:109]

; #define PG8_STAGE(bufoff, gbase, voff) do { _Pragma("unroll") for (int _i = 0; _i < 2; ++_i) \
;         __builtin_amdgcn_global_load_lds((const unsigned*)((const char*)(gbase) + (voff)[_i]), (PG8_LAS unsigned*)(lds + (bufoff) + ldsw + _i * 8192), 16, 0, 0); } while (0)
; #define PG8_LDB(dst, b, h) do { _Pragma("unroll") for (int n = 0; n < 2; ++n) _Pragma("unroll") for (int k = 0; k < 2; ++k) dst[n][k] = *(const PG8_LAS bf16x8*)(lds + PG8_SB(b, h) + boff + n * 2048 + k * 1024); } while (0)
; #define PG8_MMA(ai, bj, At, Bt) do { __builtin_amdgcn_s_setprio(1); _Pragma("unroll") for (int m = 0; m < 4; ++m) _Pragma("unroll") for (int n = 0; n < 2; ++n) _Pragma("unroll") for (int k = 0; k < 2; ++k) \
;         acc[ai][bj][m][n] = __builtin_amdgcn_mfma_f32_16x16x32_bf16(Bt[n][k], At[m][k], acc[ai][bj][m][n], 0, 0, 0); __builtin_amdgcn_s_setprio(0); } while (0)
; #define PG8_WAIT_L(n) asm volatile("s_waitcnt lgkmcnt(" #n ")" ::: "memory")
; #define PG8_BAR __builtin_amdgcn_s_barrier()
; #define PG8_SCHED __builtin_amdgcn_sched_barrier(0)
; template <class Epi, class Sched>
; __device__ __forceinline__ void gemm_phase(PG8_LAS unsigned char* lds, const Gemm g, const Sched& S, const Epi& E) {
;     ...
;             PG8_WAIT_L(8); PG8_BAR; PG8_WAIT_L(0); PG8_MMA(0, 0, At, B0); PG8_BAR; PG8_SCHED;
;             PG8_LDB(B1, 0, 1); PG8_STAGE(PG8_SB(0, 0), b2, voffB);
	s_waitcnt lgkmcnt(0)
	v_mfma_f32_16x16x32_bf16 v[98:101], v[160:163], v[204:207], v[98:101]
	v_mfma_f32_16x16x32_bf16 v[90:93], v[168:171], v[204:207], v[90:93]
	s_barrier
	s_add_i32 s64, 0, 0x14000
	s_add_i32 s63, s63, s37
	v_add_u32_e32 v155, s64, v152
	v_lshl_add_u64 v[172:173], s[24:25], 0, v[48:49]
	s_mov_b32 m0, s63
	ds_read_b128 v[208:211], v155
	ds_read_b128 v[216:219], v155 offset:2048
	ds_read_b128 v[212:215], v155 offset:1024
	ds_read_b128 v[234:237], v155 offset:3072
	global_load_lds_dwordx4 v[172:173], off
	s_add_i32 m0, s63, 0x2000
	v_lshl_add_u64 v[224:225], s[24:25], 0, v[130:131]
	global_load_lds_dwordx4 v[224:225], off
	s_barrier

; #define PG8_MMA(ai, bj, At, Bt) do { __builtin_amdgcn_s_setprio(1); _Pragma("unroll") for (int m = 0; m < 4; ++m) _Pragma("unroll") for (int n = 0; n < 2; ++n) _Pragma("unroll") for (int k = 0; k < 2; ++k) \
;         acc[ai][bj][m][n] = __builtin_amdgcn_mfma_f32_16x16x32_bf16(Bt[n][k], At[m][k], acc[ai][bj][m][n], 0, 0, 0); __builtin_amdgcn_s_setprio(0); } while (0)
; #define PG8_WAIT_L(n) asm volatile("s_waitcnt lgkmcnt(" #n ")" ::: "memory")
; #define PG8_BAR __builtin_amdgcn_s_barrier()
; template <class Epi, class Sched>
; __device__ __forceinline__ void gemm_phase(PG8_LAS unsigned char* lds, const Gemm g, const Sched& S, const Epi& E) {
;     ...
;             PG8_BAR; PG8_WAIT_L(0); PG8_MMA(0, 1, At, B1); PG8_BAR;
	s_waitcnt lgkmcnt(3)
	v_mfma_f32_16x16x32_bf16 v[102:105], v[208:211], v[176:179], v[102:105]

; #define PG8_MMA(ai, bj, At, Bt) do { __builtin_amdgcn_s_setprio(1); _Pragma("unroll") for (int m = 0; m < 4; ++m) _Pragma("unroll") for (int n = 0; n < 2; ++n) _Pragma("unroll") for (int k = 0; k < 2; ++k) \
;         acc[ai][bj][m][n] = __builtin_amdgcn_mfma_f32_16x16x32_bf16(Bt[n][k], At[m][k], acc[ai][bj][m][n], 0, 0, 0); __builtin_amdgcn_s_setprio(0); } while (0)
; #define PG8_WAIT_L(n) asm volatile("s_waitcnt lgkmcnt(" #n ")" ::: "memory")
; #define PG8_BAR __builtin_amdgcn_s_barrier()
; template <class Epi, class Sched>
; __device__ __forceinline__ void gemm_phase(PG8_LAS unsigned char* lds, const Gemm g, const Sched& S, const Epi& E) {
;     ...
;             PG8_BAR; PG8_WAIT_L(0); PG8_MMA(0, 1, At, B1); PG8_BAR;
	s_waitcnt lgkmcnt(2)
	v_mfma_f32_16x16x32_bf16 v[94:97], v[216:219], v[176:179], v[94:97]
	v_mfma_f32_16x16x32_bf16 v[86:89], v[208:211], v[184:187], v[86:89]
	v_mfma_f32_16x16x32_bf16 v[82:85], v[216:219], v[184:187], v[82:85]
	v_mfma_f32_16x16x32_bf16 v[78:81], v[208:211], v[192:195], v[78:81]
	v_mfma_f32_16x16x32_bf16 v[74:77], v[216:219], v[192:195], v[74:77]
	v_mfma_f32_16x16x32_bf16 v[70:73], v[208:211], v[200:203], v[70:73]
	v_mfma_f32_16x16x32_bf16 v[66:69], v[216:219], v[200:203], v[66:69]
	s_waitcnt lgkmcnt(1)
	v_mfma_f32_16x16x32_bf16 v[102:105], v[212:215], v[180:183], v[102:105]

; #define PG8_STAGE(bufoff, gbase, voff) do { _Pragma("unroll") for (int _i = 0; _i < 2; ++_i) \
;         __builtin_amdgcn_global_load_lds((const unsigned*)((const char*)(gbase) + (voff)[_i]), (PG8_LAS unsigned*)(lds + (bufoff) + ldsw + _i * 8192), 16, 0, 0); } while (0)
; #define PG8_LDA(dst, b, h) do { _Pragma("unroll") for (int m = 0; m < 4; ++m) _Pragma("unroll") for (int k = 0; k < 2; ++k) dst[m][k] = *(const PG8_LAS bf16x8*)(lds + PG8_SA(b, h) + aoff + m * 2048 + k * 1024); } while (0)
; #define PG8_MMA(ai, bj, At, Bt) do { __builtin_amdgcn_s_setprio(1); _Pragma("unroll") for (int m = 0; m < 4; ++m) _Pragma("unroll") for (int n = 0; n < 2; ++n) _Pragma("unroll") for (int k = 0; k < 2; ++k) \
;         acc[ai][bj][m][n] = __builtin_amdgcn_mfma_f32_16x16x32_bf16(Bt[n][k], At[m][k], acc[ai][bj][m][n], 0, 0, 0); __builtin_amdgcn_s_setprio(0); } while (0)
; #define PG8_WAIT_L(n) asm volatile("s_waitcnt lgkmcnt(" #n ")" ::: "memory")
; #define PG8_BAR __builtin_amdgcn_s_barrier()
; template <class Epi, class Sched>
; __device__ __forceinline__ void gemm_phase(PG8_LAS unsigned char* lds, const Gemm g, const Sched& S, const Epi& E) {
;     ...
;             PG8_BAR; PG8_WAIT_L(0); PG8_MMA(0, 1, At, B1); PG8_BAR;
;             PG8_LDA(At, 0, 1); PG8_STAGE(PG8_SA(0, 0), a2, voffA);
	s_waitcnt lgkmcnt(0)
	v_mfma_f32_16x16x32_bf16 v[94:97], v[234:237], v[180:183], v[94:97]
	v_mfma_f32_16x16x32_bf16 v[86:89], v[212:215], v[188:191], v[86:89]
	v_mfma_f32_16x16x32_bf16 v[82:85], v[234:237], v[188:191], v[82:85]
	v_mfma_f32_16x16x32_bf16 v[78:81], v[212:215], v[196:199], v[78:81]
	v_mfma_f32_16x16x32_bf16 v[74:77], v[234:237], v[196:199], v[74:77]
	v_mfma_f32_16x16x32_bf16 v[70:73], v[212:215], v[204:207], v[70:73]
	v_mfma_f32_16x16x32_bf16 v[66:69], v[234:237], v[204:207], v[66:69]
	s_mov_b32 m0, s43
	v_lshl_add_u64 v[228:229], s[22:23], 0, v[48:49]
	s_barrier
	ds_read_b128 v[176:179], v154 offset:16384
	ds_read_b128 v[184:187], v154 offset:18432
	ds_read_b128 v[192:195], v154 offset:20480
	ds_read_b128 v[200:203], v154 offset:22528
	ds_read_b128 v[180:183], v154 offset:17408
	ds_read_b128 v[188:191], v154 offset:19456
	ds_read_b128 v[196:199], v154 offset:21504
	ds_read_b128 v[204:207], v154 offset:23552
	global_load_lds_dwordx4 v[228:229], off
	s_mov_b32 m0, s44
	v_lshl_add_u64 v[238:239], s[22:23], 0, v[130:131]
	global_load_lds_dwordx4 v[238:239], off
	s_barrier

; #define PG8_MMA(ai, bj, At, Bt) do { __builtin_amdgcn_s_setprio(1); _Pragma("unroll") for (int m = 0; m < 4; ++m) _Pragma("unroll") for (int n = 0; n < 2; ++n) _Pragma("unroll") for (int k = 0; k < 2; ++k) \
;         acc[ai][bj][m][n] = __builtin_amdgcn_mfma_f32_16x16x32_bf16(Bt[n][k], At[m][k], acc[ai][bj][m][n], 0, 0, 0); __builtin_amdgcn_s_setprio(0); } while (0)
; #define PG8_WAIT_L(n) asm volatile("s_waitcnt lgkmcnt(" #n ")" ::: "memory")
; #define PG8_BAR __builtin_amdgcn_s_barrier()
; #define PG8_SCHED __builtin_amdgcn_sched_barrier(0)
; template <class Epi, class Sched>
; __device__ __forceinline__ void gemm_phase(PG8_LAS unsigned char* lds, const Gemm g, const Sched& S, const Epi& E) {
;     ...
;             PG8_BAR; PG8_WAIT_L(0); PG8_MMA(1, 0, At, B0); PG8_BAR; PG8_SCHED;
	s_waitcnt lgkmcnt(7)
	v_mfma_f32_16x16x32_bf16 v[62:65], v[156:159], v[176:179], v[62:65]
	v_mfma_f32_16x16x32_bf16 v[58:61], v[164:167], v[176:179], v[58:61]

; #define PG8_MMA(ai, bj, At, Bt) do { __builtin_amdgcn_s_setprio(1); _Pragma("unroll") for (int m = 0; m < 4; ++m) _Pragma("unroll") for (int n = 0; n < 2; ++n) _Pragma("unroll") for (int k = 0; k < 2; ++k) \
;         acc[ai][bj][m][n] = __builtin_amdgcn_mfma_f32_16x16x32_bf16(Bt[n][k], At[m][k], acc[ai][bj][m][n], 0, 0, 0); __builtin_amdgcn_s_setprio(0); } while (0)
; #define PG8_WAIT_L(n) asm volatile("s_waitcnt lgkmcnt(" #n ")" ::: "memory")
; #define PG8_BAR __builtin_amdgcn_s_barrier()
; #define PG8_SCHED __builtin_amdgcn_sched_barrier(0)
; template <class Epi, class Sched>
; __device__ __forceinline__ void gemm_phase(PG8_LAS unsigned char* lds, const Gemm g, const Sched& S, const Epi& E) {
;     ...
;             PG8_BAR; PG8_WAIT_L(0); PG8_MMA(1, 0, At, B0); PG8_BAR; PG8_SCHED;
	s_waitcnt lgkmcnt(6)
	v_mfma_f32_16x16x32_bf16 v[54:57], v[156:159], v[184:187], v[54:57]
	v_mfma_f32_16x16x32_bf16 v[50:53], v[164:167], v[184:187], v[50:53]

; #define PG8_MMA(ai, bj, At, Bt) do { __builtin_amdgcn_s_setprio(1); _Pragma("unroll") for (int m = 0; m < 4; ++m) _Pragma("unroll") for (int n = 0; n < 2; ++n) _Pragma("unroll") for (int k = 0; k < 2; ++k) \
;         acc[ai][bj][m][n] = __builtin_amdgcn_mfma_f32_16x16x32_bf16(Bt[n][k], At[m][k], acc[ai][bj][m][n], 0, 0, 0); __builtin_amdgcn_s_setprio(0); } while (0)
; #define PG8_WAIT_L(n) asm volatile("s_waitcnt lgkmcnt(" #n ")" ::: "memory")
; #define PG8_BAR __builtin_amdgcn_s_barrier()
; #define PG8_SCHED __builtin_amdgcn_sched_barrier(0)
; template <class Epi, class Sched>
; __device__ __forceinline__ void gemm_phase(PG8_LAS unsigned char* lds, const Gemm g, const Sched& S, const Epi& E) {
;     ...
;             PG8_BAR; PG8_WAIT_L(0); PG8_MMA(1, 0, At, B0); PG8_BAR; PG8_SCHED;
	s_waitcnt lgkmcnt(5)
	v_mfma_f32_16x16x32_bf16 v[44:47], v[156:159], v[192:195], v[44:47]
	v_mfma_f32_16x16x32_bf16 v[40:43], v[164:167], v[192:195], v[40:43]

; #define PG8_MMA(ai, bj, At, Bt) do { __builtin_amdgcn_s_setprio(1); _Pragma("unroll") for (int m = 0; m < 4; ++m) _Pragma("unroll") for (int n = 0; n < 2; ++n) _Pragma("unroll") for (int k = 0; k < 2; ++k) \
;         acc[ai][bj][m][n] = __builtin_amdgcn_mfma_f32_16x16x32_bf16(Bt[n][k], At[m][k], acc[ai][bj][m][n], 0, 0, 0); __builtin_amdgcn_s_setprio(0); } while (0)
; #define PG8_WAIT_L(n) asm volatile("s_waitcnt lgkmcnt(" #n ")" ::: "memory")
; #define PG8_BAR __builtin_amdgcn_s_barrier()
; #define PG8_SCHED __builtin_amdgcn_sched_barrier(0)
; template <class Epi, class Sched>
; __device__ __forceinline__ void gemm_phase(PG8_LAS unsigned char* lds, const Gemm g, const Sched& S, const Epi& E) {
;     ...
;             PG8_BAR; PG8_WAIT_L(0); PG8_MMA(1, 0, At, B0); PG8_BAR; PG8_SCHED;
	s_waitcnt lgkmcnt(4)
	v_mfma_f32_16x16x32_bf16 v[32:35], v[156:159], v[200:203], v[32:35]
	v_mfma_f32_16x16x32_bf16 v[24:27], v[164:167], v[200:203], v[24:27]
	s_waitcnt lgkmcnt(3)
	v_mfma_f32_16x16x32_bf16 v[62:65], v[160:163], v[180:183], v[62:65]
	v_mfma_f32_16x16x32_bf16 v[58:61], v[168:171], v[180:183], v[58:61]
	s_waitcnt lgkmcnt(2)
	v_mfma_f32_16x16x32_bf16 v[54:57], v[160:163], v[188:191], v[54:57]
	v_mfma_f32_16x16x32_bf16 v[50:53], v[168:171], v[188:191], v[50:53]
	s_waitcnt lgkmcnt(1)
	v_mfma_f32_16x16x32_bf16 v[44:47], v[160:163], v[196:199], v[44:47]
	v_mfma_f32_16x16x32_bf16 v[40:43], v[168:171], v[196:199], v[40:43]

; #define PG8_STAGE(bufoff, gbase, voff) do { _Pragma("unroll") for (int _i = 0; _i < 2; ++_i) \
;         __builtin_amdgcn_global_load_lds((const unsigned*)((const char*)(gbase) + (voff)[_i]), (PG8_LAS unsigned*)(lds + (bufoff) + ldsw + _i * 8192), 16, 0, 0); } while (0)
; #define PG8_LDA(dst, b, h) do { _Pragma("unroll") for (int m = 0; m < 4; ++m) _Pragma("unroll") for (int k = 0; k < 2; ++k) dst[m][k] = *(const PG8_LAS bf16x8*)(lds + PG8_SA(b, h) + aoff + m * 2048 + k * 1024); } while (0)
; #define PG8_LDB(dst, b, h) do { _Pragma("unroll") for (int n = 0; n < 2; ++n) _Pragma("unroll") for (int k = 0; k < 2; ++k) dst[n][k] = *(const PG8_LAS bf16x8*)(lds + PG8_SB(b, h) + boff + n * 2048 + k * 1024); } while (0)
; #define PG8_MMA(ai, bj, At, Bt) do { __builtin_amdgcn_s_setprio(1); _Pragma("unroll") for (int m = 0; m < 4; ++m) _Pragma("unroll") for (int n = 0; n < 2; ++n) _Pragma("unroll") for (int k = 0; k < 2; ++k) \
;         acc[ai][bj][m][n] = __builtin_amdgcn_mfma_f32_16x16x32_bf16(Bt[n][k], At[m][k], acc[ai][bj][m][n], 0, 0, 0); __builtin_amdgcn_s_setprio(0); } while (0)
; #define PG8_WAIT_V(n) asm volatile("s_waitcnt vmcnt(" #n ")" ::: "memory")
; #define PG8_WAIT_L(n) asm volatile("s_waitcnt lgkmcnt(" #n ")" ::: "memory")
; #define PG8_BAR __builtin_amdgcn_s_barrier()
; #define PG8_SCHED __builtin_amdgcn_sched_barrier(0)
; template <class Epi, class Sched>
; __device__ __forceinline__ void gemm_phase(PG8_LAS unsigned char* lds, const Gemm g, const Sched& S, const Epi& E) {
;     ...
;             PG8_BAR; PG8_WAIT_L(0); PG8_MMA(1, 0, At, B0); PG8_BAR; PG8_SCHED;
;             PG8_STAGE(PG8_SB(0, 1), b2 + hstep, voffB);
;             PG8_WAIT_V(6); PG8_BAR; PG8_MMA(1, 1, At, B1); PG8_BAR;
;             PG8_LDB(B0, 1, 0); PG8_SCHED; PG8_LDA(At, 1, 0); PG8_STAGE(PG8_SA(0, 1), a2 + hstep, voffA);
;             PG8_WAIT_L(8); PG8_BAR; PG8_WAIT_L(0); PG8_MMA(0, 0, At, B0); PG8_BAR; PG8_SCHED;
	s_waitcnt lgkmcnt(0)
	v_mfma_f32_16x16x32_bf16 v[32:35], v[160:163], v[204:207], v[32:35]
	v_mfma_f32_16x16x32_bf16 v[24:27], v[168:171], v[204:207], v[24:27]
	s_barrier
	s_add_u32 s24, s24, s10
	s_addc_u32 s25, s25, 0
	s_add_i32 s63, s64, s37
	v_lshl_add_u64 v[240:241], s[24:25], 0, v[48:49]
	s_mov_b32 m0, s63
	v_lshl_add_u64 v[242:243], s[24:25], 0, v[130:131]
	global_load_lds_dwordx4 v[240:241], off
	s_add_i32 m0, s63, 0x2000
	s_nop 0
	global_load_lds_dwordx4 v[242:243], off
	s_waitcnt vmcnt(6)
	s_barrier
	v_mfma_f32_16x16x32_bf16 v[36:39], v[208:211], v[176:179], v[36:39]
	v_mfma_f32_16x16x32_bf16 v[28:31], v[216:219], v[176:179], v[28:31]
	v_mfma_f32_16x16x32_bf16 v[20:23], v[208:211], v[184:187], v[20:23]
	v_mfma_f32_16x16x32_bf16 v[16:19], v[216:219], v[184:187], v[16:19]
	v_mfma_f32_16x16x32_bf16 v[12:15], v[208:211], v[192:195], v[12:15]
	v_mfma_f32_16x16x32_bf16 v[8:11], v[216:219], v[192:195], v[8:11]
	v_mfma_f32_16x16x32_bf16 v[4:7], v[208:211], v[200:203], v[4:7]
	v_mfma_f32_16x16x32_bf16 v[0:3], v[216:219], v[200:203], v[0:3]
	v_mfma_f32_16x16x32_bf16 v[36:39], v[212:215], v[180:183], v[36:39]
	v_mfma_f32_16x16x32_bf16 v[28:31], v[234:237], v[180:183], v[28:31]
	v_mfma_f32_16x16x32_bf16 v[20:23], v[212:215], v[188:191], v[20:23]
	v_mfma_f32_16x16x32_bf16 v[16:19], v[234:237], v[188:191], v[16:19]
	v_mfma_f32_16x16x32_bf16 v[12:15], v[212:215], v[196:199], v[12:15]
	v_mfma_f32_16x16x32_bf16 v[8:11], v[234:237], v[196:199], v[8:11]
	v_mfma_f32_16x16x32_bf16 v[4:7], v[212:215], v[204:207], v[4:7]
	v_mfma_f32_16x16x32_bf16 v[0:3], v[234:237], v[204:207], v[0:3]
	s_add_i32 s24, 0, 0x18000
	v_add_u32_e32 v155, s24, v152
	s_barrier
	ds_read_b128 v[156:159], v155
	ds_read_b128 v[160:163], v155 offset:1024
	ds_read_b128 v[164:167], v155 offset:2048
	ds_read_b128 v[168:171], v155 offset:3072
	s_add_u32 s22, s22, s10
	s_addc_u32 s23, s23, 0
	s_mov_b32 m0, s46
	v_lshl_add_u64 v[208:209], s[22:23], 0, v[48:49]
	ds_read_b128 v[176:179], v154 offset:32768
	ds_read_b128 v[184:187], v154 offset:34816
	ds_read_b128 v[192:195], v154 offset:36864
	ds_read_b128 v[200:203], v154 offset:38912
	ds_read_b128 v[180:183], v154 offset:33792
	ds_read_b128 v[188:191], v154 offset:35840
	ds_read_b128 v[196:199], v154 offset:37888
	ds_read_b128 v[204:207], v154 offset:39936
	global_load_lds_dwordx4 v[208:209], off
	s_mov_b32 m0, s47
	v_lshl_add_u64 v[208:209], s[22:23], 0, v[130:131]
	global_load_lds_dwordx4 v[208:209], off
	s_waitcnt lgkmcnt(8)
	s_barrier

; #define PG8_MMA(ai, bj, At, Bt) do { __builtin_amdgcn_s_setprio(1); _Pragma("unroll") for (int m = 0; m < 4; ++m) _Pragma("unroll") for (int n = 0; n < 2; ++n) _Pragma("unroll") for (int k = 0; k < 2; ++k) \
;         acc[ai][bj][m][n] = __builtin_amdgcn_mfma_f32_16x16x32_bf16(Bt[n][k], At[m][k], acc[ai][bj][m][n], 0, 0, 0); __builtin_amdgcn_s_setprio(0); } while (0)
; #define PG8_WAIT_L(n) asm volatile("s_waitcnt lgkmcnt(" #n ")" ::: "memory")
; #define PG8_BAR __builtin_amdgcn_s_barrier()
; #define PG8_SCHED __builtin_amdgcn_sched_barrier(0)
; template <class Epi, class Sched>
; __device__ __forceinline__ void gemm_phase(PG8_LAS unsigned char* lds, const Gemm g, const Sched& S, const Epi& E) {
;     ...
;             PG8_WAIT_L(8); PG8_BAR; PG8_WAIT_L(0); PG8_MMA(0, 0, At, B0); PG8_BAR; PG8_SCHED;
	s_waitcnt lgkmcnt(7)
	v_mfma_f32_16x16x32_bf16 v[126:129], v[156:159], v[176:179], v[126:129]
	v_mfma_f32_16x16x32_bf16 v[122:125], v[164:167], v[176:179], v[122:125]

; #define PG8_MMA(ai, bj, At, Bt) do { __builtin_amdgcn_s_setprio(1); _Pragma("unroll") for (int m = 0; m < 4; ++m) _Pragma("unroll") for (int n = 0; n < 2; ++n) _Pragma("unroll") for (int k = 0; k < 2; ++k) \
;         acc[ai][bj][m][n] = __builtin_amdgcn_mfma_f32_16x16x32_bf16(Bt[n][k], At[m][k], acc[ai][bj][m][n], 0, 0, 0); __builtin_amdgcn_s_setprio(0); } while (0)
; #define PG8_WAIT_L(n) asm volatile("s_waitcnt lgkmcnt(" #n ")" ::: "memory")
; #define PG8_BAR __builtin_amdgcn_s_barrier()
; #define PG8_SCHED __builtin_amdgcn_sched_barrier(0)
; template <class Epi, class Sched>
; __device__ __forceinline__ void gemm_phase(PG8_LAS unsigned char* lds, const Gemm g, const Sched& S, const Epi& E) {
;     ...
;             PG8_WAIT_L(8); PG8_BAR; PG8_WAIT_L(0); PG8_MMA(0, 0, At, B0); PG8_BAR; PG8_SCHED;
	s_waitcnt lgkmcnt(6)
	v_mfma_f32_16x16x32_bf16 v[118:121], v[156:159], v[184:187], v[118:121]
	v_mfma_f32_16x16x32_bf16 v[114:117], v[164:167], v[184:187], v[114:117]

; #define PG8_MMA(ai, bj, At, Bt) do { __builtin_amdgcn_s_setprio(1); _Pragma("unroll") for (int m = 0; m < 4; ++m) _Pragma("unroll") for (int n = 0; n < 2; ++n) _Pragma("unroll") for (int k = 0; k < 2; ++k) \
;         acc[ai][bj][m][n] = __builtin_amdgcn_mfma_f32_16x16x32_bf16(Bt[n][k], At[m][k], acc[ai][bj][m][n], 0, 0, 0); __builtin_amdgcn_s_setprio(0); } while (0)
; #define PG8_WAIT_L(n) asm volatile("s_waitcnt lgkmcnt(" #n ")" ::: "memory")
; #define PG8_BAR __builtin_amdgcn_s_barrier()
; #define PG8_SCHED __builtin_amdgcn_sched_barrier(0)
; template <class Epi, class Sched>
; __device__ __forceinline__ void gemm_phase(PG8_LAS unsigned char* lds, const Gemm g, const Sched& S, const Epi& E) {
;     ...
;             PG8_WAIT_L(8); PG8_BAR; PG8_WAIT_L(0); PG8_MMA(0, 0, At, B0); PG8_BAR; PG8_SCHED;
	s_waitcnt lgkmcnt(5)
	v_mfma_f32_16x16x32_bf16 v[110:113], v[156:159], v[192:195], v[110:113]
	v_mfma_f32_16x16x32_bf16 v[106:109], v[164:167], v[192:195], v[106:109]

; #define PG8_MMA(ai, bj, At, Bt) do { __builtin_amdgcn_s_setprio(1); _Pragma("unroll") for (int m = 0; m < 4; ++m) _Pragma("unroll") for (int n = 0; n < 2; ++n) _Pragma("unroll") for (int k = 0; k < 2; ++k) \
;         acc[ai][bj][m][n] = __builtin_amdgcn_mfma_f32_16x16x32_bf16(Bt[n][k], At[m][k], acc[ai][bj][m][n], 0, 0, 0); __builtin_amdgcn_s_setprio(0); } while (0)
; #define PG8_WAIT_L(n) asm volatile("s_waitcnt lgkmcnt(" #n ")" ::: "memory")
; #define PG8_BAR __builtin_amdgcn_s_barrier()
; #define PG8_SCHED __builtin_amdgcn_sched_barrier(0)
; template <class Epi, class Sched>
; __device__ __forceinline__ void gemm_phase(PG8_LAS unsigned char* lds, const Gemm g, const Sched& S, const Epi& E) {
;     ...
;             PG8_WAIT_L(8); PG8_BAR; PG8_WAIT_L(0); PG8_MMA(0, 0, At, B0); PG8_BAR; PG8_SCHED;
	s_waitcnt lgkmcnt(4)
	v_mfma_f32_16x16x32_bf16 v[98:101], v[156:159], v[200:203], v[98:101]
	v_mfma_f32_16x16x32_bf16 v[90:93], v[164:167], v[200:203], v[90:93]
	s_waitcnt lgkmcnt(3)
	v_mfma_f32_16x16x32_bf16 v[126:129], v[160:163], v[180:183], v[126:129]
	v_mfma_f32_16x16x32_bf16 v[122:125], v[168:171], v[180:183], v[122:125]
	s_waitcnt lgkmcnt(2)
	v_mfma_f32_16x16x32_bf16 v[118:121], v[160:163], v[188:191], v[118:121]
	v_mfma_f32_16x16x32_bf16 v[114:117], v[168:171], v[188:191], v[114:117]
	s_waitcnt lgkmcnt(1)
	v_mfma_f32_16x16x32_bf16 v[110:113], v[160:163], v[196:199], v[110:113]
	v_mfma_f32_16x16x32_bf16 v[106:109], v[168:171], v[196:199], v[106:109]

; #define PG8_STAGE(bufoff, gbase, voff) do { _Pragma("unroll") for (int _i = 0; _i < 2; ++_i) \
;         __builtin_amdgcn_global_load_lds((const unsigned*)((const char*)(gbase) + (voff)[_i]), (PG8_LAS unsigned*)(lds + (bufoff) + ldsw + _i * 8192), 16, 0, 0); } while (0)
; #define PG8_LDB(dst, b, h) do { _Pragma("unroll") for (int n = 0; n < 2; ++n) _Pragma("unroll") for (int k = 0; k < 2; ++k) dst[n][k] = *(const PG8_LAS bf16x8*)(lds + PG8_SB(b, h) + boff + n * 2048 + k * 1024); } while (0)
; #define PG8_MMA(ai, bj, At, Bt) do { __builtin_amdgcn_s_setprio(1); _Pragma("unroll") for (int m = 0; m < 4; ++m) _Pragma("unroll") for (int n = 0; n < 2; ++n) _Pragma("unroll") for (int k = 0; k < 2; ++k) \
;         acc[ai][bj][m][n] = __builtin_amdgcn_mfma_f32_16x16x32_bf16(Bt[n][k], At[m][k], acc[ai][bj][m][n], 0, 0, 0); __builtin_amdgcn_s_setprio(0); } while (0)
; #define PG8_WAIT_L(n) asm volatile("s_waitcnt lgkmcnt(" #n ")" ::: "memory")
; #define PG8_BAR __builtin_amdgcn_s_barrier()
; #define PG8_SCHED __builtin_amdgcn_sched_barrier(0)
; template <class Epi, class Sched>
; __device__ __forceinline__ void gemm_phase(PG8_LAS unsigned char* lds, const Gemm g, const Sched& S, const Epi& E) {
;     ...
;             PG8_WAIT_L(8); PG8_BAR; PG8_WAIT_L(0); PG8_MMA(0, 0, At, B0); PG8_BAR; PG8_SCHED;
;             PG8_LDB(B1, 1, 1); PG8_STAGE(PG8_SB(1, 0), b3, voffB);
	s_waitcnt lgkmcnt(0)
	v_mfma_f32_16x16x32_bf16 v[98:101], v[160:163], v[204:207], v[98:101]
	v_mfma_f32_16x16x32_bf16 v[90:93], v[168:171], v[204:207], v[90:93]
	s_barrier
	s_add_i32 s22, 0, 0x1c000
	s_add_i32 s23, s24, s37
	v_add_u32_e32 v155, s22, v152
	v_lshl_add_u64 v[172:173], v[172:173], 0, s[0:1]
	s_mov_b32 m0, s23
	ds_read_b128 v[208:211], v155
	ds_read_b128 v[216:219], v155 offset:2048
	ds_read_b128 v[212:215], v155 offset:1024
	ds_read_b128 v[234:237], v155 offset:3072
	global_load_lds_dwordx4 v[172:173], off
	s_add_i32 m0, s23, 0x2000
	v_lshl_add_u64 v[172:173], v[224:225], 0, s[0:1]
	global_load_lds_dwordx4 v[172:173], off
	s_barrier

; #define PG8_MMA(ai, bj, At, Bt) do { __builtin_amdgcn_s_setprio(1); _Pragma("unroll") for (int m = 0; m < 4; ++m) _Pragma("unroll") for (int n = 0; n < 2; ++n) _Pragma("unroll") for (int k = 0; k < 2; ++k) \
;         acc[ai][bj][m][n] = __builtin_amdgcn_mfma_f32_16x16x32_bf16(Bt[n][k], At[m][k], acc[ai][bj][m][n], 0, 0, 0); __builtin_amdgcn_s_setprio(0); } while (0)
; #define PG8_WAIT_L(n) asm volatile("s_waitcnt lgkmcnt(" #n ")" ::: "memory")
; #define PG8_BAR __builtin_amdgcn_s_barrier()
; template <class Epi, class Sched>
; __device__ __forceinline__ void gemm_phase(PG8_LAS unsigned char* lds, const Gemm g, const Sched& S, const Epi& E) {
;     ...
;             PG8_BAR; PG8_WAIT_L(0); PG8_MMA(0, 1, At, B1); PG8_BAR;
	s_waitcnt lgkmcnt(3)
	v_mfma_f32_16x16x32_bf16 v[102:105], v[208:211], v[176:179], v[102:105]

; #define PG8_MMA(ai, bj, At, Bt) do { __builtin_amdgcn_s_setprio(1); _Pragma("unroll") for (int m = 0; m < 4; ++m) _Pragma("unroll") for (int n = 0; n < 2; ++n) _Pragma("unroll") for (int k = 0; k < 2; ++k) \
;         acc[ai][bj][m][n] = __builtin_amdgcn_mfma_f32_16x16x32_bf16(Bt[n][k], At[m][k], acc[ai][bj][m][n], 0, 0, 0); __builtin_amdgcn_s_setprio(0); } while (0)
; #define PG8_WAIT_L(n) asm volatile("s_waitcnt lgkmcnt(" #n ")" ::: "memory")
; #define PG8_BAR __builtin_amdgcn_s_barrier()
; template <class Epi, class Sched>
; __device__ __forceinline__ void gemm_phase(PG8_LAS unsigned char* lds, const Gemm g, const Sched& S, const Epi& E) {
;     ...
;             PG8_BAR; PG8_WAIT_L(0); PG8_MMA(0, 1, At, B1); PG8_BAR;
	s_waitcnt lgkmcnt(2)
	v_mfma_f32_16x16x32_bf16 v[94:97], v[216:219], v[176:179], v[94:97]
	v_mfma_f32_16x16x32_bf16 v[86:89], v[208:211], v[184:187], v[86:89]
	v_mfma_f32_16x16x32_bf16 v[82:85], v[216:219], v[184:187], v[82:85]
	v_mfma_f32_16x16x32_bf16 v[78:81], v[208:211], v[192:195], v[78:81]
	v_mfma_f32_16x16x32_bf16 v[74:77], v[216:219], v[192:195], v[74:77]
	v_mfma_f32_16x16x32_bf16 v[70:73], v[208:211], v[200:203], v[70:73]
	v_mfma_f32_16x16x32_bf16 v[66:69], v[216:219], v[200:203], v[66:69]
	s_waitcnt lgkmcnt(1)
	v_mfma_f32_16x16x32_bf16 v[102:105], v[212:215], v[180:183], v[102:105]

; #define PG8_STAGE(bufoff, gbase, voff) do { _Pragma("unroll") for (int _i = 0; _i < 2; ++_i) \
;         __builtin_amdgcn_global_load_lds((const unsigned*)((const char*)(gbase) + (voff)[_i]), (PG8_LAS unsigned*)(lds + (bufoff) + ldsw + _i * 8192), 16, 0, 0); } while (0)
; #define PG8_LDA(dst, b, h) do { _Pragma("unroll") for (int m = 0; m < 4; ++m) _Pragma("unroll") for (int k = 0; k < 2; ++k) dst[m][k] = *(const PG8_LAS bf16x8*)(lds + PG8_SA(b, h) + aoff + m * 2048 + k * 1024); } while (0)
; #define PG8_MMA(ai, bj, At, Bt) do { __builtin_amdgcn_s_setprio(1); _Pragma("unroll") for (int m = 0; m < 4; ++m) _Pragma("unroll") for (int n = 0; n < 2; ++n) _Pragma("unroll") for (int k = 0; k < 2; ++k) \
;         acc[ai][bj][m][n] = __builtin_amdgcn_mfma_f32_16x16x32_bf16(Bt[n][k], At[m][k], acc[ai][bj][m][n], 0, 0, 0); __builtin_amdgcn_s_setprio(0); } while (0)
; #define PG8_WAIT_L(n) asm volatile("s_waitcnt lgkmcnt(" #n ")" ::: "memory")
; #define PG8_BAR __builtin_amdgcn_s_barrier()
; #define PG8_SCHED __builtin_amdgcn_sched_barrier(0)
; template <class Epi, class Sched>
; __device__ __forceinline__ void gemm_phase(PG8_LAS unsigned char* lds, const Gemm g, const Sched& S, const Epi& E) {
;     ...
;             PG8_BAR; PG8_WAIT_L(0); PG8_MMA(0, 1, At, B1); PG8_BAR;
;             PG8_LDA(At, 1, 1); PG8_STAGE(PG8_SA(1, 0), a3, voffA);
;             PG8_BAR; PG8_WAIT_L(0); PG8_MMA(1, 0, At, B0); PG8_BAR; PG8_SCHED;
	s_waitcnt lgkmcnt(0)
	v_mfma_f32_16x16x32_bf16 v[94:97], v[234:237], v[180:183], v[94:97]
	v_mfma_f32_16x16x32_bf16 v[86:89], v[212:215], v[188:191], v[86:89]
	v_mfma_f32_16x16x32_bf16 v[82:85], v[234:237], v[188:191], v[82:85]
	v_mfma_f32_16x16x32_bf16 v[78:81], v[212:215], v[196:199], v[78:81]
	v_mfma_f32_16x16x32_bf16 v[74:77], v[234:237], v[196:199], v[74:77]
	v_mfma_f32_16x16x32_bf16 v[70:73], v[212:215], v[204:207], v[70:73]
	v_mfma_f32_16x16x32_bf16 v[66:69], v[234:237], v[204:207], v[66:69]
	s_mov_b32 m0, s50
	v_lshl_add_u64 v[172:173], v[228:229], 0, s[0:1]
	s_barrier
	ds_read_b128 v[176:179], v154 offset:49152
	ds_read_b128 v[184:187], v154 offset:51200
	ds_read_b128 v[192:195], v154 offset:53248
	ds_read_b128 v[200:203], v154 offset:55296
	ds_read_b128 v[180:183], v154 offset:50176
	ds_read_b128 v[188:191], v154 offset:52224
	ds_read_b128 v[196:199], v154 offset:54272
	ds_read_b128 v[204:207], v154 offset:56320
	global_load_lds_dwordx4 v[172:173], off
	s_mov_b32 m0, s51
	v_lshl_add_u64 v[172:173], v[238:239], 0, s[0:1]
	global_load_lds_dwordx4 v[172:173], off
	s_barrier

; #define PG8_MMA(ai, bj, At, Bt) do { __builtin_amdgcn_s_setprio(1); _Pragma("unroll") for (int m = 0; m < 4; ++m) _Pragma("unroll") for (int n = 0; n < 2; ++n) _Pragma("unroll") for (int k = 0; k < 2; ++k) \
;         acc[ai][bj][m][n] = __builtin_amdgcn_mfma_f32_16x16x32_bf16(Bt[n][k], At[m][k], acc[ai][bj][m][n], 0, 0, 0); __builtin_amdgcn_s_setprio(0); } while (0)
; #define PG8_WAIT_L(n) asm volatile("s_waitcnt lgkmcnt(" #n ")" ::: "memory")
; #define PG8_BAR __builtin_amdgcn_s_barrier()
; #define PG8_SCHED __builtin_amdgcn_sched_barrier(0)
; template <class Epi, class Sched>
; __device__ __forceinline__ void gemm_phase(PG8_LAS unsigned char* lds, const Gemm g, const Sched& S, const Epi& E) {
;     ...
;             PG8_BAR; PG8_WAIT_L(0); PG8_MMA(1, 0, At, B0); PG8_BAR; PG8_SCHED;
	s_waitcnt lgkmcnt(7)
	v_mfma_f32_16x16x32_bf16 v[62:65], v[156:159], v[176:179], v[62:65]
	v_mfma_f32_16x16x32_bf16 v[58:61], v[164:167], v[176:179], v[58:61]

; #define PG8_MMA(ai, bj, At, Bt) do { __builtin_amdgcn_s_setprio(1); _Pragma("unroll") for (int m = 0; m < 4; ++m) _Pragma("unroll") for (int n = 0; n < 2; ++n) _Pragma("unroll") for (int k = 0; k < 2; ++k) \
;         acc[ai][bj][m][n] = __builtin_amdgcn_mfma_f32_16x16x32_bf16(Bt[n][k], At[m][k], acc[ai][bj][m][n], 0, 0, 0); __builtin_amdgcn_s_setprio(0); } while (0)
; #define PG8_WAIT_L(n) asm volatile("s_waitcnt lgkmcnt(" #n ")" ::: "memory")
; #define PG8_BAR __builtin_amdgcn_s_barrier()
; #define PG8_SCHED __builtin_amdgcn_sched_barrier(0)
; template <class Epi, class Sched>
; __device__ __forceinline__ void gemm_phase(PG8_LAS unsigned char* lds, const Gemm g, const Sched& S, const Epi& E) {
;     ...
;             PG8_BAR; PG8_WAIT_L(0); PG8_MMA(1, 0, At, B0); PG8_BAR; PG8_SCHED;
	s_waitcnt lgkmcnt(6)
	v_mfma_f32_16x16x32_bf16 v[54:57], v[156:159], v[184:187], v[54:57]
	v_mfma_f32_16x16x32_bf16 v[50:53], v[164:167], v[184:187], v[50:53]

; #define PG8_MMA(ai, bj, At, Bt) do { __builtin_amdgcn_s_setprio(1); _Pragma("unroll") for (int m = 0; m < 4; ++m) _Pragma("unroll") for (int n = 0; n < 2; ++n) _Pragma("unroll") for (int k = 0; k < 2; ++k) \
;         acc[ai][bj][m][n] = __builtin_amdgcn_mfma_f32_16x16x32_bf16(Bt[n][k], At[m][k], acc[ai][bj][m][n], 0, 0, 0); __builtin_amdgcn_s_setprio(0); } while (0)
; #define PG8_WAIT_L(n) asm volatile("s_waitcnt lgkmcnt(" #n ")" ::: "memory")
; #define PG8_BAR __builtin_amdgcn_s_barrier()
; #define PG8_SCHED __builtin_amdgcn_sched_barrier(0)
; template <class Epi, class Sched>
; __device__ __forceinline__ void gemm_phase(PG8_LAS unsigned char* lds, const Gemm g, const Sched& S, const Epi& E) {
;     ...
;             PG8_BAR; PG8_WAIT_L(0); PG8_MMA(1, 0, At, B0); PG8_BAR; PG8_SCHED;
	s_waitcnt lgkmcnt(5)
	v_mfma_f32_16x16x32_bf16 v[44:47], v[156:159], v[192:195], v[44:47]
	v_mfma_f32_16x16x32_bf16 v[40:43], v[164:167], v[192:195], v[40:43]

; #define PG8_MMA(ai, bj, At, Bt) do { __builtin_amdgcn_s_setprio(1); _Pragma("unroll") for (int m = 0; m < 4; ++m) _Pragma("unroll") for (int n = 0; n < 2; ++n) _Pragma("unroll") for (int k = 0; k < 2; ++k) \
;         acc[ai][bj][m][n] = __builtin_amdgcn_mfma_f32_16x16x32_bf16(Bt[n][k], At[m][k], acc[ai][bj][m][n], 0, 0, 0); __builtin_amdgcn_s_setprio(0); } while (0)
; #define PG8_WAIT_L(n) asm volatile("s_waitcnt lgkmcnt(" #n ")" ::: "memory")
; #define PG8_BAR __builtin_amdgcn_s_barrier()
; #define PG8_SCHED __builtin_amdgcn_sched_barrier(0)
; template <class Epi, class Sched>
; __device__ __forceinline__ void gemm_phase(PG8_LAS unsigned char* lds, const Gemm g, const Sched& S, const Epi& E) {
;     ...
;             PG8_BAR; PG8_WAIT_L(0); PG8_MMA(1, 0, At, B0); PG8_BAR; PG8_SCHED;
	s_waitcnt lgkmcnt(4)
	v_mfma_f32_16x16x32_bf16 v[32:35], v[156:159], v[200:203], v[32:35]
	v_mfma_f32_16x16x32_bf16 v[24:27], v[164:167], v[200:203], v[24:27]
	s_waitcnt lgkmcnt(3)
	v_mfma_f32_16x16x32_bf16 v[62:65], v[160:163], v[180:183], v[62:65]
	v_mfma_f32_16x16x32_bf16 v[58:61], v[168:171], v[180:183], v[58:61]
	s_waitcnt lgkmcnt(2)
	v_mfma_f32_16x16x32_bf16 v[54:57], v[160:163], v[188:191], v[54:57]
	v_mfma_f32_16x16x32_bf16 v[50:53], v[168:171], v[188:191], v[50:53]
	s_waitcnt lgkmcnt(1)
	v_mfma_f32_16x16x32_bf16 v[44:47], v[160:163], v[196:199], v[44:47]
	v_mfma_f32_16x16x32_bf16 v[40:43], v[168:171], v[196:199], v[40:43]

; #define PG8_STAGE(bufoff, gbase, voff) do { _Pragma("unroll") for (int _i = 0; _i < 2; ++_i) \
;         __builtin_amdgcn_global_load_lds((const unsigned*)((const char*)(gbase) + (voff)[_i]), (PG8_LAS unsigned*)(lds + (bufoff) + ldsw + _i * 8192), 16, 0, 0); } while (0)
; #define PG8_MMA(ai, bj, At, Bt) do { __builtin_amdgcn_s_setprio(1); _Pragma("unroll") for (int m = 0; m < 4; ++m) _Pragma("unroll") for (int n = 0; n < 2; ++n) _Pragma("unroll") for (int k = 0; k < 2; ++k) \
;         acc[ai][bj][m][n] = __builtin_amdgcn_mfma_f32_16x16x32_bf16(Bt[n][k], At[m][k], acc[ai][bj][m][n], 0, 0, 0); __builtin_amdgcn_s_setprio(0); } while (0)
; #define PG8_WAIT_V(n) asm volatile("s_waitcnt vmcnt(" #n ")" ::: "memory")
; #define PG8_WAIT_L(n) asm volatile("s_waitcnt lgkmcnt(" #n ")" ::: "memory")
; #define PG8_BAR __builtin_amdgcn_s_barrier()
; #define PG8_SCHED __builtin_amdgcn_sched_barrier(0)
; template <class Epi, class Sched>
; __device__ __forceinline__ void gemm_phase(PG8_LAS unsigned char* lds, const Gemm g, const Sched& S, const Epi& E) {
;     ...
;             PG8_BAR; PG8_WAIT_L(0); PG8_MMA(1, 0, At, B0); PG8_BAR; PG8_SCHED;
;             PG8_STAGE(PG8_SB(1, 1), b3 + hstep, voffB);
;             PG8_WAIT_V(6); PG8_BAR; PG8_MMA(1, 1, At, B1); PG8_BAR;
	s_waitcnt lgkmcnt(0)
	v_mfma_f32_16x16x32_bf16 v[32:35], v[160:163], v[204:207], v[32:35]
	v_mfma_f32_16x16x32_bf16 v[24:27], v[168:171], v[204:207], v[24:27]
	s_barrier
	s_add_i32 s22, s22, s37
	s_mov_b32 m0, s22
	v_lshl_add_u64 v[156:157], v[240:241], 0, s[0:1]
	global_load_lds_dwordx4 v[156:157], off
	s_add_i32 m0, s22, 0x2000
	v_lshl_add_u64 v[156:157], v[242:243], 0, s[0:1]
	global_load_lds_dwordx4 v[156:157], off
	s_waitcnt vmcnt(6)
	s_barrier
	v_mfma_f32_16x16x32_bf16 v[36:39], v[208:211], v[176:179], v[36:39]
	v_mfma_f32_16x16x32_bf16 v[28:31], v[216:219], v[176:179], v[28:31]
	v_mfma_f32_16x16x32_bf16 v[20:23], v[208:211], v[184:187], v[20:23]
	v_mfma_f32_16x16x32_bf16 v[16:19], v[216:219], v[184:187], v[16:19]
	v_mfma_f32_16x16x32_bf16 v[12:15], v[208:211], v[192:195], v[12:15]
	v_mfma_f32_16x16x32_bf16 v[8:11], v[216:219], v[192:195], v[8:11]
	v_mfma_f32_16x16x32_bf16 v[4:7], v[208:211], v[200:203], v[4:7]
	v_mfma_f32_16x16x32_bf16 v[0:3], v[216:219], v[200:203], v[0:3]
	v_mfma_f32_16x16x32_bf16 v[36:39], v[212:215], v[180:183], v[36:39]
	v_mfma_f32_16x16x32_bf16 v[28:31], v[234:237], v[180:183], v[28:31]
	v_mfma_f32_16x16x32_bf16 v[20:23], v[212:215], v[188:191], v[20:23]
	v_mfma_f32_16x16x32_bf16 v[16:19], v[234:237], v[188:191], v[16:19]
	v_mfma_f32_16x16x32_bf16 v[12:15], v[212:215], v[196:199], v[12:15]
	v_mfma_f32_16x16x32_bf16 v[8:11], v[234:237], v[196:199], v[8:11]
	v_mfma_f32_16x16x32_bf16 v[4:7], v[212:215], v[204:207], v[4:7]
	v_mfma_f32_16x16x32_bf16 v[0:3], v[234:237], v[204:207], v[0:3]
	s_add_u32 s20, s20, 0x100
	s_addc_u32 s21, s21, 0
	s_add_u32 s3, s3, 0x100
	s_addc_u32 s40, s40, 0
	s_cmp_ge_u32 s41, s54
	s_mov_b32 s22, s41
	s_barrier
	s_cbranch_scc0 .LBB0_288

; #define PG8_STAGE(bufoff, gbase, voff) do { _Pragma("unroll") for (int _i = 0; _i < 2; ++_i) \
;         __builtin_amdgcn_global_load_lds((const unsigned*)((const char*)(gbase) + (voff)[_i]), (PG8_LAS unsigned*)(lds + (bufoff) + ldsw + _i * 8192), 16, 0, 0); } while (0)
; #define PG8_LDA(dst, b, h) do { _Pragma("unroll") for (int m = 0; m < 4; ++m) _Pragma("unroll") for (int k = 0; k < 2; ++k) dst[m][k] = *(const PG8_LAS bf16x8*)(lds + PG8_SA(b, h) + aoff + m * 2048 + k * 1024); } while (0)
; #define PG8_LDB(dst, b, h) do { _Pragma("unroll") for (int n = 0; n < 2; ++n) _Pragma("unroll") for (int k = 0; k < 2; ++k) dst[n][k] = *(const PG8_LAS bf16x8*)(lds + PG8_SB(b, h) + boff + n * 2048 + k * 1024); } while (0)
; #define PG8_SCHED __builtin_amdgcn_sched_barrier(0)
; template <class Epi, class Sched>
; __device__ __forceinline__ void gemm_phase(PG8_LAS unsigned char* lds, const Gemm g, const Sched& S, const Epi& E) {
;     ...
;         const bool has_next = S.next(ui + 1, nxt);
;         const char* nA = has_next ? (const char*)g.A + (size_t)nxt.pm * tstepA + (size_t)nxt.kc * cstep : cA; const char* nB = has_next ? (const char*)g.Bt + (size_t)nxt.pn * tstep + (size_t)nxt.kc * cstep : cB;
;         for (int t = 0; t < nt; t += 2) {
;             const bool last = (t == nt - 2);
;             const char* a1 = cA + (size_t)(t + 1) * kstep;
;             const char* a2 = last ? nA : cA + (size_t)(t + 2) * kstep; const char* b2 = last ? nB : cB + (size_t)(t + 2) * kstep;
;             const char* a3 = a2 + kstep; const char* b3 = b2 + kstep;
;             if (last && has_next) S.a_ready(nxt);
;             PG8_LDB(B0, 0, 0); PG8_SCHED; PG8_LDA(At, 0, 0); PG8_STAGE(PG8_SA(1, 1), a1 + hstep, voffA);
.LBB0_319:
	v_mov_b64_e32 v[0:1], s[56:57]
	s_ashr_i32 s25, s24, 31
	v_cmp_lt_i64_e32 vcc, s[26:27], v[0:1]
	s_lshl_b64 s[26:27], s[24:25], 19
	s_add_u32 s26, s8, s26
	s_addc_u32 s27, s9, s27
	s_and_b64 s[28:29], vcc, exec
	s_cselect_b32 s25, s27, s31
	s_cselect_b32 s56, s26, s30
	s_ashr_i32 s23, s22, 31
	s_lshl_b64 s[28:29], s[22:23], 19
	s_add_u32 s28, s6, s28
	s_addc_u32 s29, s7, s29
	s_and_b64 s[36:37], vcc, exec
	s_cselect_b32 s23, s29, s35
	s_cselect_b32 s57, s28, s34
	s_add_u32 s30, s30, 0x40080
	s_addc_u32 s31, s31, 0
	s_add_u32 s59, s34, 0x100
	s_addc_u32 s63, s35, 0
	s_mov_b32 s64, -2
	s_add_u32 s34, s30, 0xfffc0080
	s_addc_u32 s35, s31, -1
	s_add_i32 s65, 0, 0x10000
	v_add_u32_e32 v140, s65, v143
	ds_read_b128 v[146:149], v140
	ds_read_b128 v[150:153], v140 offset:1024
	ds_read_b128 v[154:157], v140 offset:2048
	ds_read_b128 v[158:161], v140 offset:3072
	s_cmp_eq_u32 s64, 12
	s_cselect_b32 s37, s25, s35
	s_cselect_b32 s36, s56, s34
	s_cselect_b32 s35, s23, s63
	s_cselect_b32 s34, s57, s59
	v_lshl_add_u64 v[140:141], s[30:31], 0, v[136:137]
	s_add_i32 m0, s21, 0xc000
	ds_read_b128 v[162:165], v145
	ds_read_b128 v[170:173], v145 offset:2048
	ds_read_b128 v[180:183], v145 offset:4096
	ds_read_b128 v[188:191], v145 offset:6144
	ds_read_b128 v[166:169], v145 offset:1024
	ds_read_b128 v[176:179], v145 offset:3072
	ds_read_b128 v[184:187], v145 offset:5120
	ds_read_b128 v[192:195], v145 offset:7168
	global_load_lds_dwordx4 v[140:141], off
	s_add_i32 m0, s21, 0xe000
	v_lshl_add_u64 v[140:141], s[30:31], 0, v[138:139]
	global_load_lds_dwordx4 v[140:141], off
	s_waitcnt lgkmcnt(8)
	s_barrier

; #define PG8_MMA(ai, bj, At, Bt) do { __builtin_amdgcn_s_setprio(1); _Pragma("unroll") for (int m = 0; m < 4; ++m) _Pragma("unroll") for (int n = 0; n < 2; ++n) _Pragma("unroll") for (int k = 0; k < 2; ++k) \
;         acc[ai][bj][m][n] = __builtin_amdgcn_mfma_f32_16x16x32_bf16(Bt[n][k], At[m][k], acc[ai][bj][m][n], 0, 0, 0); __builtin_amdgcn_s_setprio(0); } while (0)
; #define PG8_WAIT_L(n) asm volatile("s_waitcnt lgkmcnt(" #n ")" ::: "memory")
; #define PG8_BAR __builtin_amdgcn_s_barrier()
; #define PG8_SCHED __builtin_amdgcn_sched_barrier(0)
; template <class Epi, class Sched>
; __device__ __forceinline__ void gemm_phase(PG8_LAS unsigned char* lds, const Gemm g, const Sched& S, const Epi& E) {
;     ...
;             PG8_WAIT_L(8); PG8_BAR; PG8_WAIT_L(0); PG8_MMA(0, 0, At, B0); PG8_BAR; PG8_SCHED;
	s_waitcnt lgkmcnt(7)
	v_mfma_f32_16x16x32_bf16 v[126:129], v[146:149], v[162:165], 0
	v_mfma_f32_16x16x32_bf16 v[122:125], v[154:157], v[162:165], 0

; #define PG8_MMA(ai, bj, At, Bt) do { __builtin_amdgcn_s_setprio(1); _Pragma("unroll") for (int m = 0; m < 4; ++m) _Pragma("unroll") for (int n = 0; n < 2; ++n) _Pragma("unroll") for (int k = 0; k < 2; ++k) \
;         acc[ai][bj][m][n] = __builtin_amdgcn_mfma_f32_16x16x32_bf16(Bt[n][k], At[m][k], acc[ai][bj][m][n], 0, 0, 0); __builtin_amdgcn_s_setprio(0); } while (0)
; #define PG8_WAIT_L(n) asm volatile("s_waitcnt lgkmcnt(" #n ")" ::: "memory")
; #define PG8_BAR __builtin_amdgcn_s_barrier()
; #define PG8_SCHED __builtin_amdgcn_sched_barrier(0)
; template <class Epi, class Sched>
; __device__ __forceinline__ void gemm_phase(PG8_LAS unsigned char* lds, const Gemm g, const Sched& S, const Epi& E) {
;     ...
;             PG8_WAIT_L(8); PG8_BAR; PG8_WAIT_L(0); PG8_MMA(0, 0, At, B0); PG8_BAR; PG8_SCHED;
	s_waitcnt lgkmcnt(6)
	v_mfma_f32_16x16x32_bf16 v[118:121], v[146:149], v[170:173], 0
	v_mfma_f32_16x16x32_bf16 v[110:113], v[154:157], v[170:173], 0

; #define PG8_MMA(ai, bj, At, Bt) do { __builtin_amdgcn_s_setprio(1); _Pragma("unroll") for (int m = 0; m < 4; ++m) _Pragma("unroll") for (int n = 0; n < 2; ++n) _Pragma("unroll") for (int k = 0; k < 2; ++k) \
;         acc[ai][bj][m][n] = __builtin_amdgcn_mfma_f32_16x16x32_bf16(Bt[n][k], At[m][k], acc[ai][bj][m][n], 0, 0, 0); __builtin_amdgcn_s_setprio(0); } while (0)
; #define PG8_WAIT_L(n) asm volatile("s_waitcnt lgkmcnt(" #n ")" ::: "memory")
; #define PG8_BAR __builtin_amdgcn_s_barrier()
; #define PG8_SCHED __builtin_amdgcn_sched_barrier(0)
; template <class Epi, class Sched>
; __device__ __forceinline__ void gemm_phase(PG8_LAS unsigned char* lds, const Gemm g, const Sched& S, const Epi& E) {
;     ...
;             PG8_WAIT_L(8); PG8_BAR; PG8_WAIT_L(0); PG8_MMA(0, 0, At, B0); PG8_BAR; PG8_SCHED;
	s_waitcnt lgkmcnt(5)
	v_mfma_f32_16x16x32_bf16 v[102:105], v[146:149], v[180:183], 0
	v_mfma_f32_16x16x32_bf16 v[94:97], v[154:157], v[180:183], 0

; #define PG8_MMA(ai, bj, At, Bt) do { __builtin_amdgcn_s_setprio(1); _Pragma("unroll") for (int m = 0; m < 4; ++m) _Pragma("unroll") for (int n = 0; n < 2; ++n) _Pragma("unroll") for (int k = 0; k < 2; ++k) \
;         acc[ai][bj][m][n] = __builtin_amdgcn_mfma_f32_16x16x32_bf16(Bt[n][k], At[m][k], acc[ai][bj][m][n], 0, 0, 0); __builtin_amdgcn_s_setprio(0); } while (0)
; #define PG8_WAIT_L(n) asm volatile("s_waitcnt lgkmcnt(" #n ")" ::: "memory")
; #define PG8_BAR __builtin_amdgcn_s_barrier()
; #define PG8_SCHED __builtin_amdgcn_sched_barrier(0)
; template <class Epi, class Sched>
; __device__ __forceinline__ void gemm_phase(PG8_LAS unsigned char* lds, const Gemm g, const Sched& S, const Epi& E) {
;     ...
;             PG8_WAIT_L(8); PG8_BAR; PG8_WAIT_L(0); PG8_MMA(0, 0, At, B0); PG8_BAR; PG8_SCHED;
	s_waitcnt lgkmcnt(4)
	v_mfma_f32_16x16x32_bf16 v[86:89], v[146:149], v[188:191], 0
	v_mfma_f32_16x16x32_bf16 v[78:81], v[154:157], v[188:191], 0
	s_waitcnt lgkmcnt(3)
	v_mfma_f32_16x16x32_bf16 v[126:129], v[150:153], v[166:169], v[126:129]
	v_mfma_f32_16x16x32_bf16 v[122:125], v[158:161], v[166:169], v[122:125]
	s_waitcnt lgkmcnt(2)
	v_mfma_f32_16x16x32_bf16 v[118:121], v[150:153], v[176:179], v[118:121]
	v_mfma_f32_16x16x32_bf16 v[110:113], v[158:161], v[176:179], v[110:113]
	s_waitcnt lgkmcnt(1)
	v_mfma_f32_16x16x32_bf16 v[102:105], v[150:153], v[184:187], v[102:105]
	v_mfma_f32_16x16x32_bf16 v[94:97], v[158:161], v[184:187], v[94:97]

; #define PG8_STAGE(bufoff, gbase, voff) do { _Pragma("unroll") for (int _i = 0; _i < 2; ++_i) \
;         __builtin_amdgcn_global_load_lds((const unsigned*)((const char*)(gbase) + (voff)[_i]), (PG8_LAS unsigned*)(lds + (bufoff) + ldsw + _i * 8192), 16, 0, 0); } while (0)
; #define PG8_LDB(dst, b, h) do { _Pragma("unroll") for (int n = 0; n < 2; ++n) _Pragma("unroll") for (int k = 0; k < 2; ++k) dst[n][k] = *(const PG8_LAS bf16x8*)(lds + PG8_SB(b, h) + boff + n * 2048 + k * 1024); } while (0)
; #define PG8_MMA(ai, bj, At, Bt) do { __builtin_amdgcn_s_setprio(1); _Pragma("unroll") for (int m = 0; m < 4; ++m) _Pragma("unroll") for (int n = 0; n < 2; ++n) _Pragma("unroll") for (int k = 0; k < 2; ++k) \
;         acc[ai][bj][m][n] = __builtin_amdgcn_mfma_f32_16x16x32_bf16(Bt[n][k], At[m][k], acc[ai][bj][m][n], 0, 0, 0); __builtin_amdgcn_s_setprio(0); } while (0)
; #define PG8_WAIT_L(n) asm volatile("s_waitcnt lgkmcnt(" #n ")" ::: "memory")
; #define PG8_BAR __builtin_amdgcn_s_barrier()
; #define PG8_SCHED __builtin_amdgcn_sched_barrier(0)
; template <class Epi, class Sched>
; __device__ __forceinline__ void gemm_phase(PG8_LAS unsigned char* lds, const Gemm g, const Sched& S, const Epi& E) {
;     ...
;             PG8_WAIT_L(8); PG8_BAR; PG8_WAIT_L(0); PG8_MMA(0, 0, At, B0); PG8_BAR; PG8_SCHED;
;             PG8_LDB(B1, 0, 1); PG8_STAGE(PG8_SB(0, 0), b2, voffB);
	s_waitcnt lgkmcnt(0)
	v_mfma_f32_16x16x32_bf16 v[86:89], v[150:153], v[192:195], v[86:89]
	v_mfma_f32_16x16x32_bf16 v[78:81], v[158:161], v[192:195], v[78:81]
	s_barrier
	s_add_i32 s68, 0, 0x14000
	v_add_u32_e32 v140, s68, v143
	s_add_i32 s65, s65, s13
	ds_read_b128 v[196:199], v140
	ds_read_b128 v[204:207], v140 offset:2048
	ds_read_b128 v[200:203], v140 offset:1024
	ds_read_b128 v[208:211], v140 offset:3072
	v_lshl_add_u64 v[140:141], s[34:35], 0, v[48:49]
	s_mov_b32 m0, s65
	v_lshl_add_u64 v[212:213], s[34:35], 0, v[130:131]
	global_load_lds_dwordx4 v[140:141], off
	s_add_i32 m0, s65, 0x2000
	s_nop 0
	global_load_lds_dwordx4 v[212:213], off
	s_barrier

; #define PG8_MMA(ai, bj, At, Bt) do { __builtin_amdgcn_s_setprio(1); _Pragma("unroll") for (int m = 0; m < 4; ++m) _Pragma("unroll") for (int n = 0; n < 2; ++n) _Pragma("unroll") for (int k = 0; k < 2; ++k) \
;         acc[ai][bj][m][n] = __builtin_amdgcn_mfma_f32_16x16x32_bf16(Bt[n][k], At[m][k], acc[ai][bj][m][n], 0, 0, 0); __builtin_amdgcn_s_setprio(0); } while (0)
; #define PG8_WAIT_L(n) asm volatile("s_waitcnt lgkmcnt(" #n ")" ::: "memory")
; #define PG8_BAR __builtin_amdgcn_s_barrier()
; template <class Epi, class Sched>
; __device__ __forceinline__ void gemm_phase(PG8_LAS unsigned char* lds, const Gemm g, const Sched& S, const Epi& E) {
;     ...
;             PG8_BAR; PG8_WAIT_L(0); PG8_MMA(0, 1, At, B1); PG8_BAR;
	s_waitcnt lgkmcnt(3)
	v_mfma_f32_16x16x32_bf16 v[114:117], v[196:199], v[162:165], 0

; #define PG8_MMA(ai, bj, At, Bt) do { __builtin_amdgcn_s_setprio(1); _Pragma("unroll") for (int m = 0; m < 4; ++m) _Pragma("unroll") for (int n = 0; n < 2; ++n) _Pragma("unroll") for (int k = 0; k < 2; ++k) \
;         acc[ai][bj][m][n] = __builtin_amdgcn_mfma_f32_16x16x32_bf16(Bt[n][k], At[m][k], acc[ai][bj][m][n], 0, 0, 0); __builtin_amdgcn_s_setprio(0); } while (0)
; #define PG8_WAIT_L(n) asm volatile("s_waitcnt lgkmcnt(" #n ")" ::: "memory")
; #define PG8_BAR __builtin_amdgcn_s_barrier()
; template <class Epi, class Sched>
; __device__ __forceinline__ void gemm_phase(PG8_LAS unsigned char* lds, const Gemm g, const Sched& S, const Epi& E) {
;     ...
;             PG8_BAR; PG8_WAIT_L(0); PG8_MMA(0, 1, At, B1); PG8_BAR;
	s_waitcnt lgkmcnt(2)
	v_mfma_f32_16x16x32_bf16 v[106:109], v[204:207], v[162:165], 0
	v_mfma_f32_16x16x32_bf16 v[98:101], v[196:199], v[170:173], 0
	v_mfma_f32_16x16x32_bf16 v[90:93], v[204:207], v[170:173], 0
	v_mfma_f32_16x16x32_bf16 v[82:85], v[196:199], v[180:183], 0
	v_mfma_f32_16x16x32_bf16 v[74:77], v[204:207], v[180:183], 0
	v_mfma_f32_16x16x32_bf16 v[70:73], v[196:199], v[188:191], 0
	v_mfma_f32_16x16x32_bf16 v[66:69], v[204:207], v[188:191], 0
	s_waitcnt lgkmcnt(1)
	v_mfma_f32_16x16x32_bf16 v[114:117], v[200:203], v[166:169], v[114:117]

; #define PG8_STAGE(bufoff, gbase, voff) do { _Pragma("unroll") for (int _i = 0; _i < 2; ++_i) \
;         __builtin_amdgcn_global_load_lds((const unsigned*)((const char*)(gbase) + (voff)[_i]), (PG8_LAS unsigned*)(lds + (bufoff) + ldsw + _i * 8192), 16, 0, 0); } while (0)
; #define PG8_LDA(dst, b, h) do { _Pragma("unroll") for (int m = 0; m < 4; ++m) _Pragma("unroll") for (int k = 0; k < 2; ++k) dst[m][k] = *(const PG8_LAS bf16x8*)(lds + PG8_SA(b, h) + aoff + m * 2048 + k * 1024); } while (0)
; #define PG8_MMA(ai, bj, At, Bt) do { __builtin_amdgcn_s_setprio(1); _Pragma("unroll") for (int m = 0; m < 4; ++m) _Pragma("unroll") for (int n = 0; n < 2; ++n) _Pragma("unroll") for (int k = 0; k < 2; ++k) \
;         acc[ai][bj][m][n] = __builtin_amdgcn_mfma_f32_16x16x32_bf16(Bt[n][k], At[m][k], acc[ai][bj][m][n], 0, 0, 0); __builtin_amdgcn_s_setprio(0); } while (0)
; #define PG8_WAIT_L(n) asm volatile("s_waitcnt lgkmcnt(" #n ")" ::: "memory")
; #define PG8_BAR __builtin_amdgcn_s_barrier()
; template <class Epi, class Sched>
; __device__ __forceinline__ void gemm_phase(PG8_LAS unsigned char* lds, const Gemm g, const Sched& S, const Epi& E) {
;     ...
;             PG8_BAR; PG8_WAIT_L(0); PG8_MMA(0, 1, At, B1); PG8_BAR;
;             PG8_LDA(At, 0, 1); PG8_STAGE(PG8_SA(0, 0), a2, voffA);
	s_waitcnt lgkmcnt(0)
	v_mfma_f32_16x16x32_bf16 v[106:109], v[208:211], v[166:169], v[106:109]
	v_mfma_f32_16x16x32_bf16 v[98:101], v[200:203], v[176:179], v[98:101]
	v_mfma_f32_16x16x32_bf16 v[90:93], v[208:211], v[176:179], v[90:93]
	v_mfma_f32_16x16x32_bf16 v[82:85], v[200:203], v[184:187], v[82:85]
	v_mfma_f32_16x16x32_bf16 v[74:77], v[208:211], v[184:187], v[74:77]
	v_mfma_f32_16x16x32_bf16 v[70:73], v[200:203], v[192:195], v[70:73]
	v_mfma_f32_16x16x32_bf16 v[66:69], v[208:211], v[192:195], v[66:69]
	s_mov_b32 m0, s21
	v_lshl_add_u64 v[214:215], s[36:37], 0, v[134:135]
	s_barrier
	ds_read_b128 v[162:165], v145 offset:16384
	ds_read_b128 v[170:173], v145 offset:18432
	ds_read_b128 v[180:183], v145 offset:20480
	ds_read_b128 v[188:191], v145 offset:22528
	ds_read_b128 v[166:169], v145 offset:17408
	ds_read_b128 v[176:179], v145 offset:19456
	ds_read_b128 v[184:187], v145 offset:21504
	ds_read_b128 v[192:195], v145 offset:23552
	global_load_lds_dwordx4 v[214:215], off
	s_mov_b32 m0, s46
	v_lshl_add_u64 v[216:217], s[36:37], 0, v[132:133]
	global_load_lds_dwordx4 v[216:217], off
	s_barrier

; #define PG8_MMA(ai, bj, At, Bt) do { __builtin_amdgcn_s_setprio(1); _Pragma("unroll") for (int m = 0; m < 4; ++m) _Pragma("unroll") for (int n = 0; n < 2; ++n) _Pragma("unroll") for (int k = 0; k < 2; ++k) \
;         acc[ai][bj][m][n] = __builtin_amdgcn_mfma_f32_16x16x32_bf16(Bt[n][k], At[m][k], acc[ai][bj][m][n], 0, 0, 0); __builtin_amdgcn_s_setprio(0); } while (0)
; #define PG8_WAIT_L(n) asm volatile("s_waitcnt lgkmcnt(" #n ")" ::: "memory")
; #define PG8_BAR __builtin_amdgcn_s_barrier()
; #define PG8_SCHED __builtin_amdgcn_sched_barrier(0)
; template <class Epi, class Sched>
; __device__ __forceinline__ void gemm_phase(PG8_LAS unsigned char* lds, const Gemm g, const Sched& S, const Epi& E) {
;     ...
;             PG8_BAR; PG8_WAIT_L(0); PG8_MMA(1, 0, At, B0); PG8_BAR; PG8_SCHED;
	s_waitcnt lgkmcnt(7)
	v_mfma_f32_16x16x32_bf16 v[62:65], v[146:149], v[162:165], 0
	v_mfma_f32_16x16x32_bf16 v[58:61], v[154:157], v[162:165], 0

; #define PG8_MMA(ai, bj, At, Bt) do { __builtin_amdgcn_s_setprio(1); _Pragma("unroll") for (int m = 0; m < 4; ++m) _Pragma("unroll") for (int n = 0; n < 2; ++n) _Pragma("unroll") for (int k = 0; k < 2; ++k) \
;         acc[ai][bj][m][n] = __builtin_amdgcn_mfma_f32_16x16x32_bf16(Bt[n][k], At[m][k], acc[ai][bj][m][n], 0, 0, 0); __builtin_amdgcn_s_setprio(0); } while (0)
; #define PG8_WAIT_L(n) asm volatile("s_waitcnt lgkmcnt(" #n ")" ::: "memory")
; #define PG8_BAR __builtin_amdgcn_s_barrier()
; #define PG8_SCHED __builtin_amdgcn_sched_barrier(0)
; template <class Epi, class Sched>
; __device__ __forceinline__ void gemm_phase(PG8_LAS unsigned char* lds, const Gemm g, const Sched& S, const Epi& E) {
;     ...
;             PG8_BAR; PG8_WAIT_L(0); PG8_MMA(1, 0, At, B0); PG8_BAR; PG8_SCHED;
	s_waitcnt lgkmcnt(6)
	v_mfma_f32_16x16x32_bf16 v[54:57], v[146:149], v[170:173], 0
	v_mfma_f32_16x16x32_bf16 v[44:47], v[154:157], v[170:173], 0

; #define PG8_MMA(ai, bj, At, Bt) do { __builtin_amdgcn_s_setprio(1); _Pragma("unroll") for (int m = 0; m < 4; ++m) _Pragma("unroll") for (int n = 0; n < 2; ++n) _Pragma("unroll") for (int k = 0; k < 2; ++k) \
;         acc[ai][bj][m][n] = __builtin_amdgcn_mfma_f32_16x16x32_bf16(Bt[n][k], At[m][k], acc[ai][bj][m][n], 0, 0, 0); __builtin_amdgcn_s_setprio(0); } while (0)
; #define PG8_WAIT_L(n) asm volatile("s_waitcnt lgkmcnt(" #n ")" ::: "memory")
; #define PG8_BAR __builtin_amdgcn_s_barrier()
; #define PG8_SCHED __builtin_amdgcn_sched_barrier(0)
; template <class Epi, class Sched>
; __device__ __forceinline__ void gemm_phase(PG8_LAS unsigned char* lds, const Gemm g, const Sched& S, const Epi& E) {
;     ...
;             PG8_BAR; PG8_WAIT_L(0); PG8_MMA(1, 0, At, B0); PG8_BAR; PG8_SCHED;
	s_waitcnt lgkmcnt(5)
	v_mfma_f32_16x16x32_bf16 v[36:39], v[146:149], v[180:183], 0
	v_mfma_f32_16x16x32_bf16 v[28:31], v[154:157], v[180:183], 0

; #define PG8_MMA(ai, bj, At, Bt) do { __builtin_amdgcn_s_setprio(1); _Pragma("unroll") for (int m = 0; m < 4; ++m) _Pragma("unroll") for (int n = 0; n < 2; ++n) _Pragma("unroll") for (int k = 0; k < 2; ++k) \
;         acc[ai][bj][m][n] = __builtin_amdgcn_mfma_f32_16x16x32_bf16(Bt[n][k], At[m][k], acc[ai][bj][m][n], 0, 0, 0); __builtin_amdgcn_s_setprio(0); } while (0)
; #define PG8_WAIT_L(n) asm volatile("s_waitcnt lgkmcnt(" #n ")" ::: "memory")
; #define PG8_BAR __builtin_amdgcn_s_barrier()
; #define PG8_SCHED __builtin_amdgcn_sched_barrier(0)
; template <class Epi, class Sched>
; __device__ __forceinline__ void gemm_phase(PG8_LAS unsigned char* lds, const Gemm g, const Sched& S, const Epi& E) {
;     ...
;             PG8_BAR; PG8_WAIT_L(0); PG8_MMA(1, 0, At, B0); PG8_BAR; PG8_SCHED;
	s_waitcnt lgkmcnt(4)
	v_mfma_f32_16x16x32_bf16 v[20:23], v[146:149], v[188:191], 0
	v_mfma_f32_16x16x32_bf16 v[12:15], v[154:157], v[188:191], 0
	s_waitcnt lgkmcnt(3)
	v_mfma_f32_16x16x32_bf16 v[62:65], v[150:153], v[166:169], v[62:65]
	v_mfma_f32_16x16x32_bf16 v[58:61], v[158:161], v[166:169], v[58:61]
	s_waitcnt lgkmcnt(2)
	v_mfma_f32_16x16x32_bf16 v[54:57], v[150:153], v[176:179], v[54:57]
	v_mfma_f32_16x16x32_bf16 v[44:47], v[158:161], v[176:179], v[44:47]
	s_waitcnt lgkmcnt(1)
	v_mfma_f32_16x16x32_bf16 v[36:39], v[150:153], v[184:187], v[36:39]
	v_mfma_f32_16x16x32_bf16 v[28:31], v[158:161], v[184:187], v[28:31]

; #define PG8_STAGE(bufoff, gbase, voff) do { _Pragma("unroll") for (int _i = 0; _i < 2; ++_i) \
;         __builtin_amdgcn_global_load_lds((const unsigned*)((const char*)(gbase) + (voff)[_i]), (PG8_LAS unsigned*)(lds + (bufoff) + ldsw + _i * 8192), 16, 0, 0); } while (0)
; #define PG8_LDA(dst, b, h) do { _Pragma("unroll") for (int m = 0; m < 4; ++m) _Pragma("unroll") for (int k = 0; k < 2; ++k) dst[m][k] = *(const PG8_LAS bf16x8*)(lds + PG8_SA(b, h) + aoff + m * 2048 + k * 1024); } while (0)
; #define PG8_LDB(dst, b, h) do { _Pragma("unroll") for (int n = 0; n < 2; ++n) _Pragma("unroll") for (int k = 0; k < 2; ++k) dst[n][k] = *(const PG8_LAS bf16x8*)(lds + PG8_SB(b, h) + boff + n * 2048 + k * 1024); } while (0)
; #define PG8_MMA(ai, bj, At, Bt) do { __builtin_amdgcn_s_setprio(1); _Pragma("unroll") for (int m = 0; m < 4; ++m) _Pragma("unroll") for (int n = 0; n < 2; ++n) _Pragma("unroll") for (int k = 0; k < 2; ++k) \
;         acc[ai][bj][m][n] = __builtin_amdgcn_mfma_f32_16x16x32_bf16(Bt[n][k], At[m][k], acc[ai][bj][m][n], 0, 0, 0); __builtin_amdgcn_s_setprio(0); } while (0)
; #define PG8_WAIT_V(n) asm volatile("s_waitcnt vmcnt(" #n ")" ::: "memory")
; #define PG8_WAIT_L(n) asm volatile("s_waitcnt lgkmcnt(" #n ")" ::: "memory")
; #define PG8_BAR __builtin_amdgcn_s_barrier()
; #define PG8_SCHED __builtin_amdgcn_sched_barrier(0)
; template <class Epi, class Sched>
; __device__ __forceinline__ void gemm_phase(PG8_LAS unsigned char* lds, const Gemm g, const Sched& S, const Epi& E) {
;     ...
;             PG8_BAR; PG8_WAIT_L(0); PG8_MMA(1, 0, At, B0); PG8_BAR; PG8_SCHED;
;             PG8_STAGE(PG8_SB(0, 1), b2 + hstep, voffB);
;             PG8_WAIT_V(6); PG8_BAR; PG8_MMA(1, 1, At, B1); PG8_BAR;
;             PG8_LDB(B0, 1, 0); PG8_SCHED; PG8_LDA(At, 1, 0); PG8_STAGE(PG8_SA(0, 1), a2 + hstep, voffA);
;             PG8_WAIT_L(8); PG8_BAR; PG8_WAIT_L(0); PG8_MMA(0, 0, At, B0); PG8_BAR; PG8_SCHED;
	s_waitcnt lgkmcnt(0)
	v_mfma_f32_16x16x32_bf16 v[20:23], v[150:153], v[192:195], v[20:23]
	v_mfma_f32_16x16x32_bf16 v[12:15], v[158:161], v[192:195], v[12:15]
	s_barrier
	s_add_u32 s66, s34, 0x40000
	s_addc_u32 s67, s35, 0
	s_add_i32 s65, s68, s13
	s_mov_b32 m0, s65
	v_lshl_add_u64 v[146:147], s[66:67], 0, v[48:49]
	global_load_lds_dwordx4 v[146:147], off
	s_add_i32 m0, s65, 0x2000
	v_lshl_add_u64 v[146:147], s[66:67], 0, v[130:131]
	global_load_lds_dwordx4 v[146:147], off
	s_waitcnt vmcnt(6)
	s_barrier
	v_mfma_f32_16x16x32_bf16 v[50:53], v[196:199], v[162:165], 0
	v_mfma_f32_16x16x32_bf16 v[40:43], v[204:207], v[162:165], 0
	v_mfma_f32_16x16x32_bf16 v[32:35], v[196:199], v[170:173], 0
	v_mfma_f32_16x16x32_bf16 v[24:27], v[204:207], v[170:173], 0
	v_mfma_f32_16x16x32_bf16 v[16:19], v[196:199], v[180:183], 0
	v_mfma_f32_16x16x32_bf16 v[8:11], v[204:207], v[180:183], 0
	v_mfma_f32_16x16x32_bf16 v[4:7], v[196:199], v[188:191], 0
	v_mfma_f32_16x16x32_bf16 v[0:3], v[204:207], v[188:191], 0
	v_mfma_f32_16x16x32_bf16 v[50:53], v[200:203], v[166:169], v[50:53]
	v_mfma_f32_16x16x32_bf16 v[40:43], v[208:211], v[166:169], v[40:43]
	v_mfma_f32_16x16x32_bf16 v[32:35], v[200:203], v[176:179], v[32:35]
	v_mfma_f32_16x16x32_bf16 v[24:27], v[208:211], v[176:179], v[24:27]
	v_mfma_f32_16x16x32_bf16 v[16:19], v[200:203], v[184:187], v[16:19]
	v_mfma_f32_16x16x32_bf16 v[8:11], v[208:211], v[184:187], v[8:11]
	v_mfma_f32_16x16x32_bf16 v[4:7], v[200:203], v[192:195], v[4:7]
	v_mfma_f32_16x16x32_bf16 v[0:3], v[208:211], v[192:195], v[0:3]
	s_add_i32 s65, 0, 0x18000
	v_add_u32_e32 v158, s65, v143
	s_barrier
	ds_read_b128 v[146:149], v158
	ds_read_b128 v[150:153], v158 offset:1024
	ds_read_b128 v[154:157], v158 offset:2048
	ds_read_b128 v[158:161], v158 offset:3072
	s_add_u32 s36, s36, 0x40000
	s_addc_u32 s37, s37, 0
	s_mov_b32 m0, s47
	v_lshl_add_u64 v[196:197], s[36:37], 0, v[134:135]
	ds_read_b128 v[162:165], v145 offset:32768
	ds_read_b128 v[170:173], v145 offset:34816
	ds_read_b128 v[180:183], v145 offset:36864
	ds_read_b128 v[188:191], v145 offset:38912
	ds_read_b128 v[166:169], v145 offset:33792
	ds_read_b128 v[176:179], v145 offset:35840
	ds_read_b128 v[184:187], v145 offset:37888
	ds_read_b128 v[192:195], v145 offset:39936
	global_load_lds_dwordx4 v[196:197], off
	s_mov_b32 m0, s48
	v_lshl_add_u64 v[196:197], s[36:37], 0, v[132:133]
	global_load_lds_dwordx4 v[196:197], off
	s_waitcnt lgkmcnt(8)
	s_barrier

; #define PG8_MMA(ai, bj, At, Bt) do { __builtin_amdgcn_s_setprio(1); _Pragma("unroll") for (int m = 0; m < 4; ++m) _Pragma("unroll") for (int n = 0; n < 2; ++n) _Pragma("unroll") for (int k = 0; k < 2; ++k) \
;         acc[ai][bj][m][n] = __builtin_amdgcn_mfma_f32_16x16x32_bf16(Bt[n][k], At[m][k], acc[ai][bj][m][n], 0, 0, 0); __builtin_amdgcn_s_setprio(0); } while (0)
; #define PG8_WAIT_L(n) asm volatile("s_waitcnt lgkmcnt(" #n ")" ::: "memory")
; #define PG8_BAR __builtin_amdgcn_s_barrier()
; #define PG8_SCHED __builtin_amdgcn_sched_barrier(0)
; template <class Epi, class Sched>
; __device__ __forceinline__ void gemm_phase(PG8_LAS unsigned char* lds, const Gemm g, const Sched& S, const Epi& E) {
;     ...
;             PG8_WAIT_L(8); PG8_BAR; PG8_WAIT_L(0); PG8_MMA(0, 0, At, B0); PG8_BAR; PG8_SCHED;
	s_waitcnt lgkmcnt(7)
	v_mfma_f32_16x16x32_bf16 v[126:129], v[146:149], v[162:165], v[126:129]
	v_mfma_f32_16x16x32_bf16 v[122:125], v[154:157], v[162:165], v[122:125]

; #define PG8_MMA(ai, bj, At, Bt) do { __builtin_amdgcn_s_setprio(1); _Pragma("unroll") for (int m = 0; m < 4; ++m) _Pragma("unroll") for (int n = 0; n < 2; ++n) _Pragma("unroll") for (int k = 0; k < 2; ++k) \
;         acc[ai][bj][m][n] = __builtin_amdgcn_mfma_f32_16x16x32_bf16(Bt[n][k], At[m][k], acc[ai][bj][m][n], 0, 0, 0); __builtin_amdgcn_s_setprio(0); } while (0)
; #define PG8_WAIT_L(n) asm volatile("s_waitcnt lgkmcnt(" #n ")" ::: "memory")
; #define PG8_BAR __builtin_amdgcn_s_barrier()
; #define PG8_SCHED __builtin_amdgcn_sched_barrier(0)
; template <class Epi, class Sched>
; __device__ __forceinline__ void gemm_phase(PG8_LAS unsigned char* lds, const Gemm g, const Sched& S, const Epi& E) {
;     ...
;             PG8_WAIT_L(8); PG8_BAR; PG8_WAIT_L(0); PG8_MMA(0, 0, At, B0); PG8_BAR; PG8_SCHED;
	s_waitcnt lgkmcnt(6)
	v_mfma_f32_16x16x32_bf16 v[118:121], v[146:149], v[170:173], v[118:121]
	v_mfma_f32_16x16x32_bf16 v[110:113], v[154:157], v[170:173], v[110:113]

; #define PG8_MMA(ai, bj, At, Bt) do { __builtin_amdgcn_s_setprio(1); _Pragma("unroll") for (int m = 0; m < 4; ++m) _Pragma("unroll") for (int n = 0; n < 2; ++n) _Pragma("unroll") for (int k = 0; k < 2; ++k) \
;         acc[ai][bj][m][n] = __builtin_amdgcn_mfma_f32_16x16x32_bf16(Bt[n][k], At[m][k], acc[ai][bj][m][n], 0, 0, 0); __builtin_amdgcn_s_setprio(0); } while (0)
; #define PG8_WAIT_L(n) asm volatile("s_waitcnt lgkmcnt(" #n ")" ::: "memory")
; #define PG8_BAR __builtin_amdgcn_s_barrier()
; #define PG8_SCHED __builtin_amdgcn_sched_barrier(0)
; template <class Epi, class Sched>
; __device__ __forceinline__ void gemm_phase(PG8_LAS unsigned char* lds, const Gemm g, const Sched& S, const Epi& E) {
;     ...
;             PG8_WAIT_L(8); PG8_BAR; PG8_WAIT_L(0); PG8_MMA(0, 0, At, B0); PG8_BAR; PG8_SCHED;
	s_waitcnt lgkmcnt(5)
	v_mfma_f32_16x16x32_bf16 v[102:105], v[146:149], v[180:183], v[102:105]
	v_mfma_f32_16x16x32_bf16 v[94:97], v[154:157], v[180:183], v[94:97]

; #define PG8_MMA(ai, bj, At, Bt) do { __builtin_amdgcn_s_setprio(1); _Pragma("unroll") for (int m = 0; m < 4; ++m) _Pragma("unroll") for (int n = 0; n < 2; ++n) _Pragma("unroll") for (int k = 0; k < 2; ++k) \
;         acc[ai][bj][m][n] = __builtin_amdgcn_mfma_f32_16x16x32_bf16(Bt[n][k], At[m][k], acc[ai][bj][m][n], 0, 0, 0); __builtin_amdgcn_s_setprio(0); } while (0)
; #define PG8_WAIT_L(n) asm volatile("s_waitcnt lgkmcnt(" #n ")" ::: "memory")
; #define PG8_BAR __builtin_amdgcn_s_barrier()
; #define PG8_SCHED __builtin_amdgcn_sched_barrier(0)
; template <class Epi, class Sched>
; __device__ __forceinline__ void gemm_phase(PG8_LAS unsigned char* lds, const Gemm g, const Sched& S, const Epi& E) {
;     ...
;             PG8_WAIT_L(8); PG8_BAR; PG8_WAIT_L(0); PG8_MMA(0, 0, At, B0); PG8_BAR; PG8_SCHED;
	s_waitcnt lgkmcnt(4)
	v_mfma_f32_16x16x32_bf16 v[86:89], v[146:149], v[188:191], v[86:89]
	v_mfma_f32_16x16x32_bf16 v[78:81], v[154:157], v[188:191], v[78:81]
	s_waitcnt lgkmcnt(3)
	v_mfma_f32_16x16x32_bf16 v[126:129], v[150:153], v[166:169], v[126:129]
	v_mfma_f32_16x16x32_bf16 v[122:125], v[158:161], v[166:169], v[122:125]
	s_waitcnt lgkmcnt(2)
	v_mfma_f32_16x16x32_bf16 v[118:121], v[150:153], v[176:179], v[118:121]
	v_mfma_f32_16x16x32_bf16 v[110:113], v[158:161], v[176:179], v[110:113]
	s_waitcnt lgkmcnt(1)
	v_mfma_f32_16x16x32_bf16 v[102:105], v[150:153], v[184:187], v[102:105]
	v_mfma_f32_16x16x32_bf16 v[94:97], v[158:161], v[184:187], v[94:97]

; #define PG8_STAGE(bufoff, gbase, voff) do { _Pragma("unroll") for (int _i = 0; _i < 2; ++_i) \
;         __builtin_amdgcn_global_load_lds((const unsigned*)((const char*)(gbase) + (voff)[_i]), (PG8_LAS unsigned*)(lds + (bufoff) + ldsw + _i * 8192), 16, 0, 0); } while (0)
; #define PG8_LDB(dst, b, h) do { _Pragma("unroll") for (int n = 0; n < 2; ++n) _Pragma("unroll") for (int k = 0; k < 2; ++k) dst[n][k] = *(const PG8_LAS bf16x8*)(lds + PG8_SB(b, h) + boff + n * 2048 + k * 1024); } while (0)
; #define PG8_MMA(ai, bj, At, Bt) do { __builtin_amdgcn_s_setprio(1); _Pragma("unroll") for (int m = 0; m < 4; ++m) _Pragma("unroll") for (int n = 0; n < 2; ++n) _Pragma("unroll") for (int k = 0; k < 2; ++k) \
;         acc[ai][bj][m][n] = __builtin_amdgcn_mfma_f32_16x16x32_bf16(Bt[n][k], At[m][k], acc[ai][bj][m][n], 0, 0, 0); __builtin_amdgcn_s_setprio(0); } while (0)
; #define PG8_WAIT_L(n) asm volatile("s_waitcnt lgkmcnt(" #n ")" ::: "memory")
; #define PG8_BAR __builtin_amdgcn_s_barrier()
; #define PG8_SCHED __builtin_amdgcn_sched_barrier(0)
; template <class Epi, class Sched>
; __device__ __forceinline__ void gemm_phase(PG8_LAS unsigned char* lds, const Gemm g, const Sched& S, const Epi& E) {
;     ...
;             PG8_WAIT_L(8); PG8_BAR; PG8_WAIT_L(0); PG8_MMA(0, 0, At, B0); PG8_BAR; PG8_SCHED;
;             PG8_LDB(B1, 1, 1); PG8_STAGE(PG8_SB(1, 0), b3, voffB);
	s_waitcnt lgkmcnt(0)
	v_mfma_f32_16x16x32_bf16 v[86:89], v[150:153], v[192:195], v[86:89]
	v_mfma_f32_16x16x32_bf16 v[78:81], v[158:161], v[192:195], v[78:81]
	s_barrier
	s_add_i32 s36, 0, 0x1c000
	s_add_i32 s37, s65, s13
	v_add_u32_e32 v175, s36, v143
	v_lshl_add_u64 v[140:141], v[140:141], 0, s[0:1]
	s_mov_b32 m0, s37
	ds_read_b128 v[196:199], v175
	ds_read_b128 v[204:207], v175 offset:2048
	ds_read_b128 v[200:203], v175 offset:1024
	ds_read_b128 v[208:211], v175 offset:3072
	global_load_lds_dwordx4 v[140:141], off
	s_add_i32 m0, s37, 0x2000
	v_lshl_add_u64 v[140:141], v[212:213], 0, s[0:1]
	global_load_lds_dwordx4 v[140:141], off
	s_barrier

; #define PG8_MMA(ai, bj, At, Bt) do { __builtin_amdgcn_s_setprio(1); _Pragma("unroll") for (int m = 0; m < 4; ++m) _Pragma("unroll") for (int n = 0; n < 2; ++n) _Pragma("unroll") for (int k = 0; k < 2; ++k) \
;         acc[ai][bj][m][n] = __builtin_amdgcn_mfma_f32_16x16x32_bf16(Bt[n][k], At[m][k], acc[ai][bj][m][n], 0, 0, 0); __builtin_amdgcn_s_setprio(0); } while (0)
; #define PG8_WAIT_L(n) asm volatile("s_waitcnt lgkmcnt(" #n ")" ::: "memory")
; #define PG8_BAR __builtin_amdgcn_s_barrier()
; template <class Epi, class Sched>
; __device__ __forceinline__ void gemm_phase(PG8_LAS unsigned char* lds, const Gemm g, const Sched& S, const Epi& E) {
;     ...
;             PG8_BAR; PG8_WAIT_L(0); PG8_MMA(0, 1, At, B1); PG8_BAR;
	s_waitcnt lgkmcnt(3)
	v_mfma_f32_16x16x32_bf16 v[114:117], v[196:199], v[162:165], v[114:117]

; #define PG8_MMA(ai, bj, At, Bt) do { __builtin_amdgcn_s_setprio(1); _Pragma("unroll") for (int m = 0; m < 4; ++m) _Pragma("unroll") for (int n = 0; n < 2; ++n) _Pragma("unroll") for (int k = 0; k < 2; ++k) \
;         acc[ai][bj][m][n] = __builtin_amdgcn_mfma_f32_16x16x32_bf16(Bt[n][k], At[m][k], acc[ai][bj][m][n], 0, 0, 0); __builtin_amdgcn_s_setprio(0); } while (0)
; #define PG8_WAIT_L(n) asm volatile("s_waitcnt lgkmcnt(" #n ")" ::: "memory")
; #define PG8_BAR __builtin_amdgcn_s_barrier()
; template <class Epi, class Sched>
; __device__ __forceinline__ void gemm_phase(PG8_LAS unsigned char* lds, const Gemm g, const Sched& S, const Epi& E) {
;     ...
;             PG8_BAR; PG8_WAIT_L(0); PG8_MMA(0, 1, At, B1); PG8_BAR;
	s_waitcnt lgkmcnt(2)
	v_mfma_f32_16x16x32_bf16 v[106:109], v[204:207], v[162:165], v[106:109]
	v_mfma_f32_16x16x32_bf16 v[98:101], v[196:199], v[170:173], v[98:101]
	v_mfma_f32_16x16x32_bf16 v[90:93], v[204:207], v[170:173], v[90:93]
	v_mfma_f32_16x16x32_bf16 v[82:85], v[196:199], v[180:183], v[82:85]
	v_mfma_f32_16x16x32_bf16 v[74:77], v[204:207], v[180:183], v[74:77]
	v_mfma_f32_16x16x32_bf16 v[70:73], v[196:199], v[188:191], v[70:73]
	v_mfma_f32_16x16x32_bf16 v[66:69], v[204:207], v[188:191], v[66:69]
	s_waitcnt lgkmcnt(1)
	v_mfma_f32_16x16x32_bf16 v[114:117], v[200:203], v[166:169], v[114:117]

; #define PG8_STAGE(bufoff, gbase, voff) do { _Pragma("unroll") for (int _i = 0; _i < 2; ++_i) \
;         __builtin_amdgcn_global_load_lds((const unsigned*)((const char*)(gbase) + (voff)[_i]), (PG8_LAS unsigned*)(lds + (bufoff) + ldsw + _i * 8192), 16, 0, 0); } while (0)
; #define PG8_LDA(dst, b, h) do { _Pragma("unroll") for (int m = 0; m < 4; ++m) _Pragma("unroll") for (int k = 0; k < 2; ++k) dst[m][k] = *(const PG8_LAS bf16x8*)(lds + PG8_SA(b, h) + aoff + m * 2048 + k * 1024); } while (0)
; #define PG8_MMA(ai, bj, At, Bt) do { __builtin_amdgcn_s_setprio(1); _Pragma("unroll") for (int m = 0; m < 4; ++m) _Pragma("unroll") for (int n = 0; n < 2; ++n) _Pragma("unroll") for (int k = 0; k < 2; ++k) \
;         acc[ai][bj][m][n] = __builtin_amdgcn_mfma_f32_16x16x32_bf16(Bt[n][k], At[m][k], acc[ai][bj][m][n], 0, 0, 0); __builtin_amdgcn_s_setprio(0); } while (0)
; #define PG8_WAIT_L(n) asm volatile("s_waitcnt lgkmcnt(" #n ")" ::: "memory")
; #define PG8_BAR __builtin_amdgcn_s_barrier()
; template <class Epi, class Sched>
; __device__ __forceinline__ void gemm_phase(PG8_LAS unsigned char* lds, const Gemm g, const Sched& S, const Epi& E) {
;     ...
;             PG8_BAR; PG8_WAIT_L(0); PG8_MMA(0, 1, At, B1); PG8_BAR;
;             PG8_LDA(At, 1, 1); PG8_STAGE(PG8_SA(1, 0), a3, voffA);
	s_waitcnt lgkmcnt(0)
	v_mfma_f32_16x16x32_bf16 v[106:109], v[208:211], v[166:169], v[106:109]
	v_mfma_f32_16x16x32_bf16 v[98:101], v[200:203], v[176:179], v[98:101]
	v_mfma_f32_16x16x32_bf16 v[90:93], v[208:211], v[176:179], v[90:93]
	v_mfma_f32_16x16x32_bf16 v[82:85], v[200:203], v[184:187], v[82:85]
	v_mfma_f32_16x16x32_bf16 v[74:77], v[208:211], v[184:187], v[74:77]
	v_mfma_f32_16x16x32_bf16 v[70:73], v[200:203], v[192:195], v[70:73]
	v_mfma_f32_16x16x32_bf16 v[66:69], v[208:211], v[192:195], v[66:69]
	s_mov_b32 m0, s49
	v_lshl_add_u64 v[140:141], v[214:215], 0, s[0:1]
	s_barrier
	ds_read_b128 v[162:165], v145 offset:49152
	ds_read_b128 v[170:173], v145 offset:51200
	ds_read_b128 v[180:183], v145 offset:53248
	ds_read_b128 v[188:191], v145 offset:55296
	ds_read_b128 v[166:169], v145 offset:50176
	ds_read_b128 v[176:179], v145 offset:52224
	ds_read_b128 v[184:187], v145 offset:54272
	ds_read_b128 v[192:195], v145 offset:56320
	global_load_lds_dwordx4 v[140:141], off
	s_mov_b32 m0, s50
	v_lshl_add_u64 v[140:141], v[216:217], 0, s[0:1]
	global_load_lds_dwordx4 v[140:141], off
	s_barrier

; #define PG8_MMA(ai, bj, At, Bt) do { __builtin_amdgcn_s_setprio(1); _Pragma("unroll") for (int m = 0; m < 4; ++m) _Pragma("unroll") for (int n = 0; n < 2; ++n) _Pragma("unroll") for (int k = 0; k < 2; ++k) \
;         acc[ai][bj][m][n] = __builtin_amdgcn_mfma_f32_16x16x32_bf16(Bt[n][k], At[m][k], acc[ai][bj][m][n], 0, 0, 0); __builtin_amdgcn_s_setprio(0); } while (0)
; #define PG8_WAIT_L(n) asm volatile("s_waitcnt lgkmcnt(" #n ")" ::: "memory")
; #define PG8_BAR __builtin_amdgcn_s_barrier()
; #define PG8_SCHED __builtin_amdgcn_sched_barrier(0)
; template <class Epi, class Sched>
; __device__ __forceinline__ void gemm_phase(PG8_LAS unsigned char* lds, const Gemm g, const Sched& S, const Epi& E) {
;     ...
;             PG8_BAR; PG8_WAIT_L(0); PG8_MMA(1, 0, At, B0); PG8_BAR; PG8_SCHED;
	s_waitcnt lgkmcnt(7)
	v_mfma_f32_16x16x32_bf16 v[62:65], v[146:149], v[162:165], v[62:65]
	v_mfma_f32_16x16x32_bf16 v[58:61], v[154:157], v[162:165], v[58:61]

; #define PG8_MMA(ai, bj, At, Bt) do { __builtin_amdgcn_s_setprio(1); _Pragma("unroll") for (int m = 0; m < 4; ++m) _Pragma("unroll") for (int n = 0; n < 2; ++n) _Pragma("unroll") for (int k = 0; k < 2; ++k) \
;         acc[ai][bj][m][n] = __builtin_amdgcn_mfma_f32_16x16x32_bf16(Bt[n][k], At[m][k], acc[ai][bj][m][n], 0, 0, 0); __builtin_amdgcn_s_setprio(0); } while (0)
; #define PG8_WAIT_L(n) asm volatile("s_waitcnt lgkmcnt(" #n ")" ::: "memory")
; #define PG8_BAR __builtin_amdgcn_s_barrier()
; #define PG8_SCHED __builtin_amdgcn_sched_barrier(0)
; template <class Epi, class Sched>
; __device__ __forceinline__ void gemm_phase(PG8_LAS unsigned char* lds, const Gemm g, const Sched& S, const Epi& E) {
;     ...
;             PG8_BAR; PG8_WAIT_L(0); PG8_MMA(1, 0, At, B0); PG8_BAR; PG8_SCHED;
	s_waitcnt lgkmcnt(6)
	v_mfma_f32_16x16x32_bf16 v[54:57], v[146:149], v[170:173], v[54:57]
	v_mfma_f32_16x16x32_bf16 v[44:47], v[154:157], v[170:173], v[44:47]

; #define PG8_MMA(ai, bj, At, Bt) do { __builtin_amdgcn_s_setprio(1); _Pragma("unroll") for (int m = 0; m < 4; ++m) _Pragma("unroll") for (int n = 0; n < 2; ++n) _Pragma("unroll") for (int k = 0; k < 2; ++k) \
;         acc[ai][bj][m][n] = __builtin_amdgcn_mfma_f32_16x16x32_bf16(Bt[n][k], At[m][k], acc[ai][bj][m][n], 0, 0, 0); __builtin_amdgcn_s_setprio(0); } while (0)
; #define PG8_WAIT_L(n) asm volatile("s_waitcnt lgkmcnt(" #n ")" ::: "memory")
; #define PG8_BAR __builtin_amdgcn_s_barrier()
; #define PG8_SCHED __builtin_amdgcn_sched_barrier(0)
; template <class Epi, class Sched>
; __device__ __forceinline__ void gemm_phase(PG8_LAS unsigned char* lds, const Gemm g, const Sched& S, const Epi& E) {
;     ...
;             PG8_BAR; PG8_WAIT_L(0); PG8_MMA(1, 0, At, B0); PG8_BAR; PG8_SCHED;
	s_waitcnt lgkmcnt(5)
	v_mfma_f32_16x16x32_bf16 v[36:39], v[146:149], v[180:183], v[36:39]
	v_mfma_f32_16x16x32_bf16 v[28:31], v[154:157], v[180:183], v[28:31]

; #define PG8_MMA(ai, bj, At, Bt) do { __builtin_amdgcn_s_setprio(1); _Pragma("unroll") for (int m = 0; m < 4; ++m) _Pragma("unroll") for (int n = 0; n < 2; ++n) _Pragma("unroll") for (int k = 0; k < 2; ++k) \
;         acc[ai][bj][m][n] = __builtin_amdgcn_mfma_f32_16x16x32_bf16(Bt[n][k], At[m][k], acc[ai][bj][m][n], 0, 0, 0); __builtin_amdgcn_s_setprio(0); } while (0)
; #define PG8_WAIT_L(n) asm volatile("s_waitcnt lgkmcnt(" #n ")" ::: "memory")
; #define PG8_BAR __builtin_amdgcn_s_barrier()
; #define PG8_SCHED __builtin_amdgcn_sched_barrier(0)
; template <class Epi, class Sched>
; __device__ __forceinline__ void gemm_phase(PG8_LAS unsigned char* lds, const Gemm g, const Sched& S, const Epi& E) {
;     ...
;             PG8_BAR; PG8_WAIT_L(0); PG8_MMA(1, 0, At, B0); PG8_BAR; PG8_SCHED;
	s_waitcnt lgkmcnt(4)
	v_mfma_f32_16x16x32_bf16 v[20:23], v[146:149], v[188:191], v[20:23]
	v_mfma_f32_16x16x32_bf16 v[12:15], v[154:157], v[188:191], v[12:15]
	s_waitcnt lgkmcnt(3)
	v_mfma_f32_16x16x32_bf16 v[62:65], v[150:153], v[166:169], v[62:65]
	v_mfma_f32_16x16x32_bf16 v[58:61], v[158:161], v[166:169], v[58:61]
	s_waitcnt lgkmcnt(2)
	v_mfma_f32_16x16x32_bf16 v[54:57], v[150:153], v[176:179], v[54:57]
	v_mfma_f32_16x16x32_bf16 v[44:47], v[158:161], v[176:179], v[44:47]
	s_waitcnt lgkmcnt(1)
	v_mfma_f32_16x16x32_bf16 v[36:39], v[150:153], v[184:187], v[36:39]
	v_mfma_f32_16x16x32_bf16 v[28:31], v[158:161], v[184:187], v[28:31]

; #define PG8_STAGE(bufoff, gbase, voff) do { _Pragma("unroll") for (int _i = 0; _i < 2; ++_i) \
;         __builtin_amdgcn_global_load_lds((const unsigned*)((const char*)(gbase) + (voff)[_i]), (PG8_LAS unsigned*)(lds + (bufoff) + ldsw + _i * 8192), 16, 0, 0); } while (0)
; #define PG8_LDA(dst, b, h) do { _Pragma("unroll") for (int m = 0; m < 4; ++m) _Pragma("unroll") for (int k = 0; k < 2; ++k) dst[m][k] = *(const PG8_LAS bf16x8*)(lds + PG8_SA(b, h) + aoff + m * 2048 + k * 1024); } while (0)
; #define PG8_LDB(dst, b, h) do { _Pragma("unroll") for (int n = 0; n < 2; ++n) _Pragma("unroll") for (int k = 0; k < 2; ++k) dst[n][k] = *(const PG8_LAS bf16x8*)(lds + PG8_SB(b, h) + boff + n * 2048 + k * 1024); } while (0)
; #define PG8_MMA(ai, bj, At, Bt) do { __builtin_amdgcn_s_setprio(1); _Pragma("unroll") for (int m = 0; m < 4; ++m) _Pragma("unroll") for (int n = 0; n < 2; ++n) _Pragma("unroll") for (int k = 0; k < 2; ++k) \
;         acc[ai][bj][m][n] = __builtin_amdgcn_mfma_f32_16x16x32_bf16(Bt[n][k], At[m][k], acc[ai][bj][m][n], 0, 0, 0); __builtin_amdgcn_s_setprio(0); } while (0)
; #define PG8_WAIT_V(n) asm volatile("s_waitcnt vmcnt(" #n ")" ::: "memory")
; #define PG8_WAIT_L(n) asm volatile("s_waitcnt lgkmcnt(" #n ")" ::: "memory")
; #define PG8_BAR __builtin_amdgcn_s_barrier()
; #define PG8_SCHED __builtin_amdgcn_sched_barrier(0)
; template <class Epi, class Sched>
; __device__ __forceinline__ void gemm_phase(PG8_LAS unsigned char* lds, const Gemm g, const Sched& S, const Epi& E) {
;     ...
;         for (int t = 0; t < nt; t += 2) {
;             const bool last = (t == nt - 2);
;             const char* a1 = cA + (size_t)(t + 1) * kstep;
;             const char* a2 = last ? nA : cA + (size_t)(t + 2) * kstep; const char* b2 = last ? nB : cB + (size_t)(t + 2) * kstep;
;             const char* a3 = a2 + kstep; const char* b3 = b2 + kstep;
;             if (last && has_next) S.a_ready(nxt);
;             PG8_LDB(B0, 0, 0); PG8_SCHED; PG8_LDA(At, 0, 0); PG8_STAGE(PG8_SA(1, 1), a1 + hstep, voffA);
;             PG8_WAIT_L(8); PG8_BAR; PG8_WAIT_L(0); PG8_MMA(0, 0, At, B0); PG8_BAR; PG8_SCHED;
;     ...
;             PG8_BAR; PG8_WAIT_L(0); PG8_MMA(1, 0, At, B0); PG8_BAR; PG8_SCHED;
;             PG8_STAGE(PG8_SB(1, 1), b3 + hstep, voffB);
;             PG8_WAIT_V(6); PG8_BAR; PG8_MMA(1, 1, At, B1); PG8_BAR;
	s_waitcnt lgkmcnt(0)
	v_mfma_f32_16x16x32_bf16 v[20:23], v[150:153], v[192:195], v[20:23]
	v_mfma_f32_16x16x32_bf16 v[12:15], v[158:161], v[192:195], v[12:15]
	s_barrier
	s_add_u32 s34, s34, 0x40080
	s_addc_u32 s35, s35, 0
	s_add_i32 s36, s36, s13
	s_mov_b32 m0, s36
	v_lshl_add_u64 v[140:141], s[34:35], 0, v[48:49]
	global_load_lds_dwordx4 v[140:141], off
	s_add_i32 m0, s36, 0x2000
	v_lshl_add_u64 v[140:141], s[34:35], 0, v[130:131]
	global_load_lds_dwordx4 v[140:141], off
	s_waitcnt vmcnt(6)
	s_barrier
	v_mfma_f32_16x16x32_bf16 v[50:53], v[196:199], v[162:165], v[50:53]
	v_mfma_f32_16x16x32_bf16 v[40:43], v[204:207], v[162:165], v[40:43]
	v_mfma_f32_16x16x32_bf16 v[32:35], v[196:199], v[170:173], v[32:35]
	v_mfma_f32_16x16x32_bf16 v[24:27], v[204:207], v[170:173], v[24:27]
	v_mfma_f32_16x16x32_bf16 v[16:19], v[196:199], v[180:183], v[16:19]
	v_mfma_f32_16x16x32_bf16 v[8:11], v[204:207], v[180:183], v[8:11]
	v_mfma_f32_16x16x32_bf16 v[4:7], v[196:199], v[188:191], v[4:7]
	v_mfma_f32_16x16x32_bf16 v[0:3], v[204:207], v[188:191], v[0:3]
	v_mfma_f32_16x16x32_bf16 v[50:53], v[200:203], v[166:169], v[50:53]
	v_mfma_f32_16x16x32_bf16 v[40:43], v[208:211], v[166:169], v[40:43]
	v_mfma_f32_16x16x32_bf16 v[32:35], v[200:203], v[176:179], v[32:35]
	v_mfma_f32_16x16x32_bf16 v[24:27], v[208:211], v[176:179], v[24:27]
	v_mfma_f32_16x16x32_bf16 v[16:19], v[200:203], v[184:187], v[16:19]
	v_mfma_f32_16x16x32_bf16 v[8:11], v[208:211], v[184:187], v[8:11]
	v_mfma_f32_16x16x32_bf16 v[4:7], v[200:203], v[192:195], v[4:7]
	v_mfma_f32_16x16x32_bf16 v[0:3], v[208:211], v[192:195], v[0:3]
	s_add_i32 s64, s64, 2
	s_add_u32 s30, s30, 0x100
	s_addc_u32 s31, s31, 0
	s_add_u32 s59, s59, 0x100
	s_addc_u32 s63, s63, 0
	s_cmp_gt_u32 s64, 13
	s_barrier
	s_cbranch_scc1 .Lkpeel_exit_320
.LBB0_320:
	s_add_u32 s34, s30, 0xfffc0080
	s_addc_u32 s35, s31, -1
	s_add_i32 s65, 0, 0x10000
	v_add_u32_e32 v140, s65, v143
	ds_read_b128 v[146:149], v140
	ds_read_b128 v[150:153], v140 offset:1024
	ds_read_b128 v[154:157], v140 offset:2048
	ds_read_b128 v[158:161], v140 offset:3072
	s_cmp_eq_u32 s64, 12
	s_cselect_b32 s37, s25, s35
	s_cselect_b32 s36, s56, s34
	s_cselect_b32 s35, s23, s63
	s_cselect_b32 s34, s57, s59
	v_lshl_add_u64 v[140:141], s[30:31], 0, v[136:137]
	s_add_i32 m0, s21, 0xc000
	ds_read_b128 v[162:165], v145
	ds_read_b128 v[170:173], v145 offset:2048
	ds_read_b128 v[180:183], v145 offset:4096
	ds_read_b128 v[188:191], v145 offset:6144
	ds_read_b128 v[166:169], v145 offset:1024
	ds_read_b128 v[176:179], v145 offset:3072
	ds_read_b128 v[184:187], v145 offset:5120
	ds_read_b128 v[192:195], v145 offset:7168
	global_load_lds_dwordx4 v[140:141], off
	s_add_i32 m0, s21, 0xe000
	v_lshl_add_u64 v[140:141], s[30:31], 0, v[138:139]
	global_load_lds_dwordx4 v[140:141], off
	s_waitcnt lgkmcnt(8)
	s_barrier

; #define PG8_MMA(ai, bj, At, Bt) do { __builtin_amdgcn_s_setprio(1); _Pragma("unroll") for (int m = 0; m < 4; ++m) _Pragma("unroll") for (int n = 0; n < 2; ++n) _Pragma("unroll") for (int k = 0; k < 2; ++k) \
;         acc[ai][bj][m][n] = __builtin_amdgcn_mfma_f32_16x16x32_bf16(Bt[n][k], At[m][k], acc[ai][bj][m][n], 0, 0, 0); __builtin_amdgcn_s_setprio(0); } while (0)
; #define PG8_WAIT_L(n) asm volatile("s_waitcnt lgkmcnt(" #n ")" ::: "memory")
; #define PG8_BAR __builtin_amdgcn_s_barrier()
; #define PG8_SCHED __builtin_amdgcn_sched_barrier(0)
; template <class Epi, class Sched>
; __device__ __forceinline__ void gemm_phase(PG8_LAS unsigned char* lds, const Gemm g, const Sched& S, const Epi& E) {
;     ...
;             PG8_WAIT_L(8); PG8_BAR; PG8_WAIT_L(0); PG8_MMA(0, 0, At, B0); PG8_BAR; PG8_SCHED;
	s_waitcnt lgkmcnt(7)
	v_mfma_f32_16x16x32_bf16 v[126:129], v[146:149], v[162:165], v[126:129]
	v_mfma_f32_16x16x32_bf16 v[122:125], v[154:157], v[162:165], v[122:125]

; #define PG8_MMA(ai, bj, At, Bt) do { __builtin_amdgcn_s_setprio(1); _Pragma("unroll") for (int m = 0; m < 4; ++m) _Pragma("unroll") for (int n = 0; n < 2; ++n) _Pragma("unroll") for (int k = 0; k < 2; ++k) \
;         acc[ai][bj][m][n] = __builtin_amdgcn_mfma_f32_16x16x32_bf16(Bt[n][k], At[m][k], acc[ai][bj][m][n], 0, 0, 0); __builtin_amdgcn_s_setprio(0); } while (0)
; #define PG8_WAIT_L(n) asm volatile("s_waitcnt lgkmcnt(" #n ")" ::: "memory")
; #define PG8_BAR __builtin_amdgcn_s_barrier()
; #define PG8_SCHED __builtin_amdgcn_sched_barrier(0)
; template <class Epi, class Sched>
; __device__ __forceinline__ void gemm_phase(PG8_LAS unsigned char* lds, const Gemm g, const Sched& S, const Epi& E) {
;     ...
;             PG8_WAIT_L(8); PG8_BAR; PG8_WAIT_L(0); PG8_MMA(0, 0, At, B0); PG8_BAR; PG8_SCHED;
	s_waitcnt lgkmcnt(6)
	v_mfma_f32_16x16x32_bf16 v[118:121], v[146:149], v[170:173], v[118:121]
	v_mfma_f32_16x16x32_bf16 v[110:113], v[154:157], v[170:173], v[110:113]

; #define PG8_MMA(ai, bj, At, Bt) do { __builtin_amdgcn_s_setprio(1); _Pragma("unroll") for (int m = 0; m < 4; ++m) _Pragma("unroll") for (int n = 0; n < 2; ++n) _Pragma("unroll") for (int k = 0; k < 2; ++k) \
;         acc[ai][bj][m][n] = __builtin_amdgcn_mfma_f32_16x16x32_bf16(Bt[n][k], At[m][k], acc[ai][bj][m][n], 0, 0, 0); __builtin_amdgcn_s_setprio(0); } while (0)
; #define PG8_WAIT_L(n) asm volatile("s_waitcnt lgkmcnt(" #n ")" ::: "memory")
; #define PG8_BAR __builtin_amdgcn_s_barrier()
; #define PG8_SCHED __builtin_amdgcn_sched_barrier(0)
; template <class Epi, class Sched>
; __device__ __forceinline__ void gemm_phase(PG8_LAS unsigned char* lds, const Gemm g, const Sched& S, const Epi& E) {
;     ...
;             PG8_WAIT_L(8); PG8_BAR; PG8_WAIT_L(0); PG8_MMA(0, 0, At, B0); PG8_BAR; PG8_SCHED;
	s_waitcnt lgkmcnt(5)
	v_mfma_f32_16x16x32_bf16 v[102:105], v[146:149], v[180:183], v[102:105]
	v_mfma_f32_16x16x32_bf16 v[94:97], v[154:157], v[180:183], v[94:97]

; #define PG8_MMA(ai, bj, At, Bt) do { __builtin_amdgcn_s_setprio(1); _Pragma("unroll") for (int m = 0; m < 4; ++m) _Pragma("unroll") for (int n = 0; n < 2; ++n) _Pragma("unroll") for (int k = 0; k < 2; ++k) \
;         acc[ai][bj][m][n] = __builtin_amdgcn_mfma_f32_16x16x32_bf16(Bt[n][k], At[m][k], acc[ai][bj][m][n], 0, 0, 0); __builtin_amdgcn_s_setprio(0); } while (0)
; #define PG8_WAIT_L(n) asm volatile("s_waitcnt lgkmcnt(" #n ")" ::: "memory")
; #define PG8_BAR __builtin_amdgcn_s_barrier()
; #define PG8_SCHED __builtin_amdgcn_sched_barrier(0)
; template <class Epi, class Sched>
; __device__ __forceinline__ void gemm_phase(PG8_LAS unsigned char* lds, const Gemm g, const Sched& S, const Epi& E) {
;     ...
;             PG8_WAIT_L(8); PG8_BAR; PG8_WAIT_L(0); PG8_MMA(0, 0, At, B0); PG8_BAR; PG8_SCHED;
	s_waitcnt lgkmcnt(4)
	v_mfma_f32_16x16x32_bf16 v[86:89], v[146:149], v[188:191], v[86:89]
	v_mfma_f32_16x16x32_bf16 v[78:81], v[154:157], v[188:191], v[78:81]
	s_waitcnt lgkmcnt(3)
	v_mfma_f32_16x16x32_bf16 v[126:129], v[150:153], v[166:169], v[126:129]
	v_mfma_f32_16x16x32_bf16 v[122:125], v[158:161], v[166:169], v[122:125]
	s_waitcnt lgkmcnt(2)
	v_mfma_f32_16x16x32_bf16 v[118:121], v[150:153], v[176:179], v[118:121]
	v_mfma_f32_16x16x32_bf16 v[110:113], v[158:161], v[176:179], v[110:113]
	s_waitcnt lgkmcnt(1)
	v_mfma_f32_16x16x32_bf16 v[102:105], v[150:153], v[184:187], v[102:105]
	v_mfma_f32_16x16x32_bf16 v[94:97], v[158:161], v[184:187], v[94:97]

; #define PG8_STAGE(bufoff, gbase, voff) do { _Pragma("unroll") for (int _i = 0; _i < 2; ++_i) \
;         __builtin_amdgcn_global_load_lds((const unsigned*)((const char*)(gbase) + (voff)[_i]), (PG8_LAS unsigned*)(lds + (bufoff) + ldsw + _i * 8192), 16, 0, 0); } while (0)
; #define PG8_LDB(dst, b, h) do { _Pragma("unroll") for (int n = 0; n < 2; ++n) _Pragma("unroll") for (int k = 0; k < 2; ++k) dst[n][k] = *(const PG8_LAS bf16x8*)(lds + PG8_SB(b, h) + boff + n * 2048 + k * 1024); } while (0)
; #define PG8_MMA(ai, bj, At, Bt) do { __builtin_amdgcn_s_setprio(1); _Pragma("unroll") for (int m = 0; m < 4; ++m) _Pragma("unroll") for (int n = 0; n < 2; ++n) _Pragma("unroll") for (int k = 0; k < 2; ++k) \
;         acc[ai][bj][m][n] = __builtin_amdgcn_mfma_f32_16x16x32_bf16(Bt[n][k], At[m][k], acc[ai][bj][m][n], 0, 0, 0); __builtin_amdgcn_s_setprio(0); } while (0)
; #define PG8_WAIT_L(n) asm volatile("s_waitcnt lgkmcnt(" #n ")" ::: "memory")
; #define PG8_BAR __builtin_amdgcn_s_barrier()
; #define PG8_SCHED __builtin_amdgcn_sched_barrier(0)
; template <class Epi, class Sched>
; __device__ __forceinline__ void gemm_phase(PG8_LAS unsigned char* lds, const Gemm g, const Sched& S, const Epi& E) {
;     ...
;             PG8_WAIT_L(8); PG8_BAR; PG8_WAIT_L(0); PG8_MMA(0, 0, At, B0); PG8_BAR; PG8_SCHED;
;             PG8_LDB(B1, 0, 1); PG8_STAGE(PG8_SB(0, 0), b2, voffB);
	s_waitcnt lgkmcnt(0)
	v_mfma_f32_16x16x32_bf16 v[86:89], v[150:153], v[192:195], v[86:89]
	v_mfma_f32_16x16x32_bf16 v[78:81], v[158:161], v[192:195], v[78:81]
	s_barrier
	s_add_i32 s68, 0, 0x14000
	v_add_u32_e32 v140, s68, v143
	s_add_i32 s65, s65, s13
	ds_read_b128 v[196:199], v140
	ds_read_b128 v[204:207], v140 offset:2048
	ds_read_b128 v[200:203], v140 offset:1024
	ds_read_b128 v[208:211], v140 offset:3072
	v_lshl_add_u64 v[140:141], s[34:35], 0, v[48:49]
	s_mov_b32 m0, s65
	v_lshl_add_u64 v[212:213], s[34:35], 0, v[130:131]
	global_load_lds_dwordx4 v[140:141], off
	s_add_i32 m0, s65, 0x2000
	s_nop 0
	global_load_lds_dwordx4 v[212:213], off
	s_barrier

; #define PG8_MMA(ai, bj, At, Bt) do { __builtin_amdgcn_s_setprio(1); _Pragma("unroll") for (int m = 0; m < 4; ++m) _Pragma("unroll") for (int n = 0; n < 2; ++n) _Pragma("unroll") for (int k = 0; k < 2; ++k) \
;         acc[ai][bj][m][n] = __builtin_amdgcn_mfma_f32_16x16x32_bf16(Bt[n][k], At[m][k], acc[ai][bj][m][n], 0, 0, 0); __builtin_amdgcn_s_setprio(0); } while (0)
; #define PG8_WAIT_L(n) asm volatile("s_waitcnt lgkmcnt(" #n ")" ::: "memory")
; #define PG8_BAR __builtin_amdgcn_s_barrier()
; template <class Epi, class Sched>
; __device__ __forceinline__ void gemm_phase(PG8_LAS unsigned char* lds, const Gemm g, const Sched& S, const Epi& E) {
;     ...
;             PG8_BAR; PG8_WAIT_L(0); PG8_MMA(0, 1, At, B1); PG8_BAR;
	s_waitcnt lgkmcnt(3)
	v_mfma_f32_16x16x32_bf16 v[114:117], v[196:199], v[162:165], v[114:117]

; #define PG8_MMA(ai, bj, At, Bt) do { __builtin_amdgcn_s_setprio(1); _Pragma("unroll") for (int m = 0; m < 4; ++m) _Pragma("unroll") for (int n = 0; n < 2; ++n) _Pragma("unroll") for (int k = 0; k < 2; ++k) \
;         acc[ai][bj][m][n] = __builtin_amdgcn_mfma_f32_16x16x32_bf16(Bt[n][k], At[m][k], acc[ai][bj][m][n], 0, 0, 0); __builtin_amdgcn_s_setprio(0); } while (0)
; #define PG8_WAIT_L(n) asm volatile("s_waitcnt lgkmcnt(" #n ")" ::: "memory")
; #define PG8_BAR __builtin_amdgcn_s_barrier()
; template <class Epi, class Sched>
; __device__ __forceinline__ void gemm_phase(PG8_LAS unsigned char* lds, const Gemm g, const Sched& S, const Epi& E) {
;     ...
;             PG8_BAR; PG8_WAIT_L(0); PG8_MMA(0, 1, At, B1); PG8_BAR;
	s_waitcnt lgkmcnt(2)
	v_mfma_f32_16x16x32_bf16 v[106:109], v[204:207], v[162:165], v[106:109]
	v_mfma_f32_16x16x32_bf16 v[98:101], v[196:199], v[170:173], v[98:101]
	v_mfma_f32_16x16x32_bf16 v[90:93], v[204:207], v[170:173], v[90:93]
	v_mfma_f32_16x16x32_bf16 v[82:85], v[196:199], v[180:183], v[82:85]
	v_mfma_f32_16x16x32_bf16 v[74:77], v[204:207], v[180:183], v[74:77]
	v_mfma_f32_16x16x32_bf16 v[70:73], v[196:199], v[188:191], v[70:73]
	v_mfma_f32_16x16x32_bf16 v[66:69], v[204:207], v[188:191], v[66:69]
	s_waitcnt lgkmcnt(1)
	v_mfma_f32_16x16x32_bf16 v[114:117], v[200:203], v[166:169], v[114:117]

; #define PG8_STAGE(bufoff, gbase, voff) do { _Pragma("unroll") for (int _i = 0; _i < 2; ++_i) \
;         __builtin_amdgcn_global_load_lds((const unsigned*)((const char*)(gbase) + (voff)[_i]), (PG8_LAS unsigned*)(lds + (bufoff) + ldsw + _i * 8192), 16, 0, 0); } while (0)
; #define PG8_LDA(dst, b, h) do { _Pragma("unroll") for (int m = 0; m < 4; ++m) _Pragma("unroll") for (int k = 0; k < 2; ++k) dst[m][k] = *(const PG8_LAS bf16x8*)(lds + PG8_SA(b, h) + aoff + m * 2048 + k * 1024); } while (0)
; #define PG8_MMA(ai, bj, At, Bt) do { __builtin_amdgcn_s_setprio(1); _Pragma("unroll") for (int m = 0; m < 4; ++m) _Pragma("unroll") for (int n = 0; n < 2; ++n) _Pragma("unroll") for (int k = 0; k < 2; ++k) \
;         acc[ai][bj][m][n] = __builtin_amdgcn_mfma_f32_16x16x32_bf16(Bt[n][k], At[m][k], acc[ai][bj][m][n], 0, 0, 0); __builtin_amdgcn_s_setprio(0); } while (0)
; #define PG8_WAIT_L(n) asm volatile("s_waitcnt lgkmcnt(" #n ")" ::: "memory")
; #define PG8_BAR __builtin_amdgcn_s_barrier()
; template <class Epi, class Sched>
; __device__ __forceinline__ void gemm_phase(PG8_LAS unsigned char* lds, const Gemm g, const Sched& S, const Epi& E) {
;     ...
;             PG8_BAR; PG8_WAIT_L(0); PG8_MMA(0, 1, At, B1); PG8_BAR;
;             PG8_LDA(At, 0, 1); PG8_STAGE(PG8_SA(0, 0), a2, voffA);
	s_waitcnt lgkmcnt(0)
	v_mfma_f32_16x16x32_bf16 v[106:109], v[208:211], v[166:169], v[106:109]
	v_mfma_f32_16x16x32_bf16 v[98:101], v[200:203], v[176:179], v[98:101]
	v_mfma_f32_16x16x32_bf16 v[90:93], v[208:211], v[176:179], v[90:93]
	v_mfma_f32_16x16x32_bf16 v[82:85], v[200:203], v[184:187], v[82:85]
	v_mfma_f32_16x16x32_bf16 v[74:77], v[208:211], v[184:187], v[74:77]
	v_mfma_f32_16x16x32_bf16 v[70:73], v[200:203], v[192:195], v[70:73]
	v_mfma_f32_16x16x32_bf16 v[66:69], v[208:211], v[192:195], v[66:69]
	s_mov_b32 m0, s21
	v_lshl_add_u64 v[214:215], s[36:37], 0, v[134:135]
	s_barrier
	ds_read_b128 v[162:165], v145 offset:16384
	ds_read_b128 v[170:173], v145 offset:18432
	ds_read_b128 v[180:183], v145 offset:20480
	ds_read_b128 v[188:191], v145 offset:22528
	ds_read_b128 v[166:169], v145 offset:17408
	ds_read_b128 v[176:179], v145 offset:19456
	ds_read_b128 v[184:187], v145 offset:21504
	ds_read_b128 v[192:195], v145 offset:23552
	global_load_lds_dwordx4 v[214:215], off
	s_mov_b32 m0, s46
	v_lshl_add_u64 v[216:217], s[36:37], 0, v[132:133]
	global_load_lds_dwordx4 v[216:217], off
	s_barrier

; #define PG8_MMA(ai, bj, At, Bt) do { __builtin_amdgcn_s_setprio(1); _Pragma("unroll") for (int m = 0; m < 4; ++m) _Pragma("unroll") for (int n = 0; n < 2; ++n) _Pragma("unroll") for (int k = 0; k < 2; ++k) \
;         acc[ai][bj][m][n] = __builtin_amdgcn_mfma_f32_16x16x32_bf16(Bt[n][k], At[m][k], acc[ai][bj][m][n], 0, 0, 0); __builtin_amdgcn_s_setprio(0); } while (0)
; #define PG8_WAIT_L(n) asm volatile("s_waitcnt lgkmcnt(" #n ")" ::: "memory")
; #define PG8_BAR __builtin_amdgcn_s_barrier()
; #define PG8_SCHED __builtin_amdgcn_sched_barrier(0)
; template <class Epi, class Sched>
; __device__ __forceinline__ void gemm_phase(PG8_LAS unsigned char* lds, const Gemm g, const Sched& S, const Epi& E) {
;     ...
;             PG8_BAR; PG8_WAIT_L(0); PG8_MMA(1, 0, At, B0); PG8_BAR; PG8_SCHED;
	s_waitcnt lgkmcnt(7)
	v_mfma_f32_16x16x32_bf16 v[62:65], v[146:149], v[162:165], v[62:65]
	v_mfma_f32_16x16x32_bf16 v[58:61], v[154:157], v[162:165], v[58:61]

; #define PG8_MMA(ai, bj, At, Bt) do { __builtin_amdgcn_s_setprio(1); _Pragma("unroll") for (int m = 0; m < 4; ++m) _Pragma("unroll") for (int n = 0; n < 2; ++n) _Pragma("unroll") for (int k = 0; k < 2; ++k) \
;         acc[ai][bj][m][n] = __builtin_amdgcn_mfma_f32_16x16x32_bf16(Bt[n][k], At[m][k], acc[ai][bj][m][n], 0, 0, 0); __builtin_amdgcn_s_setprio(0); } while (0)
; #define PG8_WAIT_L(n) asm volatile("s_waitcnt lgkmcnt(" #n ")" ::: "memory")
; #define PG8_BAR __builtin_amdgcn_s_barrier()
; #define PG8_SCHED __builtin_amdgcn_sched_barrier(0)
; template <class Epi, class Sched>
; __device__ __forceinline__ void gemm_phase(PG8_LAS unsigned char* lds, const Gemm g, const Sched& S, const Epi& E) {
;     ...
;             PG8_BAR; PG8_WAIT_L(0); PG8_MMA(1, 0, At, B0); PG8_BAR; PG8_SCHED;
	s_waitcnt lgkmcnt(6)
	v_mfma_f32_16x16x32_bf16 v[54:57], v[146:149], v[170:173], v[54:57]
	v_mfma_f32_16x16x32_bf16 v[44:47], v[154:157], v[170:173], v[44:47]

; #define PG8_MMA(ai, bj, At, Bt) do { __builtin_amdgcn_s_setprio(1); _Pragma("unroll") for (int m = 0; m < 4; ++m) _Pragma("unroll") for (int n = 0; n < 2; ++n) _Pragma("unroll") for (int k = 0; k < 2; ++k) \
;         acc[ai][bj][m][n] = __builtin_amdgcn_mfma_f32_16x16x32_bf16(Bt[n][k], At[m][k], acc[ai][bj][m][n], 0, 0, 0); __builtin_amdgcn_s_setprio(0); } while (0)
; #define PG8_WAIT_L(n) asm volatile("s_waitcnt lgkmcnt(" #n ")" ::: "memory")
; #define PG8_BAR __builtin_amdgcn_s_barrier()
; #define PG8_SCHED __builtin_amdgcn_sched_barrier(0)
; template <class Epi, class Sched>
; __device__ __forceinline__ void gemm_phase(PG8_LAS unsigned char* lds, const Gemm g, const Sched& S, const Epi& E) {
;     ...
;             PG8_BAR; PG8_WAIT_L(0); PG8_MMA(1, 0, At, B0); PG8_BAR; PG8_SCHED;
	s_waitcnt lgkmcnt(5)
	v_mfma_f32_16x16x32_bf16 v[36:39], v[146:149], v[180:183], v[36:39]
	v_mfma_f32_16x16x32_bf16 v[28:31], v[154:157], v[180:183], v[28:31]

; #define PG8_MMA(ai, bj, At, Bt) do { __builtin_amdgcn_s_setprio(1); _Pragma("unroll") for (int m = 0; m < 4; ++m) _Pragma("unroll") for (int n = 0; n < 2; ++n) _Pragma("unroll") for (int k = 0; k < 2; ++k) \
;         acc[ai][bj][m][n] = __builtin_amdgcn_mfma_f32_16x16x32_bf16(Bt[n][k], At[m][k], acc[ai][bj][m][n], 0, 0, 0); __builtin_amdgcn_s_setprio(0); } while (0)
; #define PG8_WAIT_L(n) asm volatile("s_waitcnt lgkmcnt(" #n ")" ::: "memory")
; #define PG8_BAR __builtin_amdgcn_s_barrier()
; #define PG8_SCHED __builtin_amdgcn_sched_barrier(0)
; template <class Epi, class Sched>
; __device__ __forceinline__ void gemm_phase(PG8_LAS unsigned char* lds, const Gemm g, const Sched& S, const Epi& E) {
;     ...
;             PG8_BAR; PG8_WAIT_L(0); PG8_MMA(1, 0, At, B0); PG8_BAR; PG8_SCHED;
	s_waitcnt lgkmcnt(4)
	v_mfma_f32_16x16x32_bf16 v[20:23], v[146:149], v[188:191], v[20:23]
	v_mfma_f32_16x16x32_bf16 v[12:15], v[154:157], v[188:191], v[12:15]
	s_waitcnt lgkmcnt(3)
	v_mfma_f32_16x16x32_bf16 v[62:65], v[150:153], v[166:169], v[62:65]
	v_mfma_f32_16x16x32_bf16 v[58:61], v[158:161], v[166:169], v[58:61]
	s_waitcnt lgkmcnt(2)
	v_mfma_f32_16x16x32_bf16 v[54:57], v[150:153], v[176:179], v[54:57]
	v_mfma_f32_16x16x32_bf16 v[44:47], v[158:161], v[176:179], v[44:47]
	s_waitcnt lgkmcnt(1)
	v_mfma_f32_16x16x32_bf16 v[36:39], v[150:153], v[184:187], v[36:39]
	v_mfma_f32_16x16x32_bf16 v[28:31], v[158:161], v[184:187], v[28:31]

; #define PG8_STAGE(bufoff, gbase, voff) do { _Pragma("unroll") for (int _i = 0; _i < 2; ++_i) \
;         __builtin_amdgcn_global_load_lds((const unsigned*)((const char*)(gbase) + (voff)[_i]), (PG8_LAS unsigned*)(lds + (bufoff) + ldsw + _i * 8192), 16, 0, 0); } while (0)
; #define PG8_LDA(dst, b, h) do { _Pragma("unroll") for (int m = 0; m < 4; ++m) _Pragma("unroll") for (int k = 0; k < 2; ++k) dst[m][k] = *(const PG8_LAS bf16x8*)(lds + PG8_SA(b, h) + aoff + m * 2048 + k * 1024); } while (0)
; #define PG8_LDB(dst, b, h) do { _Pragma("unroll") for (int n = 0; n < 2; ++n) _Pragma("unroll") for (int k = 0; k < 2; ++k) dst[n][k] = *(const PG8_LAS bf16x8*)(lds + PG8_SB(b, h) + boff + n * 2048 + k * 1024); } while (0)
; #define PG8_MMA(ai, bj, At, Bt) do { __builtin_amdgcn_s_setprio(1); _Pragma("unroll") for (int m = 0; m < 4; ++m) _Pragma("unroll") for (int n = 0; n < 2; ++n) _Pragma("unroll") for (int k = 0; k < 2; ++k) \
;         acc[ai][bj][m][n] = __builtin_amdgcn_mfma_f32_16x16x32_bf16(Bt[n][k], At[m][k], acc[ai][bj][m][n], 0, 0, 0); __builtin_amdgcn_s_setprio(0); } while (0)
; #define PG8_WAIT_V(n) asm volatile("s_waitcnt vmcnt(" #n ")" ::: "memory")
; #define PG8_WAIT_L(n) asm volatile("s_waitcnt lgkmcnt(" #n ")" ::: "memory")
; #define PG8_BAR __builtin_amdgcn_s_barrier()
; #define PG8_SCHED __builtin_amdgcn_sched_barrier(0)
; template <class Epi, class Sched>
; __device__ __forceinline__ void gemm_phase(PG8_LAS unsigned char* lds, const Gemm g, const Sched& S, const Epi& E) {
;     ...
;             PG8_BAR; PG8_WAIT_L(0); PG8_MMA(1, 0, At, B0); PG8_BAR; PG8_SCHED;
;             PG8_STAGE(PG8_SB(0, 1), b2 + hstep, voffB);
;             PG8_WAIT_V(6); PG8_BAR; PG8_MMA(1, 1, At, B1); PG8_BAR;
;             PG8_LDB(B0, 1, 0); PG8_SCHED; PG8_LDA(At, 1, 0); PG8_STAGE(PG8_SA(0, 1), a2 + hstep, voffA);
;             PG8_WAIT_L(8); PG8_BAR; PG8_WAIT_L(0); PG8_MMA(0, 0, At, B0); PG8_BAR; PG8_SCHED;
	s_waitcnt lgkmcnt(0)
	v_mfma_f32_16x16x32_bf16 v[20:23], v[150:153], v[192:195], v[20:23]
	v_mfma_f32_16x16x32_bf16 v[12:15], v[158:161], v[192:195], v[12:15]
	s_barrier
	s_add_u32 s66, s34, 0x40000
	s_addc_u32 s67, s35, 0
	s_add_i32 s65, s68, s13
	s_mov_b32 m0, s65
	v_lshl_add_u64 v[146:147], s[66:67], 0, v[48:49]
	global_load_lds_dwordx4 v[146:147], off
	s_add_i32 m0, s65, 0x2000
	v_lshl_add_u64 v[146:147], s[66:67], 0, v[130:131]
	global_load_lds_dwordx4 v[146:147], off
	s_waitcnt vmcnt(6)
	s_barrier
	v_mfma_f32_16x16x32_bf16 v[50:53], v[196:199], v[162:165], v[50:53]
	v_mfma_f32_16x16x32_bf16 v[40:43], v[204:207], v[162:165], v[40:43]
	v_mfma_f32_16x16x32_bf16 v[32:35], v[196:199], v[170:173], v[32:35]
	v_mfma_f32_16x16x32_bf16 v[24:27], v[204:207], v[170:173], v[24:27]
	v_mfma_f32_16x16x32_bf16 v[16:19], v[196:199], v[180:183], v[16:19]
	v_mfma_f32_16x16x32_bf16 v[8:11], v[204:207], v[180:183], v[8:11]
	v_mfma_f32_16x16x32_bf16 v[4:7], v[196:199], v[188:191], v[4:7]
	v_mfma_f32_16x16x32_bf16 v[0:3], v[204:207], v[188:191], v[0:3]
	v_mfma_f32_16x16x32_bf16 v[50:53], v[200:203], v[166:169], v[50:53]
	v_mfma_f32_16x16x32_bf16 v[40:43], v[208:211], v[166:169], v[40:43]
	v_mfma_f32_16x16x32_bf16 v[32:35], v[200:203], v[176:179], v[32:35]
	v_mfma_f32_16x16x32_bf16 v[24:27], v[208:211], v[176:179], v[24:27]
	v_mfma_f32_16x16x32_bf16 v[16:19], v[200:203], v[184:187], v[16:19]
	v_mfma_f32_16x16x32_bf16 v[8:11], v[208:211], v[184:187], v[8:11]
	v_mfma_f32_16x16x32_bf16 v[4:7], v[200:203], v[192:195], v[4:7]
	v_mfma_f32_16x16x32_bf16 v[0:3], v[208:211], v[192:195], v[0:3]
	s_add_i32 s65, 0, 0x18000
	v_add_u32_e32 v158, s65, v143
	s_barrier
	ds_read_b128 v[146:149], v158
	ds_read_b128 v[150:153], v158 offset:1024
	ds_read_b128 v[154:157], v158 offset:2048
	ds_read_b128 v[158:161], v158 offset:3072
	s_add_u32 s36, s36, 0x40000
	s_addc_u32 s37, s37, 0
	s_mov_b32 m0, s47
	v_lshl_add_u64 v[196:197], s[36:37], 0, v[134:135]
	ds_read_b128 v[162:165], v145 offset:32768
	ds_read_b128 v[170:173], v145 offset:34816
	ds_read_b128 v[180:183], v145 offset:36864
	ds_read_b128 v[188:191], v145 offset:38912
	ds_read_b128 v[166:169], v145 offset:33792
	ds_read_b128 v[176:179], v145 offset:35840
	ds_read_b128 v[184:187], v145 offset:37888
	ds_read_b128 v[192:195], v145 offset:39936
	global_load_lds_dwordx4 v[196:197], off
	s_mov_b32 m0, s48
	v_lshl_add_u64 v[196:197], s[36:37], 0, v[132:133]
	global_load_lds_dwordx4 v[196:197], off
	s_waitcnt lgkmcnt(8)
	s_barrier

; #define PG8_MMA(ai, bj, At, Bt) do { __builtin_amdgcn_s_setprio(1); _Pragma("unroll") for (int m = 0; m < 4; ++m) _Pragma("unroll") for (int n = 0; n < 2; ++n) _Pragma("unroll") for (int k = 0; k < 2; ++k) \
;         acc[ai][bj][m][n] = __builtin_amdgcn_mfma_f32_16x16x32_bf16(Bt[n][k], At[m][k], acc[ai][bj][m][n], 0, 0, 0); __builtin_amdgcn_s_setprio(0); } while (0)
; #define PG8_WAIT_L(n) asm volatile("s_waitcnt lgkmcnt(" #n ")" ::: "memory")
; #define PG8_BAR __builtin_amdgcn_s_barrier()
; #define PG8_SCHED __builtin_amdgcn_sched_barrier(0)
; template <class Epi, class Sched>
; __device__ __forceinline__ void gemm_phase(PG8_LAS unsigned char* lds, const Gemm g, const Sched& S, const Epi& E) {
;     ...
;             PG8_WAIT_L(8); PG8_BAR; PG8_WAIT_L(0); PG8_MMA(0, 0, At, B0); PG8_BAR; PG8_SCHED;
	s_waitcnt lgkmcnt(7)
	v_mfma_f32_16x16x32_bf16 v[126:129], v[146:149], v[162:165], v[126:129]
	v_mfma_f32_16x16x32_bf16 v[122:125], v[154:157], v[162:165], v[122:125]

; #define PG8_MMA(ai, bj, At, Bt) do { __builtin_amdgcn_s_setprio(1); _Pragma("unroll") for (int m = 0; m < 4; ++m) _Pragma("unroll") for (int n = 0; n < 2; ++n) _Pragma("unroll") for (int k = 0; k < 2; ++k) \
;         acc[ai][bj][m][n] = __builtin_amdgcn_mfma_f32_16x16x32_bf16(Bt[n][k], At[m][k], acc[ai][bj][m][n], 0, 0, 0); __builtin_amdgcn_s_setprio(0); } while (0)
; #define PG8_WAIT_L(n) asm volatile("s_waitcnt lgkmcnt(" #n ")" ::: "memory")
; #define PG8_BAR __builtin_amdgcn_s_barrier()
; #define PG8_SCHED __builtin_amdgcn_sched_barrier(0)
; template <class Epi, class Sched>
; __device__ __forceinline__ void gemm_phase(PG8_LAS unsigned char* lds, const Gemm g, const Sched& S, const Epi& E) {
;     ...
;             PG8_WAIT_L(8); PG8_BAR; PG8_WAIT_L(0); PG8_MMA(0, 0, At, B0); PG8_BAR; PG8_SCHED;
	s_waitcnt lgkmcnt(6)
	v_mfma_f32_16x16x32_bf16 v[118:121], v[146:149], v[170:173], v[118:121]
	v_mfma_f32_16x16x32_bf16 v[110:113], v[154:157], v[170:173], v[110:113]

; #define PG8_MMA(ai, bj, At, Bt) do { __builtin_amdgcn_s_setprio(1); _Pragma("unroll") for (int m = 0; m < 4; ++m) _Pragma("unroll") for (int n = 0; n < 2; ++n) _Pragma("unroll") for (int k = 0; k < 2; ++k) \
;         acc[ai][bj][m][n] = __builtin_amdgcn_mfma_f32_16x16x32_bf16(Bt[n][k], At[m][k], acc[ai][bj][m][n], 0, 0, 0); __builtin_amdgcn_s_setprio(0); } while (0)
; #define PG8_WAIT_L(n) asm volatile("s_waitcnt lgkmcnt(" #n ")" ::: "memory")
; #define PG8_BAR __builtin_amdgcn_s_barrier()
; #define PG8_SCHED __builtin_amdgcn_sched_barrier(0)
; template <class Epi, class Sched>
; __device__ __forceinline__ void gemm_phase(PG8_LAS unsigned char* lds, const Gemm g, const Sched& S, const Epi& E) {
;     ...
;             PG8_WAIT_L(8); PG8_BAR; PG8_WAIT_L(0); PG8_MMA(0, 0, At, B0); PG8_BAR; PG8_SCHED;
	s_waitcnt lgkmcnt(5)
	v_mfma_f32_16x16x32_bf16 v[102:105], v[146:149], v[180:183], v[102:105]
	v_mfma_f32_16x16x32_bf16 v[94:97], v[154:157], v[180:183], v[94:97]

; #define PG8_MMA(ai, bj, At, Bt) do { __builtin_amdgcn_s_setprio(1); _Pragma("unroll") for (int m = 0; m < 4; ++m) _Pragma("unroll") for (int n = 0; n < 2; ++n) _Pragma("unroll") for (int k = 0; k < 2; ++k) \
;         acc[ai][bj][m][n] = __builtin_amdgcn_mfma_f32_16x16x32_bf16(Bt[n][k], At[m][k], acc[ai][bj][m][n], 0, 0, 0); __builtin_amdgcn_s_setprio(0); } while (0)
; #define PG8_WAIT_L(n) asm volatile("s_waitcnt lgkmcnt(" #n ")" ::: "memory")
; #define PG8_BAR __builtin_amdgcn_s_barrier()
; #define PG8_SCHED __builtin_amdgcn_sched_barrier(0)
; template <class Epi, class Sched>
; __device__ __forceinline__ void gemm_phase(PG8_LAS unsigned char* lds, const Gemm g, const Sched& S, const Epi& E) {
;     ...
;             PG8_WAIT_L(8); PG8_BAR; PG8_WAIT_L(0); PG8_MMA(0, 0, At, B0); PG8_BAR; PG8_SCHED;
	s_waitcnt lgkmcnt(4)
	v_mfma_f32_16x16x32_bf16 v[86:89], v[146:149], v[188:191], v[86:89]
	v_mfma_f32_16x16x32_bf16 v[78:81], v[154:157], v[188:191], v[78:81]
	s_waitcnt lgkmcnt(3)
	v_mfma_f32_16x16x32_bf16 v[126:129], v[150:153], v[166:169], v[126:129]
	v_mfma_f32_16x16x32_bf16 v[122:125], v[158:161], v[166:169], v[122:125]
	s_waitcnt lgkmcnt(2)
	v_mfma_f32_16x16x32_bf16 v[118:121], v[150:153], v[176:179], v[118:121]
	v_mfma_f32_16x16x32_bf16 v[110:113], v[158:161], v[176:179], v[110:113]
	s_waitcnt lgkmcnt(1)
	v_mfma_f32_16x16x32_bf16 v[102:105], v[150:153], v[184:187], v[102:105]
	v_mfma_f32_16x16x32_bf16 v[94:97], v[158:161], v[184:187], v[94:97]

; #define PG8_STAGE(bufoff, gbase, voff) do { _Pragma("unroll") for (int _i = 0; _i < 2; ++_i) \
;         __builtin_amdgcn_global_load_lds((const unsigned*)((const char*)(gbase) + (voff)[_i]), (PG8_LAS unsigned*)(lds + (bufoff) + ldsw + _i * 8192), 16, 0, 0); } while (0)
; #define PG8_LDB(dst, b, h) do { _Pragma("unroll") for (int n = 0; n < 2; ++n) _Pragma("unroll") for (int k = 0; k < 2; ++k) dst[n][k] = *(const PG8_LAS bf16x8*)(lds + PG8_SB(b, h) + boff + n * 2048 + k * 1024); } while (0)
; #define PG8_MMA(ai, bj, At, Bt) do { __builtin_amdgcn_s_setprio(1); _Pragma("unroll") for (int m = 0; m < 4; ++m) _Pragma("unroll") for (int n = 0; n < 2; ++n) _Pragma("unroll") for (int k = 0; k < 2; ++k) \
;         acc[ai][bj][m][n] = __builtin_amdgcn_mfma_f32_16x16x32_bf16(Bt[n][k], At[m][k], acc[ai][bj][m][n], 0, 0, 0); __builtin_amdgcn_s_setprio(0); } while (0)
; #define PG8_WAIT_L(n) asm volatile("s_waitcnt lgkmcnt(" #n ")" ::: "memory")
; #define PG8_BAR __builtin_amdgcn_s_barrier()
; #define PG8_SCHED __builtin_amdgcn_sched_barrier(0)
; template <class Epi, class Sched>
; __device__ __forceinline__ void gemm_phase(PG8_LAS unsigned char* lds, const Gemm g, const Sched& S, const Epi& E) {
;     ...
;             PG8_WAIT_L(8); PG8_BAR; PG8_WAIT_L(0); PG8_MMA(0, 0, At, B0); PG8_BAR; PG8_SCHED;
;             PG8_LDB(B1, 1, 1); PG8_STAGE(PG8_SB(1, 0), b3, voffB);
	s_waitcnt lgkmcnt(0)
	v_mfma_f32_16x16x32_bf16 v[86:89], v[150:153], v[192:195], v[86:89]
	v_mfma_f32_16x16x32_bf16 v[78:81], v[158:161], v[192:195], v[78:81]
	s_barrier
	s_add_i32 s36, 0, 0x1c000
	s_add_i32 s37, s65, s13
	v_add_u32_e32 v175, s36, v143
	v_lshl_add_u64 v[140:141], v[140:141], 0, s[0:1]
	s_mov_b32 m0, s37
	ds_read_b128 v[196:199], v175
	ds_read_b128 v[204:207], v175 offset:2048
	ds_read_b128 v[200:203], v175 offset:1024
	ds_read_b128 v[208:211], v175 offset:3072
	global_load_lds_dwordx4 v[140:141], off
	s_add_i32 m0, s37, 0x2000
	v_lshl_add_u64 v[140:141], v[212:213], 0, s[0:1]
	global_load_lds_dwordx4 v[140:141], off
	s_barrier

; #define PG8_MMA(ai, bj, At, Bt) do { __builtin_amdgcn_s_setprio(1); _Pragma("unroll") for (int m = 0; m < 4; ++m) _Pragma("unroll") for (int n = 0; n < 2; ++n) _Pragma("unroll") for (int k = 0; k < 2; ++k) \
;         acc[ai][bj][m][n] = __builtin_amdgcn_mfma_f32_16x16x32_bf16(Bt[n][k], At[m][k], acc[ai][bj][m][n], 0, 0, 0); __builtin_amdgcn_s_setprio(0); } while (0)
; #define PG8_WAIT_L(n) asm volatile("s_waitcnt lgkmcnt(" #n ")" ::: "memory")
; #define PG8_BAR __builtin_amdgcn_s_barrier()
; template <class Epi, class Sched>
; __device__ __forceinline__ void gemm_phase(PG8_LAS unsigned char* lds, const Gemm g, const Sched& S, const Epi& E) {
;     ...
;             PG8_BAR; PG8_WAIT_L(0); PG8_MMA(0, 1, At, B1); PG8_BAR;
	s_waitcnt lgkmcnt(3)
	v_mfma_f32_16x16x32_bf16 v[114:117], v[196:199], v[162:165], v[114:117]

; #define PG8_MMA(ai, bj, At, Bt) do { __builtin_amdgcn_s_setprio(1); _Pragma("unroll") for (int m = 0; m < 4; ++m) _Pragma("unroll") for (int n = 0; n < 2; ++n) _Pragma("unroll") for (int k = 0; k < 2; ++k) \
;         acc[ai][bj][m][n] = __builtin_amdgcn_mfma_f32_16x16x32_bf16(Bt[n][k], At[m][k], acc[ai][bj][m][n], 0, 0, 0); __builtin_amdgcn_s_setprio(0); } while (0)
; #define PG8_WAIT_L(n) asm volatile("s_waitcnt lgkmcnt(" #n ")" ::: "memory")
; #define PG8_BAR __builtin_amdgcn_s_barrier()
; template <class Epi, class Sched>
; __device__ __forceinline__ void gemm_phase(PG8_LAS unsigned char* lds, const Gemm g, const Sched& S, const Epi& E) {
;     ...
;             PG8_BAR; PG8_WAIT_L(0); PG8_MMA(0, 1, At, B1); PG8_BAR;
	s_waitcnt lgkmcnt(2)
	v_mfma_f32_16x16x32_bf16 v[106:109], v[204:207], v[162:165], v[106:109]
	v_mfma_f32_16x16x32_bf16 v[98:101], v[196:199], v[170:173], v[98:101]
	v_mfma_f32_16x16x32_bf16 v[90:93], v[204:207], v[170:173], v[90:93]
	v_mfma_f32_16x16x32_bf16 v[82:85], v[196:199], v[180:183], v[82:85]
	v_mfma_f32_16x16x32_bf16 v[74:77], v[204:207], v[180:183], v[74:77]
	v_mfma_f32_16x16x32_bf16 v[70:73], v[196:199], v[188:191], v[70:73]
	v_mfma_f32_16x16x32_bf16 v[66:69], v[204:207], v[188:191], v[66:69]
	s_waitcnt lgkmcnt(1)
	v_mfma_f32_16x16x32_bf16 v[114:117], v[200:203], v[166:169], v[114:117]

; #define PG8_STAGE(bufoff, gbase, voff) do { _Pragma("unroll") for (int _i = 0; _i < 2; ++_i) \
;         __builtin_amdgcn_global_load_lds((const unsigned*)((const char*)(gbase) + (voff)[_i]), (PG8_LAS unsigned*)(lds + (bufoff) + ldsw + _i * 8192), 16, 0, 0); } while (0)
; #define PG8_LDA(dst, b, h) do { _Pragma("unroll") for (int m = 0; m < 4; ++m) _Pragma("unroll") for (int k = 0; k < 2; ++k) dst[m][k] = *(const PG8_LAS bf16x8*)(lds + PG8_SA(b, h) + aoff + m * 2048 + k * 1024); } while (0)
; #define PG8_MMA(ai, bj, At, Bt) do { __builtin_amdgcn_s_setprio(1); _Pragma("unroll") for (int m = 0; m < 4; ++m) _Pragma("unroll") for (int n = 0; n < 2; ++n) _Pragma("unroll") for (int k = 0; k < 2; ++k) \
;         acc[ai][bj][m][n] = __builtin_amdgcn_mfma_f32_16x16x32_bf16(Bt[n][k], At[m][k], acc[ai][bj][m][n], 0, 0, 0); __builtin_amdgcn_s_setprio(0); } while (0)
; #define PG8_WAIT_L(n) asm volatile("s_waitcnt lgkmcnt(" #n ")" ::: "memory")
; #define PG8_BAR __builtin_amdgcn_s_barrier()
; template <class Epi, class Sched>
; __device__ __forceinline__ void gemm_phase(PG8_LAS unsigned char* lds, const Gemm g, const Sched& S, const Epi& E) {
;     ...
;             PG8_BAR; PG8_WAIT_L(0); PG8_MMA(0, 1, At, B1); PG8_BAR;
;             PG8_LDA(At, 1, 1); PG8_STAGE(PG8_SA(1, 0), a3, voffA);
	s_waitcnt lgkmcnt(0)
	v_mfma_f32_16x16x32_bf16 v[106:109], v[208:211], v[166:169], v[106:109]
	v_mfma_f32_16x16x32_bf16 v[98:101], v[200:203], v[176:179], v[98:101]
	v_mfma_f32_16x16x32_bf16 v[90:93], v[208:211], v[176:179], v[90:93]
	v_mfma_f32_16x16x32_bf16 v[82:85], v[200:203], v[184:187], v[82:85]
	v_mfma_f32_16x16x32_bf16 v[74:77], v[208:211], v[184:187], v[74:77]
	v_mfma_f32_16x16x32_bf16 v[70:73], v[200:203], v[192:195], v[70:73]
	v_mfma_f32_16x16x32_bf16 v[66:69], v[208:211], v[192:195], v[66:69]
	s_mov_b32 m0, s49
	v_lshl_add_u64 v[140:141], v[214:215], 0, s[0:1]
	s_barrier
	ds_read_b128 v[162:165], v145 offset:49152
	ds_read_b128 v[170:173], v145 offset:51200
	ds_read_b128 v[180:183], v145 offset:53248
	ds_read_b128 v[188:191], v145 offset:55296
	ds_read_b128 v[166:169], v145 offset:50176
	ds_read_b128 v[176:179], v145 offset:52224
	ds_read_b128 v[184:187], v145 offset:54272
	ds_read_b128 v[192:195], v145 offset:56320
	global_load_lds_dwordx4 v[140:141], off
	s_mov_b32 m0, s50
	v_lshl_add_u64 v[140:141], v[216:217], 0, s[0:1]
	global_load_lds_dwordx4 v[140:141], off
	s_barrier

; #define PG8_MMA(ai, bj, At, Bt) do { __builtin_amdgcn_s_setprio(1); _Pragma("unroll") for (int m = 0; m < 4; ++m) _Pragma("unroll") for (int n = 0; n < 2; ++n) _Pragma("unroll") for (int k = 0; k < 2; ++k) \
;         acc[ai][bj][m][n] = __builtin_amdgcn_mfma_f32_16x16x32_bf16(Bt[n][k], At[m][k], acc[ai][bj][m][n], 0, 0, 0); __builtin_amdgcn_s_setprio(0); } while (0)
; #define PG8_WAIT_L(n) asm volatile("s_waitcnt lgkmcnt(" #n ")" ::: "memory")
; #define PG8_BAR __builtin_amdgcn_s_barrier()
; #define PG8_SCHED __builtin_amdgcn_sched_barrier(0)
; template <class Epi, class Sched>
; __device__ __forceinline__ void gemm_phase(PG8_LAS unsigned char* lds, const Gemm g, const Sched& S, const Epi& E) {
;     ...
;             PG8_BAR; PG8_WAIT_L(0); PG8_MMA(1, 0, At, B0); PG8_BAR; PG8_SCHED;
	s_waitcnt lgkmcnt(7)
	v_mfma_f32_16x16x32_bf16 v[62:65], v[146:149], v[162:165], v[62:65]
	v_mfma_f32_16x16x32_bf16 v[58:61], v[154:157], v[162:165], v[58:61]

; #define PG8_MMA(ai, bj, At, Bt) do { __builtin_amdgcn_s_setprio(1); _Pragma("unroll") for (int m = 0; m < 4; ++m) _Pragma("unroll") for (int n = 0; n < 2; ++n) _Pragma("unroll") for (int k = 0; k < 2; ++k) \
;         acc[ai][bj][m][n] = __builtin_amdgcn_mfma_f32_16x16x32_bf16(Bt[n][k], At[m][k], acc[ai][bj][m][n], 0, 0, 0); __builtin_amdgcn_s_setprio(0); } while (0)
; #define PG8_WAIT_L(n) asm volatile("s_waitcnt lgkmcnt(" #n ")" ::: "memory")
; #define PG8_BAR __builtin_amdgcn_s_barrier()
; #define PG8_SCHED __builtin_amdgcn_sched_barrier(0)
; template <class Epi, class Sched>
; __device__ __forceinline__ void gemm_phase(PG8_LAS unsigned char* lds, const Gemm g, const Sched& S, const Epi& E) {
;     ...
;             PG8_BAR; PG8_WAIT_L(0); PG8_MMA(1, 0, At, B0); PG8_BAR; PG8_SCHED;
	s_waitcnt lgkmcnt(6)
	v_mfma_f32_16x16x32_bf16 v[54:57], v[146:149], v[170:173], v[54:57]
	v_mfma_f32_16x16x32_bf16 v[44:47], v[154:157], v[170:173], v[44:47]

; #define PG8_MMA(ai, bj, At, Bt) do { __builtin_amdgcn_s_setprio(1); _Pragma("unroll") for (int m = 0; m < 4; ++m) _Pragma("unroll") for (int n = 0; n < 2; ++n) _Pragma("unroll") for (int k = 0; k < 2; ++k) \
;         acc[ai][bj][m][n] = __builtin_amdgcn_mfma_f32_16x16x32_bf16(Bt[n][k], At[m][k], acc[ai][bj][m][n], 0, 0, 0); __builtin_amdgcn_s_setprio(0); } while (0)
; #define PG8_WAIT_L(n) asm volatile("s_waitcnt lgkmcnt(" #n ")" ::: "memory")
; #define PG8_BAR __builtin_amdgcn_s_barrier()
; #define PG8_SCHED __builtin_amdgcn_sched_barrier(0)
; template <class Epi, class Sched>
; __device__ __forceinline__ void gemm_phase(PG8_LAS unsigned char* lds, const Gemm g, const Sched& S, const Epi& E) {
;     ...
;             PG8_BAR; PG8_WAIT_L(0); PG8_MMA(1, 0, At, B0); PG8_BAR; PG8_SCHED;
	s_waitcnt lgkmcnt(5)
	v_mfma_f32_16x16x32_bf16 v[36:39], v[146:149], v[180:183], v[36:39]
	v_mfma_f32_16x16x32_bf16 v[28:31], v[154:157], v[180:183], v[28:31]

; #define PG8_MMA(ai, bj, At, Bt) do { __builtin_amdgcn_s_setprio(1); _Pragma("unroll") for (int m = 0; m < 4; ++m) _Pragma("unroll") for (int n = 0; n < 2; ++n) _Pragma("unroll") for (int k = 0; k < 2; ++k) \
;         acc[ai][bj][m][n] = __builtin_amdgcn_mfma_f32_16x16x32_bf16(Bt[n][k], At[m][k], acc[ai][bj][m][n], 0, 0, 0); __builtin_amdgcn_s_setprio(0); } while (0)
; #define PG8_WAIT_L(n) asm volatile("s_waitcnt lgkmcnt(" #n ")" ::: "memory")
; #define PG8_BAR __builtin_amdgcn_s_barrier()
; #define PG8_SCHED __builtin_amdgcn_sched_barrier(0)
; template <class Epi, class Sched>
; __device__ __forceinline__ void gemm_phase(PG8_LAS unsigned char* lds, const Gemm g, const Sched& S, const Epi& E) {
;     ...
;             PG8_BAR; PG8_WAIT_L(0); PG8_MMA(1, 0, At, B0); PG8_BAR; PG8_SCHED;
	s_waitcnt lgkmcnt(4)
	v_mfma_f32_16x16x32_bf16 v[20:23], v[146:149], v[188:191], v[20:23]
	v_mfma_f32_16x16x32_bf16 v[12:15], v[154:157], v[188:191], v[12:15]
	s_waitcnt lgkmcnt(3)
	v_mfma_f32_16x16x32_bf16 v[62:65], v[150:153], v[166:169], v[62:65]
	v_mfma_f32_16x16x32_bf16 v[58:61], v[158:161], v[166:169], v[58:61]
	s_waitcnt lgkmcnt(2)
	v_mfma_f32_16x16x32_bf16 v[54:57], v[150:153], v[176:179], v[54:57]
	v_mfma_f32_16x16x32_bf16 v[44:47], v[158:161], v[176:179], v[44:47]
	s_waitcnt lgkmcnt(1)
	v_mfma_f32_16x16x32_bf16 v[36:39], v[150:153], v[184:187], v[36:39]
	v_mfma_f32_16x16x32_bf16 v[28:31], v[158:161], v[184:187], v[28:31]

; #define PG8_STAGE(bufoff, gbase, voff) do { _Pragma("unroll") for (int _i = 0; _i < 2; ++_i) \
;         __builtin_amdgcn_global_load_lds((const unsigned*)((const char*)(gbase) + (voff)[_i]), (PG8_LAS unsigned*)(lds + (bufoff) + ldsw + _i * 8192), 16, 0, 0); } while (0)
; #define PG8_MMA(ai, bj, At, Bt) do { __builtin_amdgcn_s_setprio(1); _Pragma("unroll") for (int m = 0; m < 4; ++m) _Pragma("unroll") for (int n = 0; n < 2; ++n) _Pragma("unroll") for (int k = 0; k < 2; ++k) \
;         acc[ai][bj][m][n] = __builtin_amdgcn_mfma_f32_16x16x32_bf16(Bt[n][k], At[m][k], acc[ai][bj][m][n], 0, 0, 0); __builtin_amdgcn_s_setprio(0); } while (0)
; #define PG8_WAIT_V(n) asm volatile("s_waitcnt vmcnt(" #n ")" ::: "memory")
; #define PG8_WAIT_L(n) asm volatile("s_waitcnt lgkmcnt(" #n ")" ::: "memory")
; #define PG8_BAR __builtin_amdgcn_s_barrier()
; #define PG8_SCHED __builtin_amdgcn_sched_barrier(0)
; template <class Epi, class Sched>
; __device__ __forceinline__ void gemm_phase(PG8_LAS unsigned char* lds, const Gemm g, const Sched& S, const Epi& E) {
;     ...
;             PG8_BAR; PG8_WAIT_L(0); PG8_MMA(1, 0, At, B0); PG8_BAR; PG8_SCHED;
;             PG8_STAGE(PG8_SB(1, 1), b3 + hstep, voffB);
;             PG8_WAIT_V(6); PG8_BAR; PG8_MMA(1, 1, At, B1); PG8_BAR;
	s_waitcnt lgkmcnt(0)
	v_mfma_f32_16x16x32_bf16 v[20:23], v[150:153], v[192:195], v[20:23]
	v_mfma_f32_16x16x32_bf16 v[12:15], v[158:161], v[192:195], v[12:15]
	s_barrier
	s_add_u32 s34, s34, 0x40080
	s_addc_u32 s35, s35, 0
	s_add_i32 s36, s36, s13
	s_mov_b32 m0, s36
	v_lshl_add_u64 v[140:141], s[34:35], 0, v[48:49]
	global_load_lds_dwordx4 v[140:141], off
	s_add_i32 m0, s36, 0x2000
	v_lshl_add_u64 v[140:141], s[34:35], 0, v[130:131]
	global_load_lds_dwordx4 v[140:141], off
	s_waitcnt vmcnt(6)
	s_barrier
	v_mfma_f32_16x16x32_bf16 v[50:53], v[196:199], v[162:165], v[50:53]
	v_mfma_f32_16x16x32_bf16 v[40:43], v[204:207], v[162:165], v[40:43]
	v_mfma_f32_16x16x32_bf16 v[32:35], v[196:199], v[170:173], v[32:35]
	v_mfma_f32_16x16x32_bf16 v[24:27], v[204:207], v[170:173], v[24:27]
	v_mfma_f32_16x16x32_bf16 v[16:19], v[196:199], v[180:183], v[16:19]
	v_mfma_f32_16x16x32_bf16 v[8:11], v[204:207], v[180:183], v[8:11]
	v_mfma_f32_16x16x32_bf16 v[4:7], v[196:199], v[188:191], v[4:7]
	v_mfma_f32_16x16x32_bf16 v[0:3], v[204:207], v[188:191], v[0:3]
	v_mfma_f32_16x16x32_bf16 v[50:53], v[200:203], v[166:169], v[50:53]
	v_mfma_f32_16x16x32_bf16 v[40:43], v[208:211], v[166:169], v[40:43]
	v_mfma_f32_16x16x32_bf16 v[32:35], v[200:203], v[176:179], v[32:35]
	v_mfma_f32_16x16x32_bf16 v[24:27], v[208:211], v[176:179], v[24:27]
	v_mfma_f32_16x16x32_bf16 v[16:19], v[200:203], v[184:187], v[16:19]
	v_mfma_f32_16x16x32_bf16 v[8:11], v[208:211], v[184:187], v[8:11]
	v_mfma_f32_16x16x32_bf16 v[4:7], v[200:203], v[192:195], v[4:7]
	v_mfma_f32_16x16x32_bf16 v[0:3], v[208:211], v[192:195], v[0:3]
	s_add_i32 s64, s64, 2
	s_add_u32 s30, s30, 0x100
	s_addc_u32 s31, s31, 0
	s_add_u32 s59, s59, 0x100
	s_addc_u32 s63, s63, 0
	s_cmp_gt_u32 s64, 13
	s_barrier
	s_cbranch_scc0 .LBB0_320

; #define PG8_STAGE(bufoff, gbase, voff) do { _Pragma("unroll") for (int _i = 0; _i < 2; ++_i) \
;         __builtin_amdgcn_global_load_lds((const unsigned*)((const char*)(gbase) + (voff)[_i]), (PG8_LAS unsigned*)(lds + (bufoff) + ldsw + _i * 8192), 16, 0, 0); } while (0)
; #define PG8_LDA(dst, b, h) do { _Pragma("unroll") for (int m = 0; m < 4; ++m) _Pragma("unroll") for (int k = 0; k < 2; ++k) dst[m][k] = *(const PG8_LAS bf16x8*)(lds + PG8_SA(b, h) + aoff + m * 2048 + k * 1024); } while (0)
; #define PG8_LDB(dst, b, h) do { _Pragma("unroll") for (int n = 0; n < 2; ++n) _Pragma("unroll") for (int k = 0; k < 2; ++k) dst[n][k] = *(const PG8_LAS bf16x8*)(lds + PG8_SB(b, h) + boff + n * 2048 + k * 1024); } while (0)
; #define PG8_MMA(ai, bj, At, Bt) do { __builtin_amdgcn_s_setprio(1); _Pragma("unroll") for (int m = 0; m < 4; ++m) _Pragma("unroll") for (int n = 0; n < 2; ++n) _Pragma("unroll") for (int k = 0; k < 2; ++k) \
;         acc[ai][bj][m][n] = __builtin_amdgcn_mfma_f32_16x16x32_bf16(Bt[n][k], At[m][k], acc[ai][bj][m][n], 0, 0, 0); __builtin_amdgcn_s_setprio(0); } while (0)
; #define PG8_WAIT_L(n) asm volatile("s_waitcnt lgkmcnt(" #n ")" ::: "memory")
; #define PG8_BAR __builtin_amdgcn_s_barrier()
; #define PG8_SCHED __builtin_amdgcn_sched_barrier(0)
; template <class Epi, class Sched>
; __device__ __forceinline__ void gemm_phase(PG8_LAS unsigned char* lds, const Gemm g, const Sched& S, const Epi& E) {
;     ...
;         const bool has_next = S.next(ui + 1, nxt);
;         const char* nA = has_next ? (const char*)g.A + (size_t)nxt.pm * tstepA + (size_t)nxt.kc * cstep : cA; const char* nB = has_next ? (const char*)g.Bt + (size_t)nxt.pn * tstep + (size_t)nxt.kc * cstep : cB;
;         for (int t = 0; t < nt; t += 2) {
;             const bool last = (t == nt - 2);
;             const char* a1 = cA + (size_t)(t + 1) * kstep;
;             const char* a2 = last ? nA : cA + (size_t)(t + 2) * kstep; const char* b2 = last ? nB : cB + (size_t)(t + 2) * kstep;
;             const char* a3 = a2 + kstep; const char* b3 = b2 + kstep;
;             if (last && has_next) S.a_ready(nxt);
;             PG8_LDB(B0, 0, 0); PG8_SCHED; PG8_LDA(At, 0, 0); PG8_STAGE(PG8_SA(1, 1), a1 + hstep, voffA);
;             PG8_WAIT_L(8); PG8_BAR; PG8_WAIT_L(0); PG8_MMA(0, 0, At, B0); PG8_BAR; PG8_SCHED;
.LBB0_334:
	v_mov_b64_e32 v[0:1], 0x440
	s_ashr_i32 s23, s22, 31
	v_cmp_lt_i64_e32 vcc, s[16:17], v[0:1]
	s_lshl_b64 s[16:17], s[22:23], 19
	s_add_u32 s24, s28, s16
	s_addc_u32 s25, s29, s17
	s_and_b64 s[16:17], vcc, exec
	s_cselect_b32 s23, s25, s7
	s_cselect_b32 s50, s24, s6
	s_ashr_i32 s21, s20, 31
	s_lshl_b64 s[16:17], s[20:21], 19
	s_add_u32 s26, s30, s16
	s_addc_u32 s27, s31, s17
	s_and_b64 s[16:17], vcc, exec
	s_cselect_b32 s21, s27, s13
	s_cselect_b32 s51, s26, s12
	s_add_u32 s6, s6, 0x40080
	s_addc_u32 s7, s7, 0
	s_add_u32 s54, s12, 0x100
	s_addc_u32 s55, s13, 0
	s_mov_b32 s56, -2
	s_add_u32 s12, s6, 0xfffc0080
	s_addc_u32 s13, s7, -1
	s_add_i32 s57, 0, 0x10000
	v_add_u32_e32 v48, s57, v166
	ds_read_b128 v[144:147], v48
	ds_read_b128 v[148:151], v48 offset:1024
	ds_read_b128 v[152:155], v48 offset:2048
	ds_read_b128 v[156:159], v48 offset:3072
	s_cmp_eq_u32 s56, 12
	s_cselect_b32 s17, s23, s13
	s_cselect_b32 s16, s50, s12
	s_cselect_b32 s13, s21, s55
	s_cselect_b32 s12, s51, s54
	v_lshl_add_u64 v[164:165], s[6:7], 0, v[140:141]
	s_add_i32 m0, s3, 0xc000
	ds_read_b128 v[160:163], v167
	ds_read_b128 v[176:179], v167 offset:2048
	ds_read_b128 v[184:187], v167 offset:4096
	ds_read_b128 v[192:195], v167 offset:6144
	ds_read_b128 v[168:171], v167 offset:1024
	ds_read_b128 v[180:183], v167 offset:3072
	ds_read_b128 v[188:191], v167 offset:5120
	ds_read_b128 v[196:199], v167 offset:7168
	global_load_lds_dwordx4 v[164:165], off
	s_add_i32 m0, s3, 0xe000
	v_lshl_add_u64 v[164:165], s[6:7], 0, v[142:143]
	global_load_lds_dwordx4 v[164:165], off
	s_waitcnt lgkmcnt(8)
	s_barrier

; #define PG8_MMA(ai, bj, At, Bt) do { __builtin_amdgcn_s_setprio(1); _Pragma("unroll") for (int m = 0; m < 4; ++m) _Pragma("unroll") for (int n = 0; n < 2; ++n) _Pragma("unroll") for (int k = 0; k < 2; ++k) \
;         acc[ai][bj][m][n] = __builtin_amdgcn_mfma_f32_16x16x32_bf16(Bt[n][k], At[m][k], acc[ai][bj][m][n], 0, 0, 0); __builtin_amdgcn_s_setprio(0); } while (0)
; #define PG8_WAIT_L(n) asm volatile("s_waitcnt lgkmcnt(" #n ")" ::: "memory")
; #define PG8_BAR __builtin_amdgcn_s_barrier()
; #define PG8_SCHED __builtin_amdgcn_sched_barrier(0)
; template <class Epi, class Sched>
; __device__ __forceinline__ void gemm_phase(PG8_LAS unsigned char* lds, const Gemm g, const Sched& S, const Epi& E) {
;     ...
;             PG8_WAIT_L(8); PG8_BAR; PG8_WAIT_L(0); PG8_MMA(0, 0, At, B0); PG8_BAR; PG8_SCHED;
	s_waitcnt lgkmcnt(7)
	v_mfma_f32_16x16x32_bf16 v[126:129], v[144:147], v[160:163], 0
	v_mfma_f32_16x16x32_bf16 v[122:125], v[152:155], v[160:163], 0

; #define PG8_MMA(ai, bj, At, Bt) do { __builtin_amdgcn_s_setprio(1); _Pragma("unroll") for (int m = 0; m < 4; ++m) _Pragma("unroll") for (int n = 0; n < 2; ++n) _Pragma("unroll") for (int k = 0; k < 2; ++k) \
;         acc[ai][bj][m][n] = __builtin_amdgcn_mfma_f32_16x16x32_bf16(Bt[n][k], At[m][k], acc[ai][bj][m][n], 0, 0, 0); __builtin_amdgcn_s_setprio(0); } while (0)
; #define PG8_WAIT_L(n) asm volatile("s_waitcnt lgkmcnt(" #n ")" ::: "memory")
; #define PG8_BAR __builtin_amdgcn_s_barrier()
; #define PG8_SCHED __builtin_amdgcn_sched_barrier(0)
; template <class Epi, class Sched>
; __device__ __forceinline__ void gemm_phase(PG8_LAS unsigned char* lds, const Gemm g, const Sched& S, const Epi& E) {
;     ...
;             PG8_WAIT_L(8); PG8_BAR; PG8_WAIT_L(0); PG8_MMA(0, 0, At, B0); PG8_BAR; PG8_SCHED;
	s_waitcnt lgkmcnt(6)
	v_mfma_f32_16x16x32_bf16 v[110:113], v[144:147], v[176:179], 0
	v_mfma_f32_16x16x32_bf16 v[106:109], v[152:155], v[176:179], 0

; #define PG8_MMA(ai, bj, At, Bt) do { __builtin_amdgcn_s_setprio(1); _Pragma("unroll") for (int m = 0; m < 4; ++m) _Pragma("unroll") for (int n = 0; n < 2; ++n) _Pragma("unroll") for (int k = 0; k < 2; ++k) \
;         acc[ai][bj][m][n] = __builtin_amdgcn_mfma_f32_16x16x32_bf16(Bt[n][k], At[m][k], acc[ai][bj][m][n], 0, 0, 0); __builtin_amdgcn_s_setprio(0); } while (0)
; #define PG8_WAIT_L(n) asm volatile("s_waitcnt lgkmcnt(" #n ")" ::: "memory")
; #define PG8_BAR __builtin_amdgcn_s_barrier()
; #define PG8_SCHED __builtin_amdgcn_sched_barrier(0)
; template <class Epi, class Sched>
; __device__ __forceinline__ void gemm_phase(PG8_LAS unsigned char* lds, const Gemm g, const Sched& S, const Epi& E) {
;     ...
;             PG8_WAIT_L(8); PG8_BAR; PG8_WAIT_L(0); PG8_MMA(0, 0, At, B0); PG8_BAR; PG8_SCHED;
	s_waitcnt lgkmcnt(5)
	v_mfma_f32_16x16x32_bf16 v[94:97], v[144:147], v[184:187], 0
	v_mfma_f32_16x16x32_bf16 v[90:93], v[152:155], v[184:187], 0

; #define PG8_MMA(ai, bj, At, Bt) do { __builtin_amdgcn_s_setprio(1); _Pragma("unroll") for (int m = 0; m < 4; ++m) _Pragma("unroll") for (int n = 0; n < 2; ++n) _Pragma("unroll") for (int k = 0; k < 2; ++k) \
;         acc[ai][bj][m][n] = __builtin_amdgcn_mfma_f32_16x16x32_bf16(Bt[n][k], At[m][k], acc[ai][bj][m][n], 0, 0, 0); __builtin_amdgcn_s_setprio(0); } while (0)
; #define PG8_WAIT_L(n) asm volatile("s_waitcnt lgkmcnt(" #n ")" ::: "memory")
; #define PG8_BAR __builtin_amdgcn_s_barrier()
; #define PG8_SCHED __builtin_amdgcn_sched_barrier(0)
; template <class Epi, class Sched>
; __device__ __forceinline__ void gemm_phase(PG8_LAS unsigned char* lds, const Gemm g, const Sched& S, const Epi& E) {
;     ...
;             PG8_WAIT_L(8); PG8_BAR; PG8_WAIT_L(0); PG8_MMA(0, 0, At, B0); PG8_BAR; PG8_SCHED;
	s_waitcnt lgkmcnt(4)
	v_mfma_f32_16x16x32_bf16 v[78:81], v[144:147], v[192:195], 0
	v_mfma_f32_16x16x32_bf16 v[74:77], v[152:155], v[192:195], 0
	s_waitcnt lgkmcnt(3)
	v_mfma_f32_16x16x32_bf16 v[126:129], v[148:151], v[168:171], v[126:129]
	v_mfma_f32_16x16x32_bf16 v[122:125], v[156:159], v[168:171], v[122:125]
	s_waitcnt lgkmcnt(2)
	v_mfma_f32_16x16x32_bf16 v[110:113], v[148:151], v[180:183], v[110:113]
	v_mfma_f32_16x16x32_bf16 v[106:109], v[156:159], v[180:183], v[106:109]
	s_waitcnt lgkmcnt(1)
	v_mfma_f32_16x16x32_bf16 v[94:97], v[148:151], v[188:191], v[94:97]
	v_mfma_f32_16x16x32_bf16 v[90:93], v[156:159], v[188:191], v[90:93]

; #define PG8_STAGE(bufoff, gbase, voff) do { _Pragma("unroll") for (int _i = 0; _i < 2; ++_i) \
;         __builtin_amdgcn_global_load_lds((const unsigned*)((const char*)(gbase) + (voff)[_i]), (PG8_LAS unsigned*)(lds + (bufoff) + ldsw + _i * 8192), 16, 0, 0); } while (0)
; #define PG8_LDB(dst, b, h) do { _Pragma("unroll") for (int n = 0; n < 2; ++n) _Pragma("unroll") for (int k = 0; k < 2; ++k) dst[n][k] = *(const PG8_LAS bf16x8*)(lds + PG8_SB(b, h) + boff + n * 2048 + k * 1024); } while (0)
; #define PG8_MMA(ai, bj, At, Bt) do { __builtin_amdgcn_s_setprio(1); _Pragma("unroll") for (int m = 0; m < 4; ++m) _Pragma("unroll") for (int n = 0; n < 2; ++n) _Pragma("unroll") for (int k = 0; k < 2; ++k) \
;         acc[ai][bj][m][n] = __builtin_amdgcn_mfma_f32_16x16x32_bf16(Bt[n][k], At[m][k], acc[ai][bj][m][n], 0, 0, 0); __builtin_amdgcn_s_setprio(0); } while (0)
; #define PG8_WAIT_L(n) asm volatile("s_waitcnt lgkmcnt(" #n ")" ::: "memory")
; #define PG8_BAR __builtin_amdgcn_s_barrier()
; #define PG8_SCHED __builtin_amdgcn_sched_barrier(0)
; template <class Epi, class Sched>
; __device__ __forceinline__ void gemm_phase(PG8_LAS unsigned char* lds, const Gemm g, const Sched& S, const Epi& E) {
;     ...
;             PG8_WAIT_L(8); PG8_BAR; PG8_WAIT_L(0); PG8_MMA(0, 0, At, B0); PG8_BAR; PG8_SCHED;
;             PG8_LDB(B1, 0, 1); PG8_STAGE(PG8_SB(0, 0), b2, voffB);
	s_waitcnt lgkmcnt(0)
	v_mfma_f32_16x16x32_bf16 v[78:81], v[148:151], v[196:199], v[78:81]
	v_mfma_f32_16x16x32_bf16 v[74:77], v[156:159], v[196:199], v[74:77]
	s_barrier
	s_add_i32 s59, 0, 0x14000
	s_add_i32 s57, s57, s34
	v_add_u32_e32 v48, s59, v166
	v_lshl_add_u64 v[164:165], s[12:13], 0, v[134:135]
	s_mov_b32 m0, s57
	ds_read_b128 v[200:203], v48
	ds_read_b128 v[208:211], v48 offset:2048
	ds_read_b128 v[204:207], v48 offset:1024
	ds_read_b128 v[212:215], v48 offset:3072
	global_load_lds_dwordx4 v[164:165], off
	s_add_i32 m0, s57, 0x2000
	v_lshl_add_u64 v[172:173], s[12:13], 0, v[130:131]
	global_load_lds_dwordx4 v[172:173], off
	s_barrier

; #define PG8_MMA(ai, bj, At, Bt) do { __builtin_amdgcn_s_setprio(1); _Pragma("unroll") for (int m = 0; m < 4; ++m) _Pragma("unroll") for (int n = 0; n < 2; ++n) _Pragma("unroll") for (int k = 0; k < 2; ++k) \
;         acc[ai][bj][m][n] = __builtin_amdgcn_mfma_f32_16x16x32_bf16(Bt[n][k], At[m][k], acc[ai][bj][m][n], 0, 0, 0); __builtin_amdgcn_s_setprio(0); } while (0)
; #define PG8_WAIT_L(n) asm volatile("s_waitcnt lgkmcnt(" #n ")" ::: "memory")
; #define PG8_BAR __builtin_amdgcn_s_barrier()
; template <class Epi, class Sched>
; __device__ __forceinline__ void gemm_phase(PG8_LAS unsigned char* lds, const Gemm g, const Sched& S, const Epi& E) {
;     ...
;             PG8_BAR; PG8_WAIT_L(0); PG8_MMA(0, 1, At, B1); PG8_BAR;
	s_waitcnt lgkmcnt(3)
	v_mfma_f32_16x16x32_bf16 v[118:121], v[200:203], v[160:163], 0

; #define PG8_MMA(ai, bj, At, Bt) do { __builtin_amdgcn_s_setprio(1); _Pragma("unroll") for (int m = 0; m < 4; ++m) _Pragma("unroll") for (int n = 0; n < 2; ++n) _Pragma("unroll") for (int k = 0; k < 2; ++k) \
;         acc[ai][bj][m][n] = __builtin_amdgcn_mfma_f32_16x16x32_bf16(Bt[n][k], At[m][k], acc[ai][bj][m][n], 0, 0, 0); __builtin_amdgcn_s_setprio(0); } while (0)
; #define PG8_WAIT_L(n) asm volatile("s_waitcnt lgkmcnt(" #n ")" ::: "memory")
; #define PG8_BAR __builtin_amdgcn_s_barrier()
; template <class Epi, class Sched>
; __device__ __forceinline__ void gemm_phase(PG8_LAS unsigned char* lds, const Gemm g, const Sched& S, const Epi& E) {
;     ...
;             PG8_BAR; PG8_WAIT_L(0); PG8_MMA(0, 1, At, B1); PG8_BAR;
	s_waitcnt lgkmcnt(2)
	v_mfma_f32_16x16x32_bf16 v[114:117], v[208:211], v[160:163], 0
	v_mfma_f32_16x16x32_bf16 v[102:105], v[200:203], v[176:179], 0
	v_mfma_f32_16x16x32_bf16 v[98:101], v[208:211], v[176:179], 0
	v_mfma_f32_16x16x32_bf16 v[86:89], v[200:203], v[184:187], 0
	v_mfma_f32_16x16x32_bf16 v[82:85], v[208:211], v[184:187], 0
	v_mfma_f32_16x16x32_bf16 v[70:73], v[200:203], v[192:195], 0
	v_mfma_f32_16x16x32_bf16 v[66:69], v[208:211], v[192:195], 0
	s_waitcnt lgkmcnt(1)
	v_mfma_f32_16x16x32_bf16 v[118:121], v[204:207], v[168:171], v[118:121]

; #define PG8_STAGE(bufoff, gbase, voff) do { _Pragma("unroll") for (int _i = 0; _i < 2; ++_i) \
;         __builtin_amdgcn_global_load_lds((const unsigned*)((const char*)(gbase) + (voff)[_i]), (PG8_LAS unsigned*)(lds + (bufoff) + ldsw + _i * 8192), 16, 0, 0); } while (0)
; #define PG8_LDA(dst, b, h) do { _Pragma("unroll") for (int m = 0; m < 4; ++m) _Pragma("unroll") for (int k = 0; k < 2; ++k) dst[m][k] = *(const PG8_LAS bf16x8*)(lds + PG8_SA(b, h) + aoff + m * 2048 + k * 1024); } while (0)
; #define PG8_MMA(ai, bj, At, Bt) do { __builtin_amdgcn_s_setprio(1); _Pragma("unroll") for (int m = 0; m < 4; ++m) _Pragma("unroll") for (int n = 0; n < 2; ++n) _Pragma("unroll") for (int k = 0; k < 2; ++k) \
;         acc[ai][bj][m][n] = __builtin_amdgcn_mfma_f32_16x16x32_bf16(Bt[n][k], At[m][k], acc[ai][bj][m][n], 0, 0, 0); __builtin_amdgcn_s_setprio(0); } while (0)
; #define PG8_WAIT_L(n) asm volatile("s_waitcnt lgkmcnt(" #n ")" ::: "memory")
; #define PG8_BAR __builtin_amdgcn_s_barrier()
; template <class Epi, class Sched>
; __device__ __forceinline__ void gemm_phase(PG8_LAS unsigned char* lds, const Gemm g, const Sched& S, const Epi& E) {
;     ...
;             PG8_BAR; PG8_WAIT_L(0); PG8_MMA(0, 1, At, B1); PG8_BAR;
;             PG8_LDA(At, 0, 1); PG8_STAGE(PG8_SA(0, 0), a2, voffA);
	s_waitcnt lgkmcnt(0)
	v_mfma_f32_16x16x32_bf16 v[114:117], v[212:215], v[168:171], v[114:117]
	v_mfma_f32_16x16x32_bf16 v[102:105], v[204:207], v[180:183], v[102:105]
	v_mfma_f32_16x16x32_bf16 v[98:101], v[212:215], v[180:183], v[98:101]
	v_mfma_f32_16x16x32_bf16 v[86:89], v[204:207], v[188:191], v[86:89]
	v_mfma_f32_16x16x32_bf16 v[82:85], v[212:215], v[188:191], v[82:85]
	v_mfma_f32_16x16x32_bf16 v[70:73], v[204:207], v[196:199], v[70:73]
	v_mfma_f32_16x16x32_bf16 v[66:69], v[212:215], v[196:199], v[66:69]
	s_mov_b32 m0, s3
	v_lshl_add_u64 v[216:217], s[16:17], 0, v[136:137]
	s_barrier
	ds_read_b128 v[160:163], v167 offset:16384
	ds_read_b128 v[176:179], v167 offset:18432
	ds_read_b128 v[184:187], v167 offset:20480
	ds_read_b128 v[192:195], v167 offset:22528
	ds_read_b128 v[168:171], v167 offset:17408
	ds_read_b128 v[180:183], v167 offset:19456
	ds_read_b128 v[188:191], v167 offset:21504
	ds_read_b128 v[196:199], v167 offset:23552
	global_load_lds_dwordx4 v[216:217], off
	s_mov_b32 m0, s36
	v_lshl_add_u64 v[218:219], s[16:17], 0, v[132:133]
	global_load_lds_dwordx4 v[218:219], off
	s_barrier

; #define PG8_MMA(ai, bj, At, Bt) do { __builtin_amdgcn_s_setprio(1); _Pragma("unroll") for (int m = 0; m < 4; ++m) _Pragma("unroll") for (int n = 0; n < 2; ++n) _Pragma("unroll") for (int k = 0; k < 2; ++k) \
;         acc[ai][bj][m][n] = __builtin_amdgcn_mfma_f32_16x16x32_bf16(Bt[n][k], At[m][k], acc[ai][bj][m][n], 0, 0, 0); __builtin_amdgcn_s_setprio(0); } while (0)
; #define PG8_WAIT_L(n) asm volatile("s_waitcnt lgkmcnt(" #n ")" ::: "memory")
; #define PG8_BAR __builtin_amdgcn_s_barrier()
; #define PG8_SCHED __builtin_amdgcn_sched_barrier(0)
; template <class Epi, class Sched>
; __device__ __forceinline__ void gemm_phase(PG8_LAS unsigned char* lds, const Gemm g, const Sched& S, const Epi& E) {
;     ...
;             PG8_BAR; PG8_WAIT_L(0); PG8_MMA(1, 0, At, B0); PG8_BAR; PG8_SCHED;
	s_waitcnt lgkmcnt(7)
	v_mfma_f32_16x16x32_bf16 v[62:65], v[144:147], v[160:163], 0
	v_mfma_f32_16x16x32_bf16 v[58:61], v[152:155], v[160:163], 0

; #define PG8_MMA(ai, bj, At, Bt) do { __builtin_amdgcn_s_setprio(1); _Pragma("unroll") for (int m = 0; m < 4; ++m) _Pragma("unroll") for (int n = 0; n < 2; ++n) _Pragma("unroll") for (int k = 0; k < 2; ++k) \
;         acc[ai][bj][m][n] = __builtin_amdgcn_mfma_f32_16x16x32_bf16(Bt[n][k], At[m][k], acc[ai][bj][m][n], 0, 0, 0); __builtin_amdgcn_s_setprio(0); } while (0)
; #define PG8_WAIT_L(n) asm volatile("s_waitcnt lgkmcnt(" #n ")" ::: "memory")
; #define PG8_BAR __builtin_amdgcn_s_barrier()
; #define PG8_SCHED __builtin_amdgcn_sched_barrier(0)
; template <class Epi, class Sched>
; __device__ __forceinline__ void gemm_phase(PG8_LAS unsigned char* lds, const Gemm g, const Sched& S, const Epi& E) {
;     ...
;             PG8_BAR; PG8_WAIT_L(0); PG8_MMA(1, 0, At, B0); PG8_BAR; PG8_SCHED;
	s_waitcnt lgkmcnt(6)
	v_mfma_f32_16x16x32_bf16 v[44:47], v[144:147], v[176:179], 0
	v_mfma_f32_16x16x32_bf16 v[40:43], v[152:155], v[176:179], 0

; #define PG8_MMA(ai, bj, At, Bt) do { __builtin_amdgcn_s_setprio(1); _Pragma("unroll") for (int m = 0; m < 4; ++m) _Pragma("unroll") for (int n = 0; n < 2; ++n) _Pragma("unroll") for (int k = 0; k < 2; ++k) \
;         acc[ai][bj][m][n] = __builtin_amdgcn_mfma_f32_16x16x32_bf16(Bt[n][k], At[m][k], acc[ai][bj][m][n], 0, 0, 0); __builtin_amdgcn_s_setprio(0); } while (0)
; #define PG8_WAIT_L(n) asm volatile("s_waitcnt lgkmcnt(" #n ")" ::: "memory")
; #define PG8_BAR __builtin_amdgcn_s_barrier()
; #define PG8_SCHED __builtin_amdgcn_sched_barrier(0)
; template <class Epi, class Sched>
; __device__ __forceinline__ void gemm_phase(PG8_LAS unsigned char* lds, const Gemm g, const Sched& S, const Epi& E) {
;     ...
;             PG8_BAR; PG8_WAIT_L(0); PG8_MMA(1, 0, At, B0); PG8_BAR; PG8_SCHED;
	s_waitcnt lgkmcnt(5)
	v_mfma_f32_16x16x32_bf16 v[28:31], v[144:147], v[184:187], 0
	v_mfma_f32_16x16x32_bf16 v[24:27], v[152:155], v[184:187], 0

; #define PG8_MMA(ai, bj, At, Bt) do { __builtin_amdgcn_s_setprio(1); _Pragma("unroll") for (int m = 0; m < 4; ++m) _Pragma("unroll") for (int n = 0; n < 2; ++n) _Pragma("unroll") for (int k = 0; k < 2; ++k) \
;         acc[ai][bj][m][n] = __builtin_amdgcn_mfma_f32_16x16x32_bf16(Bt[n][k], At[m][k], acc[ai][bj][m][n], 0, 0, 0); __builtin_amdgcn_s_setprio(0); } while (0)
; #define PG8_WAIT_L(n) asm volatile("s_waitcnt lgkmcnt(" #n ")" ::: "memory")
; #define PG8_BAR __builtin_amdgcn_s_barrier()
; #define PG8_SCHED __builtin_amdgcn_sched_barrier(0)
; template <class Epi, class Sched>
; __device__ __forceinline__ void gemm_phase(PG8_LAS unsigned char* lds, const Gemm g, const Sched& S, const Epi& E) {
;     ...
;             PG8_BAR; PG8_WAIT_L(0); PG8_MMA(1, 0, At, B0); PG8_BAR; PG8_SCHED;
	s_waitcnt lgkmcnt(4)
	v_mfma_f32_16x16x32_bf16 v[12:15], v[144:147], v[192:195], 0
	v_mfma_f32_16x16x32_bf16 v[8:11], v[152:155], v[192:195], 0
	s_waitcnt lgkmcnt(3)
	v_mfma_f32_16x16x32_bf16 v[62:65], v[148:151], v[168:171], v[62:65]
	v_mfma_f32_16x16x32_bf16 v[58:61], v[156:159], v[168:171], v[58:61]
	s_waitcnt lgkmcnt(2)
	v_mfma_f32_16x16x32_bf16 v[44:47], v[148:151], v[180:183], v[44:47]
	v_mfma_f32_16x16x32_bf16 v[40:43], v[156:159], v[180:183], v[40:43]
	s_waitcnt lgkmcnt(1)
	v_mfma_f32_16x16x32_bf16 v[28:31], v[148:151], v[188:191], v[28:31]
	v_mfma_f32_16x16x32_bf16 v[24:27], v[156:159], v[188:191], v[24:27]

; #define PG8_STAGE(bufoff, gbase, voff) do { _Pragma("unroll") for (int _i = 0; _i < 2; ++_i) \
;         __builtin_amdgcn_global_load_lds((const unsigned*)((const char*)(gbase) + (voff)[_i]), (PG8_LAS unsigned*)(lds + (bufoff) + ldsw + _i * 8192), 16, 0, 0); } while (0)
; #define PG8_LDA(dst, b, h) do { _Pragma("unroll") for (int m = 0; m < 4; ++m) _Pragma("unroll") for (int k = 0; k < 2; ++k) dst[m][k] = *(const PG8_LAS bf16x8*)(lds + PG8_SA(b, h) + aoff + m * 2048 + k * 1024); } while (0)
; #define PG8_LDB(dst, b, h) do { _Pragma("unroll") for (int n = 0; n < 2; ++n) _Pragma("unroll") for (int k = 0; k < 2; ++k) dst[n][k] = *(const PG8_LAS bf16x8*)(lds + PG8_SB(b, h) + boff + n * 2048 + k * 1024); } while (0)
; #define PG8_MMA(ai, bj, At, Bt) do { __builtin_amdgcn_s_setprio(1); _Pragma("unroll") for (int m = 0; m < 4; ++m) _Pragma("unroll") for (int n = 0; n < 2; ++n) _Pragma("unroll") for (int k = 0; k < 2; ++k) \
;         acc[ai][bj][m][n] = __builtin_amdgcn_mfma_f32_16x16x32_bf16(Bt[n][k], At[m][k], acc[ai][bj][m][n], 0, 0, 0); __builtin_amdgcn_s_setprio(0); } while (0)
; #define PG8_WAIT_V(n) asm volatile("s_waitcnt vmcnt(" #n ")" ::: "memory")
; #define PG8_WAIT_L(n) asm volatile("s_waitcnt lgkmcnt(" #n ")" ::: "memory")
; #define PG8_BAR __builtin_amdgcn_s_barrier()
; #define PG8_SCHED __builtin_amdgcn_sched_barrier(0)
; template <class Epi, class Sched>
; __device__ __forceinline__ void gemm_phase(PG8_LAS unsigned char* lds, const Gemm g, const Sched& S, const Epi& E) {
;     ...
;             PG8_BAR; PG8_WAIT_L(0); PG8_MMA(1, 0, At, B0); PG8_BAR; PG8_SCHED;
;             PG8_STAGE(PG8_SB(0, 1), b2 + hstep, voffB);
;             PG8_WAIT_V(6); PG8_BAR; PG8_MMA(1, 1, At, B1); PG8_BAR;
;             PG8_LDB(B0, 1, 0); PG8_SCHED; PG8_LDA(At, 1, 0); PG8_STAGE(PG8_SA(0, 1), a2 + hstep, voffA);
;             PG8_WAIT_L(8); PG8_BAR; PG8_WAIT_L(0); PG8_MMA(0, 0, At, B0); PG8_BAR; PG8_SCHED;
	s_waitcnt lgkmcnt(0)
	v_mfma_f32_16x16x32_bf16 v[12:15], v[148:151], v[196:199], v[12:15]
	v_mfma_f32_16x16x32_bf16 v[8:11], v[156:159], v[196:199], v[8:11]
	s_barrier
	s_add_u32 s64, s12, 0x40000
	s_addc_u32 s65, s13, 0
	s_add_i32 s57, s59, s34
	s_mov_b32 m0, s57
	v_lshl_add_u64 v[144:145], s[64:65], 0, v[134:135]
	global_load_lds_dwordx4 v[144:145], off
	s_add_i32 m0, s57, 0x2000
	v_lshl_add_u64 v[144:145], s[64:65], 0, v[130:131]
	global_load_lds_dwordx4 v[144:145], off
	s_waitcnt vmcnt(6)
	s_barrier
	v_mfma_f32_16x16x32_bf16 v[54:57], v[200:203], v[160:163], 0
	v_mfma_f32_16x16x32_bf16 v[50:53], v[208:211], v[160:163], 0
	v_mfma_f32_16x16x32_bf16 v[36:39], v[200:203], v[176:179], 0
	v_mfma_f32_16x16x32_bf16 v[32:35], v[208:211], v[176:179], 0
	v_mfma_f32_16x16x32_bf16 v[20:23], v[200:203], v[184:187], 0
	v_mfma_f32_16x16x32_bf16 v[16:19], v[208:211], v[184:187], 0
	v_mfma_f32_16x16x32_bf16 v[4:7], v[200:203], v[192:195], 0
	v_mfma_f32_16x16x32_bf16 v[0:3], v[208:211], v[192:195], 0
	v_mfma_f32_16x16x32_bf16 v[54:57], v[204:207], v[168:171], v[54:57]
	v_mfma_f32_16x16x32_bf16 v[50:53], v[212:215], v[168:171], v[50:53]
	v_mfma_f32_16x16x32_bf16 v[36:39], v[204:207], v[180:183], v[36:39]
	v_mfma_f32_16x16x32_bf16 v[32:35], v[212:215], v[180:183], v[32:35]
	v_mfma_f32_16x16x32_bf16 v[20:23], v[204:207], v[188:191], v[20:23]
	v_mfma_f32_16x16x32_bf16 v[16:19], v[212:215], v[188:191], v[16:19]
	v_mfma_f32_16x16x32_bf16 v[4:7], v[204:207], v[196:199], v[4:7]
	v_mfma_f32_16x16x32_bf16 v[0:3], v[212:215], v[196:199], v[0:3]
	s_add_i32 s57, 0, 0x18000
	v_add_u32_e32 v48, s57, v166
	s_barrier
	ds_read_b128 v[144:147], v48
	ds_read_b128 v[148:151], v48 offset:1024
	ds_read_b128 v[152:155], v48 offset:2048
	ds_read_b128 v[156:159], v48 offset:3072
	s_add_u32 s16, s16, 0x40000
	s_addc_u32 s17, s17, 0
	s_mov_b32 m0, s37
	v_lshl_add_u64 v[200:201], s[16:17], 0, v[136:137]
	ds_read_b128 v[160:163], v167 offset:32768
	ds_read_b128 v[176:179], v167 offset:34816
	ds_read_b128 v[184:187], v167 offset:36864
	ds_read_b128 v[192:195], v167 offset:38912
	ds_read_b128 v[168:171], v167 offset:33792
	ds_read_b128 v[180:183], v167 offset:35840
	ds_read_b128 v[188:191], v167 offset:37888
	ds_read_b128 v[196:199], v167 offset:39936
	global_load_lds_dwordx4 v[200:201], off
	s_mov_b32 m0, s38
	v_lshl_add_u64 v[200:201], s[16:17], 0, v[132:133]
	global_load_lds_dwordx4 v[200:201], off
	s_waitcnt lgkmcnt(8)
	s_barrier

; #define PG8_MMA(ai, bj, At, Bt) do { __builtin_amdgcn_s_setprio(1); _Pragma("unroll") for (int m = 0; m < 4; ++m) _Pragma("unroll") for (int n = 0; n < 2; ++n) _Pragma("unroll") for (int k = 0; k < 2; ++k) \
;         acc[ai][bj][m][n] = __builtin_amdgcn_mfma_f32_16x16x32_bf16(Bt[n][k], At[m][k], acc[ai][bj][m][n], 0, 0, 0); __builtin_amdgcn_s_setprio(0); } while (0)
; #define PG8_WAIT_L(n) asm volatile("s_waitcnt lgkmcnt(" #n ")" ::: "memory")
; #define PG8_BAR __builtin_amdgcn_s_barrier()
; #define PG8_SCHED __builtin_amdgcn_sched_barrier(0)
; template <class Epi, class Sched>
; __device__ __forceinline__ void gemm_phase(PG8_LAS unsigned char* lds, const Gemm g, const Sched& S, const Epi& E) {
;     ...
;             PG8_WAIT_L(8); PG8_BAR; PG8_WAIT_L(0); PG8_MMA(0, 0, At, B0); PG8_BAR; PG8_SCHED;
	s_waitcnt lgkmcnt(7)
	v_mfma_f32_16x16x32_bf16 v[126:129], v[144:147], v[160:163], v[126:129]
	v_mfma_f32_16x16x32_bf16 v[122:125], v[152:155], v[160:163], v[122:125]

; #define PG8_MMA(ai, bj, At, Bt) do { __builtin_amdgcn_s_setprio(1); _Pragma("unroll") for (int m = 0; m < 4; ++m) _Pragma("unroll") for (int n = 0; n < 2; ++n) _Pragma("unroll") for (int k = 0; k < 2; ++k) \
;         acc[ai][bj][m][n] = __builtin_amdgcn_mfma_f32_16x16x32_bf16(Bt[n][k], At[m][k], acc[ai][bj][m][n], 0, 0, 0); __builtin_amdgcn_s_setprio(0); } while (0)
; #define PG8_WAIT_L(n) asm volatile("s_waitcnt lgkmcnt(" #n ")" ::: "memory")
; #define PG8_BAR __builtin_amdgcn_s_barrier()
; #define PG8_SCHED __builtin_amdgcn_sched_barrier(0)
; template <class Epi, class Sched>
; __device__ __forceinline__ void gemm_phase(PG8_LAS unsigned char* lds, const Gemm g, const Sched& S, const Epi& E) {
;     ...
;             PG8_WAIT_L(8); PG8_BAR; PG8_WAIT_L(0); PG8_MMA(0, 0, At, B0); PG8_BAR; PG8_SCHED;
	s_waitcnt lgkmcnt(6)
	v_mfma_f32_16x16x32_bf16 v[110:113], v[144:147], v[176:179], v[110:113]
	v_mfma_f32_16x16x32_bf16 v[106:109], v[152:155], v[176:179], v[106:109]

; #define PG8_MMA(ai, bj, At, Bt) do { __builtin_amdgcn_s_setprio(1); _Pragma("unroll") for (int m = 0; m < 4; ++m) _Pragma("unroll") for (int n = 0; n < 2; ++n) _Pragma("unroll") for (int k = 0; k < 2; ++k) \
;         acc[ai][bj][m][n] = __builtin_amdgcn_mfma_f32_16x16x32_bf16(Bt[n][k], At[m][k], acc[ai][bj][m][n], 0, 0, 0); __builtin_amdgcn_s_setprio(0); } while (0)
; #define PG8_WAIT_L(n) asm volatile("s_waitcnt lgkmcnt(" #n ")" ::: "memory")
; #define PG8_BAR __builtin_amdgcn_s_barrier()
; #define PG8_SCHED __builtin_amdgcn_sched_barrier(0)
; template <class Epi, class Sched>
; __device__ __forceinline__ void gemm_phase(PG8_LAS unsigned char* lds, const Gemm g, const Sched& S, const Epi& E) {
;     ...
;             PG8_WAIT_L(8); PG8_BAR; PG8_WAIT_L(0); PG8_MMA(0, 0, At, B0); PG8_BAR; PG8_SCHED;
	s_waitcnt lgkmcnt(5)
	v_mfma_f32_16x16x32_bf16 v[94:97], v[144:147], v[184:187], v[94:97]
	v_mfma_f32_16x16x32_bf16 v[90:93], v[152:155], v[184:187], v[90:93]

; #define PG8_MMA(ai, bj, At, Bt) do { __builtin_amdgcn_s_setprio(1); _Pragma("unroll") for (int m = 0; m < 4; ++m) _Pragma("unroll") for (int n = 0; n < 2; ++n) _Pragma("unroll") for (int k = 0; k < 2; ++k) \
;         acc[ai][bj][m][n] = __builtin_amdgcn_mfma_f32_16x16x32_bf16(Bt[n][k], At[m][k], acc[ai][bj][m][n], 0, 0, 0); __builtin_amdgcn_s_setprio(0); } while (0)
; #define PG8_WAIT_L(n) asm volatile("s_waitcnt lgkmcnt(" #n ")" ::: "memory")
; #define PG8_BAR __builtin_amdgcn_s_barrier()
; #define PG8_SCHED __builtin_amdgcn_sched_barrier(0)
; template <class Epi, class Sched>
; __device__ __forceinline__ void gemm_phase(PG8_LAS unsigned char* lds, const Gemm g, const Sched& S, const Epi& E) {
;     ...
;             PG8_WAIT_L(8); PG8_BAR; PG8_WAIT_L(0); PG8_MMA(0, 0, At, B0); PG8_BAR; PG8_SCHED;
	s_waitcnt lgkmcnt(4)
	v_mfma_f32_16x16x32_bf16 v[78:81], v[144:147], v[192:195], v[78:81]
	v_mfma_f32_16x16x32_bf16 v[74:77], v[152:155], v[192:195], v[74:77]
	s_waitcnt lgkmcnt(3)
	v_mfma_f32_16x16x32_bf16 v[126:129], v[148:151], v[168:171], v[126:129]
	v_mfma_f32_16x16x32_bf16 v[122:125], v[156:159], v[168:171], v[122:125]
	s_waitcnt lgkmcnt(2)
	v_mfma_f32_16x16x32_bf16 v[110:113], v[148:151], v[180:183], v[110:113]
	v_mfma_f32_16x16x32_bf16 v[106:109], v[156:159], v[180:183], v[106:109]
	s_waitcnt lgkmcnt(1)
	v_mfma_f32_16x16x32_bf16 v[94:97], v[148:151], v[188:191], v[94:97]
	v_mfma_f32_16x16x32_bf16 v[90:93], v[156:159], v[188:191], v[90:93]

; #define PG8_STAGE(bufoff, gbase, voff) do { _Pragma("unroll") for (int _i = 0; _i < 2; ++_i) \
;         __builtin_amdgcn_global_load_lds((const unsigned*)((const char*)(gbase) + (voff)[_i]), (PG8_LAS unsigned*)(lds + (bufoff) + ldsw + _i * 8192), 16, 0, 0); } while (0)
; #define PG8_LDB(dst, b, h) do { _Pragma("unroll") for (int n = 0; n < 2; ++n) _Pragma("unroll") for (int k = 0; k < 2; ++k) dst[n][k] = *(const PG8_LAS bf16x8*)(lds + PG8_SB(b, h) + boff + n * 2048 + k * 1024); } while (0)
; #define PG8_MMA(ai, bj, At, Bt) do { __builtin_amdgcn_s_setprio(1); _Pragma("unroll") for (int m = 0; m < 4; ++m) _Pragma("unroll") for (int n = 0; n < 2; ++n) _Pragma("unroll") for (int k = 0; k < 2; ++k) \
;         acc[ai][bj][m][n] = __builtin_amdgcn_mfma_f32_16x16x32_bf16(Bt[n][k], At[m][k], acc[ai][bj][m][n], 0, 0, 0); __builtin_amdgcn_s_setprio(0); } while (0)
; #define PG8_WAIT_L(n) asm volatile("s_waitcnt lgkmcnt(" #n ")" ::: "memory")
; #define PG8_BAR __builtin_amdgcn_s_barrier()
; #define PG8_SCHED __builtin_amdgcn_sched_barrier(0)
; template <class Epi, class Sched>
; __device__ __forceinline__ void gemm_phase(PG8_LAS unsigned char* lds, const Gemm g, const Sched& S, const Epi& E) {
;     ...
;             PG8_WAIT_L(8); PG8_BAR; PG8_WAIT_L(0); PG8_MMA(0, 0, At, B0); PG8_BAR; PG8_SCHED;
;             PG8_LDB(B1, 1, 1); PG8_STAGE(PG8_SB(1, 0), b3, voffB);
	s_waitcnt lgkmcnt(0)
	v_mfma_f32_16x16x32_bf16 v[78:81], v[148:151], v[196:199], v[78:81]
	v_mfma_f32_16x16x32_bf16 v[74:77], v[156:159], v[196:199], v[74:77]
	s_barrier
	s_add_i32 s16, 0, 0x1c000
	s_add_i32 s17, s57, s34
	v_add_u32_e32 v48, s16, v166
	v_lshl_add_u64 v[164:165], v[164:165], 0, s[0:1]
	s_mov_b32 m0, s17
	ds_read_b128 v[200:203], v48
	ds_read_b128 v[208:211], v48 offset:2048
	ds_read_b128 v[204:207], v48 offset:1024
	ds_read_b128 v[212:215], v48 offset:3072
	global_load_lds_dwordx4 v[164:165], off
	s_add_i32 m0, s17, 0x2000
	v_lshl_add_u64 v[164:165], v[172:173], 0, s[0:1]
	global_load_lds_dwordx4 v[164:165], off
	s_barrier

; #define PG8_MMA(ai, bj, At, Bt) do { __builtin_amdgcn_s_setprio(1); _Pragma("unroll") for (int m = 0; m < 4; ++m) _Pragma("unroll") for (int n = 0; n < 2; ++n) _Pragma("unroll") for (int k = 0; k < 2; ++k) \
;         acc[ai][bj][m][n] = __builtin_amdgcn_mfma_f32_16x16x32_bf16(Bt[n][k], At[m][k], acc[ai][bj][m][n], 0, 0, 0); __builtin_amdgcn_s_setprio(0); } while (0)
; #define PG8_WAIT_L(n) asm volatile("s_waitcnt lgkmcnt(" #n ")" ::: "memory")
; #define PG8_BAR __builtin_amdgcn_s_barrier()
; template <class Epi, class Sched>
; __device__ __forceinline__ void gemm_phase(PG8_LAS unsigned char* lds, const Gemm g, const Sched& S, const Epi& E) {
;     ...
;             PG8_BAR; PG8_WAIT_L(0); PG8_MMA(0, 1, At, B1); PG8_BAR;
	s_waitcnt lgkmcnt(3)
	v_mfma_f32_16x16x32_bf16 v[118:121], v[200:203], v[160:163], v[118:121]

; #define PG8_STAGE(bufoff, gbase, voff) do { _Pragma("unroll") for (int _i = 0; _i < 2; ++_i) \
;         __builtin_amdgcn_global_load_lds((const unsigned*)((const char*)(gbase) + (voff)[_i]), (PG8_LAS unsigned*)(lds + (bufoff) + ldsw + _i * 8192), 16, 0, 0); } while (0)
; #define PG8_LDB(dst, b, h) do { _Pragma("unroll") for (int n = 0; n < 2; ++n) _Pragma("unroll") for (int k = 0; k < 2; ++k) dst[n][k] = *(const PG8_LAS bf16x8*)(lds + PG8_SB(b, h) + boff + n * 2048 + k * 1024); } while (0)
; #define PG8_MMA(ai, bj, At, Bt) do { __builtin_amdgcn_s_setprio(1); _Pragma("unroll") for (int m = 0; m < 4; ++m) _Pragma("unroll") for (int n = 0; n < 2; ++n) _Pragma("unroll") for (int k = 0; k < 2; ++k) \
;         acc[ai][bj][m][n] = __builtin_amdgcn_mfma_f32_16x16x32_bf16(Bt[n][k], At[m][k], acc[ai][bj][m][n], 0, 0, 0); __builtin_amdgcn_s_setprio(0); } while (0)
; #define PG8_WAIT_L(n) asm volatile("s_waitcnt lgkmcnt(" #n ")" ::: "memory")
; #define PG8_BAR __builtin_amdgcn_s_barrier()
; template <class Epi, class Sched>
; __device__ __forceinline__ void gemm_phase(PG8_LAS unsigned char* lds, const Gemm g, const Sched& S, const Epi& E) {
;     ...
;             PG8_LDB(B1, 1, 1); PG8_STAGE(PG8_SB(1, 0), b3, voffB);
;             PG8_BAR; PG8_WAIT_L(0); PG8_MMA(0, 1, At, B1); PG8_BAR;
	s_waitcnt lgkmcnt(2)
	v_mfma_f32_16x16x32_bf16 v[114:117], v[208:211], v[160:163], v[114:117]
	v_mfma_f32_16x16x32_bf16 v[102:105], v[200:203], v[176:179], v[102:105]
	v_mfma_f32_16x16x32_bf16 v[98:101], v[208:211], v[176:179], v[98:101]
	v_mfma_f32_16x16x32_bf16 v[86:89], v[200:203], v[184:187], v[86:89]
	v_mfma_f32_16x16x32_bf16 v[82:85], v[208:211], v[184:187], v[82:85]
	v_mfma_f32_16x16x32_bf16 v[70:73], v[200:203], v[192:195], v[70:73]
	v_mfma_f32_16x16x32_bf16 v[66:69], v[208:211], v[192:195], v[66:69]
	s_waitcnt lgkmcnt(1)
	v_mfma_f32_16x16x32_bf16 v[118:121], v[204:207], v[168:171], v[118:121]

; #define PG8_STAGE(bufoff, gbase, voff) do { _Pragma("unroll") for (int _i = 0; _i < 2; ++_i) \
;         __builtin_amdgcn_global_load_lds((const unsigned*)((const char*)(gbase) + (voff)[_i]), (PG8_LAS unsigned*)(lds + (bufoff) + ldsw + _i * 8192), 16, 0, 0); } while (0)
; #define PG8_LDA(dst, b, h) do { _Pragma("unroll") for (int m = 0; m < 4; ++m) _Pragma("unroll") for (int k = 0; k < 2; ++k) dst[m][k] = *(const PG8_LAS bf16x8*)(lds + PG8_SA(b, h) + aoff + m * 2048 + k * 1024); } while (0)
; #define PG8_MMA(ai, bj, At, Bt) do { __builtin_amdgcn_s_setprio(1); _Pragma("unroll") for (int m = 0; m < 4; ++m) _Pragma("unroll") for (int n = 0; n < 2; ++n) _Pragma("unroll") for (int k = 0; k < 2; ++k) \
;         acc[ai][bj][m][n] = __builtin_amdgcn_mfma_f32_16x16x32_bf16(Bt[n][k], At[m][k], acc[ai][bj][m][n], 0, 0, 0); __builtin_amdgcn_s_setprio(0); } while (0)
; #define PG8_WAIT_L(n) asm volatile("s_waitcnt lgkmcnt(" #n ")" ::: "memory")
; #define PG8_BAR __builtin_amdgcn_s_barrier()
; template <class Epi, class Sched>
; __device__ __forceinline__ void gemm_phase(PG8_LAS unsigned char* lds, const Gemm g, const Sched& S, const Epi& E) {
;     ...
;             PG8_BAR; PG8_WAIT_L(0); PG8_MMA(0, 1, At, B1); PG8_BAR;
;             PG8_LDA(At, 1, 1); PG8_STAGE(PG8_SA(1, 0), a3, voffA);
	s_waitcnt lgkmcnt(0)
	v_mfma_f32_16x16x32_bf16 v[114:117], v[212:215], v[168:171], v[114:117]
	v_mfma_f32_16x16x32_bf16 v[102:105], v[204:207], v[180:183], v[102:105]
	v_mfma_f32_16x16x32_bf16 v[98:101], v[212:215], v[180:183], v[98:101]
	v_mfma_f32_16x16x32_bf16 v[86:89], v[204:207], v[188:191], v[86:89]
	v_mfma_f32_16x16x32_bf16 v[82:85], v[212:215], v[188:191], v[82:85]
	v_mfma_f32_16x16x32_bf16 v[70:73], v[204:207], v[196:199], v[70:73]
	v_mfma_f32_16x16x32_bf16 v[66:69], v[212:215], v[196:199], v[66:69]
	s_mov_b32 m0, s39
	v_lshl_add_u64 v[164:165], v[216:217], 0, s[0:1]
	s_barrier
	ds_read_b128 v[160:163], v167 offset:49152
	ds_read_b128 v[176:179], v167 offset:51200
	ds_read_b128 v[184:187], v167 offset:53248
	ds_read_b128 v[192:195], v167 offset:55296
	ds_read_b128 v[168:171], v167 offset:50176
	ds_read_b128 v[180:183], v167 offset:52224
	ds_read_b128 v[188:191], v167 offset:54272
	ds_read_b128 v[196:199], v167 offset:56320
	global_load_lds_dwordx4 v[164:165], off
	s_mov_b32 m0, s42
	v_lshl_add_u64 v[164:165], v[218:219], 0, s[0:1]
	global_load_lds_dwordx4 v[164:165], off
	s_barrier

; #define PG8_MMA(ai, bj, At, Bt) do { __builtin_amdgcn_s_setprio(1); _Pragma("unroll") for (int m = 0; m < 4; ++m) _Pragma("unroll") for (int n = 0; n < 2; ++n) _Pragma("unroll") for (int k = 0; k < 2; ++k) \
;         acc[ai][bj][m][n] = __builtin_amdgcn_mfma_f32_16x16x32_bf16(Bt[n][k], At[m][k], acc[ai][bj][m][n], 0, 0, 0); __builtin_amdgcn_s_setprio(0); } while (0)
; #define PG8_WAIT_L(n) asm volatile("s_waitcnt lgkmcnt(" #n ")" ::: "memory")
; #define PG8_BAR __builtin_amdgcn_s_barrier()
; #define PG8_SCHED __builtin_amdgcn_sched_barrier(0)
; template <class Epi, class Sched>
; __device__ __forceinline__ void gemm_phase(PG8_LAS unsigned char* lds, const Gemm g, const Sched& S, const Epi& E) {
;     ...
;             PG8_BAR; PG8_WAIT_L(0); PG8_MMA(1, 0, At, B0); PG8_BAR; PG8_SCHED;
	s_waitcnt lgkmcnt(7)
	v_mfma_f32_16x16x32_bf16 v[62:65], v[144:147], v[160:163], v[62:65]
	v_mfma_f32_16x16x32_bf16 v[58:61], v[152:155], v[160:163], v[58:61]

; #define PG8_MMA(ai, bj, At, Bt) do { __builtin_amdgcn_s_setprio(1); _Pragma("unroll") for (int m = 0; m < 4; ++m) _Pragma("unroll") for (int n = 0; n < 2; ++n) _Pragma("unroll") for (int k = 0; k < 2; ++k) \
;         acc[ai][bj][m][n] = __builtin_amdgcn_mfma_f32_16x16x32_bf16(Bt[n][k], At[m][k], acc[ai][bj][m][n], 0, 0, 0); __builtin_amdgcn_s_setprio(0); } while (0)
; #define PG8_WAIT_L(n) asm volatile("s_waitcnt lgkmcnt(" #n ")" ::: "memory")
; #define PG8_BAR __builtin_amdgcn_s_barrier()
; #define PG8_SCHED __builtin_amdgcn_sched_barrier(0)
; template <class Epi, class Sched>
; __device__ __forceinline__ void gemm_phase(PG8_LAS unsigned char* lds, const Gemm g, const Sched& S, const Epi& E) {
;     ...
;             PG8_BAR; PG8_WAIT_L(0); PG8_MMA(1, 0, At, B0); PG8_BAR; PG8_SCHED;
	s_waitcnt lgkmcnt(6)
	v_mfma_f32_16x16x32_bf16 v[44:47], v[144:147], v[176:179], v[44:47]
	v_mfma_f32_16x16x32_bf16 v[40:43], v[152:155], v[176:179], v[40:43]

; #define PG8_MMA(ai, bj, At, Bt) do { __builtin_amdgcn_s_setprio(1); _Pragma("unroll") for (int m = 0; m < 4; ++m) _Pragma("unroll") for (int n = 0; n < 2; ++n) _Pragma("unroll") for (int k = 0; k < 2; ++k) \
;         acc[ai][bj][m][n] = __builtin_amdgcn_mfma_f32_16x16x32_bf16(Bt[n][k], At[m][k], acc[ai][bj][m][n], 0, 0, 0); __builtin_amdgcn_s_setprio(0); } while (0)
; #define PG8_WAIT_L(n) asm volatile("s_waitcnt lgkmcnt(" #n ")" ::: "memory")
; #define PG8_BAR __builtin_amdgcn_s_barrier()
; #define PG8_SCHED __builtin_amdgcn_sched_barrier(0)
; template <class Epi, class Sched>
; __device__ __forceinline__ void gemm_phase(PG8_LAS unsigned char* lds, const Gemm g, const Sched& S, const Epi& E) {
;     ...
;             PG8_BAR; PG8_WAIT_L(0); PG8_MMA(1, 0, At, B0); PG8_BAR; PG8_SCHED;
	s_waitcnt lgkmcnt(5)
	v_mfma_f32_16x16x32_bf16 v[28:31], v[144:147], v[184:187], v[28:31]
	v_mfma_f32_16x16x32_bf16 v[24:27], v[152:155], v[184:187], v[24:27]

; #define PG8_MMA(ai, bj, At, Bt) do { __builtin_amdgcn_s_setprio(1); _Pragma("unroll") for (int m = 0; m < 4; ++m) _Pragma("unroll") for (int n = 0; n < 2; ++n) _Pragma("unroll") for (int k = 0; k < 2; ++k) \
;         acc[ai][bj][m][n] = __builtin_amdgcn_mfma_f32_16x16x32_bf16(Bt[n][k], At[m][k], acc[ai][bj][m][n], 0, 0, 0); __builtin_amdgcn_s_setprio(0); } while (0)
; #define PG8_WAIT_L(n) asm volatile("s_waitcnt lgkmcnt(" #n ")" ::: "memory")
; #define PG8_BAR __builtin_amdgcn_s_barrier()
; #define PG8_SCHED __builtin_amdgcn_sched_barrier(0)
; template <class Epi, class Sched>
; __device__ __forceinline__ void gemm_phase(PG8_LAS unsigned char* lds, const Gemm g, const Sched& S, const Epi& E) {
;     ...
;             PG8_BAR; PG8_WAIT_L(0); PG8_MMA(1, 0, At, B0); PG8_BAR; PG8_SCHED;
	s_waitcnt lgkmcnt(4)
	v_mfma_f32_16x16x32_bf16 v[12:15], v[144:147], v[192:195], v[12:15]
	v_mfma_f32_16x16x32_bf16 v[8:11], v[152:155], v[192:195], v[8:11]
	s_waitcnt lgkmcnt(3)
	v_mfma_f32_16x16x32_bf16 v[62:65], v[148:151], v[168:171], v[62:65]
	v_mfma_f32_16x16x32_bf16 v[58:61], v[156:159], v[168:171], v[58:61]
	s_waitcnt lgkmcnt(2)
	v_mfma_f32_16x16x32_bf16 v[44:47], v[148:151], v[180:183], v[44:47]
	v_mfma_f32_16x16x32_bf16 v[40:43], v[156:159], v[180:183], v[40:43]
	s_waitcnt lgkmcnt(1)
	v_mfma_f32_16x16x32_bf16 v[28:31], v[148:151], v[188:191], v[28:31]
	v_mfma_f32_16x16x32_bf16 v[24:27], v[156:159], v[188:191], v[24:27]

; #define PG8_STAGE(bufoff, gbase, voff) do { _Pragma("unroll") for (int _i = 0; _i < 2; ++_i) \
;         __builtin_amdgcn_global_load_lds((const unsigned*)((const char*)(gbase) + (voff)[_i]), (PG8_LAS unsigned*)(lds + (bufoff) + ldsw + _i * 8192), 16, 0, 0); } while (0)
; #define PG8_LDA(dst, b, h) do { _Pragma("unroll") for (int m = 0; m < 4; ++m) _Pragma("unroll") for (int k = 0; k < 2; ++k) dst[m][k] = *(const PG8_LAS bf16x8*)(lds + PG8_SA(b, h) + aoff + m * 2048 + k * 1024); } while (0)
; #define PG8_LDB(dst, b, h) do { _Pragma("unroll") for (int n = 0; n < 2; ++n) _Pragma("unroll") for (int k = 0; k < 2; ++k) dst[n][k] = *(const PG8_LAS bf16x8*)(lds + PG8_SB(b, h) + boff + n * 2048 + k * 1024); } while (0)
; #define PG8_MMA(ai, bj, At, Bt) do { __builtin_amdgcn_s_setprio(1); _Pragma("unroll") for (int m = 0; m < 4; ++m) _Pragma("unroll") for (int n = 0; n < 2; ++n) _Pragma("unroll") for (int k = 0; k < 2; ++k) \
;         acc[ai][bj][m][n] = __builtin_amdgcn_mfma_f32_16x16x32_bf16(Bt[n][k], At[m][k], acc[ai][bj][m][n], 0, 0, 0); __builtin_amdgcn_s_setprio(0); } while (0)
; #define PG8_WAIT_V(n) asm volatile("s_waitcnt vmcnt(" #n ")" ::: "memory")
; #define PG8_WAIT_L(n) asm volatile("s_waitcnt lgkmcnt(" #n ")" ::: "memory")
; #define PG8_BAR __builtin_amdgcn_s_barrier()
; #define PG8_SCHED __builtin_amdgcn_sched_barrier(0)
; template <class Epi, class Sched>
; __device__ __forceinline__ void gemm_phase(PG8_LAS unsigned char* lds, const Gemm g, const Sched& S, const Epi& E) {
;     ...
;         for (int t = 0; t < nt; t += 2) {
;             const bool last = (t == nt - 2);
;             const char* a1 = cA + (size_t)(t + 1) * kstep;
;             const char* a2 = last ? nA : cA + (size_t)(t + 2) * kstep; const char* b2 = last ? nB : cB + (size_t)(t + 2) * kstep;
;             const char* a3 = a2 + kstep; const char* b3 = b2 + kstep;
;             if (last && has_next) S.a_ready(nxt);
;             PG8_LDB(B0, 0, 0); PG8_SCHED; PG8_LDA(At, 0, 0); PG8_STAGE(PG8_SA(1, 1), a1 + hstep, voffA);
;             PG8_WAIT_L(8); PG8_BAR; PG8_WAIT_L(0); PG8_MMA(0, 0, At, B0); PG8_BAR; PG8_SCHED;
;     ...
;             PG8_BAR; PG8_WAIT_L(0); PG8_MMA(1, 0, At, B0); PG8_BAR; PG8_SCHED;
;             PG8_STAGE(PG8_SB(1, 1), b3 + hstep, voffB);
;             PG8_WAIT_V(6); PG8_BAR; PG8_MMA(1, 1, At, B1); PG8_BAR;
	s_waitcnt lgkmcnt(0)
	v_mfma_f32_16x16x32_bf16 v[12:15], v[148:151], v[196:199], v[12:15]
	v_mfma_f32_16x16x32_bf16 v[8:11], v[156:159], v[196:199], v[8:11]
	s_barrier
	s_add_u32 s12, s12, 0x40080
	s_addc_u32 s13, s13, 0
	s_add_i32 s16, s16, s34
	s_mov_b32 m0, s16
	v_lshl_add_u64 v[144:145], s[12:13], 0, v[134:135]
	global_load_lds_dwordx4 v[144:145], off
	s_add_i32 m0, s16, 0x2000
	v_lshl_add_u64 v[144:145], s[12:13], 0, v[130:131]
	global_load_lds_dwordx4 v[144:145], off
	s_waitcnt vmcnt(6)
	s_barrier
	v_mfma_f32_16x16x32_bf16 v[54:57], v[200:203], v[160:163], v[54:57]
	v_mfma_f32_16x16x32_bf16 v[50:53], v[208:211], v[160:163], v[50:53]
	v_mfma_f32_16x16x32_bf16 v[36:39], v[200:203], v[176:179], v[36:39]
	v_mfma_f32_16x16x32_bf16 v[32:35], v[208:211], v[176:179], v[32:35]
	v_mfma_f32_16x16x32_bf16 v[20:23], v[200:203], v[184:187], v[20:23]
	v_mfma_f32_16x16x32_bf16 v[16:19], v[208:211], v[184:187], v[16:19]
	v_mfma_f32_16x16x32_bf16 v[4:7], v[200:203], v[192:195], v[4:7]
	v_mfma_f32_16x16x32_bf16 v[0:3], v[208:211], v[192:195], v[0:3]
	v_mfma_f32_16x16x32_bf16 v[54:57], v[204:207], v[168:171], v[54:57]
	v_mfma_f32_16x16x32_bf16 v[50:53], v[212:215], v[168:171], v[50:53]
	v_mfma_f32_16x16x32_bf16 v[36:39], v[204:207], v[180:183], v[36:39]
	v_mfma_f32_16x16x32_bf16 v[32:35], v[212:215], v[180:183], v[32:35]
	v_mfma_f32_16x16x32_bf16 v[20:23], v[204:207], v[188:191], v[20:23]
	v_mfma_f32_16x16x32_bf16 v[16:19], v[212:215], v[188:191], v[16:19]
	v_mfma_f32_16x16x32_bf16 v[4:7], v[204:207], v[196:199], v[4:7]
	v_mfma_f32_16x16x32_bf16 v[0:3], v[212:215], v[196:199], v[0:3]
	s_add_i32 s56, s56, 2
	s_add_u32 s6, s6, 0x100
	s_addc_u32 s7, s7, 0
	s_add_u32 s54, s54, 0x100
	s_addc_u32 s55, s55, 0
	s_cmp_gt_u32 s56, 13
	s_barrier
	s_cbranch_scc1 .Lkpeel_exit_335
.LBB0_335:
	s_add_u32 s12, s6, 0xfffc0080
	s_addc_u32 s13, s7, -1
	s_add_i32 s57, 0, 0x10000
	v_add_u32_e32 v48, s57, v166
	ds_read_b128 v[144:147], v48
	ds_read_b128 v[148:151], v48 offset:1024
	ds_read_b128 v[152:155], v48 offset:2048
	ds_read_b128 v[156:159], v48 offset:3072
	s_cmp_eq_u32 s56, 12
	s_cselect_b32 s17, s23, s13
	s_cselect_b32 s16, s50, s12
	s_cselect_b32 s13, s21, s55
	s_cselect_b32 s12, s51, s54
	v_lshl_add_u64 v[164:165], s[6:7], 0, v[140:141]
	s_add_i32 m0, s3, 0xc000
	ds_read_b128 v[160:163], v167
	ds_read_b128 v[176:179], v167 offset:2048
	ds_read_b128 v[184:187], v167 offset:4096
	ds_read_b128 v[192:195], v167 offset:6144
	ds_read_b128 v[168:171], v167 offset:1024
	ds_read_b128 v[180:183], v167 offset:3072
	ds_read_b128 v[188:191], v167 offset:5120
	ds_read_b128 v[196:199], v167 offset:7168
	global_load_lds_dwordx4 v[164:165], off
	s_add_i32 m0, s3, 0xe000
	v_lshl_add_u64 v[164:165], s[6:7], 0, v[142:143]
	global_load_lds_dwordx4 v[164:165], off
	s_waitcnt lgkmcnt(8)
	s_barrier

; #define PG8_STAGE(bufoff, gbase, voff) do { _Pragma("unroll") for (int _i = 0; _i < 2; ++_i) \
;         __builtin_amdgcn_global_load_lds((const unsigned*)((const char*)(gbase) + (voff)[_i]), (PG8_LAS unsigned*)(lds + (bufoff) + ldsw + _i * 8192), 16, 0, 0); } while (0)
; #define PG8_LDA(dst, b, h) do { _Pragma("unroll") for (int m = 0; m < 4; ++m) _Pragma("unroll") for (int k = 0; k < 2; ++k) dst[m][k] = *(const PG8_LAS bf16x8*)(lds + PG8_SA(b, h) + aoff + m * 2048 + k * 1024); } while (0)
; #define PG8_LDB(dst, b, h) do { _Pragma("unroll") for (int n = 0; n < 2; ++n) _Pragma("unroll") for (int k = 0; k < 2; ++k) dst[n][k] = *(const PG8_LAS bf16x8*)(lds + PG8_SB(b, h) + boff + n * 2048 + k * 1024); } while (0)
; #define PG8_MMA(ai, bj, At, Bt) do { __builtin_amdgcn_s_setprio(1); _Pragma("unroll") for (int m = 0; m < 4; ++m) _Pragma("unroll") for (int n = 0; n < 2; ++n) _Pragma("unroll") for (int k = 0; k < 2; ++k) \
;         acc[ai][bj][m][n] = __builtin_amdgcn_mfma_f32_16x16x32_bf16(Bt[n][k], At[m][k], acc[ai][bj][m][n], 0, 0, 0); __builtin_amdgcn_s_setprio(0); } while (0)
; #define PG8_WAIT_L(n) asm volatile("s_waitcnt lgkmcnt(" #n ")" ::: "memory")
; #define PG8_BAR __builtin_amdgcn_s_barrier()
; #define PG8_SCHED __builtin_amdgcn_sched_barrier(0)
; template <class Epi, class Sched>
; __device__ __forceinline__ void gemm_phase(PG8_LAS unsigned char* lds, const Gemm g, const Sched& S, const Epi& E) {
;     ...
;             PG8_LDB(B0, 0, 0); PG8_SCHED; PG8_LDA(At, 0, 0); PG8_STAGE(PG8_SA(1, 1), a1 + hstep, voffA);
;             PG8_WAIT_L(8); PG8_BAR; PG8_WAIT_L(0); PG8_MMA(0, 0, At, B0); PG8_BAR; PG8_SCHED;
	s_waitcnt lgkmcnt(7)
	v_mfma_f32_16x16x32_bf16 v[126:129], v[144:147], v[160:163], v[126:129]
	v_mfma_f32_16x16x32_bf16 v[122:125], v[152:155], v[160:163], v[122:125]

; #define PG8_STAGE(bufoff, gbase, voff) do { _Pragma("unroll") for (int _i = 0; _i < 2; ++_i) \
;         __builtin_amdgcn_global_load_lds((const unsigned*)((const char*)(gbase) + (voff)[_i]), (PG8_LAS unsigned*)(lds + (bufoff) + ldsw + _i * 8192), 16, 0, 0); } while (0)
; #define PG8_LDA(dst, b, h) do { _Pragma("unroll") for (int m = 0; m < 4; ++m) _Pragma("unroll") for (int k = 0; k < 2; ++k) dst[m][k] = *(const PG8_LAS bf16x8*)(lds + PG8_SA(b, h) + aoff + m * 2048 + k * 1024); } while (0)
; #define PG8_LDB(dst, b, h) do { _Pragma("unroll") for (int n = 0; n < 2; ++n) _Pragma("unroll") for (int k = 0; k < 2; ++k) dst[n][k] = *(const PG8_LAS bf16x8*)(lds + PG8_SB(b, h) + boff + n * 2048 + k * 1024); } while (0)
; #define PG8_MMA(ai, bj, At, Bt) do { __builtin_amdgcn_s_setprio(1); _Pragma("unroll") for (int m = 0; m < 4; ++m) _Pragma("unroll") for (int n = 0; n < 2; ++n) _Pragma("unroll") for (int k = 0; k < 2; ++k) \
;         acc[ai][bj][m][n] = __builtin_amdgcn_mfma_f32_16x16x32_bf16(Bt[n][k], At[m][k], acc[ai][bj][m][n], 0, 0, 0); __builtin_amdgcn_s_setprio(0); } while (0)
; #define PG8_WAIT_L(n) asm volatile("s_waitcnt lgkmcnt(" #n ")" ::: "memory")
; #define PG8_BAR __builtin_amdgcn_s_barrier()
; #define PG8_SCHED __builtin_amdgcn_sched_barrier(0)
; template <class Epi, class Sched>
; __device__ __forceinline__ void gemm_phase(PG8_LAS unsigned char* lds, const Gemm g, const Sched& S, const Epi& E) {
;     ...
;             PG8_LDB(B0, 0, 0); PG8_SCHED; PG8_LDA(At, 0, 0); PG8_STAGE(PG8_SA(1, 1), a1 + hstep, voffA);
;             PG8_WAIT_L(8); PG8_BAR; PG8_WAIT_L(0); PG8_MMA(0, 0, At, B0); PG8_BAR; PG8_SCHED;
	s_waitcnt lgkmcnt(6)
	v_mfma_f32_16x16x32_bf16 v[110:113], v[144:147], v[176:179], v[110:113]
	v_mfma_f32_16x16x32_bf16 v[106:109], v[152:155], v[176:179], v[106:109]

; #define PG8_STAGE(bufoff, gbase, voff) do { _Pragma("unroll") for (int _i = 0; _i < 2; ++_i) \
;         __builtin_amdgcn_global_load_lds((const unsigned*)((const char*)(gbase) + (voff)[_i]), (PG8_LAS unsigned*)(lds + (bufoff) + ldsw + _i * 8192), 16, 0, 0); } while (0)
; #define PG8_LDA(dst, b, h) do { _Pragma("unroll") for (int m = 0; m < 4; ++m) _Pragma("unroll") for (int k = 0; k < 2; ++k) dst[m][k] = *(const PG8_LAS bf16x8*)(lds + PG8_SA(b, h) + aoff + m * 2048 + k * 1024); } while (0)
; #define PG8_LDB(dst, b, h) do { _Pragma("unroll") for (int n = 0; n < 2; ++n) _Pragma("unroll") for (int k = 0; k < 2; ++k) dst[n][k] = *(const PG8_LAS bf16x8*)(lds + PG8_SB(b, h) + boff + n * 2048 + k * 1024); } while (0)
; #define PG8_MMA(ai, bj, At, Bt) do { __builtin_amdgcn_s_setprio(1); _Pragma("unroll") for (int m = 0; m < 4; ++m) _Pragma("unroll") for (int n = 0; n < 2; ++n) _Pragma("unroll") for (int k = 0; k < 2; ++k) \
;         acc[ai][bj][m][n] = __builtin_amdgcn_mfma_f32_16x16x32_bf16(Bt[n][k], At[m][k], acc[ai][bj][m][n], 0, 0, 0); __builtin_amdgcn_s_setprio(0); } while (0)
; #define PG8_WAIT_L(n) asm volatile("s_waitcnt lgkmcnt(" #n ")" ::: "memory")
; #define PG8_BAR __builtin_amdgcn_s_barrier()
; #define PG8_SCHED __builtin_amdgcn_sched_barrier(0)
; template <class Epi, class Sched>
; __device__ __forceinline__ void gemm_phase(PG8_LAS unsigned char* lds, const Gemm g, const Sched& S, const Epi& E) {
;     ...
;             PG8_LDB(B0, 0, 0); PG8_SCHED; PG8_LDA(At, 0, 0); PG8_STAGE(PG8_SA(1, 1), a1 + hstep, voffA);
;             PG8_WAIT_L(8); PG8_BAR; PG8_WAIT_L(0); PG8_MMA(0, 0, At, B0); PG8_BAR; PG8_SCHED;
	s_waitcnt lgkmcnt(5)
	v_mfma_f32_16x16x32_bf16 v[94:97], v[144:147], v[184:187], v[94:97]
	v_mfma_f32_16x16x32_bf16 v[90:93], v[152:155], v[184:187], v[90:93]

; #define PG8_STAGE(bufoff, gbase, voff) do { _Pragma("unroll") for (int _i = 0; _i < 2; ++_i) \
;         __builtin_amdgcn_global_load_lds((const unsigned*)((const char*)(gbase) + (voff)[_i]), (PG8_LAS unsigned*)(lds + (bufoff) + ldsw + _i * 8192), 16, 0, 0); } while (0)
; #define PG8_LDA(dst, b, h) do { _Pragma("unroll") for (int m = 0; m < 4; ++m) _Pragma("unroll") for (int k = 0; k < 2; ++k) dst[m][k] = *(const PG8_LAS bf16x8*)(lds + PG8_SA(b, h) + aoff + m * 2048 + k * 1024); } while (0)
; #define PG8_LDB(dst, b, h) do { _Pragma("unroll") for (int n = 0; n < 2; ++n) _Pragma("unroll") for (int k = 0; k < 2; ++k) dst[n][k] = *(const PG8_LAS bf16x8*)(lds + PG8_SB(b, h) + boff + n * 2048 + k * 1024); } while (0)
; #define PG8_MMA(ai, bj, At, Bt) do { __builtin_amdgcn_s_setprio(1); _Pragma("unroll") for (int m = 0; m < 4; ++m) _Pragma("unroll") for (int n = 0; n < 2; ++n) _Pragma("unroll") for (int k = 0; k < 2; ++k) \
;         acc[ai][bj][m][n] = __builtin_amdgcn_mfma_f32_16x16x32_bf16(Bt[n][k], At[m][k], acc[ai][bj][m][n], 0, 0, 0); __builtin_amdgcn_s_setprio(0); } while (0)
; #define PG8_WAIT_L(n) asm volatile("s_waitcnt lgkmcnt(" #n ")" ::: "memory")
; #define PG8_BAR __builtin_amdgcn_s_barrier()
; #define PG8_SCHED __builtin_amdgcn_sched_barrier(0)
; template <class Epi, class Sched>
; __device__ __forceinline__ void gemm_phase(PG8_LAS unsigned char* lds, const Gemm g, const Sched& S, const Epi& E) {
;     ...
;             PG8_LDB(B0, 0, 0); PG8_SCHED; PG8_LDA(At, 0, 0); PG8_STAGE(PG8_SA(1, 1), a1 + hstep, voffA);
;             PG8_WAIT_L(8); PG8_BAR; PG8_WAIT_L(0); PG8_MMA(0, 0, At, B0); PG8_BAR; PG8_SCHED;
	s_waitcnt lgkmcnt(4)
	v_mfma_f32_16x16x32_bf16 v[78:81], v[144:147], v[192:195], v[78:81]
	v_mfma_f32_16x16x32_bf16 v[74:77], v[152:155], v[192:195], v[74:77]
	s_waitcnt lgkmcnt(3)
	v_mfma_f32_16x16x32_bf16 v[126:129], v[148:151], v[168:171], v[126:129]
	v_mfma_f32_16x16x32_bf16 v[122:125], v[156:159], v[168:171], v[122:125]
	s_waitcnt lgkmcnt(2)
	v_mfma_f32_16x16x32_bf16 v[110:113], v[148:151], v[180:183], v[110:113]
	v_mfma_f32_16x16x32_bf16 v[106:109], v[156:159], v[180:183], v[106:109]
	s_waitcnt lgkmcnt(1)
	v_mfma_f32_16x16x32_bf16 v[94:97], v[148:151], v[188:191], v[94:97]
	v_mfma_f32_16x16x32_bf16 v[90:93], v[156:159], v[188:191], v[90:93]

; #define PG8_STAGE(bufoff, gbase, voff) do { _Pragma("unroll") for (int _i = 0; _i < 2; ++_i) \
;         __builtin_amdgcn_global_load_lds((const unsigned*)((const char*)(gbase) + (voff)[_i]), (PG8_LAS unsigned*)(lds + (bufoff) + ldsw + _i * 8192), 16, 0, 0); } while (0)
; #define PG8_LDB(dst, b, h) do { _Pragma("unroll") for (int n = 0; n < 2; ++n) _Pragma("unroll") for (int k = 0; k < 2; ++k) dst[n][k] = *(const PG8_LAS bf16x8*)(lds + PG8_SB(b, h) + boff + n * 2048 + k * 1024); } while (0)
; #define PG8_MMA(ai, bj, At, Bt) do { __builtin_amdgcn_s_setprio(1); _Pragma("unroll") for (int m = 0; m < 4; ++m) _Pragma("unroll") for (int n = 0; n < 2; ++n) _Pragma("unroll") for (int k = 0; k < 2; ++k) \
;         acc[ai][bj][m][n] = __builtin_amdgcn_mfma_f32_16x16x32_bf16(Bt[n][k], At[m][k], acc[ai][bj][m][n], 0, 0, 0); __builtin_amdgcn_s_setprio(0); } while (0)
; #define PG8_WAIT_L(n) asm volatile("s_waitcnt lgkmcnt(" #n ")" ::: "memory")
; #define PG8_BAR __builtin_amdgcn_s_barrier()
; #define PG8_SCHED __builtin_amdgcn_sched_barrier(0)
; template <class Epi, class Sched>
; __device__ __forceinline__ void gemm_phase(PG8_LAS unsigned char* lds, const Gemm g, const Sched& S, const Epi& E) {
;     ...
;             PG8_WAIT_L(8); PG8_BAR; PG8_WAIT_L(0); PG8_MMA(0, 0, At, B0); PG8_BAR; PG8_SCHED;
;             PG8_LDB(B1, 0, 1); PG8_STAGE(PG8_SB(0, 0), b2, voffB);
	s_waitcnt lgkmcnt(0)
	v_mfma_f32_16x16x32_bf16 v[78:81], v[148:151], v[196:199], v[78:81]
	v_mfma_f32_16x16x32_bf16 v[74:77], v[156:159], v[196:199], v[74:77]
	s_barrier
	s_add_i32 s59, 0, 0x14000
	s_add_i32 s57, s57, s34
	v_add_u32_e32 v48, s59, v166
	v_lshl_add_u64 v[164:165], s[12:13], 0, v[134:135]
	s_mov_b32 m0, s57
	ds_read_b128 v[200:203], v48
	ds_read_b128 v[208:211], v48 offset:2048
	ds_read_b128 v[204:207], v48 offset:1024
	ds_read_b128 v[212:215], v48 offset:3072
	global_load_lds_dwordx4 v[164:165], off
	s_add_i32 m0, s57, 0x2000
	v_lshl_add_u64 v[172:173], s[12:13], 0, v[130:131]
	global_load_lds_dwordx4 v[172:173], off
	s_barrier

; #define PG8_MMA(ai, bj, At, Bt) do { __builtin_amdgcn_s_setprio(1); _Pragma("unroll") for (int m = 0; m < 4; ++m) _Pragma("unroll") for (int n = 0; n < 2; ++n) _Pragma("unroll") for (int k = 0; k < 2; ++k) \
;         acc[ai][bj][m][n] = __builtin_amdgcn_mfma_f32_16x16x32_bf16(Bt[n][k], At[m][k], acc[ai][bj][m][n], 0, 0, 0); __builtin_amdgcn_s_setprio(0); } while (0)
; #define PG8_WAIT_L(n) asm volatile("s_waitcnt lgkmcnt(" #n ")" ::: "memory")
; #define PG8_BAR __builtin_amdgcn_s_barrier()
; template <class Epi, class Sched>
; __device__ __forceinline__ void gemm_phase(PG8_LAS unsigned char* lds, const Gemm g, const Sched& S, const Epi& E) {
;     ...
;             PG8_BAR; PG8_WAIT_L(0); PG8_MMA(0, 1, At, B1); PG8_BAR;
	s_waitcnt lgkmcnt(3)
	v_mfma_f32_16x16x32_bf16 v[118:121], v[200:203], v[160:163], v[118:121]

; #define PG8_MMA(ai, bj, At, Bt) do { __builtin_amdgcn_s_setprio(1); _Pragma("unroll") for (int m = 0; m < 4; ++m) _Pragma("unroll") for (int n = 0; n < 2; ++n) _Pragma("unroll") for (int k = 0; k < 2; ++k) \
;         acc[ai][bj][m][n] = __builtin_amdgcn_mfma_f32_16x16x32_bf16(Bt[n][k], At[m][k], acc[ai][bj][m][n], 0, 0, 0); __builtin_amdgcn_s_setprio(0); } while (0)
; #define PG8_WAIT_L(n) asm volatile("s_waitcnt lgkmcnt(" #n ")" ::: "memory")
; #define PG8_BAR __builtin_amdgcn_s_barrier()
; template <class Epi, class Sched>
; __device__ __forceinline__ void gemm_phase(PG8_LAS unsigned char* lds, const Gemm g, const Sched& S, const Epi& E) {
;     ...
;             PG8_BAR; PG8_WAIT_L(0); PG8_MMA(0, 1, At, B1); PG8_BAR;
	s_waitcnt lgkmcnt(2)
	v_mfma_f32_16x16x32_bf16 v[114:117], v[208:211], v[160:163], v[114:117]
	v_mfma_f32_16x16x32_bf16 v[102:105], v[200:203], v[176:179], v[102:105]
	v_mfma_f32_16x16x32_bf16 v[98:101], v[208:211], v[176:179], v[98:101]
	v_mfma_f32_16x16x32_bf16 v[86:89], v[200:203], v[184:187], v[86:89]
	v_mfma_f32_16x16x32_bf16 v[82:85], v[208:211], v[184:187], v[82:85]
	v_mfma_f32_16x16x32_bf16 v[70:73], v[200:203], v[192:195], v[70:73]
	v_mfma_f32_16x16x32_bf16 v[66:69], v[208:211], v[192:195], v[66:69]
	s_waitcnt lgkmcnt(1)
	v_mfma_f32_16x16x32_bf16 v[118:121], v[204:207], v[168:171], v[118:121]

; #define PG8_STAGE(bufoff, gbase, voff) do { _Pragma("unroll") for (int _i = 0; _i < 2; ++_i) \
;         __builtin_amdgcn_global_load_lds((const unsigned*)((const char*)(gbase) + (voff)[_i]), (PG8_LAS unsigned*)(lds + (bufoff) + ldsw + _i * 8192), 16, 0, 0); } while (0)
; #define PG8_LDA(dst, b, h) do { _Pragma("unroll") for (int m = 0; m < 4; ++m) _Pragma("unroll") for (int k = 0; k < 2; ++k) dst[m][k] = *(const PG8_LAS bf16x8*)(lds + PG8_SA(b, h) + aoff + m * 2048 + k * 1024); } while (0)
; #define PG8_MMA(ai, bj, At, Bt) do { __builtin_amdgcn_s_setprio(1); _Pragma("unroll") for (int m = 0; m < 4; ++m) _Pragma("unroll") for (int n = 0; n < 2; ++n) _Pragma("unroll") for (int k = 0; k < 2; ++k) \
;         acc[ai][bj][m][n] = __builtin_amdgcn_mfma_f32_16x16x32_bf16(Bt[n][k], At[m][k], acc[ai][bj][m][n], 0, 0, 0); __builtin_amdgcn_s_setprio(0); } while (0)
; #define PG8_WAIT_L(n) asm volatile("s_waitcnt lgkmcnt(" #n ")" ::: "memory")
; #define PG8_BAR __builtin_amdgcn_s_barrier()
; template <class Epi, class Sched>
; __device__ __forceinline__ void gemm_phase(PG8_LAS unsigned char* lds, const Gemm g, const Sched& S, const Epi& E) {
;     ...
;             PG8_BAR; PG8_WAIT_L(0); PG8_MMA(0, 1, At, B1); PG8_BAR;
;             PG8_LDA(At, 0, 1); PG8_STAGE(PG8_SA(0, 0), a2, voffA);
	s_waitcnt lgkmcnt(0)
	v_mfma_f32_16x16x32_bf16 v[114:117], v[212:215], v[168:171], v[114:117]
	v_mfma_f32_16x16x32_bf16 v[102:105], v[204:207], v[180:183], v[102:105]
	v_mfma_f32_16x16x32_bf16 v[98:101], v[212:215], v[180:183], v[98:101]
	v_mfma_f32_16x16x32_bf16 v[86:89], v[204:207], v[188:191], v[86:89]
	v_mfma_f32_16x16x32_bf16 v[82:85], v[212:215], v[188:191], v[82:85]
	v_mfma_f32_16x16x32_bf16 v[70:73], v[204:207], v[196:199], v[70:73]
	v_mfma_f32_16x16x32_bf16 v[66:69], v[212:215], v[196:199], v[66:69]
	s_mov_b32 m0, s3
	v_lshl_add_u64 v[216:217], s[16:17], 0, v[136:137]
	s_barrier
	ds_read_b128 v[160:163], v167 offset:16384
	ds_read_b128 v[176:179], v167 offset:18432
	ds_read_b128 v[184:187], v167 offset:20480
	ds_read_b128 v[192:195], v167 offset:22528
	ds_read_b128 v[168:171], v167 offset:17408
	ds_read_b128 v[180:183], v167 offset:19456
	ds_read_b128 v[188:191], v167 offset:21504
	ds_read_b128 v[196:199], v167 offset:23552
	global_load_lds_dwordx4 v[216:217], off
	s_mov_b32 m0, s36
	v_lshl_add_u64 v[218:219], s[16:17], 0, v[132:133]
	global_load_lds_dwordx4 v[218:219], off
	s_barrier

; #define PG8_MMA(ai, bj, At, Bt) do { __builtin_amdgcn_s_setprio(1); _Pragma("unroll") for (int m = 0; m < 4; ++m) _Pragma("unroll") for (int n = 0; n < 2; ++n) _Pragma("unroll") for (int k = 0; k < 2; ++k) \
;         acc[ai][bj][m][n] = __builtin_amdgcn_mfma_f32_16x16x32_bf16(Bt[n][k], At[m][k], acc[ai][bj][m][n], 0, 0, 0); __builtin_amdgcn_s_setprio(0); } while (0)
; #define PG8_WAIT_L(n) asm volatile("s_waitcnt lgkmcnt(" #n ")" ::: "memory")
; #define PG8_BAR __builtin_amdgcn_s_barrier()
; #define PG8_SCHED __builtin_amdgcn_sched_barrier(0)
; template <class Epi, class Sched>
; __device__ __forceinline__ void gemm_phase(PG8_LAS unsigned char* lds, const Gemm g, const Sched& S, const Epi& E) {
;     ...
;             PG8_BAR; PG8_WAIT_L(0); PG8_MMA(1, 0, At, B0); PG8_BAR; PG8_SCHED;
	s_waitcnt lgkmcnt(7)
	v_mfma_f32_16x16x32_bf16 v[62:65], v[144:147], v[160:163], v[62:65]
	v_mfma_f32_16x16x32_bf16 v[58:61], v[152:155], v[160:163], v[58:61]

; #define PG8_MMA(ai, bj, At, Bt) do { __builtin_amdgcn_s_setprio(1); _Pragma("unroll") for (int m = 0; m < 4; ++m) _Pragma("unroll") for (int n = 0; n < 2; ++n) _Pragma("unroll") for (int k = 0; k < 2; ++k) \
;         acc[ai][bj][m][n] = __builtin_amdgcn_mfma_f32_16x16x32_bf16(Bt[n][k], At[m][k], acc[ai][bj][m][n], 0, 0, 0); __builtin_amdgcn_s_setprio(0); } while (0)
; #define PG8_WAIT_L(n) asm volatile("s_waitcnt lgkmcnt(" #n ")" ::: "memory")
; #define PG8_BAR __builtin_amdgcn_s_barrier()
; #define PG8_SCHED __builtin_amdgcn_sched_barrier(0)
; template <class Epi, class Sched>
; __device__ __forceinline__ void gemm_phase(PG8_LAS unsigned char* lds, const Gemm g, const Sched& S, const Epi& E) {
;     ...
;             PG8_BAR; PG8_WAIT_L(0); PG8_MMA(1, 0, At, B0); PG8_BAR; PG8_SCHED;
	s_waitcnt lgkmcnt(6)
	v_mfma_f32_16x16x32_bf16 v[44:47], v[144:147], v[176:179], v[44:47]
	v_mfma_f32_16x16x32_bf16 v[40:43], v[152:155], v[176:179], v[40:43]

; #define PG8_MMA(ai, bj, At, Bt) do { __builtin_amdgcn_s_setprio(1); _Pragma("unroll") for (int m = 0; m < 4; ++m) _Pragma("unroll") for (int n = 0; n < 2; ++n) _Pragma("unroll") for (int k = 0; k < 2; ++k) \
;         acc[ai][bj][m][n] = __builtin_amdgcn_mfma_f32_16x16x32_bf16(Bt[n][k], At[m][k], acc[ai][bj][m][n], 0, 0, 0); __builtin_amdgcn_s_setprio(0); } while (0)
; #define PG8_WAIT_L(n) asm volatile("s_waitcnt lgkmcnt(" #n ")" ::: "memory")
; #define PG8_BAR __builtin_amdgcn_s_barrier()
; #define PG8_SCHED __builtin_amdgcn_sched_barrier(0)
; template <class Epi, class Sched>
; __device__ __forceinline__ void gemm_phase(PG8_LAS unsigned char* lds, const Gemm g, const Sched& S, const Epi& E) {
;     ...
;             PG8_BAR; PG8_WAIT_L(0); PG8_MMA(1, 0, At, B0); PG8_BAR; PG8_SCHED;
	s_waitcnt lgkmcnt(5)
	v_mfma_f32_16x16x32_bf16 v[28:31], v[144:147], v[184:187], v[28:31]
	v_mfma_f32_16x16x32_bf16 v[24:27], v[152:155], v[184:187], v[24:27]

; #define PG8_MMA(ai, bj, At, Bt) do { __builtin_amdgcn_s_setprio(1); _Pragma("unroll") for (int m = 0; m < 4; ++m) _Pragma("unroll") for (int n = 0; n < 2; ++n) _Pragma("unroll") for (int k = 0; k < 2; ++k) \
;         acc[ai][bj][m][n] = __builtin_amdgcn_mfma_f32_16x16x32_bf16(Bt[n][k], At[m][k], acc[ai][bj][m][n], 0, 0, 0); __builtin_amdgcn_s_setprio(0); } while (0)
; #define PG8_WAIT_L(n) asm volatile("s_waitcnt lgkmcnt(" #n ")" ::: "memory")
; #define PG8_BAR __builtin_amdgcn_s_barrier()
; #define PG8_SCHED __builtin_amdgcn_sched_barrier(0)
; template <class Epi, class Sched>
; __device__ __forceinline__ void gemm_phase(PG8_LAS unsigned char* lds, const Gemm g, const Sched& S, const Epi& E) {
;     ...
;             PG8_BAR; PG8_WAIT_L(0); PG8_MMA(1, 0, At, B0); PG8_BAR; PG8_SCHED;
	s_waitcnt lgkmcnt(4)
	v_mfma_f32_16x16x32_bf16 v[12:15], v[144:147], v[192:195], v[12:15]
	v_mfma_f32_16x16x32_bf16 v[8:11], v[152:155], v[192:195], v[8:11]
	s_waitcnt lgkmcnt(3)
	v_mfma_f32_16x16x32_bf16 v[62:65], v[148:151], v[168:171], v[62:65]
	v_mfma_f32_16x16x32_bf16 v[58:61], v[156:159], v[168:171], v[58:61]
	s_waitcnt lgkmcnt(2)
	v_mfma_f32_16x16x32_bf16 v[44:47], v[148:151], v[180:183], v[44:47]
	v_mfma_f32_16x16x32_bf16 v[40:43], v[156:159], v[180:183], v[40:43]
	s_waitcnt lgkmcnt(1)
	v_mfma_f32_16x16x32_bf16 v[28:31], v[148:151], v[188:191], v[28:31]
	v_mfma_f32_16x16x32_bf16 v[24:27], v[156:159], v[188:191], v[24:27]

; #define PG8_STAGE(bufoff, gbase, voff) do { _Pragma("unroll") for (int _i = 0; _i < 2; ++_i) \
;         __builtin_amdgcn_global_load_lds((const unsigned*)((const char*)(gbase) + (voff)[_i]), (PG8_LAS unsigned*)(lds + (bufoff) + ldsw + _i * 8192), 16, 0, 0); } while (0)
; #define PG8_LDA(dst, b, h) do { _Pragma("unroll") for (int m = 0; m < 4; ++m) _Pragma("unroll") for (int k = 0; k < 2; ++k) dst[m][k] = *(const PG8_LAS bf16x8*)(lds + PG8_SA(b, h) + aoff + m * 2048 + k * 1024); } while (0)
; #define PG8_LDB(dst, b, h) do { _Pragma("unroll") for (int n = 0; n < 2; ++n) _Pragma("unroll") for (int k = 0; k < 2; ++k) dst[n][k] = *(const PG8_LAS bf16x8*)(lds + PG8_SB(b, h) + boff + n * 2048 + k * 1024); } while (0)
; #define PG8_MMA(ai, bj, At, Bt) do { __builtin_amdgcn_s_setprio(1); _Pragma("unroll") for (int m = 0; m < 4; ++m) _Pragma("unroll") for (int n = 0; n < 2; ++n) _Pragma("unroll") for (int k = 0; k < 2; ++k) \
;         acc[ai][bj][m][n] = __builtin_amdgcn_mfma_f32_16x16x32_bf16(Bt[n][k], At[m][k], acc[ai][bj][m][n], 0, 0, 0); __builtin_amdgcn_s_setprio(0); } while (0)
; #define PG8_WAIT_V(n) asm volatile("s_waitcnt vmcnt(" #n ")" ::: "memory")
; #define PG8_WAIT_L(n) asm volatile("s_waitcnt lgkmcnt(" #n ")" ::: "memory")
; #define PG8_BAR __builtin_amdgcn_s_barrier()
; #define PG8_SCHED __builtin_amdgcn_sched_barrier(0)
; template <class Epi, class Sched>
; __device__ __forceinline__ void gemm_phase(PG8_LAS unsigned char* lds, const Gemm g, const Sched& S, const Epi& E) {
;     ...
;             PG8_BAR; PG8_WAIT_L(0); PG8_MMA(1, 0, At, B0); PG8_BAR; PG8_SCHED;
;             PG8_STAGE(PG8_SB(0, 1), b2 + hstep, voffB);
;             PG8_WAIT_V(6); PG8_BAR; PG8_MMA(1, 1, At, B1); PG8_BAR;
;             PG8_LDB(B0, 1, 0); PG8_SCHED; PG8_LDA(At, 1, 0); PG8_STAGE(PG8_SA(0, 1), a2 + hstep, voffA);
;             PG8_WAIT_L(8); PG8_BAR; PG8_WAIT_L(0); PG8_MMA(0, 0, At, B0); PG8_BAR; PG8_SCHED;
	s_waitcnt lgkmcnt(0)
	v_mfma_f32_16x16x32_bf16 v[12:15], v[148:151], v[196:199], v[12:15]
	v_mfma_f32_16x16x32_bf16 v[8:11], v[156:159], v[196:199], v[8:11]
	s_barrier
	s_add_u32 s64, s12, 0x40000
	s_addc_u32 s65, s13, 0
	s_add_i32 s57, s59, s34
	s_mov_b32 m0, s57
	v_lshl_add_u64 v[144:145], s[64:65], 0, v[134:135]
	global_load_lds_dwordx4 v[144:145], off
	s_add_i32 m0, s57, 0x2000
	v_lshl_add_u64 v[144:145], s[64:65], 0, v[130:131]
	global_load_lds_dwordx4 v[144:145], off
	s_waitcnt vmcnt(6)
	s_barrier
	v_mfma_f32_16x16x32_bf16 v[54:57], v[200:203], v[160:163], v[54:57]
	v_mfma_f32_16x16x32_bf16 v[50:53], v[208:211], v[160:163], v[50:53]
	v_mfma_f32_16x16x32_bf16 v[36:39], v[200:203], v[176:179], v[36:39]
	v_mfma_f32_16x16x32_bf16 v[32:35], v[208:211], v[176:179], v[32:35]
	v_mfma_f32_16x16x32_bf16 v[20:23], v[200:203], v[184:187], v[20:23]
	v_mfma_f32_16x16x32_bf16 v[16:19], v[208:211], v[184:187], v[16:19]
	v_mfma_f32_16x16x32_bf16 v[4:7], v[200:203], v[192:195], v[4:7]
	v_mfma_f32_16x16x32_bf16 v[0:3], v[208:211], v[192:195], v[0:3]
	v_mfma_f32_16x16x32_bf16 v[54:57], v[204:207], v[168:171], v[54:57]
	v_mfma_f32_16x16x32_bf16 v[50:53], v[212:215], v[168:171], v[50:53]
	v_mfma_f32_16x16x32_bf16 v[36:39], v[204:207], v[180:183], v[36:39]
	v_mfma_f32_16x16x32_bf16 v[32:35], v[212:215], v[180:183], v[32:35]
	v_mfma_f32_16x16x32_bf16 v[20:23], v[204:207], v[188:191], v[20:23]
	v_mfma_f32_16x16x32_bf16 v[16:19], v[212:215], v[188:191], v[16:19]
	v_mfma_f32_16x16x32_bf16 v[4:7], v[204:207], v[196:199], v[4:7]
	v_mfma_f32_16x16x32_bf16 v[0:3], v[212:215], v[196:199], v[0:3]
	s_add_i32 s57, 0, 0x18000
	v_add_u32_e32 v48, s57, v166
	s_barrier
	ds_read_b128 v[144:147], v48
	ds_read_b128 v[148:151], v48 offset:1024
	ds_read_b128 v[152:155], v48 offset:2048
	ds_read_b128 v[156:159], v48 offset:3072
	s_add_u32 s16, s16, 0x40000
	s_addc_u32 s17, s17, 0
	s_mov_b32 m0, s37
	v_lshl_add_u64 v[200:201], s[16:17], 0, v[136:137]
	ds_read_b128 v[160:163], v167 offset:32768
	ds_read_b128 v[176:179], v167 offset:34816
	ds_read_b128 v[184:187], v167 offset:36864
	ds_read_b128 v[192:195], v167 offset:38912
	ds_read_b128 v[168:171], v167 offset:33792
	ds_read_b128 v[180:183], v167 offset:35840
	ds_read_b128 v[188:191], v167 offset:37888
	ds_read_b128 v[196:199], v167 offset:39936
	global_load_lds_dwordx4 v[200:201], off
	s_mov_b32 m0, s38
	v_lshl_add_u64 v[200:201], s[16:17], 0, v[132:133]
	global_load_lds_dwordx4 v[200:201], off
	s_waitcnt lgkmcnt(8)
	s_barrier

; #define PG8_MMA(ai, bj, At, Bt) do { __builtin_amdgcn_s_setprio(1); _Pragma("unroll") for (int m = 0; m < 4; ++m) _Pragma("unroll") for (int n = 0; n < 2; ++n) _Pragma("unroll") for (int k = 0; k < 2; ++k) \
;         acc[ai][bj][m][n] = __builtin_amdgcn_mfma_f32_16x16x32_bf16(Bt[n][k], At[m][k], acc[ai][bj][m][n], 0, 0, 0); __builtin_amdgcn_s_setprio(0); } while (0)
; #define PG8_WAIT_L(n) asm volatile("s_waitcnt lgkmcnt(" #n ")" ::: "memory")
; #define PG8_BAR __builtin_amdgcn_s_barrier()
; #define PG8_SCHED __builtin_amdgcn_sched_barrier(0)
; template <class Epi, class Sched>
; __device__ __forceinline__ void gemm_phase(PG8_LAS unsigned char* lds, const Gemm g, const Sched& S, const Epi& E) {
;     ...
;             PG8_WAIT_L(8); PG8_BAR; PG8_WAIT_L(0); PG8_MMA(0, 0, At, B0); PG8_BAR; PG8_SCHED;
	s_waitcnt lgkmcnt(7)
	v_mfma_f32_16x16x32_bf16 v[126:129], v[144:147], v[160:163], v[126:129]
	v_mfma_f32_16x16x32_bf16 v[122:125], v[152:155], v[160:163], v[122:125]

; #define PG8_MMA(ai, bj, At, Bt) do { __builtin_amdgcn_s_setprio(1); _Pragma("unroll") for (int m = 0; m < 4; ++m) _Pragma("unroll") for (int n = 0; n < 2; ++n) _Pragma("unroll") for (int k = 0; k < 2; ++k) \
;         acc[ai][bj][m][n] = __builtin_amdgcn_mfma_f32_16x16x32_bf16(Bt[n][k], At[m][k], acc[ai][bj][m][n], 0, 0, 0); __builtin_amdgcn_s_setprio(0); } while (0)
; #define PG8_WAIT_L(n) asm volatile("s_waitcnt lgkmcnt(" #n ")" ::: "memory")
; #define PG8_BAR __builtin_amdgcn_s_barrier()
; #define PG8_SCHED __builtin_amdgcn_sched_barrier(0)
; template <class Epi, class Sched>
; __device__ __forceinline__ void gemm_phase(PG8_LAS unsigned char* lds, const Gemm g, const Sched& S, const Epi& E) {
;     ...
;             PG8_WAIT_L(8); PG8_BAR; PG8_WAIT_L(0); PG8_MMA(0, 0, At, B0); PG8_BAR; PG8_SCHED;
	s_waitcnt lgkmcnt(6)
	v_mfma_f32_16x16x32_bf16 v[110:113], v[144:147], v[176:179], v[110:113]
	v_mfma_f32_16x16x32_bf16 v[106:109], v[152:155], v[176:179], v[106:109]

; #define PG8_MMA(ai, bj, At, Bt) do { __builtin_amdgcn_s_setprio(1); _Pragma("unroll") for (int m = 0; m < 4; ++m) _Pragma("unroll") for (int n = 0; n < 2; ++n) _Pragma("unroll") for (int k = 0; k < 2; ++k) \
;         acc[ai][bj][m][n] = __builtin_amdgcn_mfma_f32_16x16x32_bf16(Bt[n][k], At[m][k], acc[ai][bj][m][n], 0, 0, 0); __builtin_amdgcn_s_setprio(0); } while (0)
; #define PG8_WAIT_L(n) asm volatile("s_waitcnt lgkmcnt(" #n ")" ::: "memory")
; #define PG8_BAR __builtin_amdgcn_s_barrier()
; #define PG8_SCHED __builtin_amdgcn_sched_barrier(0)
; template <class Epi, class Sched>
; __device__ __forceinline__ void gemm_phase(PG8_LAS unsigned char* lds, const Gemm g, const Sched& S, const Epi& E) {
;     ...
;             PG8_WAIT_L(8); PG8_BAR; PG8_WAIT_L(0); PG8_MMA(0, 0, At, B0); PG8_BAR; PG8_SCHED;
	s_waitcnt lgkmcnt(5)
	v_mfma_f32_16x16x32_bf16 v[94:97], v[144:147], v[184:187], v[94:97]
	v_mfma_f32_16x16x32_bf16 v[90:93], v[152:155], v[184:187], v[90:93]

; #define PG8_MMA(ai, bj, At, Bt) do { __builtin_amdgcn_s_setprio(1); _Pragma("unroll") for (int m = 0; m < 4; ++m) _Pragma("unroll") for (int n = 0; n < 2; ++n) _Pragma("unroll") for (int k = 0; k < 2; ++k) \
;         acc[ai][bj][m][n] = __builtin_amdgcn_mfma_f32_16x16x32_bf16(Bt[n][k], At[m][k], acc[ai][bj][m][n], 0, 0, 0); __builtin_amdgcn_s_setprio(0); } while (0)
; #define PG8_WAIT_L(n) asm volatile("s_waitcnt lgkmcnt(" #n ")" ::: "memory")
; #define PG8_BAR __builtin_amdgcn_s_barrier()
; #define PG8_SCHED __builtin_amdgcn_sched_barrier(0)
; template <class Epi, class Sched>
; __device__ __forceinline__ void gemm_phase(PG8_LAS unsigned char* lds, const Gemm g, const Sched& S, const Epi& E) {
;     ...
;             PG8_WAIT_L(8); PG8_BAR; PG8_WAIT_L(0); PG8_MMA(0, 0, At, B0); PG8_BAR; PG8_SCHED;
	s_waitcnt lgkmcnt(4)
	v_mfma_f32_16x16x32_bf16 v[78:81], v[144:147], v[192:195], v[78:81]
	v_mfma_f32_16x16x32_bf16 v[74:77], v[152:155], v[192:195], v[74:77]
	s_waitcnt lgkmcnt(3)
	v_mfma_f32_16x16x32_bf16 v[126:129], v[148:151], v[168:171], v[126:129]
	v_mfma_f32_16x16x32_bf16 v[122:125], v[156:159], v[168:171], v[122:125]
	s_waitcnt lgkmcnt(2)
	v_mfma_f32_16x16x32_bf16 v[110:113], v[148:151], v[180:183], v[110:113]
	v_mfma_f32_16x16x32_bf16 v[106:109], v[156:159], v[180:183], v[106:109]
	s_waitcnt lgkmcnt(1)
	v_mfma_f32_16x16x32_bf16 v[94:97], v[148:151], v[188:191], v[94:97]
	v_mfma_f32_16x16x32_bf16 v[90:93], v[156:159], v[188:191], v[90:93]

; #define PG8_STAGE(bufoff, gbase, voff) do { _Pragma("unroll") for (int _i = 0; _i < 2; ++_i) \
;         __builtin_amdgcn_global_load_lds((const unsigned*)((const char*)(gbase) + (voff)[_i]), (PG8_LAS unsigned*)(lds + (bufoff) + ldsw + _i * 8192), 16, 0, 0); } while (0)
; #define PG8_LDB(dst, b, h) do { _Pragma("unroll") for (int n = 0; n < 2; ++n) _Pragma("unroll") for (int k = 0; k < 2; ++k) dst[n][k] = *(const PG8_LAS bf16x8*)(lds + PG8_SB(b, h) + boff + n * 2048 + k * 1024); } while (0)
; #define PG8_MMA(ai, bj, At, Bt) do { __builtin_amdgcn_s_setprio(1); _Pragma("unroll") for (int m = 0; m < 4; ++m) _Pragma("unroll") for (int n = 0; n < 2; ++n) _Pragma("unroll") for (int k = 0; k < 2; ++k) \
;         acc[ai][bj][m][n] = __builtin_amdgcn_mfma_f32_16x16x32_bf16(Bt[n][k], At[m][k], acc[ai][bj][m][n], 0, 0, 0); __builtin_amdgcn_s_setprio(0); } while (0)
; #define PG8_WAIT_L(n) asm volatile("s_waitcnt lgkmcnt(" #n ")" ::: "memory")
; #define PG8_BAR __builtin_amdgcn_s_barrier()
; #define PG8_SCHED __builtin_amdgcn_sched_barrier(0)
; template <class Epi, class Sched>
; __device__ __forceinline__ void gemm_phase(PG8_LAS unsigned char* lds, const Gemm g, const Sched& S, const Epi& E) {
;     ...
;             PG8_WAIT_L(8); PG8_BAR; PG8_WAIT_L(0); PG8_MMA(0, 0, At, B0); PG8_BAR; PG8_SCHED;
;             PG8_LDB(B1, 1, 1); PG8_STAGE(PG8_SB(1, 0), b3, voffB);
	s_waitcnt lgkmcnt(0)
	v_mfma_f32_16x16x32_bf16 v[78:81], v[148:151], v[196:199], v[78:81]
	v_mfma_f32_16x16x32_bf16 v[74:77], v[156:159], v[196:199], v[74:77]
	s_barrier
	s_add_i32 s16, 0, 0x1c000
	s_add_i32 s17, s57, s34
	v_add_u32_e32 v48, s16, v166
	v_lshl_add_u64 v[164:165], v[164:165], 0, s[0:1]
	s_mov_b32 m0, s17
	ds_read_b128 v[200:203], v48
	ds_read_b128 v[208:211], v48 offset:2048
	ds_read_b128 v[204:207], v48 offset:1024
	ds_read_b128 v[212:215], v48 offset:3072
	global_load_lds_dwordx4 v[164:165], off
	s_add_i32 m0, s17, 0x2000
	v_lshl_add_u64 v[164:165], v[172:173], 0, s[0:1]
	global_load_lds_dwordx4 v[164:165], off
	s_barrier

; #define PG8_MMA(ai, bj, At, Bt) do { __builtin_amdgcn_s_setprio(1); _Pragma("unroll") for (int m = 0; m < 4; ++m) _Pragma("unroll") for (int n = 0; n < 2; ++n) _Pragma("unroll") for (int k = 0; k < 2; ++k) \
;         acc[ai][bj][m][n] = __builtin_amdgcn_mfma_f32_16x16x32_bf16(Bt[n][k], At[m][k], acc[ai][bj][m][n], 0, 0, 0); __builtin_amdgcn_s_setprio(0); } while (0)
; #define PG8_WAIT_L(n) asm volatile("s_waitcnt lgkmcnt(" #n ")" ::: "memory")
; #define PG8_BAR __builtin_amdgcn_s_barrier()
; template <class Epi, class Sched>
; __device__ __forceinline__ void gemm_phase(PG8_LAS unsigned char* lds, const Gemm g, const Sched& S, const Epi& E) {
;     ...
;             PG8_BAR; PG8_WAIT_L(0); PG8_MMA(0, 1, At, B1); PG8_BAR;
	s_waitcnt lgkmcnt(3)
	v_mfma_f32_16x16x32_bf16 v[118:121], v[200:203], v[160:163], v[118:121]

; #define PG8_MMA(ai, bj, At, Bt) do { __builtin_amdgcn_s_setprio(1); _Pragma("unroll") for (int m = 0; m < 4; ++m) _Pragma("unroll") for (int n = 0; n < 2; ++n) _Pragma("unroll") for (int k = 0; k < 2; ++k) \
;         acc[ai][bj][m][n] = __builtin_amdgcn_mfma_f32_16x16x32_bf16(Bt[n][k], At[m][k], acc[ai][bj][m][n], 0, 0, 0); __builtin_amdgcn_s_setprio(0); } while (0)
; #define PG8_WAIT_L(n) asm volatile("s_waitcnt lgkmcnt(" #n ")" ::: "memory")
; #define PG8_BAR __builtin_amdgcn_s_barrier()
; template <class Epi, class Sched>
; __device__ __forceinline__ void gemm_phase(PG8_LAS unsigned char* lds, const Gemm g, const Sched& S, const Epi& E) {
;     ...
;             PG8_BAR; PG8_WAIT_L(0); PG8_MMA(0, 1, At, B1); PG8_BAR;
	s_waitcnt lgkmcnt(2)
	v_mfma_f32_16x16x32_bf16 v[114:117], v[208:211], v[160:163], v[114:117]
	v_mfma_f32_16x16x32_bf16 v[102:105], v[200:203], v[176:179], v[102:105]
	v_mfma_f32_16x16x32_bf16 v[98:101], v[208:211], v[176:179], v[98:101]
	v_mfma_f32_16x16x32_bf16 v[86:89], v[200:203], v[184:187], v[86:89]
	v_mfma_f32_16x16x32_bf16 v[82:85], v[208:211], v[184:187], v[82:85]
	v_mfma_f32_16x16x32_bf16 v[70:73], v[200:203], v[192:195], v[70:73]
	v_mfma_f32_16x16x32_bf16 v[66:69], v[208:211], v[192:195], v[66:69]
	s_waitcnt lgkmcnt(1)
	v_mfma_f32_16x16x32_bf16 v[118:121], v[204:207], v[168:171], v[118:121]

; #define PG8_STAGE(bufoff, gbase, voff) do { _Pragma("unroll") for (int _i = 0; _i < 2; ++_i) \
;         __builtin_amdgcn_global_load_lds((const unsigned*)((const char*)(gbase) + (voff)[_i]), (PG8_LAS unsigned*)(lds + (bufoff) + ldsw + _i * 8192), 16, 0, 0); } while (0)
; #define PG8_LDA(dst, b, h) do { _Pragma("unroll") for (int m = 0; m < 4; ++m) _Pragma("unroll") for (int k = 0; k < 2; ++k) dst[m][k] = *(const PG8_LAS bf16x8*)(lds + PG8_SA(b, h) + aoff + m * 2048 + k * 1024); } while (0)
; #define PG8_MMA(ai, bj, At, Bt) do { __builtin_amdgcn_s_setprio(1); _Pragma("unroll") for (int m = 0; m < 4; ++m) _Pragma("unroll") for (int n = 0; n < 2; ++n) _Pragma("unroll") for (int k = 0; k < 2; ++k) \
;         acc[ai][bj][m][n] = __builtin_amdgcn_mfma_f32_16x16x32_bf16(Bt[n][k], At[m][k], acc[ai][bj][m][n], 0, 0, 0); __builtin_amdgcn_s_setprio(0); } while (0)
; #define PG8_WAIT_L(n) asm volatile("s_waitcnt lgkmcnt(" #n ")" ::: "memory")
; #define PG8_BAR __builtin_amdgcn_s_barrier()
; template <class Epi, class Sched>
; __device__ __forceinline__ void gemm_phase(PG8_LAS unsigned char* lds, const Gemm g, const Sched& S, const Epi& E) {
;     ...
;             PG8_BAR; PG8_WAIT_L(0); PG8_MMA(0, 1, At, B1); PG8_BAR;
;             PG8_LDA(At, 1, 1); PG8_STAGE(PG8_SA(1, 0), a3, voffA);
	s_waitcnt lgkmcnt(0)
	v_mfma_f32_16x16x32_bf16 v[114:117], v[212:215], v[168:171], v[114:117]
	v_mfma_f32_16x16x32_bf16 v[102:105], v[204:207], v[180:183], v[102:105]
	v_mfma_f32_16x16x32_bf16 v[98:101], v[212:215], v[180:183], v[98:101]
	v_mfma_f32_16x16x32_bf16 v[86:89], v[204:207], v[188:191], v[86:89]
	v_mfma_f32_16x16x32_bf16 v[82:85], v[212:215], v[188:191], v[82:85]
	v_mfma_f32_16x16x32_bf16 v[70:73], v[204:207], v[196:199], v[70:73]
	v_mfma_f32_16x16x32_bf16 v[66:69], v[212:215], v[196:199], v[66:69]
	s_mov_b32 m0, s39
	v_lshl_add_u64 v[164:165], v[216:217], 0, s[0:1]
	s_barrier
	ds_read_b128 v[160:163], v167 offset:49152
	ds_read_b128 v[176:179], v167 offset:51200
	ds_read_b128 v[184:187], v167 offset:53248
	ds_read_b128 v[192:195], v167 offset:55296
	ds_read_b128 v[168:171], v167 offset:50176
	ds_read_b128 v[180:183], v167 offset:52224
	ds_read_b128 v[188:191], v167 offset:54272
	ds_read_b128 v[196:199], v167 offset:56320
	global_load_lds_dwordx4 v[164:165], off
	s_mov_b32 m0, s42
	v_lshl_add_u64 v[164:165], v[218:219], 0, s[0:1]
	global_load_lds_dwordx4 v[164:165], off
	s_barrier

; #define PG8_MMA(ai, bj, At, Bt) do { __builtin_amdgcn_s_setprio(1); _Pragma("unroll") for (int m = 0; m < 4; ++m) _Pragma("unroll") for (int n = 0; n < 2; ++n) _Pragma("unroll") for (int k = 0; k < 2; ++k) \
;         acc[ai][bj][m][n] = __builtin_amdgcn_mfma_f32_16x16x32_bf16(Bt[n][k], At[m][k], acc[ai][bj][m][n], 0, 0, 0); __builtin_amdgcn_s_setprio(0); } while (0)
; #define PG8_WAIT_L(n) asm volatile("s_waitcnt lgkmcnt(" #n ")" ::: "memory")
; #define PG8_BAR __builtin_amdgcn_s_barrier()
; #define PG8_SCHED __builtin_amdgcn_sched_barrier(0)
; template <class Epi, class Sched>
; __device__ __forceinline__ void gemm_phase(PG8_LAS unsigned char* lds, const Gemm g, const Sched& S, const Epi& E) {
;     ...
;             PG8_BAR; PG8_WAIT_L(0); PG8_MMA(1, 0, At, B0); PG8_BAR; PG8_SCHED;
	s_waitcnt lgkmcnt(7)
	v_mfma_f32_16x16x32_bf16 v[62:65], v[144:147], v[160:163], v[62:65]
	v_mfma_f32_16x16x32_bf16 v[58:61], v[152:155], v[160:163], v[58:61]

; #define PG8_MMA(ai, bj, At, Bt) do { __builtin_amdgcn_s_setprio(1); _Pragma("unroll") for (int m = 0; m < 4; ++m) _Pragma("unroll") for (int n = 0; n < 2; ++n) _Pragma("unroll") for (int k = 0; k < 2; ++k) \
;         acc[ai][bj][m][n] = __builtin_amdgcn_mfma_f32_16x16x32_bf16(Bt[n][k], At[m][k], acc[ai][bj][m][n], 0, 0, 0); __builtin_amdgcn_s_setprio(0); } while (0)
; #define PG8_WAIT_L(n) asm volatile("s_waitcnt lgkmcnt(" #n ")" ::: "memory")
; #define PG8_BAR __builtin_amdgcn_s_barrier()
; #define PG8_SCHED __builtin_amdgcn_sched_barrier(0)
; template <class Epi, class Sched>
; __device__ __forceinline__ void gemm_phase(PG8_LAS unsigned char* lds, const Gemm g, const Sched& S, const Epi& E) {
;     ...
;             PG8_BAR; PG8_WAIT_L(0); PG8_MMA(1, 0, At, B0); PG8_BAR; PG8_SCHED;
	s_waitcnt lgkmcnt(6)
	v_mfma_f32_16x16x32_bf16 v[44:47], v[144:147], v[176:179], v[44:47]
	v_mfma_f32_16x16x32_bf16 v[40:43], v[152:155], v[176:179], v[40:43]

; #define PG8_MMA(ai, bj, At, Bt) do { __builtin_amdgcn_s_setprio(1); _Pragma("unroll") for (int m = 0; m < 4; ++m) _Pragma("unroll") for (int n = 0; n < 2; ++n) _Pragma("unroll") for (int k = 0; k < 2; ++k) \
;         acc[ai][bj][m][n] = __builtin_amdgcn_mfma_f32_16x16x32_bf16(Bt[n][k], At[m][k], acc[ai][bj][m][n], 0, 0, 0); __builtin_amdgcn_s_setprio(0); } while (0)
; #define PG8_WAIT_L(n) asm volatile("s_waitcnt lgkmcnt(" #n ")" ::: "memory")
; #define PG8_BAR __builtin_amdgcn_s_barrier()
; #define PG8_SCHED __builtin_amdgcn_sched_barrier(0)
; template <class Epi, class Sched>
; __device__ __forceinline__ void gemm_phase(PG8_LAS unsigned char* lds, const Gemm g, const Sched& S, const Epi& E) {
;     ...
;             PG8_BAR; PG8_WAIT_L(0); PG8_MMA(1, 0, At, B0); PG8_BAR; PG8_SCHED;
	s_waitcnt lgkmcnt(5)
	v_mfma_f32_16x16x32_bf16 v[28:31], v[144:147], v[184:187], v[28:31]
	v_mfma_f32_16x16x32_bf16 v[24:27], v[152:155], v[184:187], v[24:27]

; #define PG8_MMA(ai, bj, At, Bt) do { __builtin_amdgcn_s_setprio(1); _Pragma("unroll") for (int m = 0; m < 4; ++m) _Pragma("unroll") for (int n = 0; n < 2; ++n) _Pragma("unroll") for (int k = 0; k < 2; ++k) \
;         acc[ai][bj][m][n] = __builtin_amdgcn_mfma_f32_16x16x32_bf16(Bt[n][k], At[m][k], acc[ai][bj][m][n], 0, 0, 0); __builtin_amdgcn_s_setprio(0); } while (0)
; #define PG8_WAIT_L(n) asm volatile("s_waitcnt lgkmcnt(" #n ")" ::: "memory")
; #define PG8_BAR __builtin_amdgcn_s_barrier()
; #define PG8_SCHED __builtin_amdgcn_sched_barrier(0)
; template <class Epi, class Sched>
; __device__ __forceinline__ void gemm_phase(PG8_LAS unsigned char* lds, const Gemm g, const Sched& S, const Epi& E) {
;     ...
;             PG8_BAR; PG8_WAIT_L(0); PG8_MMA(1, 0, At, B0); PG8_BAR; PG8_SCHED;
	s_waitcnt lgkmcnt(4)
	v_mfma_f32_16x16x32_bf16 v[12:15], v[144:147], v[192:195], v[12:15]
	v_mfma_f32_16x16x32_bf16 v[8:11], v[152:155], v[192:195], v[8:11]
	s_waitcnt lgkmcnt(3)
	v_mfma_f32_16x16x32_bf16 v[62:65], v[148:151], v[168:171], v[62:65]
	v_mfma_f32_16x16x32_bf16 v[58:61], v[156:159], v[168:171], v[58:61]
	s_waitcnt lgkmcnt(2)
	v_mfma_f32_16x16x32_bf16 v[44:47], v[148:151], v[180:183], v[44:47]
	v_mfma_f32_16x16x32_bf16 v[40:43], v[156:159], v[180:183], v[40:43]
	s_waitcnt lgkmcnt(1)
	v_mfma_f32_16x16x32_bf16 v[28:31], v[148:151], v[188:191], v[28:31]
	v_mfma_f32_16x16x32_bf16 v[24:27], v[156:159], v[188:191], v[24:27]

; #define PG8_STAGE(bufoff, gbase, voff) do { _Pragma("unroll") for (int _i = 0; _i < 2; ++_i) \
;         __builtin_amdgcn_global_load_lds((const unsigned*)((const char*)(gbase) + (voff)[_i]), (PG8_LAS unsigned*)(lds + (bufoff) + ldsw + _i * 8192), 16, 0, 0); } while (0)
; #define PG8_MMA(ai, bj, At, Bt) do { __builtin_amdgcn_s_setprio(1); _Pragma("unroll") for (int m = 0; m < 4; ++m) _Pragma("unroll") for (int n = 0; n < 2; ++n) _Pragma("unroll") for (int k = 0; k < 2; ++k) \
;         acc[ai][bj][m][n] = __builtin_amdgcn_mfma_f32_16x16x32_bf16(Bt[n][k], At[m][k], acc[ai][bj][m][n], 0, 0, 0); __builtin_amdgcn_s_setprio(0); } while (0)
; #define PG8_WAIT_V(n) asm volatile("s_waitcnt vmcnt(" #n ")" ::: "memory")
; #define PG8_WAIT_L(n) asm volatile("s_waitcnt lgkmcnt(" #n ")" ::: "memory")
; #define PG8_BAR __builtin_amdgcn_s_barrier()
; #define PG8_SCHED __builtin_amdgcn_sched_barrier(0)
; template <class Epi, class Sched>
; __device__ __forceinline__ void gemm_phase(PG8_LAS unsigned char* lds, const Gemm g, const Sched& S, const Epi& E) {
;     ...
;             PG8_BAR; PG8_WAIT_L(0); PG8_MMA(1, 0, At, B0); PG8_BAR; PG8_SCHED;
;             PG8_STAGE(PG8_SB(1, 1), b3 + hstep, voffB);
;             PG8_WAIT_V(6); PG8_BAR; PG8_MMA(1, 1, At, B1); PG8_BAR;
;         }
	s_waitcnt lgkmcnt(0)
	v_mfma_f32_16x16x32_bf16 v[12:15], v[148:151], v[196:199], v[12:15]
	v_mfma_f32_16x16x32_bf16 v[8:11], v[156:159], v[196:199], v[8:11]
	s_barrier
	s_add_u32 s12, s12, 0x40080
	s_addc_u32 s13, s13, 0
	s_add_i32 s16, s16, s34
	s_mov_b32 m0, s16
	v_lshl_add_u64 v[144:145], s[12:13], 0, v[134:135]
	global_load_lds_dwordx4 v[144:145], off
	s_add_i32 m0, s16, 0x2000
	v_lshl_add_u64 v[144:145], s[12:13], 0, v[130:131]
	global_load_lds_dwordx4 v[144:145], off
	s_waitcnt vmcnt(6)
	s_barrier
	v_mfma_f32_16x16x32_bf16 v[54:57], v[200:203], v[160:163], v[54:57]
	v_mfma_f32_16x16x32_bf16 v[50:53], v[208:211], v[160:163], v[50:53]
	v_mfma_f32_16x16x32_bf16 v[36:39], v[200:203], v[176:179], v[36:39]
	v_mfma_f32_16x16x32_bf16 v[32:35], v[208:211], v[176:179], v[32:35]
	v_mfma_f32_16x16x32_bf16 v[20:23], v[200:203], v[184:187], v[20:23]
	v_mfma_f32_16x16x32_bf16 v[16:19], v[208:211], v[184:187], v[16:19]
	v_mfma_f32_16x16x32_bf16 v[4:7], v[200:203], v[192:195], v[4:7]
	v_mfma_f32_16x16x32_bf16 v[0:3], v[208:211], v[192:195], v[0:3]
	v_mfma_f32_16x16x32_bf16 v[54:57], v[204:207], v[168:171], v[54:57]
	v_mfma_f32_16x16x32_bf16 v[50:53], v[212:215], v[168:171], v[50:53]
	v_mfma_f32_16x16x32_bf16 v[36:39], v[204:207], v[180:183], v[36:39]
	v_mfma_f32_16x16x32_bf16 v[32:35], v[212:215], v[180:183], v[32:35]
	v_mfma_f32_16x16x32_bf16 v[20:23], v[204:207], v[188:191], v[20:23]
	v_mfma_f32_16x16x32_bf16 v[16:19], v[212:215], v[188:191], v[16:19]
	v_mfma_f32_16x16x32_bf16 v[4:7], v[204:207], v[196:199], v[4:7]
	v_mfma_f32_16x16x32_bf16 v[0:3], v[212:215], v[196:199], v[0:3]
	s_add_i32 s56, s56, 2
	s_add_u32 s6, s6, 0x100
	s_addc_u32 s7, s7, 0
	s_add_u32 s54, s54, 0x100
	s_addc_u32 s55, s55, 0
	s_cmp_gt_u32 s56, 13
	s_barrier
	s_cbranch_scc0 .LBB0_335

; #define PG8_STAGE(bufoff, gbase, voff) do { _Pragma("unroll") for (int _i = 0; _i < 2; ++_i) \
;         __builtin_amdgcn_global_load_lds((const unsigned*)((const char*)(gbase) + (voff)[_i]), (PG8_LAS unsigned*)(lds + (bufoff) + ldsw + _i * 8192), 16, 0, 0); } while (0)
; #define PG8_LDA(dst, b, h) do { _Pragma("unroll") for (int m = 0; m < 4; ++m) _Pragma("unroll") for (int k = 0; k < 2; ++k) dst[m][k] = *(const PG8_LAS bf16x8*)(lds + PG8_SA(b, h) + aoff + m * 2048 + k * 1024); } while (0)
; #define PG8_LDB(dst, b, h) do { _Pragma("unroll") for (int n = 0; n < 2; ++n) _Pragma("unroll") for (int k = 0; k < 2; ++k) dst[n][k] = *(const PG8_LAS bf16x8*)(lds + PG8_SB(b, h) + boff + n * 2048 + k * 1024); } while (0)
; #define PG8_MMA(ai, bj, At, Bt) do { __builtin_amdgcn_s_setprio(1); _Pragma("unroll") for (int m = 0; m < 4; ++m) _Pragma("unroll") for (int n = 0; n < 2; ++n) _Pragma("unroll") for (int k = 0; k < 2; ++k) \
;         acc[ai][bj][m][n] = __builtin_amdgcn_mfma_f32_16x16x32_bf16(Bt[n][k], At[m][k], acc[ai][bj][m][n], 0, 0, 0); __builtin_amdgcn_s_setprio(0); } while (0)
; #define PG8_WAIT_L(n) asm volatile("s_waitcnt lgkmcnt(" #n ")" ::: "memory")
; #define PG8_BAR __builtin_amdgcn_s_barrier()
; #define PG8_SCHED __builtin_amdgcn_sched_barrier(0)
; template <class Epi, class Sched>
; __device__ __forceinline__ void gemm_phase(PG8_LAS unsigned char* lds, const Gemm g, const Sched& S, const Epi& E) {
;     ...
;         const bool has_next = S.next(ui + 1, nxt);
;         const char* nA = has_next ? (const char*)g.A + (size_t)nxt.pm * tstepA + (size_t)nxt.kc * cstep : cA; const char* nB = has_next ? (const char*)g.Bt + (size_t)nxt.pn * tstep + (size_t)nxt.kc * cstep : cB;
;         for (int t = 0; t < nt; t += 2) {
;             const bool last = (t == nt - 2);
;             const char* a1 = cA + (size_t)(t + 1) * kstep;
;             const char* a2 = last ? nA : cA + (size_t)(t + 2) * kstep; const char* b2 = last ? nB : cB + (size_t)(t + 2) * kstep;
;             const char* a3 = a2 + kstep; const char* b3 = b2 + kstep;
;             if (last && has_next) S.a_ready(nxt);
;             PG8_LDB(B0, 0, 0); PG8_SCHED; PG8_LDA(At, 0, 0); PG8_STAGE(PG8_SA(1, 1), a1 + hstep, voffA);
;             PG8_WAIT_L(8); PG8_BAR; PG8_WAIT_L(0); PG8_MMA(0, 0, At, B0); PG8_BAR; PG8_SCHED;
.LBB0_387:
	s_ashr_i32 s39, s38, 31
	s_lshl_b64 s[16:17], s[38:39], 19
	v_readlane_b32 s3, v254, 53
	s_add_u32 s94, s3, s16
	v_readlane_b32 s3, v254, 54
	s_addc_u32 s95, s3, s17
	s_and_b64 s[16:17], s[62:63], exec
	s_cselect_b32 s3, s95, s13
	s_cselect_b32 s26, s94, s12
	s_add_u32 s6, s6, 0x40080
	s_addc_u32 s7, s7, 0
	s_add_u32 s27, s12, 0x100
	s_addc_u32 s29, s13, 0
	s_mov_b32 s30, -2
	s_add_u32 s12, s6, 0xfffc0080
	s_addc_u32 s13, s7, -1
	s_add_i32 s22, 0, 0x10000
	v_add_u32_e32 v48, s22, v250
	ds_read_b128 v[130:133], v48
	ds_read_b128 v[134:137], v48 offset:1024
	ds_read_b128 v[138:141], v48 offset:2048
	ds_read_b128 v[142:145], v48 offset:3072
	s_cmp_eq_u32 s30, 12
	s_cselect_b32 s17, s9, s13
	s_cselect_b32 s16, s8, s12
	s_cselect_b32 s13, s3, s29
	s_cselect_b32 s12, s26, s27
	v_lshl_add_u64 v[192:193], s[6:7], 0, v[184:185]
	s_add_i32 m0, s37, 0xc000
	ds_read_b128 v[146:149], v242
	ds_read_b128 v[154:157], v242 offset:2048
	ds_read_b128 v[162:165], v242 offset:4096
	ds_read_b128 v[170:173], v242 offset:6144
	ds_read_b128 v[150:153], v242 offset:1024
	ds_read_b128 v[158:161], v242 offset:3072
	ds_read_b128 v[166:169], v242 offset:5120
	ds_read_b128 v[188:191], v242 offset:7168
	global_load_lds_dwordx4 v[192:193], off
	s_add_i32 m0, s37, 0xe000
	v_lshl_add_u64 v[192:193], s[6:7], 0, v[186:187]
	global_load_lds_dwordx4 v[192:193], off
	s_waitcnt lgkmcnt(8)
	s_barrier

; #define PG8_STAGE(bufoff, gbase, voff) do { _Pragma("unroll") for (int _i = 0; _i < 2; ++_i) \
;         __builtin_amdgcn_global_load_lds((const unsigned*)((const char*)(gbase) + (voff)[_i]), (PG8_LAS unsigned*)(lds + (bufoff) + ldsw + _i * 8192), 16, 0, 0); } while (0)
; #define PG8_LDA(dst, b, h) do { _Pragma("unroll") for (int m = 0; m < 4; ++m) _Pragma("unroll") for (int k = 0; k < 2; ++k) dst[m][k] = *(const PG8_LAS bf16x8*)(lds + PG8_SA(b, h) + aoff + m * 2048 + k * 1024); } while (0)
; #define PG8_LDB(dst, b, h) do { _Pragma("unroll") for (int n = 0; n < 2; ++n) _Pragma("unroll") for (int k = 0; k < 2; ++k) dst[n][k] = *(const PG8_LAS bf16x8*)(lds + PG8_SB(b, h) + boff + n * 2048 + k * 1024); } while (0)
; #define PG8_MMA(ai, bj, At, Bt) do { __builtin_amdgcn_s_setprio(1); _Pragma("unroll") for (int m = 0; m < 4; ++m) _Pragma("unroll") for (int n = 0; n < 2; ++n) _Pragma("unroll") for (int k = 0; k < 2; ++k) \
;         acc[ai][bj][m][n] = __builtin_amdgcn_mfma_f32_16x16x32_bf16(Bt[n][k], At[m][k], acc[ai][bj][m][n], 0, 0, 0); __builtin_amdgcn_s_setprio(0); } while (0)
; #define PG8_WAIT_L(n) asm volatile("s_waitcnt lgkmcnt(" #n ")" ::: "memory")
; #define PG8_BAR __builtin_amdgcn_s_barrier()
; #define PG8_SCHED __builtin_amdgcn_sched_barrier(0)
; template <class Epi, class Sched>
; __device__ __forceinline__ void gemm_phase(PG8_LAS unsigned char* lds, const Gemm g, const Sched& S, const Epi& E) {
;     ...
;             PG8_LDB(B0, 0, 0); PG8_SCHED; PG8_LDA(At, 0, 0); PG8_STAGE(PG8_SA(1, 1), a1 + hstep, voffA);
;             PG8_WAIT_L(8); PG8_BAR; PG8_WAIT_L(0); PG8_MMA(0, 0, At, B0); PG8_BAR; PG8_SCHED;
	s_waitcnt lgkmcnt(7)
	v_mfma_f32_16x16x32_bf16 v[126:129], v[130:133], v[146:149], 0
	v_mfma_f32_16x16x32_bf16 v[62:65], v[138:141], v[146:149], 0

; #define PG8_STAGE(bufoff, gbase, voff) do { _Pragma("unroll") for (int _i = 0; _i < 2; ++_i) \
;         __builtin_amdgcn_global_load_lds((const unsigned*)((const char*)(gbase) + (voff)[_i]), (PG8_LAS unsigned*)(lds + (bufoff) + ldsw + _i * 8192), 16, 0, 0); } while (0)
; #define PG8_LDA(dst, b, h) do { _Pragma("unroll") for (int m = 0; m < 4; ++m) _Pragma("unroll") for (int k = 0; k < 2; ++k) dst[m][k] = *(const PG8_LAS bf16x8*)(lds + PG8_SA(b, h) + aoff + m * 2048 + k * 1024); } while (0)
; #define PG8_LDB(dst, b, h) do { _Pragma("unroll") for (int n = 0; n < 2; ++n) _Pragma("unroll") for (int k = 0; k < 2; ++k) dst[n][k] = *(const PG8_LAS bf16x8*)(lds + PG8_SB(b, h) + boff + n * 2048 + k * 1024); } while (0)
; #define PG8_MMA(ai, bj, At, Bt) do { __builtin_amdgcn_s_setprio(1); _Pragma("unroll") for (int m = 0; m < 4; ++m) _Pragma("unroll") for (int n = 0; n < 2; ++n) _Pragma("unroll") for (int k = 0; k < 2; ++k) \
;         acc[ai][bj][m][n] = __builtin_amdgcn_mfma_f32_16x16x32_bf16(Bt[n][k], At[m][k], acc[ai][bj][m][n], 0, 0, 0); __builtin_amdgcn_s_setprio(0); } while (0)
; #define PG8_WAIT_L(n) asm volatile("s_waitcnt lgkmcnt(" #n ")" ::: "memory")
; #define PG8_BAR __builtin_amdgcn_s_barrier()
; #define PG8_SCHED __builtin_amdgcn_sched_barrier(0)
; template <class Epi, class Sched>
; __device__ __forceinline__ void gemm_phase(PG8_LAS unsigned char* lds, const Gemm g, const Sched& S, const Epi& E) {
;     ...
;             PG8_LDB(B0, 0, 0); PG8_SCHED; PG8_LDA(At, 0, 0); PG8_STAGE(PG8_SA(1, 1), a1 + hstep, voffA);
;             PG8_WAIT_L(8); PG8_BAR; PG8_WAIT_L(0); PG8_MMA(0, 0, At, B0); PG8_BAR; PG8_SCHED;
	s_waitcnt lgkmcnt(6)
	v_mfma_f32_16x16x32_bf16 v[118:121], v[130:133], v[154:157], 0
	v_mfma_f32_16x16x32_bf16 v[54:57], v[138:141], v[154:157], 0

; #define PG8_STAGE(bufoff, gbase, voff) do { _Pragma("unroll") for (int _i = 0; _i < 2; ++_i) \
;         __builtin_amdgcn_global_load_lds((const unsigned*)((const char*)(gbase) + (voff)[_i]), (PG8_LAS unsigned*)(lds + (bufoff) + ldsw + _i * 8192), 16, 0, 0); } while (0)
; #define PG8_LDA(dst, b, h) do { _Pragma("unroll") for (int m = 0; m < 4; ++m) _Pragma("unroll") for (int k = 0; k < 2; ++k) dst[m][k] = *(const PG8_LAS bf16x8*)(lds + PG8_SA(b, h) + aoff + m * 2048 + k * 1024); } while (0)
; #define PG8_LDB(dst, b, h) do { _Pragma("unroll") for (int n = 0; n < 2; ++n) _Pragma("unroll") for (int k = 0; k < 2; ++k) dst[n][k] = *(const PG8_LAS bf16x8*)(lds + PG8_SB(b, h) + boff + n * 2048 + k * 1024); } while (0)
; #define PG8_MMA(ai, bj, At, Bt) do { __builtin_amdgcn_s_setprio(1); _Pragma("unroll") for (int m = 0; m < 4; ++m) _Pragma("unroll") for (int n = 0; n < 2; ++n) _Pragma("unroll") for (int k = 0; k < 2; ++k) \
;         acc[ai][bj][m][n] = __builtin_amdgcn_mfma_f32_16x16x32_bf16(Bt[n][k], At[m][k], acc[ai][bj][m][n], 0, 0, 0); __builtin_amdgcn_s_setprio(0); } while (0)
; #define PG8_WAIT_L(n) asm volatile("s_waitcnt lgkmcnt(" #n ")" ::: "memory")
; #define PG8_BAR __builtin_amdgcn_s_barrier()
; #define PG8_SCHED __builtin_amdgcn_sched_barrier(0)
; template <class Epi, class Sched>
; __device__ __forceinline__ void gemm_phase(PG8_LAS unsigned char* lds, const Gemm g, const Sched& S, const Epi& E) {
;     ...
;             PG8_LDB(B0, 0, 0); PG8_SCHED; PG8_LDA(At, 0, 0); PG8_STAGE(PG8_SA(1, 1), a1 + hstep, voffA);
;             PG8_WAIT_L(8); PG8_BAR; PG8_WAIT_L(0); PG8_MMA(0, 0, At, B0); PG8_BAR; PG8_SCHED;
	s_waitcnt lgkmcnt(5)
	v_mfma_f32_16x16x32_bf16 v[110:113], v[130:133], v[162:165], 0
	v_mfma_f32_16x16x32_bf16 v[44:47], v[138:141], v[162:165], 0

; #define PG8_STAGE(bufoff, gbase, voff) do { _Pragma("unroll") for (int _i = 0; _i < 2; ++_i) \
;         __builtin_amdgcn_global_load_lds((const unsigned*)((const char*)(gbase) + (voff)[_i]), (PG8_LAS unsigned*)(lds + (bufoff) + ldsw + _i * 8192), 16, 0, 0); } while (0)
; #define PG8_LDA(dst, b, h) do { _Pragma("unroll") for (int m = 0; m < 4; ++m) _Pragma("unroll") for (int k = 0; k < 2; ++k) dst[m][k] = *(const PG8_LAS bf16x8*)(lds + PG8_SA(b, h) + aoff + m * 2048 + k * 1024); } while (0)
; #define PG8_LDB(dst, b, h) do { _Pragma("unroll") for (int n = 0; n < 2; ++n) _Pragma("unroll") for (int k = 0; k < 2; ++k) dst[n][k] = *(const PG8_LAS bf16x8*)(lds + PG8_SB(b, h) + boff + n * 2048 + k * 1024); } while (0)
; #define PG8_MMA(ai, bj, At, Bt) do { __builtin_amdgcn_s_setprio(1); _Pragma("unroll") for (int m = 0; m < 4; ++m) _Pragma("unroll") for (int n = 0; n < 2; ++n) _Pragma("unroll") for (int k = 0; k < 2; ++k) \
;         acc[ai][bj][m][n] = __builtin_amdgcn_mfma_f32_16x16x32_bf16(Bt[n][k], At[m][k], acc[ai][bj][m][n], 0, 0, 0); __builtin_amdgcn_s_setprio(0); } while (0)
; #define PG8_WAIT_L(n) asm volatile("s_waitcnt lgkmcnt(" #n ")" ::: "memory")
; #define PG8_BAR __builtin_amdgcn_s_barrier()
; #define PG8_SCHED __builtin_amdgcn_sched_barrier(0)
; template <class Epi, class Sched>
; __device__ __forceinline__ void gemm_phase(PG8_LAS unsigned char* lds, const Gemm g, const Sched& S, const Epi& E) {
;     ...
;             PG8_LDB(B0, 0, 0); PG8_SCHED; PG8_LDA(At, 0, 0); PG8_STAGE(PG8_SA(1, 1), a1 + hstep, voffA);
;             PG8_WAIT_L(8); PG8_BAR; PG8_WAIT_L(0); PG8_MMA(0, 0, At, B0); PG8_BAR; PG8_SCHED;
	s_waitcnt lgkmcnt(4)
	v_mfma_f32_16x16x32_bf16 v[102:105], v[130:133], v[170:173], 0
	v_mfma_f32_16x16x32_bf16 v[36:39], v[138:141], v[170:173], 0
	s_waitcnt lgkmcnt(3)
	v_mfma_f32_16x16x32_bf16 v[126:129], v[134:137], v[150:153], v[126:129]
	v_mfma_f32_16x16x32_bf16 v[62:65], v[142:145], v[150:153], v[62:65]
	s_waitcnt lgkmcnt(2)
	v_mfma_f32_16x16x32_bf16 v[118:121], v[134:137], v[158:161], v[118:121]
	v_mfma_f32_16x16x32_bf16 v[54:57], v[142:145], v[158:161], v[54:57]
	s_waitcnt lgkmcnt(1)
	v_mfma_f32_16x16x32_bf16 v[110:113], v[134:137], v[166:169], v[110:113]
	v_mfma_f32_16x16x32_bf16 v[44:47], v[142:145], v[166:169], v[44:47]

; #define PG8_STAGE(bufoff, gbase, voff) do { _Pragma("unroll") for (int _i = 0; _i < 2; ++_i) \
;         __builtin_amdgcn_global_load_lds((const unsigned*)((const char*)(gbase) + (voff)[_i]), (PG8_LAS unsigned*)(lds + (bufoff) + ldsw + _i * 8192), 16, 0, 0); } while (0)
; #define PG8_LDB(dst, b, h) do { _Pragma("unroll") for (int n = 0; n < 2; ++n) _Pragma("unroll") for (int k = 0; k < 2; ++k) dst[n][k] = *(const PG8_LAS bf16x8*)(lds + PG8_SB(b, h) + boff + n * 2048 + k * 1024); } while (0)
; #define PG8_MMA(ai, bj, At, Bt) do { __builtin_amdgcn_s_setprio(1); _Pragma("unroll") for (int m = 0; m < 4; ++m) _Pragma("unroll") for (int n = 0; n < 2; ++n) _Pragma("unroll") for (int k = 0; k < 2; ++k) \
;         acc[ai][bj][m][n] = __builtin_amdgcn_mfma_f32_16x16x32_bf16(Bt[n][k], At[m][k], acc[ai][bj][m][n], 0, 0, 0); __builtin_amdgcn_s_setprio(0); } while (0)
; #define PG8_WAIT_L(n) asm volatile("s_waitcnt lgkmcnt(" #n ")" ::: "memory")
; #define PG8_BAR __builtin_amdgcn_s_barrier()
; #define PG8_SCHED __builtin_amdgcn_sched_barrier(0)
; template <class Epi, class Sched>
; __device__ __forceinline__ void gemm_phase(PG8_LAS unsigned char* lds, const Gemm g, const Sched& S, const Epi& E) {
;     ...
;             PG8_WAIT_L(8); PG8_BAR; PG8_WAIT_L(0); PG8_MMA(0, 0, At, B0); PG8_BAR; PG8_SCHED;
;             PG8_LDB(B1, 0, 1); PG8_STAGE(PG8_SB(0, 0), b2, voffB);
	s_waitcnt lgkmcnt(0)
	v_mfma_f32_16x16x32_bf16 v[102:105], v[134:137], v[188:191], v[102:105]
	v_mfma_f32_16x16x32_bf16 v[36:39], v[142:145], v[188:191], v[36:39]
	s_barrier
	s_add_i32 s31, 0, 0x14000
	s_add_i32 s22, s22, s36
	v_add_u32_e32 v48, s31, v250
	v_lshl_add_u64 v[208:209], s[12:13], 0, v[178:179]
	s_mov_b32 m0, s22
	ds_read_b128 v[192:195], v48
	ds_read_b128 v[200:203], v48 offset:2048
	ds_read_b128 v[196:199], v48 offset:1024
	ds_read_b128 v[204:207], v48 offset:3072
	global_load_lds_dwordx4 v[208:209], off
	s_add_i32 m0, s22, 0x2000
	v_lshl_add_u64 v[210:211], s[12:13], 0, v[182:183]
	global_load_lds_dwordx4 v[210:211], off
	s_barrier

; #define PG8_MMA(ai, bj, At, Bt) do { __builtin_amdgcn_s_setprio(1); _Pragma("unroll") for (int m = 0; m < 4; ++m) _Pragma("unroll") for (int n = 0; n < 2; ++n) _Pragma("unroll") for (int k = 0; k < 2; ++k) \
;         acc[ai][bj][m][n] = __builtin_amdgcn_mfma_f32_16x16x32_bf16(Bt[n][k], At[m][k], acc[ai][bj][m][n], 0, 0, 0); __builtin_amdgcn_s_setprio(0); } while (0)
; #define PG8_WAIT_L(n) asm volatile("s_waitcnt lgkmcnt(" #n ")" ::: "memory")
; #define PG8_BAR __builtin_amdgcn_s_barrier()
; template <class Epi, class Sched>
; __device__ __forceinline__ void gemm_phase(PG8_LAS unsigned char* lds, const Gemm g, const Sched& S, const Epi& E) {
;     ...
;             PG8_BAR; PG8_WAIT_L(0); PG8_MMA(0, 1, At, B1); PG8_BAR;
	s_waitcnt lgkmcnt(3)
	v_mfma_f32_16x16x32_bf16 v[122:125], v[192:195], v[146:149], 0

; #define PG8_MMA(ai, bj, At, Bt) do { __builtin_amdgcn_s_setprio(1); _Pragma("unroll") for (int m = 0; m < 4; ++m) _Pragma("unroll") for (int n = 0; n < 2; ++n) _Pragma("unroll") for (int k = 0; k < 2; ++k) \
;         acc[ai][bj][m][n] = __builtin_amdgcn_mfma_f32_16x16x32_bf16(Bt[n][k], At[m][k], acc[ai][bj][m][n], 0, 0, 0); __builtin_amdgcn_s_setprio(0); } while (0)
; #define PG8_WAIT_L(n) asm volatile("s_waitcnt lgkmcnt(" #n ")" ::: "memory")
; #define PG8_BAR __builtin_amdgcn_s_barrier()
; template <class Epi, class Sched>
; __device__ __forceinline__ void gemm_phase(PG8_LAS unsigned char* lds, const Gemm g, const Sched& S, const Epi& E) {
;     ...
;             PG8_BAR; PG8_WAIT_L(0); PG8_MMA(0, 1, At, B1); PG8_BAR;
	s_waitcnt lgkmcnt(2)
	v_mfma_f32_16x16x32_bf16 v[58:61], v[200:203], v[146:149], 0
	v_mfma_f32_16x16x32_bf16 v[114:117], v[192:195], v[154:157], 0
	v_mfma_f32_16x16x32_bf16 v[50:53], v[200:203], v[154:157], 0
	v_mfma_f32_16x16x32_bf16 v[106:109], v[192:195], v[162:165], 0
	v_mfma_f32_16x16x32_bf16 v[40:43], v[200:203], v[162:165], 0
	v_mfma_f32_16x16x32_bf16 v[98:101], v[192:195], v[170:173], 0
	v_mfma_f32_16x16x32_bf16 v[32:35], v[200:203], v[170:173], 0
	s_waitcnt lgkmcnt(1)
	v_mfma_f32_16x16x32_bf16 v[122:125], v[196:199], v[150:153], v[122:125]

; #define PG8_STAGE(bufoff, gbase, voff) do { _Pragma("unroll") for (int _i = 0; _i < 2; ++_i) \
;         __builtin_amdgcn_global_load_lds((const unsigned*)((const char*)(gbase) + (voff)[_i]), (PG8_LAS unsigned*)(lds + (bufoff) + ldsw + _i * 8192), 16, 0, 0); } while (0)
; #define PG8_LDA(dst, b, h) do { _Pragma("unroll") for (int m = 0; m < 4; ++m) _Pragma("unroll") for (int k = 0; k < 2; ++k) dst[m][k] = *(const PG8_LAS bf16x8*)(lds + PG8_SA(b, h) + aoff + m * 2048 + k * 1024); } while (0)
; #define PG8_MMA(ai, bj, At, Bt) do { __builtin_amdgcn_s_setprio(1); _Pragma("unroll") for (int m = 0; m < 4; ++m) _Pragma("unroll") for (int n = 0; n < 2; ++n) _Pragma("unroll") for (int k = 0; k < 2; ++k) \
;         acc[ai][bj][m][n] = __builtin_amdgcn_mfma_f32_16x16x32_bf16(Bt[n][k], At[m][k], acc[ai][bj][m][n], 0, 0, 0); __builtin_amdgcn_s_setprio(0); } while (0)
; #define PG8_WAIT_L(n) asm volatile("s_waitcnt lgkmcnt(" #n ")" ::: "memory")
; #define PG8_BAR __builtin_amdgcn_s_barrier()
; template <class Epi, class Sched>
; __device__ __forceinline__ void gemm_phase(PG8_LAS unsigned char* lds, const Gemm g, const Sched& S, const Epi& E) {
;     ...
;             PG8_BAR; PG8_WAIT_L(0); PG8_MMA(0, 1, At, B1); PG8_BAR;
;             PG8_LDA(At, 0, 1); PG8_STAGE(PG8_SA(0, 0), a2, voffA);
	s_waitcnt lgkmcnt(0)
	v_mfma_f32_16x16x32_bf16 v[58:61], v[204:207], v[150:153], v[58:61]
	v_mfma_f32_16x16x32_bf16 v[114:117], v[196:199], v[158:161], v[114:117]
	v_mfma_f32_16x16x32_bf16 v[50:53], v[204:207], v[158:161], v[50:53]
	v_mfma_f32_16x16x32_bf16 v[106:109], v[196:199], v[166:169], v[106:109]
	v_mfma_f32_16x16x32_bf16 v[40:43], v[204:207], v[166:169], v[40:43]
	v_mfma_f32_16x16x32_bf16 v[98:101], v[196:199], v[188:191], v[98:101]
	v_mfma_f32_16x16x32_bf16 v[32:35], v[204:207], v[188:191], v[32:35]
	s_mov_b32 m0, s37
	v_lshl_add_u64 v[212:213], s[16:17], 0, v[176:177]
	s_barrier
	ds_read_b128 v[146:149], v242 offset:16384
	ds_read_b128 v[154:157], v242 offset:18432
	ds_read_b128 v[162:165], v242 offset:20480
	ds_read_b128 v[170:173], v242 offset:22528
	ds_read_b128 v[150:153], v242 offset:17408
	ds_read_b128 v[158:161], v242 offset:19456
	ds_read_b128 v[166:169], v242 offset:21504
	ds_read_b128 v[188:191], v242 offset:23552
	global_load_lds_dwordx4 v[212:213], off
	s_mov_b32 m0, s10
	v_lshl_add_u64 v[214:215], s[16:17], 0, v[180:181]
	global_load_lds_dwordx4 v[214:215], off
	s_barrier

; #define PG8_MMA(ai, bj, At, Bt) do { __builtin_amdgcn_s_setprio(1); _Pragma("unroll") for (int m = 0; m < 4; ++m) _Pragma("unroll") for (int n = 0; n < 2; ++n) _Pragma("unroll") for (int k = 0; k < 2; ++k) \
;         acc[ai][bj][m][n] = __builtin_amdgcn_mfma_f32_16x16x32_bf16(Bt[n][k], At[m][k], acc[ai][bj][m][n], 0, 0, 0); __builtin_amdgcn_s_setprio(0); } while (0)
; #define PG8_WAIT_L(n) asm volatile("s_waitcnt lgkmcnt(" #n ")" ::: "memory")
; #define PG8_BAR __builtin_amdgcn_s_barrier()
; #define PG8_SCHED __builtin_amdgcn_sched_barrier(0)
; template <class Epi, class Sched>
; __device__ __forceinline__ void gemm_phase(PG8_LAS unsigned char* lds, const Gemm g, const Sched& S, const Epi& E) {
;     ...
;             PG8_BAR; PG8_WAIT_L(0); PG8_MMA(1, 0, At, B0); PG8_BAR; PG8_SCHED;
	s_waitcnt lgkmcnt(7)
	v_mfma_f32_16x16x32_bf16 v[94:97], v[130:133], v[146:149], 0
	v_mfma_f32_16x16x32_bf16 v[28:31], v[138:141], v[146:149], 0

; #define PG8_MMA(ai, bj, At, Bt) do { __builtin_amdgcn_s_setprio(1); _Pragma("unroll") for (int m = 0; m < 4; ++m) _Pragma("unroll") for (int n = 0; n < 2; ++n) _Pragma("unroll") for (int k = 0; k < 2; ++k) \
;         acc[ai][bj][m][n] = __builtin_amdgcn_mfma_f32_16x16x32_bf16(Bt[n][k], At[m][k], acc[ai][bj][m][n], 0, 0, 0); __builtin_amdgcn_s_setprio(0); } while (0)
; #define PG8_WAIT_L(n) asm volatile("s_waitcnt lgkmcnt(" #n ")" ::: "memory")
; #define PG8_BAR __builtin_amdgcn_s_barrier()
; #define PG8_SCHED __builtin_amdgcn_sched_barrier(0)
; template <class Epi, class Sched>
; __device__ __forceinline__ void gemm_phase(PG8_LAS unsigned char* lds, const Gemm g, const Sched& S, const Epi& E) {
;     ...
;             PG8_BAR; PG8_WAIT_L(0); PG8_MMA(1, 0, At, B0); PG8_BAR; PG8_SCHED;
	s_waitcnt lgkmcnt(6)
	v_mfma_f32_16x16x32_bf16 v[86:89], v[130:133], v[154:157], 0
	v_mfma_f32_16x16x32_bf16 v[20:23], v[138:141], v[154:157], 0

; #define PG8_MMA(ai, bj, At, Bt) do { __builtin_amdgcn_s_setprio(1); _Pragma("unroll") for (int m = 0; m < 4; ++m) _Pragma("unroll") for (int n = 0; n < 2; ++n) _Pragma("unroll") for (int k = 0; k < 2; ++k) \
;         acc[ai][bj][m][n] = __builtin_amdgcn_mfma_f32_16x16x32_bf16(Bt[n][k], At[m][k], acc[ai][bj][m][n], 0, 0, 0); __builtin_amdgcn_s_setprio(0); } while (0)
; #define PG8_WAIT_L(n) asm volatile("s_waitcnt lgkmcnt(" #n ")" ::: "memory")
; #define PG8_BAR __builtin_amdgcn_s_barrier()
; #define PG8_SCHED __builtin_amdgcn_sched_barrier(0)
; template <class Epi, class Sched>
; __device__ __forceinline__ void gemm_phase(PG8_LAS unsigned char* lds, const Gemm g, const Sched& S, const Epi& E) {
;     ...
;             PG8_BAR; PG8_WAIT_L(0); PG8_MMA(1, 0, At, B0); PG8_BAR; PG8_SCHED;
	s_waitcnt lgkmcnt(5)
	v_mfma_f32_16x16x32_bf16 v[78:81], v[130:133], v[162:165], 0
	v_mfma_f32_16x16x32_bf16 v[12:15], v[138:141], v[162:165], 0

; #define PG8_MMA(ai, bj, At, Bt) do { __builtin_amdgcn_s_setprio(1); _Pragma("unroll") for (int m = 0; m < 4; ++m) _Pragma("unroll") for (int n = 0; n < 2; ++n) _Pragma("unroll") for (int k = 0; k < 2; ++k) \
;         acc[ai][bj][m][n] = __builtin_amdgcn_mfma_f32_16x16x32_bf16(Bt[n][k], At[m][k], acc[ai][bj][m][n], 0, 0, 0); __builtin_amdgcn_s_setprio(0); } while (0)
; #define PG8_WAIT_L(n) asm volatile("s_waitcnt lgkmcnt(" #n ")" ::: "memory")
; #define PG8_BAR __builtin_amdgcn_s_barrier()
; #define PG8_SCHED __builtin_amdgcn_sched_barrier(0)
; template <class Epi, class Sched>
; __device__ __forceinline__ void gemm_phase(PG8_LAS unsigned char* lds, const Gemm g, const Sched& S, const Epi& E) {
;     ...
;             PG8_BAR; PG8_WAIT_L(0); PG8_MMA(1, 0, At, B0); PG8_BAR; PG8_SCHED;
	s_waitcnt lgkmcnt(4)
	v_mfma_f32_16x16x32_bf16 v[70:73], v[130:133], v[170:173], 0
	v_mfma_f32_16x16x32_bf16 v[4:7], v[138:141], v[170:173], 0
	s_waitcnt lgkmcnt(3)
	v_mfma_f32_16x16x32_bf16 v[94:97], v[134:137], v[150:153], v[94:97]
	v_mfma_f32_16x16x32_bf16 v[28:31], v[142:145], v[150:153], v[28:31]
	s_waitcnt lgkmcnt(2)
	v_mfma_f32_16x16x32_bf16 v[86:89], v[134:137], v[158:161], v[86:89]
	v_mfma_f32_16x16x32_bf16 v[20:23], v[142:145], v[158:161], v[20:23]
	s_waitcnt lgkmcnt(1)
	v_mfma_f32_16x16x32_bf16 v[78:81], v[134:137], v[166:169], v[78:81]
	v_mfma_f32_16x16x32_bf16 v[12:15], v[142:145], v[166:169], v[12:15]

; #define PG8_STAGE(bufoff, gbase, voff) do { _Pragma("unroll") for (int _i = 0; _i < 2; ++_i) \
;         __builtin_amdgcn_global_load_lds((const unsigned*)((const char*)(gbase) + (voff)[_i]), (PG8_LAS unsigned*)(lds + (bufoff) + ldsw + _i * 8192), 16, 0, 0); } while (0)
; #define PG8_LDA(dst, b, h) do { _Pragma("unroll") for (int m = 0; m < 4; ++m) _Pragma("unroll") for (int k = 0; k < 2; ++k) dst[m][k] = *(const PG8_LAS bf16x8*)(lds + PG8_SA(b, h) + aoff + m * 2048 + k * 1024); } while (0)
; #define PG8_LDB(dst, b, h) do { _Pragma("unroll") for (int n = 0; n < 2; ++n) _Pragma("unroll") for (int k = 0; k < 2; ++k) dst[n][k] = *(const PG8_LAS bf16x8*)(lds + PG8_SB(b, h) + boff + n * 2048 + k * 1024); } while (0)
; #define PG8_MMA(ai, bj, At, Bt) do { __builtin_amdgcn_s_setprio(1); _Pragma("unroll") for (int m = 0; m < 4; ++m) _Pragma("unroll") for (int n = 0; n < 2; ++n) _Pragma("unroll") for (int k = 0; k < 2; ++k) \
;         acc[ai][bj][m][n] = __builtin_amdgcn_mfma_f32_16x16x32_bf16(Bt[n][k], At[m][k], acc[ai][bj][m][n], 0, 0, 0); __builtin_amdgcn_s_setprio(0); } while (0)
; #define PG8_WAIT_V(n) asm volatile("s_waitcnt vmcnt(" #n ")" ::: "memory")
; #define PG8_WAIT_L(n) asm volatile("s_waitcnt lgkmcnt(" #n ")" ::: "memory")
; #define PG8_BAR __builtin_amdgcn_s_barrier()
; #define PG8_SCHED __builtin_amdgcn_sched_barrier(0)
; template <class Epi, class Sched>
; __device__ __forceinline__ void gemm_phase(PG8_LAS unsigned char* lds, const Gemm g, const Sched& S, const Epi& E) {
;     ...
;             PG8_BAR; PG8_WAIT_L(0); PG8_MMA(1, 0, At, B0); PG8_BAR; PG8_SCHED;
;             PG8_STAGE(PG8_SB(0, 1), b2 + hstep, voffB);
;             PG8_WAIT_V(6); PG8_BAR; PG8_MMA(1, 1, At, B1); PG8_BAR;
;             PG8_LDB(B0, 1, 0); PG8_SCHED; PG8_LDA(At, 1, 0); PG8_STAGE(PG8_SA(0, 1), a2 + hstep, voffA);
;             PG8_WAIT_L(8); PG8_BAR; PG8_WAIT_L(0); PG8_MMA(0, 0, At, B0); PG8_BAR; PG8_SCHED;
	s_waitcnt lgkmcnt(0)
	v_mfma_f32_16x16x32_bf16 v[70:73], v[134:137], v[188:191], v[70:73]
	v_mfma_f32_16x16x32_bf16 v[4:7], v[142:145], v[188:191], v[4:7]
	s_barrier
	s_add_u32 s22, s12, 0x40000
	s_addc_u32 s23, s13, 0
	s_add_i32 s31, s31, s36
	s_mov_b32 m0, s31
	v_lshl_add_u64 v[130:131], s[22:23], 0, v[178:179]
	global_load_lds_dwordx4 v[130:131], off
	s_add_i32 m0, s31, 0x2000
	v_lshl_add_u64 v[130:131], s[22:23], 0, v[182:183]
	global_load_lds_dwordx4 v[130:131], off
	s_waitcnt vmcnt(6)
	s_barrier
	v_mfma_f32_16x16x32_bf16 v[90:93], v[192:195], v[146:149], 0
	v_mfma_f32_16x16x32_bf16 v[24:27], v[200:203], v[146:149], 0
	v_mfma_f32_16x16x32_bf16 v[82:85], v[192:195], v[154:157], 0
	v_mfma_f32_16x16x32_bf16 v[16:19], v[200:203], v[154:157], 0
	v_mfma_f32_16x16x32_bf16 v[74:77], v[192:195], v[162:165], 0
	v_mfma_f32_16x16x32_bf16 v[8:11], v[200:203], v[162:165], 0
	v_mfma_f32_16x16x32_bf16 v[66:69], v[192:195], v[170:173], 0
	v_mfma_f32_16x16x32_bf16 v[0:3], v[200:203], v[170:173], 0
	v_mfma_f32_16x16x32_bf16 v[90:93], v[196:199], v[150:153], v[90:93]
	v_mfma_f32_16x16x32_bf16 v[24:27], v[204:207], v[150:153], v[24:27]
	v_mfma_f32_16x16x32_bf16 v[82:85], v[196:199], v[158:161], v[82:85]
	v_mfma_f32_16x16x32_bf16 v[16:19], v[204:207], v[158:161], v[16:19]
	v_mfma_f32_16x16x32_bf16 v[74:77], v[196:199], v[166:169], v[74:77]
	v_mfma_f32_16x16x32_bf16 v[8:11], v[204:207], v[166:169], v[8:11]
	v_mfma_f32_16x16x32_bf16 v[66:69], v[196:199], v[188:191], v[66:69]
	v_mfma_f32_16x16x32_bf16 v[0:3], v[204:207], v[188:191], v[0:3]
	s_add_i32 s22, 0, 0x18000
	v_add_u32_e32 v48, s22, v250
	s_barrier
	ds_read_b128 v[130:133], v48
	ds_read_b128 v[134:137], v48 offset:1024
	ds_read_b128 v[138:141], v48 offset:2048
	ds_read_b128 v[142:145], v48 offset:3072
	s_add_u32 s16, s16, 0x40000
	s_addc_u32 s17, s17, 0
	s_mov_b32 m0, s11
	v_lshl_add_u64 v[192:193], s[16:17], 0, v[176:177]
	ds_read_b128 v[146:149], v242 offset:32768
	ds_read_b128 v[154:157], v242 offset:34816
	ds_read_b128 v[162:165], v242 offset:36864
	ds_read_b128 v[170:173], v242 offset:38912
	ds_read_b128 v[150:153], v242 offset:33792
	ds_read_b128 v[158:161], v242 offset:35840
	ds_read_b128 v[166:169], v242 offset:37888
	ds_read_b128 v[188:191], v242 offset:39936
	global_load_lds_dwordx4 v[192:193], off
	s_mov_b32 m0, s24
	v_lshl_add_u64 v[192:193], s[16:17], 0, v[180:181]
	global_load_lds_dwordx4 v[192:193], off
	s_waitcnt lgkmcnt(8)
	s_barrier

; #define PG8_MMA(ai, bj, At, Bt) do { __builtin_amdgcn_s_setprio(1); _Pragma("unroll") for (int m = 0; m < 4; ++m) _Pragma("unroll") for (int n = 0; n < 2; ++n) _Pragma("unroll") for (int k = 0; k < 2; ++k) \
;         acc[ai][bj][m][n] = __builtin_amdgcn_mfma_f32_16x16x32_bf16(Bt[n][k], At[m][k], acc[ai][bj][m][n], 0, 0, 0); __builtin_amdgcn_s_setprio(0); } while (0)
; #define PG8_WAIT_L(n) asm volatile("s_waitcnt lgkmcnt(" #n ")" ::: "memory")
; #define PG8_BAR __builtin_amdgcn_s_barrier()
; #define PG8_SCHED __builtin_amdgcn_sched_barrier(0)
; template <class Epi, class Sched>
; __device__ __forceinline__ void gemm_phase(PG8_LAS unsigned char* lds, const Gemm g, const Sched& S, const Epi& E) {
;     ...
;             PG8_WAIT_L(8); PG8_BAR; PG8_WAIT_L(0); PG8_MMA(0, 0, At, B0); PG8_BAR; PG8_SCHED;
	s_waitcnt lgkmcnt(7)
	v_mfma_f32_16x16x32_bf16 v[126:129], v[130:133], v[146:149], v[126:129]
	v_mfma_f32_16x16x32_bf16 v[62:65], v[138:141], v[146:149], v[62:65]

; #define PG8_MMA(ai, bj, At, Bt) do { __builtin_amdgcn_s_setprio(1); _Pragma("unroll") for (int m = 0; m < 4; ++m) _Pragma("unroll") for (int n = 0; n < 2; ++n) _Pragma("unroll") for (int k = 0; k < 2; ++k) \
;         acc[ai][bj][m][n] = __builtin_amdgcn_mfma_f32_16x16x32_bf16(Bt[n][k], At[m][k], acc[ai][bj][m][n], 0, 0, 0); __builtin_amdgcn_s_setprio(0); } while (0)
; #define PG8_WAIT_L(n) asm volatile("s_waitcnt lgkmcnt(" #n ")" ::: "memory")
; #define PG8_BAR __builtin_amdgcn_s_barrier()
; #define PG8_SCHED __builtin_amdgcn_sched_barrier(0)
; template <class Epi, class Sched>
; __device__ __forceinline__ void gemm_phase(PG8_LAS unsigned char* lds, const Gemm g, const Sched& S, const Epi& E) {
;     ...
;             PG8_WAIT_L(8); PG8_BAR; PG8_WAIT_L(0); PG8_MMA(0, 0, At, B0); PG8_BAR; PG8_SCHED;
	s_waitcnt lgkmcnt(6)
	v_mfma_f32_16x16x32_bf16 v[118:121], v[130:133], v[154:157], v[118:121]
	v_mfma_f32_16x16x32_bf16 v[54:57], v[138:141], v[154:157], v[54:57]

; #define PG8_MMA(ai, bj, At, Bt) do { __builtin_amdgcn_s_setprio(1); _Pragma("unroll") for (int m = 0; m < 4; ++m) _Pragma("unroll") for (int n = 0; n < 2; ++n) _Pragma("unroll") for (int k = 0; k < 2; ++k) \
;         acc[ai][bj][m][n] = __builtin_amdgcn_mfma_f32_16x16x32_bf16(Bt[n][k], At[m][k], acc[ai][bj][m][n], 0, 0, 0); __builtin_amdgcn_s_setprio(0); } while (0)
; #define PG8_WAIT_L(n) asm volatile("s_waitcnt lgkmcnt(" #n ")" ::: "memory")
; #define PG8_BAR __builtin_amdgcn_s_barrier()
; #define PG8_SCHED __builtin_amdgcn_sched_barrier(0)
; template <class Epi, class Sched>
; __device__ __forceinline__ void gemm_phase(PG8_LAS unsigned char* lds, const Gemm g, const Sched& S, const Epi& E) {
;     ...
;             PG8_WAIT_L(8); PG8_BAR; PG8_WAIT_L(0); PG8_MMA(0, 0, At, B0); PG8_BAR; PG8_SCHED;
	s_waitcnt lgkmcnt(5)
	v_mfma_f32_16x16x32_bf16 v[110:113], v[130:133], v[162:165], v[110:113]
	v_mfma_f32_16x16x32_bf16 v[44:47], v[138:141], v[162:165], v[44:47]

; #define PG8_MMA(ai, bj, At, Bt) do { __builtin_amdgcn_s_setprio(1); _Pragma("unroll") for (int m = 0; m < 4; ++m) _Pragma("unroll") for (int n = 0; n < 2; ++n) _Pragma("unroll") for (int k = 0; k < 2; ++k) \
;         acc[ai][bj][m][n] = __builtin_amdgcn_mfma_f32_16x16x32_bf16(Bt[n][k], At[m][k], acc[ai][bj][m][n], 0, 0, 0); __builtin_amdgcn_s_setprio(0); } while (0)
; #define PG8_WAIT_L(n) asm volatile("s_waitcnt lgkmcnt(" #n ")" ::: "memory")
; #define PG8_BAR __builtin_amdgcn_s_barrier()
; #define PG8_SCHED __builtin_amdgcn_sched_barrier(0)
; template <class Epi, class Sched>
; __device__ __forceinline__ void gemm_phase(PG8_LAS unsigned char* lds, const Gemm g, const Sched& S, const Epi& E) {
;     ...
;             PG8_WAIT_L(8); PG8_BAR; PG8_WAIT_L(0); PG8_MMA(0, 0, At, B0); PG8_BAR; PG8_SCHED;
	s_waitcnt lgkmcnt(4)
	v_mfma_f32_16x16x32_bf16 v[102:105], v[130:133], v[170:173], v[102:105]
	v_mfma_f32_16x16x32_bf16 v[36:39], v[138:141], v[170:173], v[36:39]
	s_waitcnt lgkmcnt(3)
	v_mfma_f32_16x16x32_bf16 v[126:129], v[134:137], v[150:153], v[126:129]
	v_mfma_f32_16x16x32_bf16 v[62:65], v[142:145], v[150:153], v[62:65]
	s_waitcnt lgkmcnt(2)
	v_mfma_f32_16x16x32_bf16 v[118:121], v[134:137], v[158:161], v[118:121]
	v_mfma_f32_16x16x32_bf16 v[54:57], v[142:145], v[158:161], v[54:57]
	s_waitcnt lgkmcnt(1)
	v_mfma_f32_16x16x32_bf16 v[110:113], v[134:137], v[166:169], v[110:113]
	v_mfma_f32_16x16x32_bf16 v[44:47], v[142:145], v[166:169], v[44:47]

; #define PG8_STAGE(bufoff, gbase, voff) do { _Pragma("unroll") for (int _i = 0; _i < 2; ++_i) \
;         __builtin_amdgcn_global_load_lds((const unsigned*)((const char*)(gbase) + (voff)[_i]), (PG8_LAS unsigned*)(lds + (bufoff) + ldsw + _i * 8192), 16, 0, 0); } while (0)
; #define PG8_LDB(dst, b, h) do { _Pragma("unroll") for (int n = 0; n < 2; ++n) _Pragma("unroll") for (int k = 0; k < 2; ++k) dst[n][k] = *(const PG8_LAS bf16x8*)(lds + PG8_SB(b, h) + boff + n * 2048 + k * 1024); } while (0)
; #define PG8_MMA(ai, bj, At, Bt) do { __builtin_amdgcn_s_setprio(1); _Pragma("unroll") for (int m = 0; m < 4; ++m) _Pragma("unroll") for (int n = 0; n < 2; ++n) _Pragma("unroll") for (int k = 0; k < 2; ++k) \
;         acc[ai][bj][m][n] = __builtin_amdgcn_mfma_f32_16x16x32_bf16(Bt[n][k], At[m][k], acc[ai][bj][m][n], 0, 0, 0); __builtin_amdgcn_s_setprio(0); } while (0)
; #define PG8_WAIT_L(n) asm volatile("s_waitcnt lgkmcnt(" #n ")" ::: "memory")
; #define PG8_BAR __builtin_amdgcn_s_barrier()
; #define PG8_SCHED __builtin_amdgcn_sched_barrier(0)
; template <class Epi, class Sched>
; __device__ __forceinline__ void gemm_phase(PG8_LAS unsigned char* lds, const Gemm g, const Sched& S, const Epi& E) {
;     ...
;             PG8_WAIT_L(8); PG8_BAR; PG8_WAIT_L(0); PG8_MMA(0, 0, At, B0); PG8_BAR; PG8_SCHED;
;             PG8_LDB(B1, 1, 1); PG8_STAGE(PG8_SB(1, 0), b3, voffB);
	s_waitcnt lgkmcnt(0)
	v_mfma_f32_16x16x32_bf16 v[102:105], v[134:137], v[188:191], v[102:105]
	v_mfma_f32_16x16x32_bf16 v[36:39], v[142:145], v[188:191], v[36:39]
	s_barrier
	s_add_i32 s16, 0, 0x1c000
	s_add_i32 s17, s22, s36
	v_add_u32_e32 v48, s16, v250
	v_lshl_add_u64 v[208:209], v[208:209], 0, s[0:1]
	s_mov_b32 m0, s17
	ds_read_b128 v[192:195], v48
	ds_read_b128 v[200:203], v48 offset:2048
	ds_read_b128 v[196:199], v48 offset:1024
	ds_read_b128 v[204:207], v48 offset:3072
	global_load_lds_dwordx4 v[208:209], off
	s_add_i32 m0, s17, 0x2000
	v_lshl_add_u64 v[208:209], v[210:211], 0, s[0:1]
	global_load_lds_dwordx4 v[208:209], off
	s_barrier

; #define PG8_MMA(ai, bj, At, Bt) do { __builtin_amdgcn_s_setprio(1); _Pragma("unroll") for (int m = 0; m < 4; ++m) _Pragma("unroll") for (int n = 0; n < 2; ++n) _Pragma("unroll") for (int k = 0; k < 2; ++k) \
;         acc[ai][bj][m][n] = __builtin_amdgcn_mfma_f32_16x16x32_bf16(Bt[n][k], At[m][k], acc[ai][bj][m][n], 0, 0, 0); __builtin_amdgcn_s_setprio(0); } while (0)
; #define PG8_WAIT_L(n) asm volatile("s_waitcnt lgkmcnt(" #n ")" ::: "memory")
; #define PG8_BAR __builtin_amdgcn_s_barrier()
; template <class Epi, class Sched>
; __device__ __forceinline__ void gemm_phase(PG8_LAS unsigned char* lds, const Gemm g, const Sched& S, const Epi& E) {
;     ...
;             PG8_BAR; PG8_WAIT_L(0); PG8_MMA(0, 1, At, B1); PG8_BAR;
	s_waitcnt lgkmcnt(3)
	v_mfma_f32_16x16x32_bf16 v[122:125], v[192:195], v[146:149], v[122:125]

; #define PG8_MMA(ai, bj, At, Bt) do { __builtin_amdgcn_s_setprio(1); _Pragma("unroll") for (int m = 0; m < 4; ++m) _Pragma("unroll") for (int n = 0; n < 2; ++n) _Pragma("unroll") for (int k = 0; k < 2; ++k) \
;         acc[ai][bj][m][n] = __builtin_amdgcn_mfma_f32_16x16x32_bf16(Bt[n][k], At[m][k], acc[ai][bj][m][n], 0, 0, 0); __builtin_amdgcn_s_setprio(0); } while (0)
; #define PG8_WAIT_L(n) asm volatile("s_waitcnt lgkmcnt(" #n ")" ::: "memory")
; #define PG8_BAR __builtin_amdgcn_s_barrier()
; template <class Epi, class Sched>
; __device__ __forceinline__ void gemm_phase(PG8_LAS unsigned char* lds, const Gemm g, const Sched& S, const Epi& E) {
;     ...
;             PG8_BAR; PG8_WAIT_L(0); PG8_MMA(0, 1, At, B1); PG8_BAR;
	s_waitcnt lgkmcnt(2)
	v_mfma_f32_16x16x32_bf16 v[58:61], v[200:203], v[146:149], v[58:61]
	v_mfma_f32_16x16x32_bf16 v[114:117], v[192:195], v[154:157], v[114:117]
	v_mfma_f32_16x16x32_bf16 v[50:53], v[200:203], v[154:157], v[50:53]
	v_mfma_f32_16x16x32_bf16 v[106:109], v[192:195], v[162:165], v[106:109]
	v_mfma_f32_16x16x32_bf16 v[40:43], v[200:203], v[162:165], v[40:43]
	v_mfma_f32_16x16x32_bf16 v[98:101], v[192:195], v[170:173], v[98:101]
	v_mfma_f32_16x16x32_bf16 v[32:35], v[200:203], v[170:173], v[32:35]
	s_waitcnt lgkmcnt(1)
	v_mfma_f32_16x16x32_bf16 v[122:125], v[196:199], v[150:153], v[122:125]

; #define PG8_STAGE(bufoff, gbase, voff) do { _Pragma("unroll") for (int _i = 0; _i < 2; ++_i) \
;         __builtin_amdgcn_global_load_lds((const unsigned*)((const char*)(gbase) + (voff)[_i]), (PG8_LAS unsigned*)(lds + (bufoff) + ldsw + _i * 8192), 16, 0, 0); } while (0)
; #define PG8_LDA(dst, b, h) do { _Pragma("unroll") for (int m = 0; m < 4; ++m) _Pragma("unroll") for (int k = 0; k < 2; ++k) dst[m][k] = *(const PG8_LAS bf16x8*)(lds + PG8_SA(b, h) + aoff + m * 2048 + k * 1024); } while (0)
; #define PG8_MMA(ai, bj, At, Bt) do { __builtin_amdgcn_s_setprio(1); _Pragma("unroll") for (int m = 0; m < 4; ++m) _Pragma("unroll") for (int n = 0; n < 2; ++n) _Pragma("unroll") for (int k = 0; k < 2; ++k) \
;         acc[ai][bj][m][n] = __builtin_amdgcn_mfma_f32_16x16x32_bf16(Bt[n][k], At[m][k], acc[ai][bj][m][n], 0, 0, 0); __builtin_amdgcn_s_setprio(0); } while (0)
; #define PG8_WAIT_L(n) asm volatile("s_waitcnt lgkmcnt(" #n ")" ::: "memory")
; #define PG8_BAR __builtin_amdgcn_s_barrier()
; template <class Epi, class Sched>
; __device__ __forceinline__ void gemm_phase(PG8_LAS unsigned char* lds, const Gemm g, const Sched& S, const Epi& E) {
;     ...
;             PG8_BAR; PG8_WAIT_L(0); PG8_MMA(0, 1, At, B1); PG8_BAR;
;             PG8_LDA(At, 1, 1); PG8_STAGE(PG8_SA(1, 0), a3, voffA);
	s_waitcnt lgkmcnt(0)
	v_mfma_f32_16x16x32_bf16 v[58:61], v[204:207], v[150:153], v[58:61]
	v_mfma_f32_16x16x32_bf16 v[114:117], v[196:199], v[158:161], v[114:117]
	v_mfma_f32_16x16x32_bf16 v[50:53], v[204:207], v[158:161], v[50:53]
	v_mfma_f32_16x16x32_bf16 v[106:109], v[196:199], v[166:169], v[106:109]
	v_mfma_f32_16x16x32_bf16 v[40:43], v[204:207], v[166:169], v[40:43]
	v_mfma_f32_16x16x32_bf16 v[98:101], v[196:199], v[188:191], v[98:101]
	v_mfma_f32_16x16x32_bf16 v[32:35], v[204:207], v[188:191], v[32:35]
	s_mov_b32 m0, s25
	v_lshl_add_u64 v[208:209], v[212:213], 0, s[0:1]
	s_barrier
	ds_read_b128 v[146:149], v242 offset:49152
	ds_read_b128 v[154:157], v242 offset:51200
	ds_read_b128 v[162:165], v242 offset:53248
	ds_read_b128 v[170:173], v242 offset:55296
	ds_read_b128 v[150:153], v242 offset:50176
	ds_read_b128 v[158:161], v242 offset:52224
	ds_read_b128 v[166:169], v242 offset:54272
	ds_read_b128 v[188:191], v242 offset:56320
	global_load_lds_dwordx4 v[208:209], off
	s_mov_b32 m0, s18
	v_lshl_add_u64 v[208:209], v[214:215], 0, s[0:1]
	global_load_lds_dwordx4 v[208:209], off
	s_barrier

; #define PG8_MMA(ai, bj, At, Bt) do { __builtin_amdgcn_s_setprio(1); _Pragma("unroll") for (int m = 0; m < 4; ++m) _Pragma("unroll") for (int n = 0; n < 2; ++n) _Pragma("unroll") for (int k = 0; k < 2; ++k) \
;         acc[ai][bj][m][n] = __builtin_amdgcn_mfma_f32_16x16x32_bf16(Bt[n][k], At[m][k], acc[ai][bj][m][n], 0, 0, 0); __builtin_amdgcn_s_setprio(0); } while (0)
; #define PG8_WAIT_L(n) asm volatile("s_waitcnt lgkmcnt(" #n ")" ::: "memory")
; #define PG8_BAR __builtin_amdgcn_s_barrier()
; #define PG8_SCHED __builtin_amdgcn_sched_barrier(0)
; template <class Epi, class Sched>
; __device__ __forceinline__ void gemm_phase(PG8_LAS unsigned char* lds, const Gemm g, const Sched& S, const Epi& E) {
;     ...
;             PG8_BAR; PG8_WAIT_L(0); PG8_MMA(1, 0, At, B0); PG8_BAR; PG8_SCHED;
	s_waitcnt lgkmcnt(7)
	v_mfma_f32_16x16x32_bf16 v[94:97], v[130:133], v[146:149], v[94:97]
	v_mfma_f32_16x16x32_bf16 v[28:31], v[138:141], v[146:149], v[28:31]

; #define PG8_MMA(ai, bj, At, Bt) do { __builtin_amdgcn_s_setprio(1); _Pragma("unroll") for (int m = 0; m < 4; ++m) _Pragma("unroll") for (int n = 0; n < 2; ++n) _Pragma("unroll") for (int k = 0; k < 2; ++k) \
;         acc[ai][bj][m][n] = __builtin_amdgcn_mfma_f32_16x16x32_bf16(Bt[n][k], At[m][k], acc[ai][bj][m][n], 0, 0, 0); __builtin_amdgcn_s_setprio(0); } while (0)
; #define PG8_WAIT_L(n) asm volatile("s_waitcnt lgkmcnt(" #n ")" ::: "memory")
; #define PG8_BAR __builtin_amdgcn_s_barrier()
; #define PG8_SCHED __builtin_amdgcn_sched_barrier(0)
; template <class Epi, class Sched>
; __device__ __forceinline__ void gemm_phase(PG8_LAS unsigned char* lds, const Gemm g, const Sched& S, const Epi& E) {
;     ...
;             PG8_BAR; PG8_WAIT_L(0); PG8_MMA(1, 0, At, B0); PG8_BAR; PG8_SCHED;
	s_waitcnt lgkmcnt(6)
	v_mfma_f32_16x16x32_bf16 v[86:89], v[130:133], v[154:157], v[86:89]
	v_mfma_f32_16x16x32_bf16 v[20:23], v[138:141], v[154:157], v[20:23]

; #define PG8_MMA(ai, bj, At, Bt) do { __builtin_amdgcn_s_setprio(1); _Pragma("unroll") for (int m = 0; m < 4; ++m) _Pragma("unroll") for (int n = 0; n < 2; ++n) _Pragma("unroll") for (int k = 0; k < 2; ++k) \
;         acc[ai][bj][m][n] = __builtin_amdgcn_mfma_f32_16x16x32_bf16(Bt[n][k], At[m][k], acc[ai][bj][m][n], 0, 0, 0); __builtin_amdgcn_s_setprio(0); } while (0)
; #define PG8_WAIT_L(n) asm volatile("s_waitcnt lgkmcnt(" #n ")" ::: "memory")
; #define PG8_BAR __builtin_amdgcn_s_barrier()
; #define PG8_SCHED __builtin_amdgcn_sched_barrier(0)
; template <class Epi, class Sched>
; __device__ __forceinline__ void gemm_phase(PG8_LAS unsigned char* lds, const Gemm g, const Sched& S, const Epi& E) {
;     ...
;             PG8_BAR; PG8_WAIT_L(0); PG8_MMA(1, 0, At, B0); PG8_BAR; PG8_SCHED;
	s_waitcnt lgkmcnt(5)
	v_mfma_f32_16x16x32_bf16 v[78:81], v[130:133], v[162:165], v[78:81]
	v_mfma_f32_16x16x32_bf16 v[12:15], v[138:141], v[162:165], v[12:15]

; #define PG8_MMA(ai, bj, At, Bt) do { __builtin_amdgcn_s_setprio(1); _Pragma("unroll") for (int m = 0; m < 4; ++m) _Pragma("unroll") for (int n = 0; n < 2; ++n) _Pragma("unroll") for (int k = 0; k < 2; ++k) \
;         acc[ai][bj][m][n] = __builtin_amdgcn_mfma_f32_16x16x32_bf16(Bt[n][k], At[m][k], acc[ai][bj][m][n], 0, 0, 0); __builtin_amdgcn_s_setprio(0); } while (0)
; #define PG8_WAIT_L(n) asm volatile("s_waitcnt lgkmcnt(" #n ")" ::: "memory")
; #define PG8_BAR __builtin_amdgcn_s_barrier()
; #define PG8_SCHED __builtin_amdgcn_sched_barrier(0)
; template <class Epi, class Sched>
; __device__ __forceinline__ void gemm_phase(PG8_LAS unsigned char* lds, const Gemm g, const Sched& S, const Epi& E) {
;     ...
;             PG8_BAR; PG8_WAIT_L(0); PG8_MMA(1, 0, At, B0); PG8_BAR; PG8_SCHED;
	s_waitcnt lgkmcnt(4)
	v_mfma_f32_16x16x32_bf16 v[70:73], v[130:133], v[170:173], v[70:73]
	v_mfma_f32_16x16x32_bf16 v[4:7], v[138:141], v[170:173], v[4:7]
	s_waitcnt lgkmcnt(3)
	v_mfma_f32_16x16x32_bf16 v[94:97], v[134:137], v[150:153], v[94:97]
	v_mfma_f32_16x16x32_bf16 v[28:31], v[142:145], v[150:153], v[28:31]
	s_waitcnt lgkmcnt(2)
	v_mfma_f32_16x16x32_bf16 v[86:89], v[134:137], v[158:161], v[86:89]
	v_mfma_f32_16x16x32_bf16 v[20:23], v[142:145], v[158:161], v[20:23]
	s_waitcnt lgkmcnt(1)
	v_mfma_f32_16x16x32_bf16 v[78:81], v[134:137], v[166:169], v[78:81]
	v_mfma_f32_16x16x32_bf16 v[12:15], v[142:145], v[166:169], v[12:15]

; #define PG8_STAGE(bufoff, gbase, voff) do { _Pragma("unroll") for (int _i = 0; _i < 2; ++_i) \
;         __builtin_amdgcn_global_load_lds((const unsigned*)((const char*)(gbase) + (voff)[_i]), (PG8_LAS unsigned*)(lds + (bufoff) + ldsw + _i * 8192), 16, 0, 0); } while (0)
; #define PG8_LDA(dst, b, h) do { _Pragma("unroll") for (int m = 0; m < 4; ++m) _Pragma("unroll") for (int k = 0; k < 2; ++k) dst[m][k] = *(const PG8_LAS bf16x8*)(lds + PG8_SA(b, h) + aoff + m * 2048 + k * 1024); } while (0)
; #define PG8_LDB(dst, b, h) do { _Pragma("unroll") for (int n = 0; n < 2; ++n) _Pragma("unroll") for (int k = 0; k < 2; ++k) dst[n][k] = *(const PG8_LAS bf16x8*)(lds + PG8_SB(b, h) + boff + n * 2048 + k * 1024); } while (0)
; #define PG8_MMA(ai, bj, At, Bt) do { __builtin_amdgcn_s_setprio(1); _Pragma("unroll") for (int m = 0; m < 4; ++m) _Pragma("unroll") for (int n = 0; n < 2; ++n) _Pragma("unroll") for (int k = 0; k < 2; ++k) \
;         acc[ai][bj][m][n] = __builtin_amdgcn_mfma_f32_16x16x32_bf16(Bt[n][k], At[m][k], acc[ai][bj][m][n], 0, 0, 0); __builtin_amdgcn_s_setprio(0); } while (0)
; #define PG8_WAIT_V(n) asm volatile("s_waitcnt vmcnt(" #n ")" ::: "memory")
; #define PG8_WAIT_L(n) asm volatile("s_waitcnt lgkmcnt(" #n ")" ::: "memory")
; #define PG8_BAR __builtin_amdgcn_s_barrier()
; #define PG8_SCHED __builtin_amdgcn_sched_barrier(0)
; template <class Epi, class Sched>
; __device__ __forceinline__ void gemm_phase(PG8_LAS unsigned char* lds, const Gemm g, const Sched& S, const Epi& E) {
;     ...
;         for (int t = 0; t < nt; t += 2) {
;             const bool last = (t == nt - 2);
;             const char* a1 = cA + (size_t)(t + 1) * kstep;
;             const char* a2 = last ? nA : cA + (size_t)(t + 2) * kstep; const char* b2 = last ? nB : cB + (size_t)(t + 2) * kstep;
;             const char* a3 = a2 + kstep; const char* b3 = b2 + kstep;
;             if (last && has_next) S.a_ready(nxt);
;             PG8_LDB(B0, 0, 0); PG8_SCHED; PG8_LDA(At, 0, 0); PG8_STAGE(PG8_SA(1, 1), a1 + hstep, voffA);
;             PG8_WAIT_L(8); PG8_BAR; PG8_WAIT_L(0); PG8_MMA(0, 0, At, B0); PG8_BAR; PG8_SCHED;
;     ...
;             PG8_BAR; PG8_WAIT_L(0); PG8_MMA(1, 0, At, B0); PG8_BAR; PG8_SCHED;
;             PG8_STAGE(PG8_SB(1, 1), b3 + hstep, voffB);
;             PG8_WAIT_V(6); PG8_BAR; PG8_MMA(1, 1, At, B1); PG8_BAR;
	s_waitcnt lgkmcnt(0)
	v_mfma_f32_16x16x32_bf16 v[70:73], v[134:137], v[188:191], v[70:73]
	v_mfma_f32_16x16x32_bf16 v[4:7], v[142:145], v[188:191], v[4:7]
	s_barrier
	s_add_u32 s12, s12, 0x40080
	s_addc_u32 s13, s13, 0
	s_add_i32 s16, s16, s36
	s_mov_b32 m0, s16
	v_lshl_add_u64 v[130:131], s[12:13], 0, v[178:179]
	global_load_lds_dwordx4 v[130:131], off
	s_add_i32 m0, s16, 0x2000
	v_lshl_add_u64 v[130:131], s[12:13], 0, v[182:183]
	global_load_lds_dwordx4 v[130:131], off
	s_waitcnt vmcnt(6)
	s_barrier
	v_mfma_f32_16x16x32_bf16 v[90:93], v[192:195], v[146:149], v[90:93]
	v_mfma_f32_16x16x32_bf16 v[24:27], v[200:203], v[146:149], v[24:27]
	v_mfma_f32_16x16x32_bf16 v[82:85], v[192:195], v[154:157], v[82:85]
	v_mfma_f32_16x16x32_bf16 v[16:19], v[200:203], v[154:157], v[16:19]
	v_mfma_f32_16x16x32_bf16 v[74:77], v[192:195], v[162:165], v[74:77]
	v_mfma_f32_16x16x32_bf16 v[8:11], v[200:203], v[162:165], v[8:11]
	v_mfma_f32_16x16x32_bf16 v[66:69], v[192:195], v[170:173], v[66:69]
	v_mfma_f32_16x16x32_bf16 v[0:3], v[200:203], v[170:173], v[0:3]
	v_mfma_f32_16x16x32_bf16 v[90:93], v[196:199], v[150:153], v[90:93]
	v_mfma_f32_16x16x32_bf16 v[24:27], v[204:207], v[150:153], v[24:27]
	v_mfma_f32_16x16x32_bf16 v[82:85], v[196:199], v[158:161], v[82:85]
	v_mfma_f32_16x16x32_bf16 v[16:19], v[204:207], v[158:161], v[16:19]
	v_mfma_f32_16x16x32_bf16 v[74:77], v[196:199], v[166:169], v[74:77]
	v_mfma_f32_16x16x32_bf16 v[8:11], v[204:207], v[166:169], v[8:11]
	v_mfma_f32_16x16x32_bf16 v[66:69], v[196:199], v[188:191], v[66:69]
	v_mfma_f32_16x16x32_bf16 v[0:3], v[204:207], v[188:191], v[0:3]
	s_add_i32 s30, s30, 2
	s_add_u32 s6, s6, 0x100
	s_addc_u32 s7, s7, 0
	s_add_u32 s27, s27, 0x100
	s_addc_u32 s29, s29, 0
	s_cmp_gt_u32 s30, 13
	s_barrier
	s_cbranch_scc1 .Lkpeel_exit_388
.LBB0_388:
	s_add_u32 s12, s6, 0xfffc0080
	s_addc_u32 s13, s7, -1
	s_add_i32 s22, 0, 0x10000
	v_add_u32_e32 v48, s22, v250
	ds_read_b128 v[130:133], v48
	ds_read_b128 v[134:137], v48 offset:1024
	ds_read_b128 v[138:141], v48 offset:2048
	ds_read_b128 v[142:145], v48 offset:3072
	s_cmp_eq_u32 s30, 12
	s_cselect_b32 s17, s9, s13
	s_cselect_b32 s16, s8, s12
	s_cselect_b32 s13, s3, s29
	s_cselect_b32 s12, s26, s27
	v_lshl_add_u64 v[192:193], s[6:7], 0, v[184:185]
	s_add_i32 m0, s37, 0xc000
	ds_read_b128 v[146:149], v242
	ds_read_b128 v[154:157], v242 offset:2048
	ds_read_b128 v[162:165], v242 offset:4096
	ds_read_b128 v[170:173], v242 offset:6144
	ds_read_b128 v[150:153], v242 offset:1024
	ds_read_b128 v[158:161], v242 offset:3072
	ds_read_b128 v[166:169], v242 offset:5120
	ds_read_b128 v[188:191], v242 offset:7168
	global_load_lds_dwordx4 v[192:193], off
	s_add_i32 m0, s37, 0xe000
	v_lshl_add_u64 v[192:193], s[6:7], 0, v[186:187]
	global_load_lds_dwordx4 v[192:193], off
	s_waitcnt lgkmcnt(8)
	s_barrier

; #define PG8_MMA(ai, bj, At, Bt) do { __builtin_amdgcn_s_setprio(1); _Pragma("unroll") for (int m = 0; m < 4; ++m) _Pragma("unroll") for (int n = 0; n < 2; ++n) _Pragma("unroll") for (int k = 0; k < 2; ++k) \
;         acc[ai][bj][m][n] = __builtin_amdgcn_mfma_f32_16x16x32_bf16(Bt[n][k], At[m][k], acc[ai][bj][m][n], 0, 0, 0); __builtin_amdgcn_s_setprio(0); } while (0)
; #define PG8_WAIT_L(n) asm volatile("s_waitcnt lgkmcnt(" #n ")" ::: "memory")
; #define PG8_BAR __builtin_amdgcn_s_barrier()
; #define PG8_SCHED __builtin_amdgcn_sched_barrier(0)
; template <class Epi, class Sched>
; __device__ __forceinline__ void gemm_phase(PG8_LAS unsigned char* lds, const Gemm g, const Sched& S, const Epi& E) {
;     ...
;             PG8_WAIT_L(8); PG8_BAR; PG8_WAIT_L(0); PG8_MMA(0, 0, At, B0); PG8_BAR; PG8_SCHED;
	s_waitcnt lgkmcnt(7)
	v_mfma_f32_16x16x32_bf16 v[126:129], v[130:133], v[146:149], v[126:129]
	v_mfma_f32_16x16x32_bf16 v[62:65], v[138:141], v[146:149], v[62:65]

; #define PG8_MMA(ai, bj, At, Bt) do { __builtin_amdgcn_s_setprio(1); _Pragma("unroll") for (int m = 0; m < 4; ++m) _Pragma("unroll") for (int n = 0; n < 2; ++n) _Pragma("unroll") for (int k = 0; k < 2; ++k) \
;         acc[ai][bj][m][n] = __builtin_amdgcn_mfma_f32_16x16x32_bf16(Bt[n][k], At[m][k], acc[ai][bj][m][n], 0, 0, 0); __builtin_amdgcn_s_setprio(0); } while (0)
; #define PG8_WAIT_L(n) asm volatile("s_waitcnt lgkmcnt(" #n ")" ::: "memory")
; #define PG8_BAR __builtin_amdgcn_s_barrier()
; #define PG8_SCHED __builtin_amdgcn_sched_barrier(0)
; template <class Epi, class Sched>
; __device__ __forceinline__ void gemm_phase(PG8_LAS unsigned char* lds, const Gemm g, const Sched& S, const Epi& E) {
;     ...
;             PG8_WAIT_L(8); PG8_BAR; PG8_WAIT_L(0); PG8_MMA(0, 0, At, B0); PG8_BAR; PG8_SCHED;
	s_waitcnt lgkmcnt(6)
	v_mfma_f32_16x16x32_bf16 v[118:121], v[130:133], v[154:157], v[118:121]
	v_mfma_f32_16x16x32_bf16 v[54:57], v[138:141], v[154:157], v[54:57]

; #define PG8_MMA(ai, bj, At, Bt) do { __builtin_amdgcn_s_setprio(1); _Pragma("unroll") for (int m = 0; m < 4; ++m) _Pragma("unroll") for (int n = 0; n < 2; ++n) _Pragma("unroll") for (int k = 0; k < 2; ++k) \
;         acc[ai][bj][m][n] = __builtin_amdgcn_mfma_f32_16x16x32_bf16(Bt[n][k], At[m][k], acc[ai][bj][m][n], 0, 0, 0); __builtin_amdgcn_s_setprio(0); } while (0)
; #define PG8_WAIT_L(n) asm volatile("s_waitcnt lgkmcnt(" #n ")" ::: "memory")
; #define PG8_BAR __builtin_amdgcn_s_barrier()
; #define PG8_SCHED __builtin_amdgcn_sched_barrier(0)
; template <class Epi, class Sched>
; __device__ __forceinline__ void gemm_phase(PG8_LAS unsigned char* lds, const Gemm g, const Sched& S, const Epi& E) {
;     ...
;             PG8_WAIT_L(8); PG8_BAR; PG8_WAIT_L(0); PG8_MMA(0, 0, At, B0); PG8_BAR; PG8_SCHED;
	s_waitcnt lgkmcnt(5)
	v_mfma_f32_16x16x32_bf16 v[110:113], v[130:133], v[162:165], v[110:113]
	v_mfma_f32_16x16x32_bf16 v[44:47], v[138:141], v[162:165], v[44:47]

; #define PG8_MMA(ai, bj, At, Bt) do { __builtin_amdgcn_s_setprio(1); _Pragma("unroll") for (int m = 0; m < 4; ++m) _Pragma("unroll") for (int n = 0; n < 2; ++n) _Pragma("unroll") for (int k = 0; k < 2; ++k) \
;         acc[ai][bj][m][n] = __builtin_amdgcn_mfma_f32_16x16x32_bf16(Bt[n][k], At[m][k], acc[ai][bj][m][n], 0, 0, 0); __builtin_amdgcn_s_setprio(0); } while (0)
; #define PG8_WAIT_L(n) asm volatile("s_waitcnt lgkmcnt(" #n ")" ::: "memory")
; #define PG8_BAR __builtin_amdgcn_s_barrier()
; #define PG8_SCHED __builtin_amdgcn_sched_barrier(0)
; template <class Epi, class Sched>
; __device__ __forceinline__ void gemm_phase(PG8_LAS unsigned char* lds, const Gemm g, const Sched& S, const Epi& E) {
;     ...
;             PG8_WAIT_L(8); PG8_BAR; PG8_WAIT_L(0); PG8_MMA(0, 0, At, B0); PG8_BAR; PG8_SCHED;
	s_waitcnt lgkmcnt(4)
	v_mfma_f32_16x16x32_bf16 v[102:105], v[130:133], v[170:173], v[102:105]
	v_mfma_f32_16x16x32_bf16 v[36:39], v[138:141], v[170:173], v[36:39]
	s_waitcnt lgkmcnt(3)
	v_mfma_f32_16x16x32_bf16 v[126:129], v[134:137], v[150:153], v[126:129]
	v_mfma_f32_16x16x32_bf16 v[62:65], v[142:145], v[150:153], v[62:65]
	s_waitcnt lgkmcnt(2)
	v_mfma_f32_16x16x32_bf16 v[118:121], v[134:137], v[158:161], v[118:121]
	v_mfma_f32_16x16x32_bf16 v[54:57], v[142:145], v[158:161], v[54:57]
	s_waitcnt lgkmcnt(1)
	v_mfma_f32_16x16x32_bf16 v[110:113], v[134:137], v[166:169], v[110:113]
	v_mfma_f32_16x16x32_bf16 v[44:47], v[142:145], v[166:169], v[44:47]

; #define PG8_STAGE(bufoff, gbase, voff) do { _Pragma("unroll") for (int _i = 0; _i < 2; ++_i) \
;         __builtin_amdgcn_global_load_lds((const unsigned*)((const char*)(gbase) + (voff)[_i]), (PG8_LAS unsigned*)(lds + (bufoff) + ldsw + _i * 8192), 16, 0, 0); } while (0)
; #define PG8_LDB(dst, b, h) do { _Pragma("unroll") for (int n = 0; n < 2; ++n) _Pragma("unroll") for (int k = 0; k < 2; ++k) dst[n][k] = *(const PG8_LAS bf16x8*)(lds + PG8_SB(b, h) + boff + n * 2048 + k * 1024); } while (0)
; template <class Epi, class Sched>
; __device__ __forceinline__ void gemm_phase(PG8_LAS unsigned char* lds, const Gemm g, const Sched& S, const Epi& E) {
;     ...
;             PG8_LDB(B1, 0, 1); PG8_STAGE(PG8_SB(0, 0), b2, voffB);
	s_waitcnt lgkmcnt(0)
	v_mfma_f32_16x16x32_bf16 v[102:105], v[134:137], v[188:191], v[102:105]
	v_mfma_f32_16x16x32_bf16 v[36:39], v[142:145], v[188:191], v[36:39]
	s_barrier
	s_add_i32 s31, 0, 0x14000
	s_add_i32 s22, s22, s36
	v_add_u32_e32 v48, s31, v250
	v_lshl_add_u64 v[208:209], s[12:13], 0, v[178:179]
	s_mov_b32 m0, s22
	ds_read_b128 v[192:195], v48
	ds_read_b128 v[200:203], v48 offset:2048
	ds_read_b128 v[196:199], v48 offset:1024
	ds_read_b128 v[204:207], v48 offset:3072
	global_load_lds_dwordx4 v[208:209], off
	s_add_i32 m0, s22, 0x2000
	v_lshl_add_u64 v[210:211], s[12:13], 0, v[182:183]
	global_load_lds_dwordx4 v[210:211], off
	s_barrier

; #define PG8_MMA(ai, bj, At, Bt) do { __builtin_amdgcn_s_setprio(1); _Pragma("unroll") for (int m = 0; m < 4; ++m) _Pragma("unroll") for (int n = 0; n < 2; ++n) _Pragma("unroll") for (int k = 0; k < 2; ++k) \
;         acc[ai][bj][m][n] = __builtin_amdgcn_mfma_f32_16x16x32_bf16(Bt[n][k], At[m][k], acc[ai][bj][m][n], 0, 0, 0); __builtin_amdgcn_s_setprio(0); } while (0)
; #define PG8_WAIT_L(n) asm volatile("s_waitcnt lgkmcnt(" #n ")" ::: "memory")
; #define PG8_BAR __builtin_amdgcn_s_barrier()
; template <class Epi, class Sched>
; __device__ __forceinline__ void gemm_phase(PG8_LAS unsigned char* lds, const Gemm g, const Sched& S, const Epi& E) {
;     ...
;             PG8_BAR; PG8_WAIT_L(0); PG8_MMA(0, 1, At, B1); PG8_BAR;
	s_waitcnt lgkmcnt(3)
	v_mfma_f32_16x16x32_bf16 v[122:125], v[192:195], v[146:149], v[122:125]

; #define PG8_MMA(ai, bj, At, Bt) do { __builtin_amdgcn_s_setprio(1); _Pragma("unroll") for (int m = 0; m < 4; ++m) _Pragma("unroll") for (int n = 0; n < 2; ++n) _Pragma("unroll") for (int k = 0; k < 2; ++k) \
;         acc[ai][bj][m][n] = __builtin_amdgcn_mfma_f32_16x16x32_bf16(Bt[n][k], At[m][k], acc[ai][bj][m][n], 0, 0, 0); __builtin_amdgcn_s_setprio(0); } while (0)
; #define PG8_WAIT_L(n) asm volatile("s_waitcnt lgkmcnt(" #n ")" ::: "memory")
; #define PG8_BAR __builtin_amdgcn_s_barrier()
; template <class Epi, class Sched>
; __device__ __forceinline__ void gemm_phase(PG8_LAS unsigned char* lds, const Gemm g, const Sched& S, const Epi& E) {
;     ...
;             PG8_BAR; PG8_WAIT_L(0); PG8_MMA(0, 1, At, B1); PG8_BAR;
	s_waitcnt lgkmcnt(2)
	v_mfma_f32_16x16x32_bf16 v[58:61], v[200:203], v[146:149], v[58:61]
	v_mfma_f32_16x16x32_bf16 v[114:117], v[192:195], v[154:157], v[114:117]
	v_mfma_f32_16x16x32_bf16 v[50:53], v[200:203], v[154:157], v[50:53]
	v_mfma_f32_16x16x32_bf16 v[106:109], v[192:195], v[162:165], v[106:109]
	v_mfma_f32_16x16x32_bf16 v[40:43], v[200:203], v[162:165], v[40:43]
	v_mfma_f32_16x16x32_bf16 v[98:101], v[192:195], v[170:173], v[98:101]
	v_mfma_f32_16x16x32_bf16 v[32:35], v[200:203], v[170:173], v[32:35]
	s_waitcnt lgkmcnt(1)
	v_mfma_f32_16x16x32_bf16 v[122:125], v[196:199], v[150:153], v[122:125]

; #define PG8_STAGE(bufoff, gbase, voff) do { _Pragma("unroll") for (int _i = 0; _i < 2; ++_i) \
;         __builtin_amdgcn_global_load_lds((const unsigned*)((const char*)(gbase) + (voff)[_i]), (PG8_LAS unsigned*)(lds + (bufoff) + ldsw + _i * 8192), 16, 0, 0); } while (0)
; #define PG8_LDA(dst, b, h) do { _Pragma("unroll") for (int m = 0; m < 4; ++m) _Pragma("unroll") for (int k = 0; k < 2; ++k) dst[m][k] = *(const PG8_LAS bf16x8*)(lds + PG8_SA(b, h) + aoff + m * 2048 + k * 1024); } while (0)
; #define PG8_MMA(ai, bj, At, Bt) do { __builtin_amdgcn_s_setprio(1); _Pragma("unroll") for (int m = 0; m < 4; ++m) _Pragma("unroll") for (int n = 0; n < 2; ++n) _Pragma("unroll") for (int k = 0; k < 2; ++k) \
;         acc[ai][bj][m][n] = __builtin_amdgcn_mfma_f32_16x16x32_bf16(Bt[n][k], At[m][k], acc[ai][bj][m][n], 0, 0, 0); __builtin_amdgcn_s_setprio(0); } while (0)
; #define PG8_WAIT_L(n) asm volatile("s_waitcnt lgkmcnt(" #n ")" ::: "memory")
; #define PG8_BAR __builtin_amdgcn_s_barrier()
; template <class Epi, class Sched>
; __device__ __forceinline__ void gemm_phase(PG8_LAS unsigned char* lds, const Gemm g, const Sched& S, const Epi& E) {
;     ...
;             PG8_BAR; PG8_WAIT_L(0); PG8_MMA(0, 1, At, B1); PG8_BAR;
;             PG8_LDA(At, 0, 1); PG8_STAGE(PG8_SA(0, 0), a2, voffA);
	s_waitcnt lgkmcnt(0)
	v_mfma_f32_16x16x32_bf16 v[58:61], v[204:207], v[150:153], v[58:61]
	v_mfma_f32_16x16x32_bf16 v[114:117], v[196:199], v[158:161], v[114:117]
	v_mfma_f32_16x16x32_bf16 v[50:53], v[204:207], v[158:161], v[50:53]
	v_mfma_f32_16x16x32_bf16 v[106:109], v[196:199], v[166:169], v[106:109]
	v_mfma_f32_16x16x32_bf16 v[40:43], v[204:207], v[166:169], v[40:43]
	v_mfma_f32_16x16x32_bf16 v[98:101], v[196:199], v[188:191], v[98:101]
	v_mfma_f32_16x16x32_bf16 v[32:35], v[204:207], v[188:191], v[32:35]
	s_mov_b32 m0, s37
	v_lshl_add_u64 v[212:213], s[16:17], 0, v[176:177]
	s_barrier
	ds_read_b128 v[146:149], v242 offset:16384
	ds_read_b128 v[154:157], v242 offset:18432
	ds_read_b128 v[162:165], v242 offset:20480
	ds_read_b128 v[170:173], v242 offset:22528
	ds_read_b128 v[150:153], v242 offset:17408
	ds_read_b128 v[158:161], v242 offset:19456
	ds_read_b128 v[166:169], v242 offset:21504
	ds_read_b128 v[188:191], v242 offset:23552
	global_load_lds_dwordx4 v[212:213], off
	s_mov_b32 m0, s10
	v_lshl_add_u64 v[214:215], s[16:17], 0, v[180:181]
	global_load_lds_dwordx4 v[214:215], off
	s_barrier

; #define PG8_MMA(ai, bj, At, Bt) do { __builtin_amdgcn_s_setprio(1); _Pragma("unroll") for (int m = 0; m < 4; ++m) _Pragma("unroll") for (int n = 0; n < 2; ++n) _Pragma("unroll") for (int k = 0; k < 2; ++k) \
;         acc[ai][bj][m][n] = __builtin_amdgcn_mfma_f32_16x16x32_bf16(Bt[n][k], At[m][k], acc[ai][bj][m][n], 0, 0, 0); __builtin_amdgcn_s_setprio(0); } while (0)
; #define PG8_WAIT_L(n) asm volatile("s_waitcnt lgkmcnt(" #n ")" ::: "memory")
; #define PG8_BAR __builtin_amdgcn_s_barrier()
; #define PG8_SCHED __builtin_amdgcn_sched_barrier(0)
; template <class Epi, class Sched>
; __device__ __forceinline__ void gemm_phase(PG8_LAS unsigned char* lds, const Gemm g, const Sched& S, const Epi& E) {
;     ...
;             PG8_BAR; PG8_WAIT_L(0); PG8_MMA(1, 0, At, B0); PG8_BAR; PG8_SCHED;
	s_waitcnt lgkmcnt(7)
	v_mfma_f32_16x16x32_bf16 v[94:97], v[130:133], v[146:149], v[94:97]
	v_mfma_f32_16x16x32_bf16 v[28:31], v[138:141], v[146:149], v[28:31]

; #define PG8_MMA(ai, bj, At, Bt) do { __builtin_amdgcn_s_setprio(1); _Pragma("unroll") for (int m = 0; m < 4; ++m) _Pragma("unroll") for (int n = 0; n < 2; ++n) _Pragma("unroll") for (int k = 0; k < 2; ++k) \
;         acc[ai][bj][m][n] = __builtin_amdgcn_mfma_f32_16x16x32_bf16(Bt[n][k], At[m][k], acc[ai][bj][m][n], 0, 0, 0); __builtin_amdgcn_s_setprio(0); } while (0)
; #define PG8_WAIT_L(n) asm volatile("s_waitcnt lgkmcnt(" #n ")" ::: "memory")
; #define PG8_BAR __builtin_amdgcn_s_barrier()
; #define PG8_SCHED __builtin_amdgcn_sched_barrier(0)
; template <class Epi, class Sched>
; __device__ __forceinline__ void gemm_phase(PG8_LAS unsigned char* lds, const Gemm g, const Sched& S, const Epi& E) {
;     ...
;             PG8_BAR; PG8_WAIT_L(0); PG8_MMA(1, 0, At, B0); PG8_BAR; PG8_SCHED;
	s_waitcnt lgkmcnt(6)
	v_mfma_f32_16x16x32_bf16 v[86:89], v[130:133], v[154:157], v[86:89]
	v_mfma_f32_16x16x32_bf16 v[20:23], v[138:141], v[154:157], v[20:23]

; #define PG8_MMA(ai, bj, At, Bt) do { __builtin_amdgcn_s_setprio(1); _Pragma("unroll") for (int m = 0; m < 4; ++m) _Pragma("unroll") for (int n = 0; n < 2; ++n) _Pragma("unroll") for (int k = 0; k < 2; ++k) \
;         acc[ai][bj][m][n] = __builtin_amdgcn_mfma_f32_16x16x32_bf16(Bt[n][k], At[m][k], acc[ai][bj][m][n], 0, 0, 0); __builtin_amdgcn_s_setprio(0); } while (0)
; #define PG8_WAIT_L(n) asm volatile("s_waitcnt lgkmcnt(" #n ")" ::: "memory")
; #define PG8_BAR __builtin_amdgcn_s_barrier()
; #define PG8_SCHED __builtin_amdgcn_sched_barrier(0)
; template <class Epi, class Sched>
; __device__ __forceinline__ void gemm_phase(PG8_LAS unsigned char* lds, const Gemm g, const Sched& S, const Epi& E) {
;     ...
;             PG8_BAR; PG8_WAIT_L(0); PG8_MMA(1, 0, At, B0); PG8_BAR; PG8_SCHED;
	s_waitcnt lgkmcnt(5)
	v_mfma_f32_16x16x32_bf16 v[78:81], v[130:133], v[162:165], v[78:81]
	v_mfma_f32_16x16x32_bf16 v[12:15], v[138:141], v[162:165], v[12:15]

; #define PG8_MMA(ai, bj, At, Bt) do { __builtin_amdgcn_s_setprio(1); _Pragma("unroll") for (int m = 0; m < 4; ++m) _Pragma("unroll") for (int n = 0; n < 2; ++n) _Pragma("unroll") for (int k = 0; k < 2; ++k) \
;         acc[ai][bj][m][n] = __builtin_amdgcn_mfma_f32_16x16x32_bf16(Bt[n][k], At[m][k], acc[ai][bj][m][n], 0, 0, 0); __builtin_amdgcn_s_setprio(0); } while (0)
; #define PG8_WAIT_L(n) asm volatile("s_waitcnt lgkmcnt(" #n ")" ::: "memory")
; #define PG8_BAR __builtin_amdgcn_s_barrier()
; #define PG8_SCHED __builtin_amdgcn_sched_barrier(0)
; template <class Epi, class Sched>
; __device__ __forceinline__ void gemm_phase(PG8_LAS unsigned char* lds, const Gemm g, const Sched& S, const Epi& E) {
;     ...
;             PG8_BAR; PG8_WAIT_L(0); PG8_MMA(1, 0, At, B0); PG8_BAR; PG8_SCHED;
	s_waitcnt lgkmcnt(4)
	v_mfma_f32_16x16x32_bf16 v[70:73], v[130:133], v[170:173], v[70:73]
	v_mfma_f32_16x16x32_bf16 v[4:7], v[138:141], v[170:173], v[4:7]
	s_waitcnt lgkmcnt(3)
	v_mfma_f32_16x16x32_bf16 v[94:97], v[134:137], v[150:153], v[94:97]
	v_mfma_f32_16x16x32_bf16 v[28:31], v[142:145], v[150:153], v[28:31]
	s_waitcnt lgkmcnt(2)
	v_mfma_f32_16x16x32_bf16 v[86:89], v[134:137], v[158:161], v[86:89]
	v_mfma_f32_16x16x32_bf16 v[20:23], v[142:145], v[158:161], v[20:23]
	s_waitcnt lgkmcnt(1)
	v_mfma_f32_16x16x32_bf16 v[78:81], v[134:137], v[166:169], v[78:81]
	v_mfma_f32_16x16x32_bf16 v[12:15], v[142:145], v[166:169], v[12:15]

; #define PG8_STAGE(bufoff, gbase, voff) do { _Pragma("unroll") for (int _i = 0; _i < 2; ++_i) \
;         __builtin_amdgcn_global_load_lds((const unsigned*)((const char*)(gbase) + (voff)[_i]), (PG8_LAS unsigned*)(lds + (bufoff) + ldsw + _i * 8192), 16, 0, 0); } while (0)
; #define PG8_LDA(dst, b, h) do { _Pragma("unroll") for (int m = 0; m < 4; ++m) _Pragma("unroll") for (int k = 0; k < 2; ++k) dst[m][k] = *(const PG8_LAS bf16x8*)(lds + PG8_SA(b, h) + aoff + m * 2048 + k * 1024); } while (0)
; #define PG8_LDB(dst, b, h) do { _Pragma("unroll") for (int n = 0; n < 2; ++n) _Pragma("unroll") for (int k = 0; k < 2; ++k) dst[n][k] = *(const PG8_LAS bf16x8*)(lds + PG8_SB(b, h) + boff + n * 2048 + k * 1024); } while (0)
; #define PG8_MMA(ai, bj, At, Bt) do { __builtin_amdgcn_s_setprio(1); _Pragma("unroll") for (int m = 0; m < 4; ++m) _Pragma("unroll") for (int n = 0; n < 2; ++n) _Pragma("unroll") for (int k = 0; k < 2; ++k) \
;         acc[ai][bj][m][n] = __builtin_amdgcn_mfma_f32_16x16x32_bf16(Bt[n][k], At[m][k], acc[ai][bj][m][n], 0, 0, 0); __builtin_amdgcn_s_setprio(0); } while (0)
; #define PG8_WAIT_V(n) asm volatile("s_waitcnt vmcnt(" #n ")" ::: "memory")
; #define PG8_WAIT_L(n) asm volatile("s_waitcnt lgkmcnt(" #n ")" ::: "memory")
; #define PG8_BAR __builtin_amdgcn_s_barrier()
; #define PG8_SCHED __builtin_amdgcn_sched_barrier(0)
; template <class Epi, class Sched>
; __device__ __forceinline__ void gemm_phase(PG8_LAS unsigned char* lds, const Gemm g, const Sched& S, const Epi& E) {
;     ...
;             PG8_BAR; PG8_WAIT_L(0); PG8_MMA(1, 0, At, B0); PG8_BAR; PG8_SCHED;
;             PG8_STAGE(PG8_SB(0, 1), b2 + hstep, voffB);
;             PG8_WAIT_V(6); PG8_BAR; PG8_MMA(1, 1, At, B1); PG8_BAR;
;             PG8_LDB(B0, 1, 0); PG8_SCHED; PG8_LDA(At, 1, 0); PG8_STAGE(PG8_SA(0, 1), a2 + hstep, voffA);
;             PG8_WAIT_L(8); PG8_BAR; PG8_WAIT_L(0); PG8_MMA(0, 0, At, B0); PG8_BAR; PG8_SCHED;
	s_waitcnt lgkmcnt(0)
	v_mfma_f32_16x16x32_bf16 v[70:73], v[134:137], v[188:191], v[70:73]
	v_mfma_f32_16x16x32_bf16 v[4:7], v[142:145], v[188:191], v[4:7]
	s_barrier
	s_add_u32 s22, s12, 0x40000
	s_addc_u32 s23, s13, 0
	s_add_i32 s31, s31, s36
	s_mov_b32 m0, s31
	v_lshl_add_u64 v[130:131], s[22:23], 0, v[178:179]
	global_load_lds_dwordx4 v[130:131], off
	s_add_i32 m0, s31, 0x2000
	v_lshl_add_u64 v[130:131], s[22:23], 0, v[182:183]
	global_load_lds_dwordx4 v[130:131], off
	s_waitcnt vmcnt(6)
	s_barrier
	v_mfma_f32_16x16x32_bf16 v[90:93], v[192:195], v[146:149], v[90:93]
	v_mfma_f32_16x16x32_bf16 v[24:27], v[200:203], v[146:149], v[24:27]
	v_mfma_f32_16x16x32_bf16 v[82:85], v[192:195], v[154:157], v[82:85]
	v_mfma_f32_16x16x32_bf16 v[16:19], v[200:203], v[154:157], v[16:19]
	v_mfma_f32_16x16x32_bf16 v[74:77], v[192:195], v[162:165], v[74:77]
	v_mfma_f32_16x16x32_bf16 v[8:11], v[200:203], v[162:165], v[8:11]
	v_mfma_f32_16x16x32_bf16 v[66:69], v[192:195], v[170:173], v[66:69]
	v_mfma_f32_16x16x32_bf16 v[0:3], v[200:203], v[170:173], v[0:3]
	v_mfma_f32_16x16x32_bf16 v[90:93], v[196:199], v[150:153], v[90:93]
	v_mfma_f32_16x16x32_bf16 v[24:27], v[204:207], v[150:153], v[24:27]
	v_mfma_f32_16x16x32_bf16 v[82:85], v[196:199], v[158:161], v[82:85]
	v_mfma_f32_16x16x32_bf16 v[16:19], v[204:207], v[158:161], v[16:19]
	v_mfma_f32_16x16x32_bf16 v[74:77], v[196:199], v[166:169], v[74:77]
	v_mfma_f32_16x16x32_bf16 v[8:11], v[204:207], v[166:169], v[8:11]
	v_mfma_f32_16x16x32_bf16 v[66:69], v[196:199], v[188:191], v[66:69]
	v_mfma_f32_16x16x32_bf16 v[0:3], v[204:207], v[188:191], v[0:3]
	s_add_i32 s22, 0, 0x18000
	v_add_u32_e32 v48, s22, v250
	s_barrier
	ds_read_b128 v[130:133], v48
	ds_read_b128 v[134:137], v48 offset:1024
	ds_read_b128 v[138:141], v48 offset:2048
	ds_read_b128 v[142:145], v48 offset:3072
	s_add_u32 s16, s16, 0x40000
	s_addc_u32 s17, s17, 0
	s_mov_b32 m0, s11
	v_lshl_add_u64 v[192:193], s[16:17], 0, v[176:177]
	ds_read_b128 v[146:149], v242 offset:32768
	ds_read_b128 v[154:157], v242 offset:34816
	ds_read_b128 v[162:165], v242 offset:36864
	ds_read_b128 v[170:173], v242 offset:38912
	ds_read_b128 v[150:153], v242 offset:33792
	ds_read_b128 v[158:161], v242 offset:35840
	ds_read_b128 v[166:169], v242 offset:37888
	ds_read_b128 v[188:191], v242 offset:39936
	global_load_lds_dwordx4 v[192:193], off
	s_mov_b32 m0, s24
	v_lshl_add_u64 v[192:193], s[16:17], 0, v[180:181]
	global_load_lds_dwordx4 v[192:193], off
	s_waitcnt lgkmcnt(8)
	s_barrier

; #define PG8_MMA(ai, bj, At, Bt) do { __builtin_amdgcn_s_setprio(1); _Pragma("unroll") for (int m = 0; m < 4; ++m) _Pragma("unroll") for (int n = 0; n < 2; ++n) _Pragma("unroll") for (int k = 0; k < 2; ++k) \
;         acc[ai][bj][m][n] = __builtin_amdgcn_mfma_f32_16x16x32_bf16(Bt[n][k], At[m][k], acc[ai][bj][m][n], 0, 0, 0); __builtin_amdgcn_s_setprio(0); } while (0)
; #define PG8_WAIT_L(n) asm volatile("s_waitcnt lgkmcnt(" #n ")" ::: "memory")
; #define PG8_BAR __builtin_amdgcn_s_barrier()
; #define PG8_SCHED __builtin_amdgcn_sched_barrier(0)
; template <class Epi, class Sched>
; __device__ __forceinline__ void gemm_phase(PG8_LAS unsigned char* lds, const Gemm g, const Sched& S, const Epi& E) {
;     ...
;             PG8_WAIT_L(8); PG8_BAR; PG8_WAIT_L(0); PG8_MMA(0, 0, At, B0); PG8_BAR; PG8_SCHED;
	s_waitcnt lgkmcnt(7)
	v_mfma_f32_16x16x32_bf16 v[126:129], v[130:133], v[146:149], v[126:129]
	v_mfma_f32_16x16x32_bf16 v[62:65], v[138:141], v[146:149], v[62:65]

; #define PG8_MMA(ai, bj, At, Bt) do { __builtin_amdgcn_s_setprio(1); _Pragma("unroll") for (int m = 0; m < 4; ++m) _Pragma("unroll") for (int n = 0; n < 2; ++n) _Pragma("unroll") for (int k = 0; k < 2; ++k) \
;         acc[ai][bj][m][n] = __builtin_amdgcn_mfma_f32_16x16x32_bf16(Bt[n][k], At[m][k], acc[ai][bj][m][n], 0, 0, 0); __builtin_amdgcn_s_setprio(0); } while (0)
; #define PG8_WAIT_L(n) asm volatile("s_waitcnt lgkmcnt(" #n ")" ::: "memory")
; #define PG8_BAR __builtin_amdgcn_s_barrier()
; #define PG8_SCHED __builtin_amdgcn_sched_barrier(0)
; template <class Epi, class Sched>
; __device__ __forceinline__ void gemm_phase(PG8_LAS unsigned char* lds, const Gemm g, const Sched& S, const Epi& E) {
;     ...
;             PG8_WAIT_L(8); PG8_BAR; PG8_WAIT_L(0); PG8_MMA(0, 0, At, B0); PG8_BAR; PG8_SCHED;
	s_waitcnt lgkmcnt(6)
	v_mfma_f32_16x16x32_bf16 v[118:121], v[130:133], v[154:157], v[118:121]
	v_mfma_f32_16x16x32_bf16 v[54:57], v[138:141], v[154:157], v[54:57]

; #define PG8_MMA(ai, bj, At, Bt) do { __builtin_amdgcn_s_setprio(1); _Pragma("unroll") for (int m = 0; m < 4; ++m) _Pragma("unroll") for (int n = 0; n < 2; ++n) _Pragma("unroll") for (int k = 0; k < 2; ++k) \
;         acc[ai][bj][m][n] = __builtin_amdgcn_mfma_f32_16x16x32_bf16(Bt[n][k], At[m][k], acc[ai][bj][m][n], 0, 0, 0); __builtin_amdgcn_s_setprio(0); } while (0)
; #define PG8_WAIT_L(n) asm volatile("s_waitcnt lgkmcnt(" #n ")" ::: "memory")
; #define PG8_BAR __builtin_amdgcn_s_barrier()
; #define PG8_SCHED __builtin_amdgcn_sched_barrier(0)
; template <class Epi, class Sched>
; __device__ __forceinline__ void gemm_phase(PG8_LAS unsigned char* lds, const Gemm g, const Sched& S, const Epi& E) {
;     ...
;             PG8_WAIT_L(8); PG8_BAR; PG8_WAIT_L(0); PG8_MMA(0, 0, At, B0); PG8_BAR; PG8_SCHED;
	s_waitcnt lgkmcnt(5)
	v_mfma_f32_16x16x32_bf16 v[110:113], v[130:133], v[162:165], v[110:113]
	v_mfma_f32_16x16x32_bf16 v[44:47], v[138:141], v[162:165], v[44:47]

; #define PG8_MMA(ai, bj, At, Bt) do { __builtin_amdgcn_s_setprio(1); _Pragma("unroll") for (int m = 0; m < 4; ++m) _Pragma("unroll") for (int n = 0; n < 2; ++n) _Pragma("unroll") for (int k = 0; k < 2; ++k) \
;         acc[ai][bj][m][n] = __builtin_amdgcn_mfma_f32_16x16x32_bf16(Bt[n][k], At[m][k], acc[ai][bj][m][n], 0, 0, 0); __builtin_amdgcn_s_setprio(0); } while (0)
; #define PG8_WAIT_L(n) asm volatile("s_waitcnt lgkmcnt(" #n ")" ::: "memory")
; #define PG8_BAR __builtin_amdgcn_s_barrier()
; #define PG8_SCHED __builtin_amdgcn_sched_barrier(0)
; template <class Epi, class Sched>
; __device__ __forceinline__ void gemm_phase(PG8_LAS unsigned char* lds, const Gemm g, const Sched& S, const Epi& E) {
;     ...
;             PG8_WAIT_L(8); PG8_BAR; PG8_WAIT_L(0); PG8_MMA(0, 0, At, B0); PG8_BAR; PG8_SCHED;
	s_waitcnt lgkmcnt(4)
	v_mfma_f32_16x16x32_bf16 v[102:105], v[130:133], v[170:173], v[102:105]
	v_mfma_f32_16x16x32_bf16 v[36:39], v[138:141], v[170:173], v[36:39]
	s_waitcnt lgkmcnt(3)
	v_mfma_f32_16x16x32_bf16 v[126:129], v[134:137], v[150:153], v[126:129]
	v_mfma_f32_16x16x32_bf16 v[62:65], v[142:145], v[150:153], v[62:65]
	s_waitcnt lgkmcnt(2)
	v_mfma_f32_16x16x32_bf16 v[118:121], v[134:137], v[158:161], v[118:121]
	v_mfma_f32_16x16x32_bf16 v[54:57], v[142:145], v[158:161], v[54:57]
	s_waitcnt lgkmcnt(1)
	v_mfma_f32_16x16x32_bf16 v[110:113], v[134:137], v[166:169], v[110:113]
	v_mfma_f32_16x16x32_bf16 v[44:47], v[142:145], v[166:169], v[44:47]

; #define PG8_STAGE(bufoff, gbase, voff) do { _Pragma("unroll") for (int _i = 0; _i < 2; ++_i) \
;         __builtin_amdgcn_global_load_lds((const unsigned*)((const char*)(gbase) + (voff)[_i]), (PG8_LAS unsigned*)(lds + (bufoff) + ldsw + _i * 8192), 16, 0, 0); } while (0)
; #define PG8_LDB(dst, b, h) do { _Pragma("unroll") for (int n = 0; n < 2; ++n) _Pragma("unroll") for (int k = 0; k < 2; ++k) dst[n][k] = *(const PG8_LAS bf16x8*)(lds + PG8_SB(b, h) + boff + n * 2048 + k * 1024); } while (0)
; #define PG8_MMA(ai, bj, At, Bt) do { __builtin_amdgcn_s_setprio(1); _Pragma("unroll") for (int m = 0; m < 4; ++m) _Pragma("unroll") for (int n = 0; n < 2; ++n) _Pragma("unroll") for (int k = 0; k < 2; ++k) \
;         acc[ai][bj][m][n] = __builtin_amdgcn_mfma_f32_16x16x32_bf16(Bt[n][k], At[m][k], acc[ai][bj][m][n], 0, 0, 0); __builtin_amdgcn_s_setprio(0); } while (0)
; #define PG8_WAIT_L(n) asm volatile("s_waitcnt lgkmcnt(" #n ")" ::: "memory")
; #define PG8_BAR __builtin_amdgcn_s_barrier()
; #define PG8_SCHED __builtin_amdgcn_sched_barrier(0)
; template <class Epi, class Sched>
; __device__ __forceinline__ void gemm_phase(PG8_LAS unsigned char* lds, const Gemm g, const Sched& S, const Epi& E) {
;     ...
;             PG8_WAIT_L(8); PG8_BAR; PG8_WAIT_L(0); PG8_MMA(0, 0, At, B0); PG8_BAR; PG8_SCHED;
;             PG8_LDB(B1, 1, 1); PG8_STAGE(PG8_SB(1, 0), b3, voffB);
	s_waitcnt lgkmcnt(0)
	v_mfma_f32_16x16x32_bf16 v[102:105], v[134:137], v[188:191], v[102:105]
	v_mfma_f32_16x16x32_bf16 v[36:39], v[142:145], v[188:191], v[36:39]
	s_barrier
	s_add_i32 s16, 0, 0x1c000
	s_add_i32 s17, s22, s36
	v_add_u32_e32 v48, s16, v250
	v_lshl_add_u64 v[208:209], v[208:209], 0, s[0:1]
	s_mov_b32 m0, s17
	ds_read_b128 v[192:195], v48
	ds_read_b128 v[200:203], v48 offset:2048
	ds_read_b128 v[196:199], v48 offset:1024
	ds_read_b128 v[204:207], v48 offset:3072
	global_load_lds_dwordx4 v[208:209], off
	s_add_i32 m0, s17, 0x2000
	v_lshl_add_u64 v[208:209], v[210:211], 0, s[0:1]
	global_load_lds_dwordx4 v[208:209], off
	s_barrier

; #define PG8_MMA(ai, bj, At, Bt) do { __builtin_amdgcn_s_setprio(1); _Pragma("unroll") for (int m = 0; m < 4; ++m) _Pragma("unroll") for (int n = 0; n < 2; ++n) _Pragma("unroll") for (int k = 0; k < 2; ++k) \
;         acc[ai][bj][m][n] = __builtin_amdgcn_mfma_f32_16x16x32_bf16(Bt[n][k], At[m][k], acc[ai][bj][m][n], 0, 0, 0); __builtin_amdgcn_s_setprio(0); } while (0)
; #define PG8_WAIT_L(n) asm volatile("s_waitcnt lgkmcnt(" #n ")" ::: "memory")
; #define PG8_BAR __builtin_amdgcn_s_barrier()
; template <class Epi, class Sched>
; __device__ __forceinline__ void gemm_phase(PG8_LAS unsigned char* lds, const Gemm g, const Sched& S, const Epi& E) {
;     ...
;             PG8_BAR; PG8_WAIT_L(0); PG8_MMA(0, 1, At, B1); PG8_BAR;
	s_waitcnt lgkmcnt(3)
	v_mfma_f32_16x16x32_bf16 v[122:125], v[192:195], v[146:149], v[122:125]

; #define PG8_MMA(ai, bj, At, Bt) do { __builtin_amdgcn_s_setprio(1); _Pragma("unroll") for (int m = 0; m < 4; ++m) _Pragma("unroll") for (int n = 0; n < 2; ++n) _Pragma("unroll") for (int k = 0; k < 2; ++k) \
;         acc[ai][bj][m][n] = __builtin_amdgcn_mfma_f32_16x16x32_bf16(Bt[n][k], At[m][k], acc[ai][bj][m][n], 0, 0, 0); __builtin_amdgcn_s_setprio(0); } while (0)
; #define PG8_WAIT_L(n) asm volatile("s_waitcnt lgkmcnt(" #n ")" ::: "memory")
; #define PG8_BAR __builtin_amdgcn_s_barrier()
; template <class Epi, class Sched>
; __device__ __forceinline__ void gemm_phase(PG8_LAS unsigned char* lds, const Gemm g, const Sched& S, const Epi& E) {
;     ...
;             PG8_BAR; PG8_WAIT_L(0); PG8_MMA(0, 1, At, B1); PG8_BAR;
	s_waitcnt lgkmcnt(2)
	v_mfma_f32_16x16x32_bf16 v[58:61], v[200:203], v[146:149], v[58:61]
	v_mfma_f32_16x16x32_bf16 v[114:117], v[192:195], v[154:157], v[114:117]
	v_mfma_f32_16x16x32_bf16 v[50:53], v[200:203], v[154:157], v[50:53]
	v_mfma_f32_16x16x32_bf16 v[106:109], v[192:195], v[162:165], v[106:109]
	v_mfma_f32_16x16x32_bf16 v[40:43], v[200:203], v[162:165], v[40:43]
	v_mfma_f32_16x16x32_bf16 v[98:101], v[192:195], v[170:173], v[98:101]
	v_mfma_f32_16x16x32_bf16 v[32:35], v[200:203], v[170:173], v[32:35]
	s_waitcnt lgkmcnt(1)
	v_mfma_f32_16x16x32_bf16 v[122:125], v[196:199], v[150:153], v[122:125]

; #define PG8_STAGE(bufoff, gbase, voff) do { _Pragma("unroll") for (int _i = 0; _i < 2; ++_i) \
;         __builtin_amdgcn_global_load_lds((const unsigned*)((const char*)(gbase) + (voff)[_i]), (PG8_LAS unsigned*)(lds + (bufoff) + ldsw + _i * 8192), 16, 0, 0); } while (0)
; #define PG8_LDA(dst, b, h) do { _Pragma("unroll") for (int m = 0; m < 4; ++m) _Pragma("unroll") for (int k = 0; k < 2; ++k) dst[m][k] = *(const PG8_LAS bf16x8*)(lds + PG8_SA(b, h) + aoff + m * 2048 + k * 1024); } while (0)
; #define PG8_MMA(ai, bj, At, Bt) do { __builtin_amdgcn_s_setprio(1); _Pragma("unroll") for (int m = 0; m < 4; ++m) _Pragma("unroll") for (int n = 0; n < 2; ++n) _Pragma("unroll") for (int k = 0; k < 2; ++k) \
;         acc[ai][bj][m][n] = __builtin_amdgcn_mfma_f32_16x16x32_bf16(Bt[n][k], At[m][k], acc[ai][bj][m][n], 0, 0, 0); __builtin_amdgcn_s_setprio(0); } while (0)
; #define PG8_WAIT_L(n) asm volatile("s_waitcnt lgkmcnt(" #n ")" ::: "memory")
; #define PG8_BAR __builtin_amdgcn_s_barrier()
; template <class Epi, class Sched>
; __device__ __forceinline__ void gemm_phase(PG8_LAS unsigned char* lds, const Gemm g, const Sched& S, const Epi& E) {
;     ...
;             PG8_BAR; PG8_WAIT_L(0); PG8_MMA(0, 1, At, B1); PG8_BAR;
;             PG8_LDA(At, 1, 1); PG8_STAGE(PG8_SA(1, 0), a3, voffA);
	s_waitcnt lgkmcnt(0)
	v_mfma_f32_16x16x32_bf16 v[58:61], v[204:207], v[150:153], v[58:61]
	v_mfma_f32_16x16x32_bf16 v[114:117], v[196:199], v[158:161], v[114:117]
	v_mfma_f32_16x16x32_bf16 v[50:53], v[204:207], v[158:161], v[50:53]
	v_mfma_f32_16x16x32_bf16 v[106:109], v[196:199], v[166:169], v[106:109]
	v_mfma_f32_16x16x32_bf16 v[40:43], v[204:207], v[166:169], v[40:43]
	v_mfma_f32_16x16x32_bf16 v[98:101], v[196:199], v[188:191], v[98:101]
	v_mfma_f32_16x16x32_bf16 v[32:35], v[204:207], v[188:191], v[32:35]
	s_mov_b32 m0, s25
	v_lshl_add_u64 v[208:209], v[212:213], 0, s[0:1]
	s_barrier
	ds_read_b128 v[146:149], v242 offset:49152
	ds_read_b128 v[154:157], v242 offset:51200
	ds_read_b128 v[162:165], v242 offset:53248
	ds_read_b128 v[170:173], v242 offset:55296
	ds_read_b128 v[150:153], v242 offset:50176
	ds_read_b128 v[158:161], v242 offset:52224
	ds_read_b128 v[166:169], v242 offset:54272
	ds_read_b128 v[188:191], v242 offset:56320
	global_load_lds_dwordx4 v[208:209], off
	s_mov_b32 m0, s18
	v_lshl_add_u64 v[208:209], v[214:215], 0, s[0:1]
	global_load_lds_dwordx4 v[208:209], off
	s_barrier

; #define PG8_MMA(ai, bj, At, Bt) do { __builtin_amdgcn_s_setprio(1); _Pragma("unroll") for (int m = 0; m < 4; ++m) _Pragma("unroll") for (int n = 0; n < 2; ++n) _Pragma("unroll") for (int k = 0; k < 2; ++k) \
;         acc[ai][bj][m][n] = __builtin_amdgcn_mfma_f32_16x16x32_bf16(Bt[n][k], At[m][k], acc[ai][bj][m][n], 0, 0, 0); __builtin_amdgcn_s_setprio(0); } while (0)
; #define PG8_WAIT_L(n) asm volatile("s_waitcnt lgkmcnt(" #n ")" ::: "memory")
; #define PG8_BAR __builtin_amdgcn_s_barrier()
; #define PG8_SCHED __builtin_amdgcn_sched_barrier(0)
; template <class Epi, class Sched>
; __device__ __forceinline__ void gemm_phase(PG8_LAS unsigned char* lds, const Gemm g, const Sched& S, const Epi& E) {
;     ...
;             PG8_BAR; PG8_WAIT_L(0); PG8_MMA(1, 0, At, B0); PG8_BAR; PG8_SCHED;
	s_waitcnt lgkmcnt(7)
	v_mfma_f32_16x16x32_bf16 v[94:97], v[130:133], v[146:149], v[94:97]
	v_mfma_f32_16x16x32_bf16 v[28:31], v[138:141], v[146:149], v[28:31]

; #define PG8_MMA(ai, bj, At, Bt) do { __builtin_amdgcn_s_setprio(1); _Pragma("unroll") for (int m = 0; m < 4; ++m) _Pragma("unroll") for (int n = 0; n < 2; ++n) _Pragma("unroll") for (int k = 0; k < 2; ++k) \
;         acc[ai][bj][m][n] = __builtin_amdgcn_mfma_f32_16x16x32_bf16(Bt[n][k], At[m][k], acc[ai][bj][m][n], 0, 0, 0); __builtin_amdgcn_s_setprio(0); } while (0)
; #define PG8_WAIT_L(n) asm volatile("s_waitcnt lgkmcnt(" #n ")" ::: "memory")
; #define PG8_BAR __builtin_amdgcn_s_barrier()
; #define PG8_SCHED __builtin_amdgcn_sched_barrier(0)
; template <class Epi, class Sched>
; __device__ __forceinline__ void gemm_phase(PG8_LAS unsigned char* lds, const Gemm g, const Sched& S, const Epi& E) {
;     ...
;             PG8_BAR; PG8_WAIT_L(0); PG8_MMA(1, 0, At, B0); PG8_BAR; PG8_SCHED;
	s_waitcnt lgkmcnt(6)
	v_mfma_f32_16x16x32_bf16 v[86:89], v[130:133], v[154:157], v[86:89]
	v_mfma_f32_16x16x32_bf16 v[20:23], v[138:141], v[154:157], v[20:23]

; #define PG8_MMA(ai, bj, At, Bt) do { __builtin_amdgcn_s_setprio(1); _Pragma("unroll") for (int m = 0; m < 4; ++m) _Pragma("unroll") for (int n = 0; n < 2; ++n) _Pragma("unroll") for (int k = 0; k < 2; ++k) \
;         acc[ai][bj][m][n] = __builtin_amdgcn_mfma_f32_16x16x32_bf16(Bt[n][k], At[m][k], acc[ai][bj][m][n], 0, 0, 0); __builtin_amdgcn_s_setprio(0); } while (0)
; #define PG8_WAIT_L(n) asm volatile("s_waitcnt lgkmcnt(" #n ")" ::: "memory")
; #define PG8_BAR __builtin_amdgcn_s_barrier()
; #define PG8_SCHED __builtin_amdgcn_sched_barrier(0)
; template <class Epi, class Sched>
; __device__ __forceinline__ void gemm_phase(PG8_LAS unsigned char* lds, const Gemm g, const Sched& S, const Epi& E) {
;     ...
;             PG8_BAR; PG8_WAIT_L(0); PG8_MMA(1, 0, At, B0); PG8_BAR; PG8_SCHED;
	s_waitcnt lgkmcnt(5)
	v_mfma_f32_16x16x32_bf16 v[78:81], v[130:133], v[162:165], v[78:81]
	v_mfma_f32_16x16x32_bf16 v[12:15], v[138:141], v[162:165], v[12:15]

; #define PG8_MMA(ai, bj, At, Bt) do { __builtin_amdgcn_s_setprio(1); _Pragma("unroll") for (int m = 0; m < 4; ++m) _Pragma("unroll") for (int n = 0; n < 2; ++n) _Pragma("unroll") for (int k = 0; k < 2; ++k) \
;         acc[ai][bj][m][n] = __builtin_amdgcn_mfma_f32_16x16x32_bf16(Bt[n][k], At[m][k], acc[ai][bj][m][n], 0, 0, 0); __builtin_amdgcn_s_setprio(0); } while (0)
; #define PG8_WAIT_L(n) asm volatile("s_waitcnt lgkmcnt(" #n ")" ::: "memory")
; #define PG8_BAR __builtin_amdgcn_s_barrier()
; #define PG8_SCHED __builtin_amdgcn_sched_barrier(0)
; template <class Epi, class Sched>
; __device__ __forceinline__ void gemm_phase(PG8_LAS unsigned char* lds, const Gemm g, const Sched& S, const Epi& E) {
;     ...
;             PG8_BAR; PG8_WAIT_L(0); PG8_MMA(1, 0, At, B0); PG8_BAR; PG8_SCHED;
	s_waitcnt lgkmcnt(4)
	v_mfma_f32_16x16x32_bf16 v[70:73], v[130:133], v[170:173], v[70:73]
	v_mfma_f32_16x16x32_bf16 v[4:7], v[138:141], v[170:173], v[4:7]
	s_waitcnt lgkmcnt(3)
	v_mfma_f32_16x16x32_bf16 v[94:97], v[134:137], v[150:153], v[94:97]
	v_mfma_f32_16x16x32_bf16 v[28:31], v[142:145], v[150:153], v[28:31]
	s_waitcnt lgkmcnt(2)
	v_mfma_f32_16x16x32_bf16 v[86:89], v[134:137], v[158:161], v[86:89]
	v_mfma_f32_16x16x32_bf16 v[20:23], v[142:145], v[158:161], v[20:23]
	s_waitcnt lgkmcnt(1)
	v_mfma_f32_16x16x32_bf16 v[78:81], v[134:137], v[166:169], v[78:81]
	v_mfma_f32_16x16x32_bf16 v[12:15], v[142:145], v[166:169], v[12:15]

; #define PG8_STAGE(bufoff, gbase, voff) do { _Pragma("unroll") for (int _i = 0; _i < 2; ++_i) \
;         __builtin_amdgcn_global_load_lds((const unsigned*)((const char*)(gbase) + (voff)[_i]), (PG8_LAS unsigned*)(lds + (bufoff) + ldsw + _i * 8192), 16, 0, 0); } while (0)
; #define PG8_MMA(ai, bj, At, Bt) do { __builtin_amdgcn_s_setprio(1); _Pragma("unroll") for (int m = 0; m < 4; ++m) _Pragma("unroll") for (int n = 0; n < 2; ++n) _Pragma("unroll") for (int k = 0; k < 2; ++k) \
;         acc[ai][bj][m][n] = __builtin_amdgcn_mfma_f32_16x16x32_bf16(Bt[n][k], At[m][k], acc[ai][bj][m][n], 0, 0, 0); __builtin_amdgcn_s_setprio(0); } while (0)
; #define PG8_WAIT_V(n) asm volatile("s_waitcnt vmcnt(" #n ")" ::: "memory")
; #define PG8_WAIT_L(n) asm volatile("s_waitcnt lgkmcnt(" #n ")" ::: "memory")
; #define PG8_BAR __builtin_amdgcn_s_barrier()
; #define PG8_SCHED __builtin_amdgcn_sched_barrier(0)
; template <class Epi, class Sched>
; __device__ __forceinline__ void gemm_phase(PG8_LAS unsigned char* lds, const Gemm g, const Sched& S, const Epi& E) {
;     ...
;         for (int t = 0; t < nt; t += 2) {
;     ...
;             PG8_BAR; PG8_WAIT_L(0); PG8_MMA(1, 0, At, B0); PG8_BAR; PG8_SCHED;
;             PG8_STAGE(PG8_SB(1, 1), b3 + hstep, voffB);
;             PG8_WAIT_V(6); PG8_BAR; PG8_MMA(1, 1, At, B1); PG8_BAR;
;         }
	s_waitcnt lgkmcnt(0)
	v_mfma_f32_16x16x32_bf16 v[70:73], v[134:137], v[188:191], v[70:73]
	v_mfma_f32_16x16x32_bf16 v[4:7], v[142:145], v[188:191], v[4:7]
	s_barrier
	s_add_u32 s12, s12, 0x40080
	s_addc_u32 s13, s13, 0
	s_add_i32 s16, s16, s36
	s_mov_b32 m0, s16
	v_lshl_add_u64 v[130:131], s[12:13], 0, v[178:179]
	global_load_lds_dwordx4 v[130:131], off
	s_add_i32 m0, s16, 0x2000
	v_lshl_add_u64 v[130:131], s[12:13], 0, v[182:183]
	global_load_lds_dwordx4 v[130:131], off
	s_waitcnt vmcnt(6)
	s_barrier
	v_mfma_f32_16x16x32_bf16 v[90:93], v[192:195], v[146:149], v[90:93]
	v_mfma_f32_16x16x32_bf16 v[24:27], v[200:203], v[146:149], v[24:27]
	v_mfma_f32_16x16x32_bf16 v[82:85], v[192:195], v[154:157], v[82:85]
	v_mfma_f32_16x16x32_bf16 v[16:19], v[200:203], v[154:157], v[16:19]
	v_mfma_f32_16x16x32_bf16 v[74:77], v[192:195], v[162:165], v[74:77]
	v_mfma_f32_16x16x32_bf16 v[8:11], v[200:203], v[162:165], v[8:11]
	v_mfma_f32_16x16x32_bf16 v[66:69], v[192:195], v[170:173], v[66:69]
	v_mfma_f32_16x16x32_bf16 v[0:3], v[200:203], v[170:173], v[0:3]
	v_mfma_f32_16x16x32_bf16 v[90:93], v[196:199], v[150:153], v[90:93]
	v_mfma_f32_16x16x32_bf16 v[24:27], v[204:207], v[150:153], v[24:27]
	v_mfma_f32_16x16x32_bf16 v[82:85], v[196:199], v[158:161], v[82:85]
	v_mfma_f32_16x16x32_bf16 v[16:19], v[204:207], v[158:161], v[16:19]
	v_mfma_f32_16x16x32_bf16 v[74:77], v[196:199], v[166:169], v[74:77]
	v_mfma_f32_16x16x32_bf16 v[8:11], v[204:207], v[166:169], v[8:11]
	v_mfma_f32_16x16x32_bf16 v[66:69], v[196:199], v[188:191], v[66:69]
	v_mfma_f32_16x16x32_bf16 v[0:3], v[204:207], v[188:191], v[0:3]
	s_add_i32 s30, s30, 2
	s_add_u32 s6, s6, 0x100
	s_addc_u32 s7, s7, 0
	s_add_u32 s27, s27, 0x100
	s_addc_u32 s29, s29, 0
	s_cmp_gt_u32 s30, 13
	s_barrier
	s_cbranch_scc0 .LBB0_388
